# GEMM k-tile staging groups moved earlier (after MFMA 1,4,7,10) so the last LDS writes are not right before the barrier
# baseline (speedup 1.0000x reference)
; #define MFMA(a, b, c) __builtin_amdgcn_mfma_f32_32x32x16_bf16((a), (b), (c), 0, 0, 0)
; template <int TM, int TN>
; DI void gemm_mainloop(const u16* __restrict__ A, long lda, const u16* __restrict__ Bt, long ldb, int K, char* smem,
;                       f32x16 (&acc)[TM][TN]) {
;     ...
;   const int nk = K / 64;
;   const int lrow = tid >> 3, lch = (tid & 7) * 8;
;   const u16* gA = A + (long)lrow * lda + lch;
;   const u16* gB = Bt + (long)lrow * ldb + lch;
;   const int soff = lrow * LD + lch;
;     ...
;   GEMM_GLOAD(0)
;   __syncthreads();
;   GEMM_SSTORE(0)
;   if (nk > 1) GEMM_GLOAD(64)
;   __syncthreads();
;   for (int kt = 0; kt < nk; kt++) {
;     const int buf = kt & 1;
;     const u16* cA = sA + buf * BM * LD + (wm * 32 * TM + r) * LD + h * 8;
;     const u16* cB = sB + buf * BN * LD + (wn * 32 * TN + r) * LD + h * 8;
;     bf16x8 af[TM], bfr[TN];
; #pragma unroll
;     for (int tm = 0; tm < TM; tm++) af[tm] = *(const bf16x8*)(cA + tm * 32 * LD);
; #pragma unroll
;     for (int tn = 0; tn < TN; tn++) bfr[tn] = *(const bf16x8*)(cB + tn * 32 * LD);
;     if (kt + 1 < nk) GEMM_SSTORE(buf ^ 1)
;     __builtin_amdgcn_sched_barrier(0);
;     __builtin_amdgcn_s_setprio(1);
; #pragma unroll
;     for (int tm = 0; tm < TM; tm++)
; #pragma unroll
;       for (int tn = 0; tn < TN; tn++) acc[tm][tn] = MFMA(af[tm], bfr[tn], acc[tm][tn]);
; #pragma unroll
;     for (int tm = 0; tm < TM; tm++) af[tm] = *(const bf16x8*)(cA + tm * 32 * LD + 16);
; #pragma unroll
;     for (int tn = 0; tn < TN; tn++) bfr[tn] = *(const bf16x8*)(cB + tn * 32 * LD + 16);
; #pragma unroll
;     for (int tm = 0; tm < TM; tm++)
; #pragma unroll
;       for (int tn = 0; tn < TN; tn++) acc[tm][tn] = MFMA(af[tm], bfr[tn], acc[tm][tn]);
; template <class Epi>
; DI void phase_gemm128(const Sched& sc, const u16* A, long lda, const u16* Bt, long ldb, int K, int MT, int NT, int SN, char* smem, const Epi& epi) {
;     ...
;     for (int st = xg; st < nfull; st += 8) {
;       int sm = st / sng, sn = st % sng;
;       int mt = sm * SM + xi / SN, nt = sn * SN + xi % SN;
;       gemm_tile<2, 2>(A, lda, Bt, ldb, K, mt * 128, nt * 128, smem, epi);
.LBB0_146:
	s_mul_hi_u32 s4, s36, 0xcccccccd
	s_lshr_b32 s4, s4, 2
	s_mul_i32 s5, s4, 5
	s_sub_i32 s5, s36, s5
	s_lshl_b32 s37, s4, 11
	s_add_i32 s37, s37, s3
	s_lshl_b32 s4, s5, 9
	s_add_i32 s4, s4, s20
	s_mul_i32 s16, s37, 0x880
	s_mul_hi_i32 s5, s37, 0x880
	s_add_u32 s16, s8, s16
	v_mov_b32_e32 v1, v0
	s_addc_u32 s17, s9, s5
	s_mul_i32 s5, s4, 0x880
	v_lshlrev_b32_e32 v2, 3, v1
	v_ashrrev_i32_e32 v68, 3, v1
	v_and_b32_e32 v69, 56, v2
	v_mov_b64_e32 v[2:3], s[16:17]
	v_mad_i64_i32 v[2:3], s[16:17], v68, s21, v[2:3]
	v_lshlrev_b32_e32 v66, 1, v69
	v_lshl_add_u64 v[72:73], v[2:3], 0, v[66:67]
	s_ashr_i32 s19, s5, 31
	v_add_co_u32_e32 v70, vcc, s23, v72
	s_add_u32 s18, s10, s5
	s_nop 0
	v_addc_co_u32_e32 v71, vcc, 0, v73, vcc
	s_addc_u32 s19, s11, s19
	v_add_co_u32_e32 v74, vcc, s24, v72
	v_mov_b64_e32 v[2:3], s[18:19]
	s_nop 0
	v_addc_co_u32_e32 v75, vcc, 0, v73, vcc
	v_mad_i64_i32 v[18:19], s[16:17], v68, s21, v[2:3]
	v_add_co_u32_e32 v76, vcc, s25, v72
	v_lshl_add_u64 v[78:79], v[18:19], 0, v[66:67]
	s_nop 0
	v_addc_co_u32_e32 v77, vcc, 0, v73, vcc
	v_add_co_u32_e32 v80, vcc, s23, v78
	global_load_dwordx4 v[2:5], v[72:73], off
	s_nop 0
	v_addc_co_u32_e32 v81, vcc, 0, v79, vcc
	v_add_co_u32_e32 v82, vcc, s24, v78
	global_load_dwordx4 v[6:9], v[70:71], off
	s_nop 0
	v_addc_co_u32_e32 v83, vcc, 0, v79, vcc
	v_add_co_u32_e32 v84, vcc, s25, v78
	global_load_dwordx4 v[10:13], v[74:75], off
	s_nop 0
	v_addc_co_u32_e32 v85, vcc, 0, v79, vcc
	global_load_dwordx4 v[14:17], v[76:77], off
	global_load_dwordx4 v[18:21], v[78:79], off
	global_load_dwordx4 v[22:25], v[80:81], off
	global_load_dwordx4 v[26:29], v[82:83], off
	global_load_dwordx4 v[30:33], v[84:85], off
	s_barrier
	global_load_dwordx4 v[34:37], v[72:73], off offset:128
	global_load_dwordx4 v[38:41], v[70:71], off offset:128
	global_load_dwordx4 v[42:45], v[74:75], off offset:128
	global_load_dwordx4 v[46:49], v[76:77], off offset:128
	global_load_dwordx4 v[50:53], v[78:79], off offset:128
	global_load_dwordx4 v[54:57], v[80:81], off offset:128
	global_load_dwordx4 v[58:61], v[82:83], off offset:128
	global_load_dwordx4 v[62:65], v[84:85], off offset:128
	v_and_b32_e32 v66, 31, v1
	v_lshrrev_b32_e32 v86, 1, v1
	v_and_b32_e32 v1, 0x5f, v1
	v_mul_lo_u32 v68, v68, s22
	v_and_or_b32 v87, v86, s26, v66
	v_and_b32_e32 v86, 16, v86
	v_add_lshl_u32 v66, v68, v69, 1
	v_mad_u64_u32 v[68:69], s[16:17], v87, s27, v[86:87]
	v_mad_u32_u24 v1, v1, s27, v86
	v_add_u32_e32 v69, 0x9000, v66
	s_waitcnt vmcnt(15)
	ds_write_b128 v66, v[2:5]
	s_waitcnt vmcnt(14)
	ds_write_b128 v66, v[6:9] offset:4608
	s_waitcnt vmcnt(13)
	ds_write_b128 v66, v[10:13] offset:9216
	s_waitcnt vmcnt(12)
	ds_write_b128 v66, v[14:17] offset:13824
	s_waitcnt vmcnt(11)
	ds_write_b128 v66, v[18:21] offset:36864
	s_waitcnt vmcnt(10)
	ds_write_b128 v66, v[22:25] offset:41472
	s_waitcnt vmcnt(9)
	ds_write_b128 v66, v[26:29] offset:46080
	s_waitcnt vmcnt(8)
	ds_write_b128 v66, v[30:33] offset:50688
	s_waitcnt lgkmcnt(0)
	s_barrier
	ds_read_b128 v[2:5], v68
	ds_read_b128 v[18:21], v68 offset:4608
	ds_read_b128 v[6:9], v1 offset:36864
	ds_read_b128 v[22:25], v1 offset:41472
	s_waitcnt vmcnt(7)
	ds_write_b128 v66, v[34:37] offset:18432
	s_waitcnt vmcnt(6)
	ds_write_b128 v66, v[38:41] offset:23040
	s_waitcnt vmcnt(5)
	ds_write_b128 v66, v[42:45] offset:27648
	s_waitcnt vmcnt(4)
	ds_write_b128 v66, v[46:49] offset:32256
	s_waitcnt vmcnt(3)
	ds_write_b128 v66, v[50:53] offset:55296
	s_waitcnt vmcnt(2)
	ds_write_b128 v66, v[54:57] offset:59904
	s_waitcnt vmcnt(1)
	ds_write_b128 v66, v[58:61] offset:64512
	s_waitcnt vmcnt(0)
	ds_write_b128 v69, v[62:65] offset:32256
	s_setprio 1
	ds_read_b128 v[86:89], v68 offset:32
	s_waitcnt lgkmcnt(10)
	v_mfma_f32_32x32x16_bf16 v[34:49], v[2:5], v[6:9], 0
	ds_read_b128 v[90:93], v1 offset:36896
	ds_read_b128 v[94:97], v1 offset:41504
	ds_read_b128 v[98:101], v68 offset:4704
	global_load_dwordx4 v[102:105], v[70:71], off offset:256
	global_load_dwordx4 v[106:109], v[74:75], off offset:256
	global_load_dwordx4 v[110:113], v[76:77], off offset:256
	global_load_dwordx4 v[114:117], v[84:85], off offset:256
	s_waitcnt lgkmcnt(12)
	v_mfma_f32_32x32x16_bf16 v[50:65], v[2:5], v[22:25], 0
	global_load_dwordx4 v[118:121], v[82:83], off offset:256
	global_load_dwordx4 v[122:125], v[80:81], off offset:256
	global_load_dwordx4 v[140:143], v[72:73], off offset:256
	global_load_dwordx4 v[144:147], v[78:79], off offset:256
	s_waitcnt lgkmcnt(2)
	v_mfma_f32_32x32x16_bf16 v[34:49], v[86:89], v[90:93], v[34:49]
	s_waitcnt lgkmcnt(1)
	v_mfma_f32_32x32x16_bf16 v[50:65], v[86:89], v[94:97], v[50:65]
	ds_read_b128 v[86:89], v68 offset:4640
	v_mfma_f32_32x32x16_bf16 v[2:17], v[18:21], v[6:9], 0
	v_mfma_f32_32x32x16_bf16 v[18:33], v[18:21], v[22:25], 0
	s_waitcnt lgkmcnt(0)
	v_mfma_f32_32x32x16_bf16 v[2:17], v[86:89], v[90:93], v[2:17]
	ds_read_b128 v[90:93], v1 offset:36928
	v_mfma_f32_32x32x16_bf16 v[18:33], v[86:89], v[94:97], v[18:33]
	ds_read_b128 v[86:89], v68 offset:64
	ds_read_b128 v[94:97], v1 offset:41536
	s_waitcnt lgkmcnt(1)
	v_mfma_f32_32x32x16_bf16 v[34:49], v[86:89], v[90:93], v[34:49]
	s_waitcnt lgkmcnt(0)
	v_mfma_f32_32x32x16_bf16 v[50:65], v[86:89], v[94:97], v[50:65]
	ds_read_b128 v[86:89], v68 offset:4672
	s_waitcnt lgkmcnt(0)
	v_mfma_f32_32x32x16_bf16 v[2:17], v[86:89], v[90:93], v[2:17]
	ds_read_b128 v[90:93], v1 offset:36960
	v_mfma_f32_32x32x16_bf16 v[18:33], v[86:89], v[94:97], v[18:33]
	ds_read_b128 v[86:89], v68 offset:96
	ds_read_b128 v[94:97], v1 offset:41568
	s_waitcnt lgkmcnt(1)
	v_mfma_f32_32x32x16_bf16 v[34:49], v[86:89], v[90:93], v[34:49]
	s_waitcnt lgkmcnt(0)
	v_mfma_f32_32x32x16_bf16 v[50:65], v[86:89], v[94:97], v[50:65]
	v_mfma_f32_32x32x16_bf16 v[2:17], v[98:101], v[90:93], v[2:17]
	v_mfma_f32_32x32x16_bf16 v[18:33], v[98:101], v[94:97], v[18:33]
	s_setprio 0
	s_barrier
; #define MFMA(a, b, c) __builtin_amdgcn_mfma_f32_32x32x16_bf16((a), (b), (c), 0, 0, 0)
; template <int TM, int TN>
; DI void gemm_mainloop(const u16* __restrict__ A, long lda, const u16* __restrict__ Bt, long ldb, int K, char* smem,
;                       f32x16 (&acc)[TM][TN]) {
;     ...
;   for (int kt = 0; kt < nk; kt++) {
;     const int buf = kt & 1;
;     const u16* cA = sA + buf * BM * LD + (wm * 32 * TM + r) * LD + h * 8;
;     const u16* cB = sB + buf * BN * LD + (wn * 32 * TN + r) * LD + h * 8;
;     bf16x8 af[TM], bfr[TN];
; #pragma unroll
;     for (int tm = 0; tm < TM; tm++) af[tm] = *(const bf16x8*)(cA + tm * 32 * LD);
; #pragma unroll
;     for (int tn = 0; tn < TN; tn++) bfr[tn] = *(const bf16x8*)(cB + tn * 32 * LD);
;     if (kt + 1 < nk) GEMM_SSTORE(buf ^ 1)
;     __builtin_amdgcn_sched_barrier(0);
;     __builtin_amdgcn_s_setprio(1);
; #pragma unroll
;     for (int tm = 0; tm < TM; tm++)
; #pragma unroll
;       for (int tn = 0; tn < TN; tn++) acc[tm][tn] = MFMA(af[tm], bfr[tn], acc[tm][tn]);
; #pragma unroll
;     for (int tm = 0; tm < TM; tm++) af[tm] = *(const bf16x8*)(cA + tm * 32 * LD + 16);
; #pragma unroll
;     for (int tn = 0; tn < TN; tn++) bfr[tn] = *(const bf16x8*)(cB + tn * 32 * LD + 16);
; #pragma unroll
;     for (int tm = 0; tm < TM; tm++)
; #pragma unroll
;       for (int tn = 0; tn < TN; tn++) acc[tm][tn] = MFMA(af[tm], bfr[tn], acc[tm][tn]);
;     __builtin_amdgcn_sched_group_barrier(0x8, 4, 0);
;     if (kt + 2 < nk) GEMM_GLOAD((kt + 2) * 64)
; #pragma unroll
;     for (int ks = 2; ks < 4; ks++) {
; #pragma unroll
;       for (int tm = 0; tm < TM; tm++) af[tm] = *(const bf16x8*)(cA + tm * 32 * LD + ks * 16);
; #pragma unroll
;       for (int tn = 0; tn < TN; tn++) bfr[tn] = *(const bf16x8*)(cB + tn * 32 * LD + ks * 16);
; #pragma unroll
;       for (int tm = 0; tm < TM; tm++)
; #pragma unroll
;         for (int tn = 0; tn < TN; tn++) acc[tm][tn] = MFMA(af[tm], bfr[tn], acc[tm][tn]);
;     }
;     __builtin_amdgcn_s_setprio(0);
;     __syncthreads();
;   }
	ds_read_b128 v[94:97], v68 offset:18432
	ds_read_b128 v[98:101], v68 offset:23040
	ds_read_b128 v[126:129], v1 offset:55296
	ds_read_b128 v[130:133], v1 offset:59904
	s_setprio 1
	ds_read_b128 v[86:89], v68 offset:18464
	s_waitcnt lgkmcnt(2)
	v_mfma_f32_32x32x16_bf16 v[34:49], v[94:97], v[126:129], v[34:49]
	s_waitcnt vmcnt(1)
	ds_write_b128 v66, v[140:143]
	ds_write_b128 v66, v[102:105] offset:4608
	global_load_dwordx4 v[140:143], v[72:73], off offset:384
	global_load_dwordx4 v[102:105], v[70:71], off offset:384
	ds_read_b128 v[90:93], v1 offset:55328
	s_waitcnt lgkmcnt(4)
	v_mfma_f32_32x32x16_bf16 v[50:65], v[94:97], v[130:133], v[50:65]
	ds_read_b128 v[94:97], v1 offset:59936
	s_waitcnt lgkmcnt(1)
	v_mfma_f32_32x32x16_bf16 v[34:49], v[86:89], v[90:93], v[34:49]
	s_waitcnt lgkmcnt(0)
	v_mfma_f32_32x32x16_bf16 v[50:65], v[86:89], v[94:97], v[50:65]
	ds_write_b128 v66, v[106:109] offset:9216
	ds_write_b128 v66, v[110:113] offset:13824
	global_load_dwordx4 v[106:109], v[74:75], off offset:384
	global_load_dwordx4 v[110:113], v[76:77], off offset:384
	ds_read_b128 v[86:89], v68 offset:23072
	v_mfma_f32_32x32x16_bf16 v[2:17], v[98:101], v[126:129], v[2:17]
	v_mfma_f32_32x32x16_bf16 v[18:33], v[98:101], v[130:133], v[18:33]
	ds_read_b128 v[98:101], v68 offset:23136
	s_waitcnt lgkmcnt(1)
	v_mfma_f32_32x32x16_bf16 v[2:17], v[86:89], v[90:93], v[2:17]
	s_waitcnt vmcnt(4)
	ds_write_b128 v66, v[144:147] offset:36864
	ds_write_b128 v66, v[122:125] offset:41472
	global_load_dwordx4 v[144:147], v[78:79], off offset:384
	global_load_dwordx4 v[122:125], v[80:81], off offset:384
	ds_read_b128 v[90:93], v1 offset:55360
	v_mfma_f32_32x32x16_bf16 v[18:33], v[86:89], v[94:97], v[18:33]
	ds_read_b128 v[86:89], v68 offset:18496
	ds_read_b128 v[94:97], v1 offset:59968
	s_waitcnt lgkmcnt(1)
	v_mfma_f32_32x32x16_bf16 v[34:49], v[86:89], v[90:93], v[34:49]
	s_waitcnt lgkmcnt(0)
	v_mfma_f32_32x32x16_bf16 v[50:65], v[86:89], v[94:97], v[50:65]
	ds_write_b128 v66, v[118:121] offset:46080
	ds_write_b128 v66, v[114:117] offset:50688
	global_load_dwordx4 v[118:121], v[82:83], off offset:384
	global_load_dwordx4 v[114:117], v[84:85], off offset:384
	ds_read_b128 v[86:89], v68 offset:23104
	s_waitcnt lgkmcnt(0)
	v_mfma_f32_32x32x16_bf16 v[2:17], v[86:89], v[90:93], v[2:17]
	ds_read_b128 v[90:93], v1 offset:55392
	v_mfma_f32_32x32x16_bf16 v[18:33], v[86:89], v[94:97], v[18:33]
	ds_read_b128 v[86:89], v68 offset:18528
	ds_read_b128 v[94:97], v1 offset:60000
	s_waitcnt lgkmcnt(1)
	v_mfma_f32_32x32x16_bf16 v[34:49], v[86:89], v[90:93], v[34:49]
	s_waitcnt lgkmcnt(0)
	v_mfma_f32_32x32x16_bf16 v[50:65], v[86:89], v[94:97], v[50:65]
	v_mfma_f32_32x32x16_bf16 v[2:17], v[98:101], v[90:93], v[2:17]
	v_mfma_f32_32x32x16_bf16 v[18:33], v[98:101], v[94:97], v[18:33]
	s_setprio 0
	s_barrier
	ds_read_b128 v[94:97], v68
	ds_read_b128 v[98:101], v68 offset:4608
	ds_read_b128 v[126:129], v1 offset:36864
	ds_read_b128 v[130:133], v1 offset:41472
	s_setprio 1
	ds_read_b128 v[86:89], v68 offset:32
	s_waitcnt lgkmcnt(2)
	v_mfma_f32_32x32x16_bf16 v[34:49], v[94:97], v[126:129], v[34:49]
	s_waitcnt vmcnt(7)
	ds_write_b128 v66, v[140:143] offset:18432
	s_waitcnt vmcnt(6)
	ds_write_b128 v66, v[102:105] offset:23040
	global_load_dwordx4 v[140:143], v[72:73], off offset:512
	global_load_dwordx4 v[102:105], v[70:71], off offset:512
	ds_read_b128 v[90:93], v1 offset:36896
	s_waitcnt lgkmcnt(4)
	v_mfma_f32_32x32x16_bf16 v[50:65], v[94:97], v[130:133], v[50:65]
	ds_read_b128 v[94:97], v1 offset:41504
	s_waitcnt lgkmcnt(1)
	v_mfma_f32_32x32x16_bf16 v[34:49], v[86:89], v[90:93], v[34:49]
	s_waitcnt lgkmcnt(0)
	v_mfma_f32_32x32x16_bf16 v[50:65], v[86:89], v[94:97], v[50:65]
	s_waitcnt vmcnt(7)
	ds_write_b128 v66, v[106:109] offset:27648
	s_waitcnt vmcnt(6)
	ds_write_b128 v66, v[110:113] offset:32256
	global_load_dwordx4 v[106:109], v[74:75], off offset:512
	global_load_dwordx4 v[110:113], v[76:77], off offset:512
	ds_read_b128 v[86:89], v68 offset:4640
	v_mfma_f32_32x32x16_bf16 v[2:17], v[98:101], v[126:129], v[2:17]
	v_mfma_f32_32x32x16_bf16 v[18:33], v[98:101], v[130:133], v[18:33]
	ds_read_b128 v[98:101], v68 offset:4704
	s_waitcnt lgkmcnt(1)
	v_mfma_f32_32x32x16_bf16 v[2:17], v[86:89], v[90:93], v[2:17]
	s_waitcnt vmcnt(7)
	ds_write_b128 v66, v[144:147] offset:55296
	s_waitcnt vmcnt(6)
	ds_write_b128 v66, v[122:125] offset:59904
	global_load_dwordx4 v[144:147], v[78:79], off offset:512
	global_load_dwordx4 v[122:125], v[80:81], off offset:512
	ds_read_b128 v[90:93], v1 offset:36928
	v_mfma_f32_32x32x16_bf16 v[18:33], v[86:89], v[94:97], v[18:33]
	ds_read_b128 v[86:89], v68 offset:64
	ds_read_b128 v[94:97], v1 offset:41536
	s_waitcnt lgkmcnt(1)
	v_mfma_f32_32x32x16_bf16 v[34:49], v[86:89], v[90:93], v[34:49]
	s_waitcnt lgkmcnt(0)
	v_mfma_f32_32x32x16_bf16 v[50:65], v[86:89], v[94:97], v[50:65]
	s_waitcnt vmcnt(7)
	ds_write_b128 v66, v[118:121] offset:64512
	s_waitcnt vmcnt(6)
	ds_write_b128 v69, v[114:117] offset:32256
	global_load_dwordx4 v[118:121], v[82:83], off offset:512
	global_load_dwordx4 v[114:117], v[84:85], off offset:512
	ds_read_b128 v[86:89], v68 offset:4672
	s_waitcnt lgkmcnt(0)
	v_mfma_f32_32x32x16_bf16 v[2:17], v[86:89], v[90:93], v[2:17]
	ds_read_b128 v[90:93], v1 offset:36960
	v_mfma_f32_32x32x16_bf16 v[18:33], v[86:89], v[94:97], v[18:33]
	ds_read_b128 v[86:89], v68 offset:96
	ds_read_b128 v[94:97], v1 offset:41568
	s_waitcnt lgkmcnt(1)
	v_mfma_f32_32x32x16_bf16 v[34:49], v[86:89], v[90:93], v[34:49]
	s_waitcnt lgkmcnt(0)
	v_mfma_f32_32x32x16_bf16 v[50:65], v[86:89], v[94:97], v[50:65]
	v_mfma_f32_32x32x16_bf16 v[2:17], v[98:101], v[90:93], v[2:17]
	v_mfma_f32_32x32x16_bf16 v[18:33], v[98:101], v[94:97], v[18:33]
	s_setprio 0
	s_barrier
; #define MFMA(a, b, c) __builtin_amdgcn_mfma_f32_32x32x16_bf16((a), (b), (c), 0, 0, 0)
; template <int TM, int TN>
; DI void gemm_mainloop(const u16* __restrict__ A, long lda, const u16* __restrict__ Bt, long ldb, int K, char* smem,
;                       f32x16 (&acc)[TM][TN]) {
;     ...
;   for (int kt = 0; kt < nk; kt++) {
;     const int buf = kt & 1;
;     const u16* cA = sA + buf * BM * LD + (wm * 32 * TM + r) * LD + h * 8;
;     const u16* cB = sB + buf * BN * LD + (wn * 32 * TN + r) * LD + h * 8;
;     bf16x8 af[TM], bfr[TN];
; #pragma unroll
;     for (int tm = 0; tm < TM; tm++) af[tm] = *(const bf16x8*)(cA + tm * 32 * LD);
; #pragma unroll
;     for (int tn = 0; tn < TN; tn++) bfr[tn] = *(const bf16x8*)(cB + tn * 32 * LD);
;     if (kt + 1 < nk) GEMM_SSTORE(buf ^ 1)
;     __builtin_amdgcn_sched_barrier(0);
;     __builtin_amdgcn_s_setprio(1);
; #pragma unroll
;     for (int tm = 0; tm < TM; tm++)
; #pragma unroll
;       for (int tn = 0; tn < TN; tn++) acc[tm][tn] = MFMA(af[tm], bfr[tn], acc[tm][tn]);
; #pragma unroll
;     for (int tm = 0; tm < TM; tm++) af[tm] = *(const bf16x8*)(cA + tm * 32 * LD + 16);
; #pragma unroll
;     for (int tn = 0; tn < TN; tn++) bfr[tn] = *(const bf16x8*)(cB + tn * 32 * LD + 16);
; #pragma unroll
;     for (int tm = 0; tm < TM; tm++)
; #pragma unroll
;       for (int tn = 0; tn < TN; tn++) acc[tm][tn] = MFMA(af[tm], bfr[tn], acc[tm][tn]);
;     __builtin_amdgcn_sched_group_barrier(0x8, 4, 0);
;     if (kt + 2 < nk) GEMM_GLOAD((kt + 2) * 64)
; #pragma unroll
;     for (int ks = 2; ks < 4; ks++) {
; #pragma unroll
;       for (int tm = 0; tm < TM; tm++) af[tm] = *(const bf16x8*)(cA + tm * 32 * LD + ks * 16);
; #pragma unroll
;       for (int tn = 0; tn < TN; tn++) bfr[tn] = *(const bf16x8*)(cB + tn * 32 * LD + ks * 16);
; #pragma unroll
;       for (int tm = 0; tm < TM; tm++)
; #pragma unroll
;         for (int tn = 0; tn < TN; tn++) acc[tm][tn] = MFMA(af[tm], bfr[tn], acc[tm][tn]);
;     }
;     __builtin_amdgcn_s_setprio(0);
;     __syncthreads();
;   }
	ds_read_b128 v[94:97], v68 offset:18432
	ds_read_b128 v[98:101], v68 offset:23040
	ds_read_b128 v[126:129], v1 offset:55296
	ds_read_b128 v[130:133], v1 offset:59904
	s_setprio 1
	ds_read_b128 v[86:89], v68 offset:18464
	s_waitcnt lgkmcnt(2)
	v_mfma_f32_32x32x16_bf16 v[34:49], v[94:97], v[126:129], v[34:49]
	s_waitcnt vmcnt(7)
	ds_write_b128 v66, v[140:143]
	s_waitcnt vmcnt(6)
	ds_write_b128 v66, v[102:105] offset:4608
	global_load_dwordx4 v[140:143], v[72:73], off offset:640
	global_load_dwordx4 v[102:105], v[70:71], off offset:640
	ds_read_b128 v[90:93], v1 offset:55328
	s_waitcnt lgkmcnt(4)
	v_mfma_f32_32x32x16_bf16 v[50:65], v[94:97], v[130:133], v[50:65]
	ds_read_b128 v[94:97], v1 offset:59936
	s_waitcnt lgkmcnt(1)
	v_mfma_f32_32x32x16_bf16 v[34:49], v[86:89], v[90:93], v[34:49]
	s_waitcnt lgkmcnt(0)
	v_mfma_f32_32x32x16_bf16 v[50:65], v[86:89], v[94:97], v[50:65]
	s_waitcnt vmcnt(7)
	ds_write_b128 v66, v[106:109] offset:9216
	s_waitcnt vmcnt(6)
	ds_write_b128 v66, v[110:113] offset:13824
	global_load_dwordx4 v[106:109], v[74:75], off offset:640
	global_load_dwordx4 v[110:113], v[76:77], off offset:640
	ds_read_b128 v[86:89], v68 offset:23072
	v_mfma_f32_32x32x16_bf16 v[2:17], v[98:101], v[126:129], v[2:17]
	v_mfma_f32_32x32x16_bf16 v[18:33], v[98:101], v[130:133], v[18:33]
	ds_read_b128 v[98:101], v68 offset:23136
	s_waitcnt lgkmcnt(1)
	v_mfma_f32_32x32x16_bf16 v[2:17], v[86:89], v[90:93], v[2:17]
	s_waitcnt vmcnt(7)
	ds_write_b128 v66, v[144:147] offset:36864
	s_waitcnt vmcnt(6)
	ds_write_b128 v66, v[122:125] offset:41472
	global_load_dwordx4 v[144:147], v[78:79], off offset:640
	global_load_dwordx4 v[122:125], v[80:81], off offset:640
	ds_read_b128 v[90:93], v1 offset:55360
	v_mfma_f32_32x32x16_bf16 v[18:33], v[86:89], v[94:97], v[18:33]
	ds_read_b128 v[86:89], v68 offset:18496
	ds_read_b128 v[94:97], v1 offset:59968
	s_waitcnt lgkmcnt(1)
	v_mfma_f32_32x32x16_bf16 v[34:49], v[86:89], v[90:93], v[34:49]
	s_waitcnt lgkmcnt(0)
	v_mfma_f32_32x32x16_bf16 v[50:65], v[86:89], v[94:97], v[50:65]
	s_waitcnt vmcnt(7)
	ds_write_b128 v66, v[118:121] offset:46080
	s_waitcnt vmcnt(6)
	ds_write_b128 v66, v[114:117] offset:50688
	global_load_dwordx4 v[118:121], v[82:83], off offset:640
	global_load_dwordx4 v[114:117], v[84:85], off offset:640
	ds_read_b128 v[86:89], v68 offset:23104
	s_waitcnt lgkmcnt(0)
	v_mfma_f32_32x32x16_bf16 v[2:17], v[86:89], v[90:93], v[2:17]
	ds_read_b128 v[90:93], v1 offset:55392
	v_mfma_f32_32x32x16_bf16 v[18:33], v[86:89], v[94:97], v[18:33]
	ds_read_b128 v[86:89], v68 offset:18528
	ds_read_b128 v[94:97], v1 offset:60000
	s_waitcnt lgkmcnt(1)
	v_mfma_f32_32x32x16_bf16 v[34:49], v[86:89], v[90:93], v[34:49]
	s_waitcnt lgkmcnt(0)
	v_mfma_f32_32x32x16_bf16 v[50:65], v[86:89], v[94:97], v[50:65]
	v_mfma_f32_32x32x16_bf16 v[2:17], v[98:101], v[90:93], v[2:17]
	v_mfma_f32_32x32x16_bf16 v[18:33], v[98:101], v[94:97], v[18:33]
	s_setprio 0
	s_barrier
	ds_read_b128 v[94:97], v68
	ds_read_b128 v[98:101], v68 offset:4608
	ds_read_b128 v[126:129], v1 offset:36864
	ds_read_b128 v[130:133], v1 offset:41472
	s_setprio 1
	ds_read_b128 v[86:89], v68 offset:32
	s_waitcnt lgkmcnt(2)
	v_mfma_f32_32x32x16_bf16 v[34:49], v[94:97], v[126:129], v[34:49]
	s_waitcnt vmcnt(7)
	ds_write_b128 v66, v[140:143] offset:18432
	s_waitcnt vmcnt(6)
	ds_write_b128 v66, v[102:105] offset:23040
	global_load_dwordx4 v[140:143], v[72:73], off offset:768
	global_load_dwordx4 v[102:105], v[70:71], off offset:768
	ds_read_b128 v[90:93], v1 offset:36896
	s_waitcnt lgkmcnt(4)
	v_mfma_f32_32x32x16_bf16 v[50:65], v[94:97], v[130:133], v[50:65]
	ds_read_b128 v[94:97], v1 offset:41504
	s_waitcnt lgkmcnt(1)
	v_mfma_f32_32x32x16_bf16 v[34:49], v[86:89], v[90:93], v[34:49]
	s_waitcnt lgkmcnt(0)
	v_mfma_f32_32x32x16_bf16 v[50:65], v[86:89], v[94:97], v[50:65]
	s_waitcnt vmcnt(7)
	ds_write_b128 v66, v[106:109] offset:27648
	s_waitcnt vmcnt(6)
	ds_write_b128 v66, v[110:113] offset:32256
	global_load_dwordx4 v[106:109], v[74:75], off offset:768
	global_load_dwordx4 v[110:113], v[76:77], off offset:768
	ds_read_b128 v[86:89], v68 offset:4640
	v_mfma_f32_32x32x16_bf16 v[2:17], v[98:101], v[126:129], v[2:17]
	v_mfma_f32_32x32x16_bf16 v[18:33], v[98:101], v[130:133], v[18:33]
	ds_read_b128 v[98:101], v68 offset:4704
	s_waitcnt lgkmcnt(1)
	v_mfma_f32_32x32x16_bf16 v[2:17], v[86:89], v[90:93], v[2:17]
	s_waitcnt vmcnt(7)
	ds_write_b128 v66, v[144:147] offset:55296
	s_waitcnt vmcnt(6)
	ds_write_b128 v66, v[122:125] offset:59904
	global_load_dwordx4 v[144:147], v[78:79], off offset:768
	global_load_dwordx4 v[122:125], v[80:81], off offset:768
	ds_read_b128 v[90:93], v1 offset:36928
	v_mfma_f32_32x32x16_bf16 v[18:33], v[86:89], v[94:97], v[18:33]
	ds_read_b128 v[86:89], v68 offset:64
	ds_read_b128 v[94:97], v1 offset:41536
	s_waitcnt lgkmcnt(1)
	v_mfma_f32_32x32x16_bf16 v[34:49], v[86:89], v[90:93], v[34:49]
	s_waitcnt lgkmcnt(0)
	v_mfma_f32_32x32x16_bf16 v[50:65], v[86:89], v[94:97], v[50:65]
	s_waitcnt vmcnt(7)
	ds_write_b128 v66, v[118:121] offset:64512
	s_waitcnt vmcnt(6)
	ds_write_b128 v69, v[114:117] offset:32256
	global_load_dwordx4 v[118:121], v[82:83], off offset:768
	global_load_dwordx4 v[114:117], v[84:85], off offset:768
	ds_read_b128 v[86:89], v68 offset:4672
	s_waitcnt lgkmcnt(0)
	v_mfma_f32_32x32x16_bf16 v[2:17], v[86:89], v[90:93], v[2:17]
	ds_read_b128 v[90:93], v1 offset:36960
	v_mfma_f32_32x32x16_bf16 v[18:33], v[86:89], v[94:97], v[18:33]
	ds_read_b128 v[86:89], v68 offset:96
	ds_read_b128 v[94:97], v1 offset:41568
	s_waitcnt lgkmcnt(1)
	v_mfma_f32_32x32x16_bf16 v[34:49], v[86:89], v[90:93], v[34:49]
	s_waitcnt lgkmcnt(0)
	v_mfma_f32_32x32x16_bf16 v[50:65], v[86:89], v[94:97], v[50:65]
	v_mfma_f32_32x32x16_bf16 v[2:17], v[98:101], v[90:93], v[2:17]
	v_mfma_f32_32x32x16_bf16 v[18:33], v[98:101], v[94:97], v[18:33]
	s_setprio 0
	s_barrier
; #define MFMA(a, b, c) __builtin_amdgcn_mfma_f32_32x32x16_bf16((a), (b), (c), 0, 0, 0)
; template <int TM, int TN>
; DI void gemm_mainloop(const u16* __restrict__ A, long lda, const u16* __restrict__ Bt, long ldb, int K, char* smem,
;                       f32x16 (&acc)[TM][TN]) {
;     ...
;   for (int kt = 0; kt < nk; kt++) {
;     const int buf = kt & 1;
;     const u16* cA = sA + buf * BM * LD + (wm * 32 * TM + r) * LD + h * 8;
;     const u16* cB = sB + buf * BN * LD + (wn * 32 * TN + r) * LD + h * 8;
;     bf16x8 af[TM], bfr[TN];
; #pragma unroll
;     for (int tm = 0; tm < TM; tm++) af[tm] = *(const bf16x8*)(cA + tm * 32 * LD);
; #pragma unroll
;     for (int tn = 0; tn < TN; tn++) bfr[tn] = *(const bf16x8*)(cB + tn * 32 * LD);
;     if (kt + 1 < nk) GEMM_SSTORE(buf ^ 1)
;     __builtin_amdgcn_sched_barrier(0);
;     __builtin_amdgcn_s_setprio(1);
; #pragma unroll
;     for (int tm = 0; tm < TM; tm++)
; #pragma unroll
;       for (int tn = 0; tn < TN; tn++) acc[tm][tn] = MFMA(af[tm], bfr[tn], acc[tm][tn]);
; #pragma unroll
;     for (int tm = 0; tm < TM; tm++) af[tm] = *(const bf16x8*)(cA + tm * 32 * LD + 16);
; #pragma unroll
;     for (int tn = 0; tn < TN; tn++) bfr[tn] = *(const bf16x8*)(cB + tn * 32 * LD + 16);
; #pragma unroll
;     for (int tm = 0; tm < TM; tm++)
; #pragma unroll
;       for (int tn = 0; tn < TN; tn++) acc[tm][tn] = MFMA(af[tm], bfr[tn], acc[tm][tn]);
;     __builtin_amdgcn_sched_group_barrier(0x8, 4, 0);
;     if (kt + 2 < nk) GEMM_GLOAD((kt + 2) * 64)
; #pragma unroll
;     for (int ks = 2; ks < 4; ks++) {
; #pragma unroll
;       for (int tm = 0; tm < TM; tm++) af[tm] = *(const bf16x8*)(cA + tm * 32 * LD + ks * 16);
; #pragma unroll
;       for (int tn = 0; tn < TN; tn++) bfr[tn] = *(const bf16x8*)(cB + tn * 32 * LD + ks * 16);
; #pragma unroll
;       for (int tm = 0; tm < TM; tm++)
; #pragma unroll
;         for (int tn = 0; tn < TN; tn++) acc[tm][tn] = MFMA(af[tm], bfr[tn], acc[tm][tn]);
;     }
;     __builtin_amdgcn_s_setprio(0);
;     __syncthreads();
;   }
	ds_read_b128 v[94:97], v68 offset:18432
	ds_read_b128 v[98:101], v68 offset:23040
	ds_read_b128 v[126:129], v1 offset:55296
	ds_read_b128 v[130:133], v1 offset:59904
	s_setprio 1
	ds_read_b128 v[86:89], v68 offset:18464
	s_waitcnt lgkmcnt(2)
	v_mfma_f32_32x32x16_bf16 v[34:49], v[94:97], v[126:129], v[34:49]
	s_waitcnt vmcnt(7)
	ds_write_b128 v66, v[140:143]
	s_waitcnt vmcnt(6)
	ds_write_b128 v66, v[102:105] offset:4608
	global_load_dwordx4 v[140:143], v[72:73], off offset:896
	global_load_dwordx4 v[102:105], v[70:71], off offset:896
	ds_read_b128 v[90:93], v1 offset:55328
	s_waitcnt lgkmcnt(4)
	v_mfma_f32_32x32x16_bf16 v[50:65], v[94:97], v[130:133], v[50:65]
	ds_read_b128 v[94:97], v1 offset:59936
	s_waitcnt lgkmcnt(1)
	v_mfma_f32_32x32x16_bf16 v[34:49], v[86:89], v[90:93], v[34:49]
	s_waitcnt lgkmcnt(0)
	v_mfma_f32_32x32x16_bf16 v[50:65], v[86:89], v[94:97], v[50:65]
	s_waitcnt vmcnt(7)
	ds_write_b128 v66, v[106:109] offset:9216
	s_waitcnt vmcnt(6)
	ds_write_b128 v66, v[110:113] offset:13824
	global_load_dwordx4 v[106:109], v[74:75], off offset:896
	global_load_dwordx4 v[110:113], v[76:77], off offset:896
	ds_read_b128 v[86:89], v68 offset:23072
	v_mfma_f32_32x32x16_bf16 v[2:17], v[98:101], v[126:129], v[2:17]
	v_mfma_f32_32x32x16_bf16 v[18:33], v[98:101], v[130:133], v[18:33]
	ds_read_b128 v[98:101], v68 offset:23136
	s_waitcnt lgkmcnt(1)
	v_mfma_f32_32x32x16_bf16 v[2:17], v[86:89], v[90:93], v[2:17]
	s_waitcnt vmcnt(7)
	ds_write_b128 v66, v[144:147] offset:36864
	s_waitcnt vmcnt(6)
	ds_write_b128 v66, v[122:125] offset:41472
	global_load_dwordx4 v[144:147], v[78:79], off offset:896
	global_load_dwordx4 v[122:125], v[80:81], off offset:896
	ds_read_b128 v[90:93], v1 offset:55360
	v_mfma_f32_32x32x16_bf16 v[18:33], v[86:89], v[94:97], v[18:33]
	ds_read_b128 v[86:89], v68 offset:18496
	ds_read_b128 v[94:97], v1 offset:59968
	s_waitcnt lgkmcnt(1)
	v_mfma_f32_32x32x16_bf16 v[34:49], v[86:89], v[90:93], v[34:49]
	s_waitcnt lgkmcnt(0)
	v_mfma_f32_32x32x16_bf16 v[50:65], v[86:89], v[94:97], v[50:65]
	s_waitcnt vmcnt(7)
	ds_write_b128 v66, v[118:121] offset:46080
	s_waitcnt vmcnt(6)
	ds_write_b128 v66, v[114:117] offset:50688
	global_load_dwordx4 v[118:121], v[82:83], off offset:896
	global_load_dwordx4 v[114:117], v[84:85], off offset:896
	ds_read_b128 v[86:89], v68 offset:23104
	s_waitcnt lgkmcnt(0)
	v_mfma_f32_32x32x16_bf16 v[2:17], v[86:89], v[90:93], v[2:17]
	ds_read_b128 v[90:93], v1 offset:55392
	v_mfma_f32_32x32x16_bf16 v[18:33], v[86:89], v[94:97], v[18:33]
	ds_read_b128 v[86:89], v68 offset:18528
	ds_read_b128 v[94:97], v1 offset:60000
	s_waitcnt lgkmcnt(1)
	v_mfma_f32_32x32x16_bf16 v[34:49], v[86:89], v[90:93], v[34:49]
	s_waitcnt lgkmcnt(0)
	v_mfma_f32_32x32x16_bf16 v[50:65], v[86:89], v[94:97], v[50:65]
	v_mfma_f32_32x32x16_bf16 v[2:17], v[98:101], v[90:93], v[2:17]
	v_mfma_f32_32x32x16_bf16 v[18:33], v[98:101], v[94:97], v[18:33]
	s_setprio 0
	s_barrier
	ds_read_b128 v[94:97], v68
	ds_read_b128 v[98:101], v68 offset:4608
	ds_read_b128 v[126:129], v1 offset:36864
	ds_read_b128 v[130:133], v1 offset:41472
	s_setprio 1
	ds_read_b128 v[86:89], v68 offset:32
	s_waitcnt lgkmcnt(2)
	v_mfma_f32_32x32x16_bf16 v[34:49], v[94:97], v[126:129], v[34:49]
	s_waitcnt vmcnt(7)
	ds_write_b128 v66, v[140:143] offset:18432
	s_waitcnt vmcnt(6)
	ds_write_b128 v66, v[102:105] offset:23040
	global_load_dwordx4 v[140:143], v[72:73], off offset:1024
	global_load_dwordx4 v[102:105], v[70:71], off offset:1024
	ds_read_b128 v[90:93], v1 offset:36896
	s_waitcnt lgkmcnt(4)
	v_mfma_f32_32x32x16_bf16 v[50:65], v[94:97], v[130:133], v[50:65]
	ds_read_b128 v[94:97], v1 offset:41504
	s_waitcnt lgkmcnt(1)
	v_mfma_f32_32x32x16_bf16 v[34:49], v[86:89], v[90:93], v[34:49]
	s_waitcnt lgkmcnt(0)
	v_mfma_f32_32x32x16_bf16 v[50:65], v[86:89], v[94:97], v[50:65]
	s_waitcnt vmcnt(7)
	ds_write_b128 v66, v[106:109] offset:27648
	s_waitcnt vmcnt(6)
	ds_write_b128 v66, v[110:113] offset:32256
	global_load_dwordx4 v[106:109], v[74:75], off offset:1024
	global_load_dwordx4 v[110:113], v[76:77], off offset:1024
	ds_read_b128 v[86:89], v68 offset:4640
	v_mfma_f32_32x32x16_bf16 v[2:17], v[98:101], v[126:129], v[2:17]
	v_mfma_f32_32x32x16_bf16 v[18:33], v[98:101], v[130:133], v[18:33]
	ds_read_b128 v[98:101], v68 offset:4704
	s_waitcnt lgkmcnt(1)
	v_mfma_f32_32x32x16_bf16 v[2:17], v[86:89], v[90:93], v[2:17]
	s_waitcnt vmcnt(7)
	ds_write_b128 v66, v[144:147] offset:55296
	s_waitcnt vmcnt(6)
	ds_write_b128 v66, v[122:125] offset:59904
	global_load_dwordx4 v[144:147], v[78:79], off offset:1024
	global_load_dwordx4 v[122:125], v[80:81], off offset:1024
	ds_read_b128 v[90:93], v1 offset:36928
	v_mfma_f32_32x32x16_bf16 v[18:33], v[86:89], v[94:97], v[18:33]
	ds_read_b128 v[86:89], v68 offset:64
	ds_read_b128 v[94:97], v1 offset:41536
	s_waitcnt lgkmcnt(1)
	v_mfma_f32_32x32x16_bf16 v[34:49], v[86:89], v[90:93], v[34:49]
	s_waitcnt lgkmcnt(0)
	v_mfma_f32_32x32x16_bf16 v[50:65], v[86:89], v[94:97], v[50:65]
	s_waitcnt vmcnt(7)
	ds_write_b128 v66, v[118:121] offset:64512
	s_waitcnt vmcnt(6)
	ds_write_b128 v69, v[114:117] offset:32256
	global_load_dwordx4 v[118:121], v[82:83], off offset:1024
	global_load_dwordx4 v[114:117], v[84:85], off offset:1024
	ds_read_b128 v[86:89], v68 offset:4672
	s_waitcnt lgkmcnt(0)
	v_mfma_f32_32x32x16_bf16 v[2:17], v[86:89], v[90:93], v[2:17]
	ds_read_b128 v[90:93], v1 offset:36960
	v_mfma_f32_32x32x16_bf16 v[18:33], v[86:89], v[94:97], v[18:33]
	ds_read_b128 v[86:89], v68 offset:96
	ds_read_b128 v[94:97], v1 offset:41568
	s_waitcnt lgkmcnt(1)
	v_mfma_f32_32x32x16_bf16 v[34:49], v[86:89], v[90:93], v[34:49]
	s_waitcnt lgkmcnt(0)
	v_mfma_f32_32x32x16_bf16 v[50:65], v[86:89], v[94:97], v[50:65]
	v_mfma_f32_32x32x16_bf16 v[2:17], v[98:101], v[90:93], v[2:17]
	v_mfma_f32_32x32x16_bf16 v[18:33], v[98:101], v[94:97], v[18:33]
	s_setprio 0
	s_barrier
; #define MFMA(a, b, c) __builtin_amdgcn_mfma_f32_32x32x16_bf16((a), (b), (c), 0, 0, 0)
; template <int TM, int TN>
; DI void gemm_mainloop(const u16* __restrict__ A, long lda, const u16* __restrict__ Bt, long ldb, int K, char* smem,
;                       f32x16 (&acc)[TM][TN]) {
;     ...
;   for (int kt = 0; kt < nk; kt++) {
;     const int buf = kt & 1;
;     const u16* cA = sA + buf * BM * LD + (wm * 32 * TM + r) * LD + h * 8;
;     const u16* cB = sB + buf * BN * LD + (wn * 32 * TN + r) * LD + h * 8;
;     bf16x8 af[TM], bfr[TN];
; #pragma unroll
;     for (int tm = 0; tm < TM; tm++) af[tm] = *(const bf16x8*)(cA + tm * 32 * LD);
; #pragma unroll
;     for (int tn = 0; tn < TN; tn++) bfr[tn] = *(const bf16x8*)(cB + tn * 32 * LD);
;     if (kt + 1 < nk) GEMM_SSTORE(buf ^ 1)
;     __builtin_amdgcn_sched_barrier(0);
;     __builtin_amdgcn_s_setprio(1);
; #pragma unroll
;     for (int tm = 0; tm < TM; tm++)
; #pragma unroll
;       for (int tn = 0; tn < TN; tn++) acc[tm][tn] = MFMA(af[tm], bfr[tn], acc[tm][tn]);
; #pragma unroll
;     for (int tm = 0; tm < TM; tm++) af[tm] = *(const bf16x8*)(cA + tm * 32 * LD + 16);
; #pragma unroll
;     for (int tn = 0; tn < TN; tn++) bfr[tn] = *(const bf16x8*)(cB + tn * 32 * LD + 16);
; #pragma unroll
;     for (int tm = 0; tm < TM; tm++)
; #pragma unroll
;       for (int tn = 0; tn < TN; tn++) acc[tm][tn] = MFMA(af[tm], bfr[tn], acc[tm][tn]);
;     __builtin_amdgcn_sched_group_barrier(0x8, 4, 0);
;     if (kt + 2 < nk) GEMM_GLOAD((kt + 2) * 64)
; #pragma unroll
;     for (int ks = 2; ks < 4; ks++) {
; #pragma unroll
;       for (int tm = 0; tm < TM; tm++) af[tm] = *(const bf16x8*)(cA + tm * 32 * LD + ks * 16);
; #pragma unroll
;       for (int tn = 0; tn < TN; tn++) bfr[tn] = *(const bf16x8*)(cB + tn * 32 * LD + ks * 16);
; #pragma unroll
;       for (int tm = 0; tm < TM; tm++)
; #pragma unroll
;         for (int tn = 0; tn < TN; tn++) acc[tm][tn] = MFMA(af[tm], bfr[tn], acc[tm][tn]);
;     }
;     __builtin_amdgcn_s_setprio(0);
;     __syncthreads();
;   }
	ds_read_b128 v[94:97], v68 offset:18432
	ds_read_b128 v[98:101], v68 offset:23040
	ds_read_b128 v[126:129], v1 offset:55296
	ds_read_b128 v[130:133], v1 offset:59904
	s_setprio 1
	ds_read_b128 v[86:89], v68 offset:18464
	s_waitcnt lgkmcnt(2)
	v_mfma_f32_32x32x16_bf16 v[34:49], v[94:97], v[126:129], v[34:49]
	s_waitcnt vmcnt(7)
	ds_write_b128 v66, v[140:143]
	s_waitcnt vmcnt(6)
	ds_write_b128 v66, v[102:105] offset:4608
	global_load_dwordx4 v[140:143], v[72:73], off offset:1152
	global_load_dwordx4 v[102:105], v[70:71], off offset:1152
	ds_read_b128 v[90:93], v1 offset:55328
	s_waitcnt lgkmcnt(4)
	v_mfma_f32_32x32x16_bf16 v[50:65], v[94:97], v[130:133], v[50:65]
	ds_read_b128 v[94:97], v1 offset:59936
	s_waitcnt lgkmcnt(1)
	v_mfma_f32_32x32x16_bf16 v[34:49], v[86:89], v[90:93], v[34:49]
	s_waitcnt lgkmcnt(0)
	v_mfma_f32_32x32x16_bf16 v[50:65], v[86:89], v[94:97], v[50:65]
	s_waitcnt vmcnt(7)
	ds_write_b128 v66, v[106:109] offset:9216
	s_waitcnt vmcnt(6)
	ds_write_b128 v66, v[110:113] offset:13824
	global_load_dwordx4 v[106:109], v[74:75], off offset:1152
	global_load_dwordx4 v[110:113], v[76:77], off offset:1152
	ds_read_b128 v[86:89], v68 offset:23072
	v_mfma_f32_32x32x16_bf16 v[2:17], v[98:101], v[126:129], v[2:17]
	v_mfma_f32_32x32x16_bf16 v[18:33], v[98:101], v[130:133], v[18:33]
	ds_read_b128 v[98:101], v68 offset:23136
	s_waitcnt lgkmcnt(1)
	v_mfma_f32_32x32x16_bf16 v[2:17], v[86:89], v[90:93], v[2:17]
	s_waitcnt vmcnt(7)
	ds_write_b128 v66, v[144:147] offset:36864
	s_waitcnt vmcnt(6)
	ds_write_b128 v66, v[122:125] offset:41472
	global_load_dwordx4 v[144:147], v[78:79], off offset:1152
	global_load_dwordx4 v[122:125], v[80:81], off offset:1152
	ds_read_b128 v[90:93], v1 offset:55360
	v_mfma_f32_32x32x16_bf16 v[18:33], v[86:89], v[94:97], v[18:33]
	ds_read_b128 v[86:89], v68 offset:18496
	ds_read_b128 v[94:97], v1 offset:59968
	s_waitcnt lgkmcnt(1)
	v_mfma_f32_32x32x16_bf16 v[34:49], v[86:89], v[90:93], v[34:49]
	s_waitcnt lgkmcnt(0)
	v_mfma_f32_32x32x16_bf16 v[50:65], v[86:89], v[94:97], v[50:65]
	s_waitcnt vmcnt(7)
	ds_write_b128 v66, v[118:121] offset:46080
	s_waitcnt vmcnt(6)
	ds_write_b128 v66, v[114:117] offset:50688
	global_load_dwordx4 v[118:121], v[82:83], off offset:1152
	global_load_dwordx4 v[114:117], v[84:85], off offset:1152
	ds_read_b128 v[86:89], v68 offset:23104
	s_waitcnt lgkmcnt(0)
	v_mfma_f32_32x32x16_bf16 v[2:17], v[86:89], v[90:93], v[2:17]
	ds_read_b128 v[90:93], v1 offset:55392
	v_mfma_f32_32x32x16_bf16 v[18:33], v[86:89], v[94:97], v[18:33]
	ds_read_b128 v[86:89], v68 offset:18528
	ds_read_b128 v[94:97], v1 offset:60000
	s_waitcnt lgkmcnt(1)
	v_mfma_f32_32x32x16_bf16 v[34:49], v[86:89], v[90:93], v[34:49]
	s_waitcnt lgkmcnt(0)
	v_mfma_f32_32x32x16_bf16 v[50:65], v[86:89], v[94:97], v[50:65]
	v_mfma_f32_32x32x16_bf16 v[2:17], v[98:101], v[90:93], v[2:17]
	v_mfma_f32_32x32x16_bf16 v[18:33], v[98:101], v[94:97], v[18:33]
	s_setprio 0
	s_barrier
	ds_read_b128 v[94:97], v68
	ds_read_b128 v[98:101], v68 offset:4608
	ds_read_b128 v[126:129], v1 offset:36864
	ds_read_b128 v[130:133], v1 offset:41472
	s_setprio 1
	ds_read_b128 v[86:89], v68 offset:32
	s_waitcnt lgkmcnt(2)
	v_mfma_f32_32x32x16_bf16 v[34:49], v[94:97], v[126:129], v[34:49]
	s_waitcnt vmcnt(7)
	ds_write_b128 v66, v[140:143] offset:18432
	s_waitcnt vmcnt(6)
	ds_write_b128 v66, v[102:105] offset:23040
	global_load_dwordx4 v[140:143], v[72:73], off offset:1280
	global_load_dwordx4 v[102:105], v[70:71], off offset:1280
	ds_read_b128 v[90:93], v1 offset:36896
	s_waitcnt lgkmcnt(4)
	v_mfma_f32_32x32x16_bf16 v[50:65], v[94:97], v[130:133], v[50:65]
	ds_read_b128 v[94:97], v1 offset:41504
	s_waitcnt lgkmcnt(1)
	v_mfma_f32_32x32x16_bf16 v[34:49], v[86:89], v[90:93], v[34:49]
	s_waitcnt lgkmcnt(0)
	v_mfma_f32_32x32x16_bf16 v[50:65], v[86:89], v[94:97], v[50:65]
	s_waitcnt vmcnt(7)
	ds_write_b128 v66, v[106:109] offset:27648
	s_waitcnt vmcnt(6)
	ds_write_b128 v66, v[110:113] offset:32256
	global_load_dwordx4 v[106:109], v[74:75], off offset:1280
	global_load_dwordx4 v[110:113], v[76:77], off offset:1280
	ds_read_b128 v[86:89], v68 offset:4640
	v_mfma_f32_32x32x16_bf16 v[2:17], v[98:101], v[126:129], v[2:17]
	v_mfma_f32_32x32x16_bf16 v[18:33], v[98:101], v[130:133], v[18:33]
	ds_read_b128 v[98:101], v68 offset:4704
	s_waitcnt lgkmcnt(1)
	v_mfma_f32_32x32x16_bf16 v[2:17], v[86:89], v[90:93], v[2:17]
	s_waitcnt vmcnt(7)
	ds_write_b128 v66, v[144:147] offset:55296
	s_waitcnt vmcnt(6)
	ds_write_b128 v66, v[122:125] offset:59904
	global_load_dwordx4 v[144:147], v[78:79], off offset:1280
	global_load_dwordx4 v[122:125], v[80:81], off offset:1280
	ds_read_b128 v[90:93], v1 offset:36928
	v_mfma_f32_32x32x16_bf16 v[18:33], v[86:89], v[94:97], v[18:33]
	ds_read_b128 v[86:89], v68 offset:64
	ds_read_b128 v[94:97], v1 offset:41536
	s_waitcnt lgkmcnt(1)
	v_mfma_f32_32x32x16_bf16 v[34:49], v[86:89], v[90:93], v[34:49]
	s_waitcnt lgkmcnt(0)
	v_mfma_f32_32x32x16_bf16 v[50:65], v[86:89], v[94:97], v[50:65]
	s_waitcnt vmcnt(7)
	ds_write_b128 v66, v[118:121] offset:64512
	s_waitcnt vmcnt(6)
	ds_write_b128 v69, v[114:117] offset:32256
	global_load_dwordx4 v[118:121], v[82:83], off offset:1280
	global_load_dwordx4 v[114:117], v[84:85], off offset:1280
	ds_read_b128 v[86:89], v68 offset:4672
	s_waitcnt lgkmcnt(0)
	v_mfma_f32_32x32x16_bf16 v[2:17], v[86:89], v[90:93], v[2:17]
	ds_read_b128 v[90:93], v1 offset:36960
	v_mfma_f32_32x32x16_bf16 v[18:33], v[86:89], v[94:97], v[18:33]
	ds_read_b128 v[86:89], v68 offset:96
	ds_read_b128 v[94:97], v1 offset:41568
	s_waitcnt lgkmcnt(1)
	v_mfma_f32_32x32x16_bf16 v[34:49], v[86:89], v[90:93], v[34:49]
	s_waitcnt lgkmcnt(0)
	v_mfma_f32_32x32x16_bf16 v[50:65], v[86:89], v[94:97], v[50:65]
	v_mfma_f32_32x32x16_bf16 v[2:17], v[98:101], v[90:93], v[2:17]
	v_mfma_f32_32x32x16_bf16 v[18:33], v[98:101], v[94:97], v[18:33]
	s_setprio 0
	s_barrier
; #define MFMA(a, b, c) __builtin_amdgcn_mfma_f32_32x32x16_bf16((a), (b), (c), 0, 0, 0)
; template <int TM, int TN>
; DI void gemm_mainloop(const u16* __restrict__ A, long lda, const u16* __restrict__ Bt, long ldb, int K, char* smem,
;                       f32x16 (&acc)[TM][TN]) {
;     ...
;   for (int kt = 0; kt < nk; kt++) {
;     const int buf = kt & 1;
;     const u16* cA = sA + buf * BM * LD + (wm * 32 * TM + r) * LD + h * 8;
;     const u16* cB = sB + buf * BN * LD + (wn * 32 * TN + r) * LD + h * 8;
;     bf16x8 af[TM], bfr[TN];
; #pragma unroll
;     for (int tm = 0; tm < TM; tm++) af[tm] = *(const bf16x8*)(cA + tm * 32 * LD);
; #pragma unroll
;     for (int tn = 0; tn < TN; tn++) bfr[tn] = *(const bf16x8*)(cB + tn * 32 * LD);
;     if (kt + 1 < nk) GEMM_SSTORE(buf ^ 1)
;     __builtin_amdgcn_sched_barrier(0);
;     __builtin_amdgcn_s_setprio(1);
; #pragma unroll
;     for (int tm = 0; tm < TM; tm++)
; #pragma unroll
;       for (int tn = 0; tn < TN; tn++) acc[tm][tn] = MFMA(af[tm], bfr[tn], acc[tm][tn]);
; #pragma unroll
;     for (int tm = 0; tm < TM; tm++) af[tm] = *(const bf16x8*)(cA + tm * 32 * LD + 16);
; #pragma unroll
;     for (int tn = 0; tn < TN; tn++) bfr[tn] = *(const bf16x8*)(cB + tn * 32 * LD + 16);
; #pragma unroll
;     for (int tm = 0; tm < TM; tm++)
; #pragma unroll
;       for (int tn = 0; tn < TN; tn++) acc[tm][tn] = MFMA(af[tm], bfr[tn], acc[tm][tn]);
;     __builtin_amdgcn_sched_group_barrier(0x8, 4, 0);
;     if (kt + 2 < nk) GEMM_GLOAD((kt + 2) * 64)
; #pragma unroll
;     for (int ks = 2; ks < 4; ks++) {
; #pragma unroll
;       for (int tm = 0; tm < TM; tm++) af[tm] = *(const bf16x8*)(cA + tm * 32 * LD + ks * 16);
; #pragma unroll
;       for (int tn = 0; tn < TN; tn++) bfr[tn] = *(const bf16x8*)(cB + tn * 32 * LD + ks * 16);
; #pragma unroll
;       for (int tm = 0; tm < TM; tm++)
; #pragma unroll
;         for (int tn = 0; tn < TN; tn++) acc[tm][tn] = MFMA(af[tm], bfr[tn], acc[tm][tn]);
;     }
;     __builtin_amdgcn_s_setprio(0);
;     __syncthreads();
;   }
	ds_read_b128 v[94:97], v68 offset:18432
	ds_read_b128 v[98:101], v68 offset:23040
	ds_read_b128 v[126:129], v1 offset:55296
	ds_read_b128 v[130:133], v1 offset:59904
	s_setprio 1
	ds_read_b128 v[86:89], v68 offset:18464
	s_waitcnt lgkmcnt(2)
	v_mfma_f32_32x32x16_bf16 v[34:49], v[94:97], v[126:129], v[34:49]
	s_waitcnt vmcnt(7)
	ds_write_b128 v66, v[140:143]
	s_waitcnt vmcnt(6)
	ds_write_b128 v66, v[102:105] offset:4608
	global_load_dwordx4 v[140:143], v[72:73], off offset:1408
	global_load_dwordx4 v[102:105], v[70:71], off offset:1408
	ds_read_b128 v[90:93], v1 offset:55328
	s_waitcnt lgkmcnt(4)
	v_mfma_f32_32x32x16_bf16 v[50:65], v[94:97], v[130:133], v[50:65]
	ds_read_b128 v[94:97], v1 offset:59936
	s_waitcnt lgkmcnt(1)
	v_mfma_f32_32x32x16_bf16 v[34:49], v[86:89], v[90:93], v[34:49]
	s_waitcnt lgkmcnt(0)
	v_mfma_f32_32x32x16_bf16 v[50:65], v[86:89], v[94:97], v[50:65]
	s_waitcnt vmcnt(7)
	ds_write_b128 v66, v[106:109] offset:9216
	s_waitcnt vmcnt(6)
	ds_write_b128 v66, v[110:113] offset:13824
	global_load_dwordx4 v[106:109], v[74:75], off offset:1408
	global_load_dwordx4 v[110:113], v[76:77], off offset:1408
	ds_read_b128 v[86:89], v68 offset:23072
	v_mfma_f32_32x32x16_bf16 v[2:17], v[98:101], v[126:129], v[2:17]
	v_mfma_f32_32x32x16_bf16 v[18:33], v[98:101], v[130:133], v[18:33]
	ds_read_b128 v[98:101], v68 offset:23136
	s_waitcnt lgkmcnt(1)
	v_mfma_f32_32x32x16_bf16 v[2:17], v[86:89], v[90:93], v[2:17]
	s_waitcnt vmcnt(7)
	ds_write_b128 v66, v[144:147] offset:36864
	s_waitcnt vmcnt(6)
	ds_write_b128 v66, v[122:125] offset:41472
	global_load_dwordx4 v[144:147], v[78:79], off offset:1408
	global_load_dwordx4 v[122:125], v[80:81], off offset:1408
	ds_read_b128 v[90:93], v1 offset:55360
	v_mfma_f32_32x32x16_bf16 v[18:33], v[86:89], v[94:97], v[18:33]
	ds_read_b128 v[86:89], v68 offset:18496
	ds_read_b128 v[94:97], v1 offset:59968
	s_waitcnt lgkmcnt(1)
	v_mfma_f32_32x32x16_bf16 v[34:49], v[86:89], v[90:93], v[34:49]
	s_waitcnt lgkmcnt(0)
	v_mfma_f32_32x32x16_bf16 v[50:65], v[86:89], v[94:97], v[50:65]
	s_waitcnt vmcnt(7)
	ds_write_b128 v66, v[118:121] offset:46080
	s_waitcnt vmcnt(6)
	ds_write_b128 v66, v[114:117] offset:50688
	global_load_dwordx4 v[118:121], v[82:83], off offset:1408
	global_load_dwordx4 v[114:117], v[84:85], off offset:1408
	ds_read_b128 v[86:89], v68 offset:23104
	s_waitcnt lgkmcnt(0)
	v_mfma_f32_32x32x16_bf16 v[2:17], v[86:89], v[90:93], v[2:17]
	ds_read_b128 v[90:93], v1 offset:55392
	v_mfma_f32_32x32x16_bf16 v[18:33], v[86:89], v[94:97], v[18:33]
	ds_read_b128 v[86:89], v68 offset:18528
	ds_read_b128 v[94:97], v1 offset:60000
	s_waitcnt lgkmcnt(1)
	v_mfma_f32_32x32x16_bf16 v[34:49], v[86:89], v[90:93], v[34:49]
	s_waitcnt lgkmcnt(0)
	v_mfma_f32_32x32x16_bf16 v[50:65], v[86:89], v[94:97], v[50:65]
	v_mfma_f32_32x32x16_bf16 v[2:17], v[98:101], v[90:93], v[2:17]
	v_mfma_f32_32x32x16_bf16 v[18:33], v[98:101], v[94:97], v[18:33]
	s_setprio 0
	s_barrier
	ds_read_b128 v[94:97], v68
	ds_read_b128 v[98:101], v68 offset:4608
	ds_read_b128 v[126:129], v1 offset:36864
	ds_read_b128 v[130:133], v1 offset:41472
	s_setprio 1
	ds_read_b128 v[86:89], v68 offset:32
	s_waitcnt lgkmcnt(2)
	v_mfma_f32_32x32x16_bf16 v[34:49], v[94:97], v[126:129], v[34:49]
	s_waitcnt vmcnt(7)
	ds_write_b128 v66, v[140:143] offset:18432
	s_waitcnt vmcnt(6)
	ds_write_b128 v66, v[102:105] offset:23040
	global_load_dwordx4 v[140:143], v[72:73], off offset:1536
	global_load_dwordx4 v[102:105], v[70:71], off offset:1536
	ds_read_b128 v[90:93], v1 offset:36896
	s_waitcnt lgkmcnt(4)
	v_mfma_f32_32x32x16_bf16 v[50:65], v[94:97], v[130:133], v[50:65]
	ds_read_b128 v[94:97], v1 offset:41504
	s_waitcnt lgkmcnt(1)
	v_mfma_f32_32x32x16_bf16 v[34:49], v[86:89], v[90:93], v[34:49]
	s_waitcnt lgkmcnt(0)
	v_mfma_f32_32x32x16_bf16 v[50:65], v[86:89], v[94:97], v[50:65]
	s_waitcnt vmcnt(7)
	ds_write_b128 v66, v[106:109] offset:27648
	s_waitcnt vmcnt(6)
	ds_write_b128 v66, v[110:113] offset:32256
	global_load_dwordx4 v[106:109], v[74:75], off offset:1536
	global_load_dwordx4 v[110:113], v[76:77], off offset:1536
	ds_read_b128 v[86:89], v68 offset:4640
	v_mfma_f32_32x32x16_bf16 v[2:17], v[98:101], v[126:129], v[2:17]
	v_mfma_f32_32x32x16_bf16 v[18:33], v[98:101], v[130:133], v[18:33]
	ds_read_b128 v[98:101], v68 offset:4704
	s_waitcnt lgkmcnt(1)
	v_mfma_f32_32x32x16_bf16 v[2:17], v[86:89], v[90:93], v[2:17]
	s_waitcnt vmcnt(7)
	ds_write_b128 v66, v[144:147] offset:55296
	s_waitcnt vmcnt(6)
	ds_write_b128 v66, v[122:125] offset:59904
	global_load_dwordx4 v[144:147], v[78:79], off offset:1536
	global_load_dwordx4 v[122:125], v[80:81], off offset:1536
	ds_read_b128 v[90:93], v1 offset:36928
	v_mfma_f32_32x32x16_bf16 v[18:33], v[86:89], v[94:97], v[18:33]
	ds_read_b128 v[86:89], v68 offset:64
	ds_read_b128 v[94:97], v1 offset:41536
	s_waitcnt lgkmcnt(1)
	v_mfma_f32_32x32x16_bf16 v[34:49], v[86:89], v[90:93], v[34:49]
	s_waitcnt lgkmcnt(0)
	v_mfma_f32_32x32x16_bf16 v[50:65], v[86:89], v[94:97], v[50:65]
	s_waitcnt vmcnt(7)
	ds_write_b128 v66, v[118:121] offset:64512
	s_waitcnt vmcnt(6)
	ds_write_b128 v69, v[114:117] offset:32256
	global_load_dwordx4 v[118:121], v[82:83], off offset:1536
	global_load_dwordx4 v[114:117], v[84:85], off offset:1536
	ds_read_b128 v[86:89], v68 offset:4672
	s_waitcnt lgkmcnt(0)
	v_mfma_f32_32x32x16_bf16 v[2:17], v[86:89], v[90:93], v[2:17]
	ds_read_b128 v[90:93], v1 offset:36960
	v_mfma_f32_32x32x16_bf16 v[18:33], v[86:89], v[94:97], v[18:33]
	ds_read_b128 v[86:89], v68 offset:96
	ds_read_b128 v[94:97], v1 offset:41568
	s_waitcnt lgkmcnt(1)
	v_mfma_f32_32x32x16_bf16 v[34:49], v[86:89], v[90:93], v[34:49]
	s_waitcnt lgkmcnt(0)
	v_mfma_f32_32x32x16_bf16 v[50:65], v[86:89], v[94:97], v[50:65]
	v_mfma_f32_32x32x16_bf16 v[2:17], v[98:101], v[90:93], v[2:17]
	v_mfma_f32_32x32x16_bf16 v[18:33], v[98:101], v[94:97], v[18:33]
	s_setprio 0
	s_barrier
; #define MFMA(a, b, c) __builtin_amdgcn_mfma_f32_32x32x16_bf16((a), (b), (c), 0, 0, 0)
; template <int TM, int TN>
; DI void gemm_mainloop(const u16* __restrict__ A, long lda, const u16* __restrict__ Bt, long ldb, int K, char* smem,
;                       f32x16 (&acc)[TM][TN]) {
;     ...
;   for (int kt = 0; kt < nk; kt++) {
;     const int buf = kt & 1;
;     const u16* cA = sA + buf * BM * LD + (wm * 32 * TM + r) * LD + h * 8;
;     const u16* cB = sB + buf * BN * LD + (wn * 32 * TN + r) * LD + h * 8;
;     bf16x8 af[TM], bfr[TN];
; #pragma unroll
;     for (int tm = 0; tm < TM; tm++) af[tm] = *(const bf16x8*)(cA + tm * 32 * LD);
; #pragma unroll
;     for (int tn = 0; tn < TN; tn++) bfr[tn] = *(const bf16x8*)(cB + tn * 32 * LD);
;     if (kt + 1 < nk) GEMM_SSTORE(buf ^ 1)
;     __builtin_amdgcn_sched_barrier(0);
;     __builtin_amdgcn_s_setprio(1);
; #pragma unroll
;     for (int tm = 0; tm < TM; tm++)
; #pragma unroll
;       for (int tn = 0; tn < TN; tn++) acc[tm][tn] = MFMA(af[tm], bfr[tn], acc[tm][tn]);
; #pragma unroll
;     for (int tm = 0; tm < TM; tm++) af[tm] = *(const bf16x8*)(cA + tm * 32 * LD + 16);
; #pragma unroll
;     for (int tn = 0; tn < TN; tn++) bfr[tn] = *(const bf16x8*)(cB + tn * 32 * LD + 16);
; #pragma unroll
;     for (int tm = 0; tm < TM; tm++)
; #pragma unroll
;       for (int tn = 0; tn < TN; tn++) acc[tm][tn] = MFMA(af[tm], bfr[tn], acc[tm][tn]);
;     __builtin_amdgcn_sched_group_barrier(0x8, 4, 0);
;     if (kt + 2 < nk) GEMM_GLOAD((kt + 2) * 64)
; #pragma unroll
;     for (int ks = 2; ks < 4; ks++) {
; #pragma unroll
;       for (int tm = 0; tm < TM; tm++) af[tm] = *(const bf16x8*)(cA + tm * 32 * LD + ks * 16);
; #pragma unroll
;       for (int tn = 0; tn < TN; tn++) bfr[tn] = *(const bf16x8*)(cB + tn * 32 * LD + ks * 16);
; #pragma unroll
;       for (int tm = 0; tm < TM; tm++)
; #pragma unroll
;         for (int tn = 0; tn < TN; tn++) acc[tm][tn] = MFMA(af[tm], bfr[tn], acc[tm][tn]);
;     }
;     __builtin_amdgcn_s_setprio(0);
;     __syncthreads();
;   }
	ds_read_b128 v[94:97], v68 offset:18432
	ds_read_b128 v[98:101], v68 offset:23040
	ds_read_b128 v[126:129], v1 offset:55296
	ds_read_b128 v[130:133], v1 offset:59904
	s_setprio 1
	ds_read_b128 v[86:89], v68 offset:18464
	s_waitcnt lgkmcnt(2)
	v_mfma_f32_32x32x16_bf16 v[34:49], v[94:97], v[126:129], v[34:49]
	s_waitcnt vmcnt(7)
	ds_write_b128 v66, v[140:143]
	s_waitcnt vmcnt(6)
	ds_write_b128 v66, v[102:105] offset:4608
	global_load_dwordx4 v[140:143], v[72:73], off offset:1664
	global_load_dwordx4 v[102:105], v[70:71], off offset:1664
	ds_read_b128 v[90:93], v1 offset:55328
	s_waitcnt lgkmcnt(4)
	v_mfma_f32_32x32x16_bf16 v[50:65], v[94:97], v[130:133], v[50:65]
	ds_read_b128 v[94:97], v1 offset:59936
	s_waitcnt lgkmcnt(1)
	v_mfma_f32_32x32x16_bf16 v[34:49], v[86:89], v[90:93], v[34:49]
	s_waitcnt lgkmcnt(0)
	v_mfma_f32_32x32x16_bf16 v[50:65], v[86:89], v[94:97], v[50:65]
	s_waitcnt vmcnt(7)
	ds_write_b128 v66, v[106:109] offset:9216
	s_waitcnt vmcnt(6)
	ds_write_b128 v66, v[110:113] offset:13824
	global_load_dwordx4 v[106:109], v[74:75], off offset:1664
	global_load_dwordx4 v[110:113], v[76:77], off offset:1664
	ds_read_b128 v[86:89], v68 offset:23072
	v_mfma_f32_32x32x16_bf16 v[2:17], v[98:101], v[126:129], v[2:17]
	v_mfma_f32_32x32x16_bf16 v[18:33], v[98:101], v[130:133], v[18:33]
	ds_read_b128 v[98:101], v68 offset:23136
	s_waitcnt lgkmcnt(1)
	v_mfma_f32_32x32x16_bf16 v[2:17], v[86:89], v[90:93], v[2:17]
	s_waitcnt vmcnt(7)
	ds_write_b128 v66, v[144:147] offset:36864
	s_waitcnt vmcnt(6)
	ds_write_b128 v66, v[122:125] offset:41472
	global_load_dwordx4 v[144:147], v[78:79], off offset:1664
	global_load_dwordx4 v[122:125], v[80:81], off offset:1664
	ds_read_b128 v[90:93], v1 offset:55360
	v_mfma_f32_32x32x16_bf16 v[18:33], v[86:89], v[94:97], v[18:33]
	ds_read_b128 v[86:89], v68 offset:18496
	ds_read_b128 v[94:97], v1 offset:59968
	s_waitcnt lgkmcnt(1)
	v_mfma_f32_32x32x16_bf16 v[34:49], v[86:89], v[90:93], v[34:49]
	s_waitcnt lgkmcnt(0)
	v_mfma_f32_32x32x16_bf16 v[50:65], v[86:89], v[94:97], v[50:65]
	s_waitcnt vmcnt(7)
	ds_write_b128 v66, v[118:121] offset:46080
	s_waitcnt vmcnt(6)
	ds_write_b128 v66, v[114:117] offset:50688
	global_load_dwordx4 v[118:121], v[82:83], off offset:1664
	global_load_dwordx4 v[114:117], v[84:85], off offset:1664
	ds_read_b128 v[86:89], v68 offset:23104
	s_waitcnt lgkmcnt(0)
	v_mfma_f32_32x32x16_bf16 v[2:17], v[86:89], v[90:93], v[2:17]
	ds_read_b128 v[90:93], v1 offset:55392
	v_mfma_f32_32x32x16_bf16 v[18:33], v[86:89], v[94:97], v[18:33]
	ds_read_b128 v[86:89], v68 offset:18528
	ds_read_b128 v[94:97], v1 offset:60000
	s_waitcnt lgkmcnt(1)
	v_mfma_f32_32x32x16_bf16 v[34:49], v[86:89], v[90:93], v[34:49]
	s_waitcnt lgkmcnt(0)
	v_mfma_f32_32x32x16_bf16 v[50:65], v[86:89], v[94:97], v[50:65]
	v_mfma_f32_32x32x16_bf16 v[2:17], v[98:101], v[90:93], v[2:17]
	v_mfma_f32_32x32x16_bf16 v[18:33], v[98:101], v[94:97], v[18:33]
	s_setprio 0
	s_barrier
	ds_read_b128 v[94:97], v68
	ds_read_b128 v[98:101], v68 offset:4608
	ds_read_b128 v[126:129], v1 offset:36864
	ds_read_b128 v[130:133], v1 offset:41472
	s_setprio 1
	ds_read_b128 v[86:89], v68 offset:32
	s_waitcnt lgkmcnt(2)
	v_mfma_f32_32x32x16_bf16 v[34:49], v[94:97], v[126:129], v[34:49]
	s_waitcnt vmcnt(7)
	ds_write_b128 v66, v[140:143] offset:18432
	s_waitcnt vmcnt(6)
	ds_write_b128 v66, v[102:105] offset:23040
	global_load_dwordx4 v[140:143], v[72:73], off offset:1792
	global_load_dwordx4 v[102:105], v[70:71], off offset:1792
	ds_read_b128 v[90:93], v1 offset:36896
	s_waitcnt lgkmcnt(4)
	v_mfma_f32_32x32x16_bf16 v[50:65], v[94:97], v[130:133], v[50:65]
	ds_read_b128 v[94:97], v1 offset:41504
	s_waitcnt lgkmcnt(1)
	v_mfma_f32_32x32x16_bf16 v[34:49], v[86:89], v[90:93], v[34:49]
	s_waitcnt lgkmcnt(0)
	v_mfma_f32_32x32x16_bf16 v[50:65], v[86:89], v[94:97], v[50:65]
	s_waitcnt vmcnt(7)
	ds_write_b128 v66, v[106:109] offset:27648
	s_waitcnt vmcnt(6)
	ds_write_b128 v66, v[110:113] offset:32256
	global_load_dwordx4 v[106:109], v[74:75], off offset:1792
	global_load_dwordx4 v[110:113], v[76:77], off offset:1792
	ds_read_b128 v[86:89], v68 offset:4640
	v_mfma_f32_32x32x16_bf16 v[2:17], v[98:101], v[126:129], v[2:17]
	v_mfma_f32_32x32x16_bf16 v[18:33], v[98:101], v[130:133], v[18:33]
	ds_read_b128 v[98:101], v68 offset:4704
	s_waitcnt lgkmcnt(1)
	v_mfma_f32_32x32x16_bf16 v[2:17], v[86:89], v[90:93], v[2:17]
	s_waitcnt vmcnt(7)
	ds_write_b128 v66, v[144:147] offset:55296
	s_waitcnt vmcnt(6)
	ds_write_b128 v66, v[122:125] offset:59904
	global_load_dwordx4 v[144:147], v[78:79], off offset:1792
	global_load_dwordx4 v[122:125], v[80:81], off offset:1792
	ds_read_b128 v[90:93], v1 offset:36928
	v_mfma_f32_32x32x16_bf16 v[18:33], v[86:89], v[94:97], v[18:33]
	ds_read_b128 v[86:89], v68 offset:64
	ds_read_b128 v[94:97], v1 offset:41536
	s_waitcnt lgkmcnt(1)
	v_mfma_f32_32x32x16_bf16 v[34:49], v[86:89], v[90:93], v[34:49]
	s_waitcnt lgkmcnt(0)
	v_mfma_f32_32x32x16_bf16 v[50:65], v[86:89], v[94:97], v[50:65]
	s_waitcnt vmcnt(7)
	ds_write_b128 v66, v[118:121] offset:64512
	s_waitcnt vmcnt(6)
	ds_write_b128 v69, v[114:117] offset:32256
	global_load_dwordx4 v[118:121], v[82:83], off offset:1792
	global_load_dwordx4 v[114:117], v[84:85], off offset:1792
	ds_read_b128 v[86:89], v68 offset:4672
	s_waitcnt lgkmcnt(0)
	v_mfma_f32_32x32x16_bf16 v[2:17], v[86:89], v[90:93], v[2:17]
	ds_read_b128 v[90:93], v1 offset:36960
	v_mfma_f32_32x32x16_bf16 v[18:33], v[86:89], v[94:97], v[18:33]
	ds_read_b128 v[86:89], v68 offset:96
	ds_read_b128 v[94:97], v1 offset:41568
	s_waitcnt lgkmcnt(1)
	v_mfma_f32_32x32x16_bf16 v[34:49], v[86:89], v[90:93], v[34:49]
	s_waitcnt lgkmcnt(0)
	v_mfma_f32_32x32x16_bf16 v[50:65], v[86:89], v[94:97], v[50:65]
	v_mfma_f32_32x32x16_bf16 v[2:17], v[98:101], v[90:93], v[2:17]
	v_mfma_f32_32x32x16_bf16 v[18:33], v[98:101], v[94:97], v[18:33]
	s_setprio 0
	s_barrier
; #define MFMA(a, b, c) __builtin_amdgcn_mfma_f32_32x32x16_bf16((a), (b), (c), 0, 0, 0)
; template <int TM, int TN>
; DI void gemm_mainloop(const u16* __restrict__ A, long lda, const u16* __restrict__ Bt, long ldb, int K, char* smem,
;                       f32x16 (&acc)[TM][TN]) {
;     ...
;   for (int kt = 0; kt < nk; kt++) {
;     const int buf = kt & 1;
;     const u16* cA = sA + buf * BM * LD + (wm * 32 * TM + r) * LD + h * 8;
;     const u16* cB = sB + buf * BN * LD + (wn * 32 * TN + r) * LD + h * 8;
;     bf16x8 af[TM], bfr[TN];
; #pragma unroll
;     for (int tm = 0; tm < TM; tm++) af[tm] = *(const bf16x8*)(cA + tm * 32 * LD);
; #pragma unroll
;     for (int tn = 0; tn < TN; tn++) bfr[tn] = *(const bf16x8*)(cB + tn * 32 * LD);
;     if (kt + 1 < nk) GEMM_SSTORE(buf ^ 1)
;     __builtin_amdgcn_sched_barrier(0);
;     __builtin_amdgcn_s_setprio(1);
; #pragma unroll
;     for (int tm = 0; tm < TM; tm++)
; #pragma unroll
;       for (int tn = 0; tn < TN; tn++) acc[tm][tn] = MFMA(af[tm], bfr[tn], acc[tm][tn]);
; #pragma unroll
;     for (int tm = 0; tm < TM; tm++) af[tm] = *(const bf16x8*)(cA + tm * 32 * LD + 16);
; #pragma unroll
;     for (int tn = 0; tn < TN; tn++) bfr[tn] = *(const bf16x8*)(cB + tn * 32 * LD + 16);
; #pragma unroll
;     for (int tm = 0; tm < TM; tm++)
; #pragma unroll
;       for (int tn = 0; tn < TN; tn++) acc[tm][tn] = MFMA(af[tm], bfr[tn], acc[tm][tn]);
;     __builtin_amdgcn_sched_group_barrier(0x8, 4, 0);
;     if (kt + 2 < nk) GEMM_GLOAD((kt + 2) * 64)
; #pragma unroll
;     for (int ks = 2; ks < 4; ks++) {
; #pragma unroll
;       for (int tm = 0; tm < TM; tm++) af[tm] = *(const bf16x8*)(cA + tm * 32 * LD + ks * 16);
; #pragma unroll
;       for (int tn = 0; tn < TN; tn++) bfr[tn] = *(const bf16x8*)(cB + tn * 32 * LD + ks * 16);
; #pragma unroll
;       for (int tm = 0; tm < TM; tm++)
; #pragma unroll
;         for (int tn = 0; tn < TN; tn++) acc[tm][tn] = MFMA(af[tm], bfr[tn], acc[tm][tn]);
;     }
;     __builtin_amdgcn_s_setprio(0);
;     __syncthreads();
;   }
	ds_read_b128 v[94:97], v68 offset:18432
	ds_read_b128 v[98:101], v68 offset:23040
	ds_read_b128 v[126:129], v1 offset:55296
	ds_read_b128 v[130:133], v1 offset:59904
	s_setprio 1
	ds_read_b128 v[86:89], v68 offset:18464
	s_waitcnt lgkmcnt(2)
	v_mfma_f32_32x32x16_bf16 v[34:49], v[94:97], v[126:129], v[34:49]
	s_waitcnt vmcnt(7)
	ds_write_b128 v66, v[140:143]
	s_waitcnt vmcnt(6)
	ds_write_b128 v66, v[102:105] offset:4608
	global_load_dwordx4 v[140:143], v[72:73], off offset:1920
	global_load_dwordx4 v[102:105], v[70:71], off offset:1920
	ds_read_b128 v[90:93], v1 offset:55328
	s_waitcnt lgkmcnt(4)
	v_mfma_f32_32x32x16_bf16 v[50:65], v[94:97], v[130:133], v[50:65]
	ds_read_b128 v[94:97], v1 offset:59936
	s_waitcnt lgkmcnt(1)
	v_mfma_f32_32x32x16_bf16 v[34:49], v[86:89], v[90:93], v[34:49]
	s_waitcnt lgkmcnt(0)
	v_mfma_f32_32x32x16_bf16 v[50:65], v[86:89], v[94:97], v[50:65]
	s_waitcnt vmcnt(7)
	ds_write_b128 v66, v[106:109] offset:9216
	s_waitcnt vmcnt(6)
	ds_write_b128 v66, v[110:113] offset:13824
	global_load_dwordx4 v[106:109], v[74:75], off offset:1920
	global_load_dwordx4 v[110:113], v[76:77], off offset:1920
	ds_read_b128 v[86:89], v68 offset:23072
	v_mfma_f32_32x32x16_bf16 v[2:17], v[98:101], v[126:129], v[2:17]
	v_mfma_f32_32x32x16_bf16 v[18:33], v[98:101], v[130:133], v[18:33]
	ds_read_b128 v[98:101], v68 offset:23136
	s_waitcnt lgkmcnt(1)
	v_mfma_f32_32x32x16_bf16 v[2:17], v[86:89], v[90:93], v[2:17]
	s_waitcnt vmcnt(7)
	ds_write_b128 v66, v[144:147] offset:36864
	s_waitcnt vmcnt(6)
	ds_write_b128 v66, v[122:125] offset:41472
	global_load_dwordx4 v[144:147], v[78:79], off offset:1920
	global_load_dwordx4 v[122:125], v[80:81], off offset:1920
	ds_read_b128 v[90:93], v1 offset:55360
	v_mfma_f32_32x32x16_bf16 v[18:33], v[86:89], v[94:97], v[18:33]
	ds_read_b128 v[86:89], v68 offset:18496
	ds_read_b128 v[94:97], v1 offset:59968
	s_waitcnt lgkmcnt(1)
	v_mfma_f32_32x32x16_bf16 v[34:49], v[86:89], v[90:93], v[34:49]
	s_waitcnt lgkmcnt(0)
	v_mfma_f32_32x32x16_bf16 v[50:65], v[86:89], v[94:97], v[50:65]
	s_waitcnt vmcnt(7)
	ds_write_b128 v66, v[118:121] offset:46080
	s_waitcnt vmcnt(6)
	ds_write_b128 v66, v[114:117] offset:50688
	global_load_dwordx4 v[118:121], v[82:83], off offset:1920
	global_load_dwordx4 v[114:117], v[84:85], off offset:1920
	ds_read_b128 v[86:89], v68 offset:23104
	s_waitcnt lgkmcnt(0)
	v_mfma_f32_32x32x16_bf16 v[2:17], v[86:89], v[90:93], v[2:17]
	ds_read_b128 v[90:93], v1 offset:55392
	v_mfma_f32_32x32x16_bf16 v[18:33], v[86:89], v[94:97], v[18:33]
	ds_read_b128 v[86:89], v68 offset:18528
	ds_read_b128 v[94:97], v1 offset:60000
	s_waitcnt lgkmcnt(1)
	v_mfma_f32_32x32x16_bf16 v[34:49], v[86:89], v[90:93], v[34:49]
	s_waitcnt lgkmcnt(0)
	v_mfma_f32_32x32x16_bf16 v[50:65], v[86:89], v[94:97], v[50:65]
	s_nop 0
	v_mfma_f32_32x32x16_bf16 v[2:17], v[98:101], v[90:93], v[2:17]
	v_mfma_f32_32x32x16_bf16 v[18:33], v[98:101], v[94:97], v[18:33]
	s_setprio 0
	s_barrier
	ds_read_b128 v[74:77], v68
	ds_read_b128 v[78:81], v68 offset:4608
	ds_read_b128 v[82:85], v1 offset:36864
	ds_read_b128 v[90:93], v1 offset:41472
	s_setprio 1
	ds_read_b128 v[70:73], v68 offset:32
	s_waitcnt lgkmcnt(2)
	v_mfma_f32_32x32x16_bf16 v[34:49], v[74:77], v[82:85], v[34:49]
	s_waitcnt vmcnt(7)
	ds_write_b128 v66, v[140:143] offset:18432
	s_waitcnt vmcnt(6)
	ds_write_b128 v66, v[102:105] offset:23040
	s_waitcnt lgkmcnt(3)
	v_mfma_f32_32x32x16_bf16 v[50:65], v[74:77], v[90:93], v[50:65]
	ds_read_b128 v[74:77], v1 offset:36896
	v_mfma_f32_32x32x16_bf16 v[2:17], v[78:81], v[82:85], v[2:17]
	v_mfma_f32_32x32x16_bf16 v[18:33], v[78:81], v[90:93], v[18:33]
	s_waitcnt vmcnt(5)
	ds_write_b128 v66, v[106:109] offset:27648
	s_waitcnt vmcnt(4)
	ds_write_b128 v66, v[110:113] offset:32256
	ds_read_b128 v[78:81], v1 offset:41504
	s_waitcnt lgkmcnt(3)
	v_mfma_f32_32x32x16_bf16 v[34:49], v[70:73], v[74:77], v[34:49]
	s_waitcnt lgkmcnt(0)
	v_mfma_f32_32x32x16_bf16 v[50:65], v[70:73], v[78:81], v[50:65]
	ds_read_b128 v[70:73], v68 offset:4640
	s_waitcnt lgkmcnt(0)
	v_mfma_f32_32x32x16_bf16 v[2:17], v[70:73], v[74:77], v[2:17]
	s_waitcnt vmcnt(3)
	ds_write_b128 v66, v[144:147] offset:55296
	s_waitcnt vmcnt(2)
	ds_write_b128 v66, v[122:125] offset:59904
	ds_read_b128 v[74:77], v1 offset:36928
	v_mfma_f32_32x32x16_bf16 v[18:33], v[70:73], v[78:81], v[18:33]
	ds_read_b128 v[70:73], v68 offset:64
	ds_read_b128 v[78:81], v1 offset:41536
	s_waitcnt lgkmcnt(1)
	v_mfma_f32_32x32x16_bf16 v[34:49], v[70:73], v[74:77], v[34:49]
	s_waitcnt lgkmcnt(0)
	v_mfma_f32_32x32x16_bf16 v[50:65], v[70:73], v[78:81], v[50:65]
	s_waitcnt vmcnt(1)
	ds_write_b128 v66, v[118:121] offset:64512
	s_waitcnt vmcnt(0)
	ds_write_b128 v69, v[114:117] offset:32256
	ds_read_b128 v[70:73], v68 offset:4672
	s_waitcnt lgkmcnt(0)
	v_mfma_f32_32x32x16_bf16 v[2:17], v[70:73], v[74:77], v[2:17]
	ds_read_b128 v[74:77], v1 offset:36960
	v_mfma_f32_32x32x16_bf16 v[18:33], v[70:73], v[78:81], v[18:33]
	ds_read_b128 v[70:73], v68 offset:96
	ds_read_b128 v[78:81], v1 offset:41568
	s_waitcnt lgkmcnt(1)
	v_mfma_f32_32x32x16_bf16 v[34:49], v[70:73], v[74:77], v[34:49]
	s_waitcnt lgkmcnt(0)
	v_mfma_f32_32x32x16_bf16 v[50:65], v[70:73], v[78:81], v[50:65]
	ds_read_b128 v[70:73], v68 offset:4704
	s_waitcnt lgkmcnt(0)
	v_mfma_f32_32x32x16_bf16 v[2:17], v[70:73], v[74:77], v[2:17]
	v_mfma_f32_32x32x16_bf16 v[18:33], v[70:73], v[78:81], v[18:33]
	s_setprio 0
	s_barrier
; #define MFMA(a, b, c) __builtin_amdgcn_mfma_f32_32x32x16_bf16((a), (b), (c), 0, 0, 0)
; DI int crow(int i, int h) { return (i & 3) + 8 * (i >> 2) + 4 * h; }
; template <int TM, int TN>
; DI void gemm_mainloop(const u16* __restrict__ A, long lda, const u16* __restrict__ Bt, long ldb, int K, char* smem,
;                       f32x16 (&acc)[TM][TN]) {
;     ...
;     for (int tn = 0; tn < TN; tn++) bfr[tn] = *(const bf16x8*)(cB + tn * 32 * LD + 16);
; #pragma unroll
;     for (int tm = 0; tm < TM; tm++)
; #pragma unroll
;       for (int tn = 0; tn < TN; tn++) acc[tm][tn] = MFMA(af[tm], bfr[tn], acc[tm][tn]);
;     __builtin_amdgcn_sched_group_barrier(0x8, 4, 0);
;     if (kt + 2 < nk) GEMM_GLOAD((kt + 2) * 64)
; #pragma unroll
;     for (int ks = 2; ks < 4; ks++) {
; #pragma unroll
;       for (int tm = 0; tm < TM; tm++) af[tm] = *(const bf16x8*)(cA + tm * 32 * LD + ks * 16);
; #pragma unroll
;       for (int tn = 0; tn < TN; tn++) bfr[tn] = *(const bf16x8*)(cB + tn * 32 * LD + ks * 16);
; #pragma unroll
;       for (int tm = 0; tm < TM; tm++)
; #pragma unroll
;         for (int tn = 0; tn < TN; tn++) acc[tm][tn] = MFMA(af[tm], bfr[tn], acc[tm][tn]);
;     }
;     __builtin_amdgcn_s_setprio(0);
;     __syncthreads();
;   }
; template <int TM, int TN, class Epi>
; DI void gemm_tile(const u16* A, long lda, const u16* Bt, long ldb, int K, int m0, int n0, char* smem, const Epi& epi) {
;     ...
; #pragma unroll
;   for (int tm = 0; tm < TM; tm++)
; #pragma unroll
;     for (int tn = 0; tn < TN; tn++)
; #pragma unroll
;       for (int i = 0; i < 16; i++)
;         Ct[(wm * 32 * TM + tm * 32 + crow(i, h)) * LDC + wn * 32 * TN + tn * 32 + r] = acc[tm][tn][i];
;   __syncthreads();
;   epi(Ct, LDC, m0, n0, tid, BM);
;   __syncthreads();
;   (void)BM;
; }
;   DI void operator()(const float* Ct, int ldc, int m0, int n0, int tid, int bm) const {
; #pragma unroll 4
;     for (int it = 0; it < bm / 16; it++) {
;       int id = tid + 256 * it; int row = id >> 4, c8 = (id & 15) * 8;
;       int n = n0 + c8;
;       if (n < nmax) {
;         const float* c = Ct + row * ldc + c8;
;         float4 a = *(const float4*)c, b = *(const float4*)(c + 4);
;         uint4 v; v.x = pk2(a.x, a.y); v.y = pk2(a.z, a.w); v.z = pk2(b.x, b.y); v.w = pk2(b.z, b.w);
;         *(uint4*)(out + (long)(m0 + row) * ldo + n) = v;
;         if (gates != nullptr && n == 1952) {
	ds_read_b128 v[70:73], v68 offset:18432
	ds_read_b128 v[74:77], v68 offset:23040
	ds_read_b128 v[78:81], v1 offset:55296
	ds_read_b128 v[82:85], v1 offset:59904
	s_setprio 1
	s_waitcnt lgkmcnt(1)
	v_mfma_f32_32x32x16_bf16 v[34:49], v[70:73], v[78:81], v[34:49]
	s_waitcnt lgkmcnt(0)
	v_mfma_f32_32x32x16_bf16 v[50:65], v[70:73], v[82:85], v[50:65]
	ds_read_b128 v[70:73], v68 offset:18464
	v_mfma_f32_32x32x16_bf16 v[2:17], v[74:77], v[78:81], v[2:17]
	ds_read_b128 v[78:81], v1 offset:59936
	v_mfma_f32_32x32x16_bf16 v[18:33], v[74:77], v[82:85], v[18:33]
	ds_read_b128 v[74:77], v1 offset:55328
	s_waitcnt lgkmcnt(0)
	v_mfma_f32_32x32x16_bf16 v[34:49], v[70:73], v[74:77], v[34:49]
	v_mfma_f32_32x32x16_bf16 v[50:65], v[70:73], v[78:81], v[50:65]
	ds_read_b128 v[70:73], v68 offset:23072
	s_waitcnt lgkmcnt(0)
	v_mfma_f32_32x32x16_bf16 v[2:17], v[70:73], v[74:77], v[2:17]
	ds_read_b128 v[74:77], v1 offset:55360
	v_mfma_f32_32x32x16_bf16 v[18:33], v[70:73], v[78:81], v[18:33]
	ds_read_b128 v[70:73], v68 offset:18496
	ds_read_b128 v[78:81], v1 offset:59968
	s_waitcnt lgkmcnt(1)
	v_mfma_f32_32x32x16_bf16 v[34:49], v[70:73], v[74:77], v[34:49]
	s_waitcnt lgkmcnt(0)
	v_mfma_f32_32x32x16_bf16 v[50:65], v[70:73], v[78:81], v[50:65]
	ds_read_b128 v[70:73], v68 offset:23104
	s_waitcnt lgkmcnt(0)
	v_mfma_f32_32x32x16_bf16 v[2:17], v[70:73], v[74:77], v[2:17]
	ds_read_b128 v[74:77], v1 offset:55392
	v_mfma_f32_32x32x16_bf16 v[18:33], v[70:73], v[78:81], v[18:33]
	ds_read_b128 v[70:73], v68 offset:18528
	ds_read_b128 v[78:81], v1 offset:60000
	s_waitcnt lgkmcnt(1)
	v_mfma_f32_32x32x16_bf16 v[34:49], v[70:73], v[74:77], v[34:49]
	s_waitcnt lgkmcnt(0)
	v_mfma_f32_32x32x16_bf16 v[50:65], v[70:73], v[78:81], v[50:65]
	ds_read_b128 v[68:71], v68 offset:23136
	s_waitcnt lgkmcnt(0)
	v_mfma_f32_32x32x16_bf16 v[2:17], v[68:71], v[74:77], v[2:17]
	v_mfma_f32_32x32x16_bf16 v[18:33], v[68:71], v[78:81], v[18:33]
	s_setprio 0
	v_mov_b32_e32 v1, v0
	s_barrier
	s_mov_b32 s38, 0
	v_lshrrev_b32_e32 v66, 1, v1
	v_and_b32_e32 v66, 0xfffffc0, v66
	v_lshrrev_b32_e32 v68, 3, v1
	v_and_or_b32 v66, v68, 4, v66
	v_and_b32_e32 v68, 0x5f, v1
	v_mul_lo_u32 v66, v66, s28
	v_lshl_add_u32 v66, v68, 2, v66
	ds_write2_b32 v66, v34, v50 offset1:32
	v_add_u32_e32 v34, 0x400, v66
	ds_write2_b32 v34, v36, v52 offset0:8 offset1:40
	ds_write2_b32 v34, v37, v53 offset0:140 offset1:172
	v_add_u32_e32 v34, 0x1000, v66
	ds_write2_b32 v34, v38, v54 offset0:32 offset1:64
	ds_write2_b32 v34, v39, v55 offset0:164 offset1:196
	v_add_u32_e32 v34, 0x1400, v66
	ds_write2_b32 v34, v40, v56 offset0:40 offset1:72
	ds_write2_b32 v34, v41, v57 offset0:172 offset1:204
	v_add_u32_e32 v34, 0x2000, v66
	ds_write2_b32 v34, v42, v58 offset0:64 offset1:96
	ds_write2_b32 v34, v43, v59 offset0:196 offset1:228
	v_add_u32_e32 v34, 0x2400, v66
	ds_write2_b32 v34, v44, v60 offset0:72 offset1:104
	ds_write2_b32 v34, v45, v61 offset0:204 offset1:236
	v_add_u32_e32 v34, 0x3000, v66
	ds_write2_b32 v34, v46, v62 offset0:96 offset1:128
	v_add_u32_e32 v34, 0x3200, v66
	ds_write2_b32 v34, v47, v63 offset0:100 offset1:132
	v_add_u32_e32 v34, 0x3400, v66
	ds_write2_b32 v34, v48, v64 offset0:104 offset1:136
	v_add_u32_e32 v34, 0x3600, v66
	ds_write2_b32 v34, v49, v65 offset0:108 offset1:140
	v_add_u32_e32 v34, 0x4000, v66
	ds_write2_b32 v34, v2, v18 offset0:128 offset1:160
	v_add_u32_e32 v2, 0x4400, v66
	ds_write2_b32 v2, v3, v19 offset0:4 offset1:36
	ds_write2_b32 v2, v4, v20 offset0:136 offset1:168
	v_add_u32_e32 v2, 0x4800, v66
	ds_write2_b32 v2, v5, v21 offset0:12 offset1:44
	v_add_u32_e32 v2, 0x5000, v66
	ds_write2_b32 v2, v6, v22 offset0:160 offset1:192
	v_add_u32_e32 v2, 0x5400, v66
	ds_write2_b32 v2, v7, v23 offset0:36 offset1:68
	ds_write2_b32 v2, v8, v24 offset0:168 offset1:200
	v_add_u32_e32 v2, 0x5800, v66
	ds_write2_b32 v2, v9, v25 offset0:44 offset1:76
	v_add_u32_e32 v2, 0x6000, v66
	ds_write2_b32 v2, v10, v26 offset0:192 offset1:224
	v_add_u32_e32 v2, 0x6400, v66
	ds_write2_b32 v2, v11, v27 offset0:68 offset1:100
	ds_write2_b32 v2, v12, v28 offset0:200 offset1:232
	v_add_u32_e32 v2, 0x6800, v66
	ds_write2_b32 v2, v13, v29 offset0:76 offset1:108
	v_add_u32_e32 v2, 0x7200, v66
	ds_write2_b32 v2, v14, v30 offset0:96 offset1:128
	v_add_u32_e32 v2, 0x7400, v66
	ds_write2_b32 v2, v15, v31 offset0:100 offset1:132
	v_add_u32_e32 v2, 0x7600, v66
	ds_write2_b32 v2, v16, v32 offset0:104 offset1:136
	v_add_u32_e32 v2, 0x7800, v66
	ds_write2_b32 v2, v17, v33 offset0:108 offset1:140
	v_lshlrev_b32_e32 v2, 3, v1
	v_and_b32_e32 v3, 0x78, v2
	v_or_b32_e32 v2, s4, v3
	v_lshlrev_b32_e32 v10, 2, v3
	v_ashrrev_i32_e32 v3, 31, v2
	v_cmp_eq_u32_e32 vcc, s29, v2
	v_cmp_gt_i32_e64 s[4:5], s30, v2
	v_lshl_add_u64 v[12:13], v[2:3], 1, s[6:7]
	ds_write2_b32 v66, v35, v51 offset0:132 offset1:164
	s_waitcnt lgkmcnt(0)
	s_barrier
	s_branch .LBB0_148

; #define MFMA(a, b, c) __builtin_amdgcn_mfma_f32_32x32x16_bf16((a), (b), (c), 0, 0, 0)
; DI u16* wsb(const Params& p, size_t off) { return (u16*)(p.ws + off); }
; template <int TM, int TN>
; DI void gemm_mainloop(const u16* __restrict__ A, long lda, const u16* __restrict__ Bt, long ldb, int K, char* smem,
;                       f32x16 (&acc)[TM][TN]) {
;     ...
;   const int nk = K / 64;
;   const int lrow = tid >> 3, lch = (tid & 7) * 8;
;   const u16* gA = A + (long)lrow * lda + lch;
;   const u16* gB = Bt + (long)lrow * ldb + lch;
;   const int soff = lrow * LD + lch;
;     ...
;   GEMM_GLOAD(0)
;   __syncthreads();
;   GEMM_SSTORE(0)
;   if (nk > 1) GEMM_GLOAD(64)
;   __syncthreads();
;   for (int kt = 0; kt < nk; kt++) {
;     const int buf = kt & 1;
;     const u16* cA = sA + buf * BM * LD + (wm * 32 * TM + r) * LD + h * 8;
;     const u16* cB = sB + buf * BN * LD + (wn * 32 * TN + r) * LD + h * 8;
;     bf16x8 af[TM], bfr[TN];
; #pragma unroll
;     for (int tm = 0; tm < TM; tm++) af[tm] = *(const bf16x8*)(cA + tm * 32 * LD);
; #pragma unroll
;     for (int tn = 0; tn < TN; tn++) bfr[tn] = *(const bf16x8*)(cB + tn * 32 * LD);
;     if (kt + 1 < nk) GEMM_SSTORE(buf ^ 1)
;     __builtin_amdgcn_sched_barrier(0);
;     __builtin_amdgcn_s_setprio(1);
; #pragma unroll
;     for (int tm = 0; tm < TM; tm++)
; #pragma unroll
;       for (int tn = 0; tn < TN; tn++) acc[tm][tn] = MFMA(af[tm], bfr[tn], acc[tm][tn]);
; #pragma unroll
;     for (int tm = 0; tm < TM; tm++) af[tm] = *(const bf16x8*)(cA + tm * 32 * LD + 16);
; #pragma unroll
;     for (int tn = 0; tn < TN; tn++) bfr[tn] = *(const bf16x8*)(cB + tn * 32 * LD + 16);
; #pragma unroll
;     for (int tm = 0; tm < TM; tm++)
; #pragma unroll
;       for (int tn = 0; tn < TN; tn++) acc[tm][tn] = MFMA(af[tm], bfr[tn], acc[tm][tn]);
; DI void phase_inproj(const Params& p, const Sched& sc, int l, char* smem) {
;     ...
;     for (int u = blockIdx.x; u < 128; u += gridDim.x) {
;       int l2 = u >> 6, which = (u >> 5) & 1, mt = (u >> 3) & 3, nt = u & 7;
;       const u16* W2 = wsb(p, WS_W) + (size_t)l2 * W_LAYER + (which ? W_XV : W_XK);
;       EpiF32 epi{p.out + (which ? O_PMEMV : O_PMEMK) + (size_t)l2 * 524288, 1024};
;       gemm_tile<2, 2>(wsb(p, WS_HM), LDA, W2, LDW, 1024, mt * 128, nt * 128, smem, epi);
.LBB0_159:
	s_ashr_i32 s22, s21, 6
	s_ashr_i32 s23, s22, 31
	s_mul_i32 s25, s22, 0x2168000
	s_mul_hi_i32 s24, s22, 0x2168000
	s_add_u32 s25, s10, s25
	s_addc_u32 s24, s11, s24
	s_bitcmp0_b32 s21, 5
	s_cselect_b32 s26, s5, 0xc88000
	s_cselect_b32 s27, s6, 0xb50e040
	s_add_u32 s28, s25, s26
	s_addc_u32 s29, s24, 0
	s_add_u32 s26, s8, s27
	s_addc_u32 s27, s9, 0
	s_lshl_b64 s[24:25], s[22:23], 21
	s_add_u32 s23, s26, s24
	s_addc_u32 s24, s27, s25
	s_lshl_b32 s22, s21, 4
	s_and_b32 s22, s22, 0x180
	s_lshl_b32 s25, s21, 7
	s_and_b32 s25, s25, 0x380
	s_mul_i32 s26, s22, 0x880
	s_add_u32 s26, s3, s26
	v_mov_b32_e32 v1, v0
	s_addc_u32 s27, s4, 0
	s_mul_i32 s30, s25, 0x880
	v_lshlrev_b32_e32 v2, 3, v1
	v_ashrrev_i32_e32 v68, 3, v1
	v_and_b32_e32 v69, 56, v2
	v_mov_b64_e32 v[2:3], s[26:27]
	v_mad_i64_i32 v[2:3], s[26:27], v68, s7, v[2:3]
	v_lshlrev_b32_e32 v66, 1, v69
	v_lshl_add_u64 v[72:73], v[2:3], 0, v[66:67]
	v_add_co_u32_e32 v70, vcc, s15, v72
	s_add_u32 s28, s28, s30
	s_nop 0
	v_addc_co_u32_e32 v71, vcc, 0, v73, vcc
	s_addc_u32 s29, s29, 0
	v_add_co_u32_e32 v74, vcc, s16, v72
	v_mov_b64_e32 v[2:3], s[28:29]
	s_nop 0
	v_addc_co_u32_e32 v75, vcc, 0, v73, vcc
	v_mad_i64_i32 v[18:19], s[26:27], v68, s7, v[2:3]
	v_add_co_u32_e32 v78, vcc, s17, v72
	v_lshl_add_u64 v[76:77], v[18:19], 0, v[66:67]
	s_nop 0
	v_addc_co_u32_e32 v79, vcc, 0, v73, vcc
	v_add_co_u32_e32 v80, vcc, s15, v76
	global_load_dwordx4 v[2:5], v[72:73], off
	s_nop 0
	v_addc_co_u32_e32 v81, vcc, 0, v77, vcc
	v_add_co_u32_e32 v82, vcc, s16, v76
	global_load_dwordx4 v[6:9], v[70:71], off
	s_nop 0
	v_addc_co_u32_e32 v83, vcc, 0, v77, vcc
	v_add_co_u32_e32 v84, vcc, s17, v76
	global_load_dwordx4 v[10:13], v[74:75], off
	s_nop 0
	v_addc_co_u32_e32 v85, vcc, 0, v77, vcc
	global_load_dwordx4 v[14:17], v[78:79], off
	global_load_dwordx4 v[18:21], v[76:77], off
	global_load_dwordx4 v[22:25], v[80:81], off
	global_load_dwordx4 v[26:29], v[82:83], off
	global_load_dwordx4 v[30:33], v[84:85], off
	s_barrier
	global_load_dwordx4 v[34:37], v[72:73], off offset:128
	global_load_dwordx4 v[38:41], v[70:71], off offset:128
	global_load_dwordx4 v[42:45], v[74:75], off offset:128
	global_load_dwordx4 v[46:49], v[78:79], off offset:128
	global_load_dwordx4 v[50:53], v[76:77], off offset:128
	global_load_dwordx4 v[54:57], v[80:81], off offset:128
	global_load_dwordx4 v[58:61], v[82:83], off offset:128
	global_load_dwordx4 v[62:65], v[84:85], off offset:128
	v_and_b32_e32 v66, 31, v1
	v_lshrrev_b32_e32 v86, 1, v1
	v_mul_lo_u32 v68, v68, s14
	v_and_or_b32 v87, v86, s18, v66
	v_and_b32_e32 v86, 16, v86
	v_add_lshl_u32 v66, v68, v69, 1
	v_mad_u64_u32 v[68:69], s[26:27], v87, s19, v[86:87]
	v_and_b32_e32 v1, 0x5f, v1
	v_mad_u32_u24 v1, v1, s19, v86
	v_add_u32_e32 v69, 0x9000, v66
	s_waitcnt vmcnt(15)
	ds_write_b128 v66, v[2:5]
	s_waitcnt vmcnt(14)
	ds_write_b128 v66, v[6:9] offset:4608
	s_waitcnt vmcnt(13)
	ds_write_b128 v66, v[10:13] offset:9216
	s_waitcnt vmcnt(12)
	ds_write_b128 v66, v[14:17] offset:13824
	s_waitcnt vmcnt(11)
	ds_write_b128 v66, v[18:21] offset:36864
	s_waitcnt vmcnt(10)
	ds_write_b128 v66, v[22:25] offset:41472
	s_waitcnt vmcnt(9)
	ds_write_b128 v66, v[26:29] offset:46080
	s_waitcnt vmcnt(8)
	ds_write_b128 v66, v[30:33] offset:50688
	s_waitcnt lgkmcnt(0)
	s_barrier
	ds_read_b128 v[2:5], v68
	ds_read_b128 v[18:21], v68 offset:4608
	ds_read_b128 v[6:9], v1 offset:36864
	ds_read_b128 v[22:25], v1 offset:41472
	s_waitcnt vmcnt(7)
	ds_write_b128 v66, v[34:37] offset:18432
	s_waitcnt vmcnt(6)
	ds_write_b128 v66, v[38:41] offset:23040
	s_waitcnt vmcnt(5)
	ds_write_b128 v66, v[42:45] offset:27648
	s_waitcnt vmcnt(4)
	ds_write_b128 v66, v[46:49] offset:32256
	s_waitcnt vmcnt(3)
	ds_write_b128 v66, v[50:53] offset:55296
	s_waitcnt vmcnt(2)
	ds_write_b128 v66, v[54:57] offset:59904
	s_waitcnt vmcnt(1)
	ds_write_b128 v66, v[58:61] offset:64512
	s_waitcnt vmcnt(0)
	ds_write_b128 v69, v[62:65] offset:32256
	s_setprio 1
	ds_read_b128 v[86:89], v68 offset:32
	s_waitcnt lgkmcnt(10)
	v_mfma_f32_32x32x16_bf16 v[34:49], v[2:5], v[6:9], 0
	ds_read_b128 v[90:93], v1 offset:36896
	ds_read_b128 v[94:97], v1 offset:41504
	ds_read_b128 v[98:101], v68 offset:4704
	global_load_dwordx4 v[102:105], v[70:71], off offset:256
	global_load_dwordx4 v[106:109], v[74:75], off offset:256
	global_load_dwordx4 v[110:113], v[78:79], off offset:256
	global_load_dwordx4 v[114:117], v[84:85], off offset:256
	s_waitcnt lgkmcnt(12)
	v_mfma_f32_32x32x16_bf16 v[50:65], v[2:5], v[22:25], 0
	global_load_dwordx4 v[118:121], v[82:83], off offset:256
	global_load_dwordx4 v[122:125], v[80:81], off offset:256
	global_load_dwordx4 v[140:143], v[72:73], off offset:256
	global_load_dwordx4 v[144:147], v[76:77], off offset:256
	s_waitcnt lgkmcnt(2)
	v_mfma_f32_32x32x16_bf16 v[34:49], v[86:89], v[90:93], v[34:49]
	s_waitcnt lgkmcnt(1)
	v_mfma_f32_32x32x16_bf16 v[50:65], v[86:89], v[94:97], v[50:65]
	ds_read_b128 v[86:89], v68 offset:4640
	v_mfma_f32_32x32x16_bf16 v[2:17], v[18:21], v[6:9], 0
	v_mfma_f32_32x32x16_bf16 v[18:33], v[18:21], v[22:25], 0
	s_waitcnt lgkmcnt(0)
	v_mfma_f32_32x32x16_bf16 v[2:17], v[86:89], v[90:93], v[2:17]
	ds_read_b128 v[90:93], v1 offset:36928
	v_mfma_f32_32x32x16_bf16 v[18:33], v[86:89], v[94:97], v[18:33]
	ds_read_b128 v[86:89], v68 offset:64
	ds_read_b128 v[94:97], v1 offset:41536
	s_waitcnt lgkmcnt(1)
	v_mfma_f32_32x32x16_bf16 v[34:49], v[86:89], v[90:93], v[34:49]
	s_waitcnt lgkmcnt(0)
	v_mfma_f32_32x32x16_bf16 v[50:65], v[86:89], v[94:97], v[50:65]
	ds_read_b128 v[86:89], v68 offset:4672
	s_waitcnt lgkmcnt(0)
	v_mfma_f32_32x32x16_bf16 v[2:17], v[86:89], v[90:93], v[2:17]
	ds_read_b128 v[90:93], v1 offset:36960
	v_mfma_f32_32x32x16_bf16 v[18:33], v[86:89], v[94:97], v[18:33]
	ds_read_b128 v[86:89], v68 offset:96
	ds_read_b128 v[94:97], v1 offset:41568
	s_waitcnt lgkmcnt(1)
	v_mfma_f32_32x32x16_bf16 v[34:49], v[86:89], v[90:93], v[34:49]
	s_waitcnt lgkmcnt(0)
	v_mfma_f32_32x32x16_bf16 v[50:65], v[86:89], v[94:97], v[50:65]
	v_mfma_f32_32x32x16_bf16 v[2:17], v[98:101], v[90:93], v[2:17]
	v_mfma_f32_32x32x16_bf16 v[18:33], v[98:101], v[94:97], v[18:33]
	s_setprio 0
	s_barrier
; #define MFMA(a, b, c) __builtin_amdgcn_mfma_f32_32x32x16_bf16((a), (b), (c), 0, 0, 0)
; template <int TM, int TN>
; DI void gemm_mainloop(const u16* __restrict__ A, long lda, const u16* __restrict__ Bt, long ldb, int K, char* smem,
;                       f32x16 (&acc)[TM][TN]) {
;     ...
;   for (int kt = 0; kt < nk; kt++) {
;     const int buf = kt & 1;
;     const u16* cA = sA + buf * BM * LD + (wm * 32 * TM + r) * LD + h * 8;
;     const u16* cB = sB + buf * BN * LD + (wn * 32 * TN + r) * LD + h * 8;
;     bf16x8 af[TM], bfr[TN];
; #pragma unroll
;     for (int tm = 0; tm < TM; tm++) af[tm] = *(const bf16x8*)(cA + tm * 32 * LD);
; #pragma unroll
;     for (int tn = 0; tn < TN; tn++) bfr[tn] = *(const bf16x8*)(cB + tn * 32 * LD);
;     if (kt + 1 < nk) GEMM_SSTORE(buf ^ 1)
;     __builtin_amdgcn_sched_barrier(0);
;     __builtin_amdgcn_s_setprio(1);
; #pragma unroll
;     for (int tm = 0; tm < TM; tm++)
; #pragma unroll
;       for (int tn = 0; tn < TN; tn++) acc[tm][tn] = MFMA(af[tm], bfr[tn], acc[tm][tn]);
; #pragma unroll
;     for (int tm = 0; tm < TM; tm++) af[tm] = *(const bf16x8*)(cA + tm * 32 * LD + 16);
; #pragma unroll
;     for (int tn = 0; tn < TN; tn++) bfr[tn] = *(const bf16x8*)(cB + tn * 32 * LD + 16);
; #pragma unroll
;     for (int tm = 0; tm < TM; tm++)
; #pragma unroll
;       for (int tn = 0; tn < TN; tn++) acc[tm][tn] = MFMA(af[tm], bfr[tn], acc[tm][tn]);
;     __builtin_amdgcn_sched_group_barrier(0x8, 4, 0);
;     if (kt + 2 < nk) GEMM_GLOAD((kt + 2) * 64)
; #pragma unroll
;     for (int ks = 2; ks < 4; ks++) {
; #pragma unroll
;       for (int tm = 0; tm < TM; tm++) af[tm] = *(const bf16x8*)(cA + tm * 32 * LD + ks * 16);
; #pragma unroll
;       for (int tn = 0; tn < TN; tn++) bfr[tn] = *(const bf16x8*)(cB + tn * 32 * LD + ks * 16);
; #pragma unroll
;       for (int tm = 0; tm < TM; tm++)
; #pragma unroll
;         for (int tn = 0; tn < TN; tn++) acc[tm][tn] = MFMA(af[tm], bfr[tn], acc[tm][tn]);
;     }
;     __builtin_amdgcn_s_setprio(0);
;     __syncthreads();
;   }
	ds_read_b128 v[94:97], v68 offset:18432
	ds_read_b128 v[98:101], v68 offset:23040
	ds_read_b128 v[126:129], v1 offset:55296
	ds_read_b128 v[130:133], v1 offset:59904
	s_setprio 1
	ds_read_b128 v[86:89], v68 offset:18464
	s_waitcnt lgkmcnt(2)
	v_mfma_f32_32x32x16_bf16 v[34:49], v[94:97], v[126:129], v[34:49]
	s_waitcnt vmcnt(1)
	ds_write_b128 v66, v[140:143]
	ds_write_b128 v66, v[102:105] offset:4608
	global_load_dwordx4 v[140:143], v[72:73], off offset:384
	global_load_dwordx4 v[102:105], v[70:71], off offset:384
	ds_read_b128 v[90:93], v1 offset:55328
	s_waitcnt lgkmcnt(4)
	v_mfma_f32_32x32x16_bf16 v[50:65], v[94:97], v[130:133], v[50:65]
	ds_read_b128 v[94:97], v1 offset:59936
	s_waitcnt lgkmcnt(1)
	v_mfma_f32_32x32x16_bf16 v[34:49], v[86:89], v[90:93], v[34:49]
	s_waitcnt lgkmcnt(0)
	v_mfma_f32_32x32x16_bf16 v[50:65], v[86:89], v[94:97], v[50:65]
	ds_write_b128 v66, v[106:109] offset:9216
	ds_write_b128 v66, v[110:113] offset:13824
	global_load_dwordx4 v[106:109], v[74:75], off offset:384
	global_load_dwordx4 v[110:113], v[78:79], off offset:384
	ds_read_b128 v[86:89], v68 offset:23072
	v_mfma_f32_32x32x16_bf16 v[2:17], v[98:101], v[126:129], v[2:17]
	v_mfma_f32_32x32x16_bf16 v[18:33], v[98:101], v[130:133], v[18:33]
	ds_read_b128 v[98:101], v68 offset:23136
	s_waitcnt lgkmcnt(1)
	v_mfma_f32_32x32x16_bf16 v[2:17], v[86:89], v[90:93], v[2:17]
	s_waitcnt vmcnt(4)
	ds_write_b128 v66, v[144:147] offset:36864
	ds_write_b128 v66, v[122:125] offset:41472
	global_load_dwordx4 v[144:147], v[76:77], off offset:384
	global_load_dwordx4 v[122:125], v[80:81], off offset:384
	ds_read_b128 v[90:93], v1 offset:55360
	v_mfma_f32_32x32x16_bf16 v[18:33], v[86:89], v[94:97], v[18:33]
	ds_read_b128 v[86:89], v68 offset:18496
	ds_read_b128 v[94:97], v1 offset:59968
	s_waitcnt lgkmcnt(1)
	v_mfma_f32_32x32x16_bf16 v[34:49], v[86:89], v[90:93], v[34:49]
	s_waitcnt lgkmcnt(0)
	v_mfma_f32_32x32x16_bf16 v[50:65], v[86:89], v[94:97], v[50:65]
	ds_write_b128 v66, v[118:121] offset:46080
	ds_write_b128 v66, v[114:117] offset:50688
	global_load_dwordx4 v[118:121], v[82:83], off offset:384
	global_load_dwordx4 v[114:117], v[84:85], off offset:384
	ds_read_b128 v[86:89], v68 offset:23104
	s_waitcnt lgkmcnt(0)
	v_mfma_f32_32x32x16_bf16 v[2:17], v[86:89], v[90:93], v[2:17]
	ds_read_b128 v[90:93], v1 offset:55392
	v_mfma_f32_32x32x16_bf16 v[18:33], v[86:89], v[94:97], v[18:33]
	ds_read_b128 v[86:89], v68 offset:18528
	ds_read_b128 v[94:97], v1 offset:60000
	s_waitcnt lgkmcnt(1)
	v_mfma_f32_32x32x16_bf16 v[34:49], v[86:89], v[90:93], v[34:49]
	s_waitcnt lgkmcnt(0)
	v_mfma_f32_32x32x16_bf16 v[50:65], v[86:89], v[94:97], v[50:65]
	v_mfma_f32_32x32x16_bf16 v[2:17], v[98:101], v[90:93], v[2:17]
	v_mfma_f32_32x32x16_bf16 v[18:33], v[98:101], v[94:97], v[18:33]
	s_setprio 0
	s_barrier
	ds_read_b128 v[94:97], v68
	ds_read_b128 v[98:101], v68 offset:4608
	ds_read_b128 v[126:129], v1 offset:36864
	ds_read_b128 v[130:133], v1 offset:41472
	s_setprio 1
	ds_read_b128 v[86:89], v68 offset:32
	s_waitcnt lgkmcnt(2)
	v_mfma_f32_32x32x16_bf16 v[34:49], v[94:97], v[126:129], v[34:49]
	s_waitcnt vmcnt(7)
	ds_write_b128 v66, v[140:143] offset:18432
	s_waitcnt vmcnt(6)
	ds_write_b128 v66, v[102:105] offset:23040
	global_load_dwordx4 v[140:143], v[72:73], off offset:512
	global_load_dwordx4 v[102:105], v[70:71], off offset:512
	ds_read_b128 v[90:93], v1 offset:36896
	s_waitcnt lgkmcnt(4)
	v_mfma_f32_32x32x16_bf16 v[50:65], v[94:97], v[130:133], v[50:65]
	ds_read_b128 v[94:97], v1 offset:41504
	s_waitcnt lgkmcnt(1)
	v_mfma_f32_32x32x16_bf16 v[34:49], v[86:89], v[90:93], v[34:49]
	s_waitcnt lgkmcnt(0)
	v_mfma_f32_32x32x16_bf16 v[50:65], v[86:89], v[94:97], v[50:65]
	s_waitcnt vmcnt(7)
	ds_write_b128 v66, v[106:109] offset:27648
	s_waitcnt vmcnt(6)
	ds_write_b128 v66, v[110:113] offset:32256
	global_load_dwordx4 v[106:109], v[74:75], off offset:512
	global_load_dwordx4 v[110:113], v[78:79], off offset:512
	ds_read_b128 v[86:89], v68 offset:4640
	v_mfma_f32_32x32x16_bf16 v[2:17], v[98:101], v[126:129], v[2:17]
	v_mfma_f32_32x32x16_bf16 v[18:33], v[98:101], v[130:133], v[18:33]
	ds_read_b128 v[98:101], v68 offset:4704
	s_waitcnt lgkmcnt(1)
	v_mfma_f32_32x32x16_bf16 v[2:17], v[86:89], v[90:93], v[2:17]
	s_waitcnt vmcnt(7)
	ds_write_b128 v66, v[144:147] offset:55296
	s_waitcnt vmcnt(6)
	ds_write_b128 v66, v[122:125] offset:59904
	global_load_dwordx4 v[144:147], v[76:77], off offset:512
	global_load_dwordx4 v[122:125], v[80:81], off offset:512
	ds_read_b128 v[90:93], v1 offset:36928
	v_mfma_f32_32x32x16_bf16 v[18:33], v[86:89], v[94:97], v[18:33]
	ds_read_b128 v[86:89], v68 offset:64
	ds_read_b128 v[94:97], v1 offset:41536
	s_waitcnt lgkmcnt(1)
	v_mfma_f32_32x32x16_bf16 v[34:49], v[86:89], v[90:93], v[34:49]
	s_waitcnt lgkmcnt(0)
	v_mfma_f32_32x32x16_bf16 v[50:65], v[86:89], v[94:97], v[50:65]
	s_waitcnt vmcnt(7)
	ds_write_b128 v66, v[118:121] offset:64512
	s_waitcnt vmcnt(6)
	ds_write_b128 v69, v[114:117] offset:32256
	global_load_dwordx4 v[118:121], v[82:83], off offset:512
	global_load_dwordx4 v[114:117], v[84:85], off offset:512
	ds_read_b128 v[86:89], v68 offset:4672
	s_waitcnt lgkmcnt(0)
	v_mfma_f32_32x32x16_bf16 v[2:17], v[86:89], v[90:93], v[2:17]
	ds_read_b128 v[90:93], v1 offset:36960
	v_mfma_f32_32x32x16_bf16 v[18:33], v[86:89], v[94:97], v[18:33]
	ds_read_b128 v[86:89], v68 offset:96
	ds_read_b128 v[94:97], v1 offset:41568
	s_waitcnt lgkmcnt(1)
	v_mfma_f32_32x32x16_bf16 v[34:49], v[86:89], v[90:93], v[34:49]
	s_waitcnt lgkmcnt(0)
	v_mfma_f32_32x32x16_bf16 v[50:65], v[86:89], v[94:97], v[50:65]
	v_mfma_f32_32x32x16_bf16 v[2:17], v[98:101], v[90:93], v[2:17]
	v_mfma_f32_32x32x16_bf16 v[18:33], v[98:101], v[94:97], v[18:33]
	s_setprio 0
	s_barrier
; #define MFMA(a, b, c) __builtin_amdgcn_mfma_f32_32x32x16_bf16((a), (b), (c), 0, 0, 0)
; template <int TM, int TN>
; DI void gemm_mainloop(const u16* __restrict__ A, long lda, const u16* __restrict__ Bt, long ldb, int K, char* smem,
;                       f32x16 (&acc)[TM][TN]) {
;     ...
;   for (int kt = 0; kt < nk; kt++) {
;     const int buf = kt & 1;
;     const u16* cA = sA + buf * BM * LD + (wm * 32 * TM + r) * LD + h * 8;
;     const u16* cB = sB + buf * BN * LD + (wn * 32 * TN + r) * LD + h * 8;
;     bf16x8 af[TM], bfr[TN];
; #pragma unroll
;     for (int tm = 0; tm < TM; tm++) af[tm] = *(const bf16x8*)(cA + tm * 32 * LD);
; #pragma unroll
;     for (int tn = 0; tn < TN; tn++) bfr[tn] = *(const bf16x8*)(cB + tn * 32 * LD);
;     if (kt + 1 < nk) GEMM_SSTORE(buf ^ 1)
;     __builtin_amdgcn_sched_barrier(0);
;     __builtin_amdgcn_s_setprio(1);
; #pragma unroll
;     for (int tm = 0; tm < TM; tm++)
; #pragma unroll
;       for (int tn = 0; tn < TN; tn++) acc[tm][tn] = MFMA(af[tm], bfr[tn], acc[tm][tn]);
; #pragma unroll
;     for (int tm = 0; tm < TM; tm++) af[tm] = *(const bf16x8*)(cA + tm * 32 * LD + 16);
; #pragma unroll
;     for (int tn = 0; tn < TN; tn++) bfr[tn] = *(const bf16x8*)(cB + tn * 32 * LD + 16);
; #pragma unroll
;     for (int tm = 0; tm < TM; tm++)
; #pragma unroll
;       for (int tn = 0; tn < TN; tn++) acc[tm][tn] = MFMA(af[tm], bfr[tn], acc[tm][tn]);
;     __builtin_amdgcn_sched_group_barrier(0x8, 4, 0);
;     if (kt + 2 < nk) GEMM_GLOAD((kt + 2) * 64)
; #pragma unroll
;     for (int ks = 2; ks < 4; ks++) {
; #pragma unroll
;       for (int tm = 0; tm < TM; tm++) af[tm] = *(const bf16x8*)(cA + tm * 32 * LD + ks * 16);
; #pragma unroll
;       for (int tn = 0; tn < TN; tn++) bfr[tn] = *(const bf16x8*)(cB + tn * 32 * LD + ks * 16);
; #pragma unroll
;       for (int tm = 0; tm < TM; tm++)
; #pragma unroll
;         for (int tn = 0; tn < TN; tn++) acc[tm][tn] = MFMA(af[tm], bfr[tn], acc[tm][tn]);
;     }
;     __builtin_amdgcn_s_setprio(0);
;     __syncthreads();
;   }
	ds_read_b128 v[94:97], v68 offset:18432
	ds_read_b128 v[98:101], v68 offset:23040
	ds_read_b128 v[126:129], v1 offset:55296
	ds_read_b128 v[130:133], v1 offset:59904
	s_setprio 1
	ds_read_b128 v[86:89], v68 offset:18464
	s_waitcnt lgkmcnt(2)
	v_mfma_f32_32x32x16_bf16 v[34:49], v[94:97], v[126:129], v[34:49]
	s_waitcnt vmcnt(7)
	ds_write_b128 v66, v[140:143]
	s_waitcnt vmcnt(6)
	ds_write_b128 v66, v[102:105] offset:4608
	global_load_dwordx4 v[140:143], v[72:73], off offset:640
	global_load_dwordx4 v[102:105], v[70:71], off offset:640
	ds_read_b128 v[90:93], v1 offset:55328
	s_waitcnt lgkmcnt(4)
	v_mfma_f32_32x32x16_bf16 v[50:65], v[94:97], v[130:133], v[50:65]
	ds_read_b128 v[94:97], v1 offset:59936
	s_waitcnt lgkmcnt(1)
	v_mfma_f32_32x32x16_bf16 v[34:49], v[86:89], v[90:93], v[34:49]
	s_waitcnt lgkmcnt(0)
	v_mfma_f32_32x32x16_bf16 v[50:65], v[86:89], v[94:97], v[50:65]
	s_waitcnt vmcnt(7)
	ds_write_b128 v66, v[106:109] offset:9216
	s_waitcnt vmcnt(6)
	ds_write_b128 v66, v[110:113] offset:13824
	global_load_dwordx4 v[106:109], v[74:75], off offset:640
	global_load_dwordx4 v[110:113], v[78:79], off offset:640
	ds_read_b128 v[86:89], v68 offset:23072
	v_mfma_f32_32x32x16_bf16 v[2:17], v[98:101], v[126:129], v[2:17]
	v_mfma_f32_32x32x16_bf16 v[18:33], v[98:101], v[130:133], v[18:33]
	ds_read_b128 v[98:101], v68 offset:23136
	s_waitcnt lgkmcnt(1)
	v_mfma_f32_32x32x16_bf16 v[2:17], v[86:89], v[90:93], v[2:17]
	s_waitcnt vmcnt(7)
	ds_write_b128 v66, v[144:147] offset:36864
	s_waitcnt vmcnt(6)
	ds_write_b128 v66, v[122:125] offset:41472
	global_load_dwordx4 v[144:147], v[76:77], off offset:640
	global_load_dwordx4 v[122:125], v[80:81], off offset:640
	ds_read_b128 v[90:93], v1 offset:55360
	v_mfma_f32_32x32x16_bf16 v[18:33], v[86:89], v[94:97], v[18:33]
	ds_read_b128 v[86:89], v68 offset:18496
	ds_read_b128 v[94:97], v1 offset:59968
	s_waitcnt lgkmcnt(1)
	v_mfma_f32_32x32x16_bf16 v[34:49], v[86:89], v[90:93], v[34:49]
	s_waitcnt lgkmcnt(0)
	v_mfma_f32_32x32x16_bf16 v[50:65], v[86:89], v[94:97], v[50:65]
	s_waitcnt vmcnt(7)
	ds_write_b128 v66, v[118:121] offset:46080
	s_waitcnt vmcnt(6)
	ds_write_b128 v66, v[114:117] offset:50688
	global_load_dwordx4 v[118:121], v[82:83], off offset:640
	global_load_dwordx4 v[114:117], v[84:85], off offset:640
	ds_read_b128 v[86:89], v68 offset:23104
	s_waitcnt lgkmcnt(0)
	v_mfma_f32_32x32x16_bf16 v[2:17], v[86:89], v[90:93], v[2:17]
	ds_read_b128 v[90:93], v1 offset:55392
	v_mfma_f32_32x32x16_bf16 v[18:33], v[86:89], v[94:97], v[18:33]
	ds_read_b128 v[86:89], v68 offset:18528
	ds_read_b128 v[94:97], v1 offset:60000
	s_waitcnt lgkmcnt(1)
	v_mfma_f32_32x32x16_bf16 v[34:49], v[86:89], v[90:93], v[34:49]
	s_waitcnt lgkmcnt(0)
	v_mfma_f32_32x32x16_bf16 v[50:65], v[86:89], v[94:97], v[50:65]
	v_mfma_f32_32x32x16_bf16 v[2:17], v[98:101], v[90:93], v[2:17]
	v_mfma_f32_32x32x16_bf16 v[18:33], v[98:101], v[94:97], v[18:33]
	s_setprio 0
	s_barrier
	ds_read_b128 v[94:97], v68
	ds_read_b128 v[98:101], v68 offset:4608
	ds_read_b128 v[126:129], v1 offset:36864
	ds_read_b128 v[130:133], v1 offset:41472
	s_setprio 1
	ds_read_b128 v[86:89], v68 offset:32
	s_waitcnt lgkmcnt(2)
	v_mfma_f32_32x32x16_bf16 v[34:49], v[94:97], v[126:129], v[34:49]
	s_waitcnt vmcnt(7)
	ds_write_b128 v66, v[140:143] offset:18432
	s_waitcnt vmcnt(6)
	ds_write_b128 v66, v[102:105] offset:23040
	global_load_dwordx4 v[140:143], v[72:73], off offset:768
	global_load_dwordx4 v[102:105], v[70:71], off offset:768
	ds_read_b128 v[90:93], v1 offset:36896
	s_waitcnt lgkmcnt(4)
	v_mfma_f32_32x32x16_bf16 v[50:65], v[94:97], v[130:133], v[50:65]
	ds_read_b128 v[94:97], v1 offset:41504
	s_waitcnt lgkmcnt(1)
	v_mfma_f32_32x32x16_bf16 v[34:49], v[86:89], v[90:93], v[34:49]
	s_waitcnt lgkmcnt(0)
	v_mfma_f32_32x32x16_bf16 v[50:65], v[86:89], v[94:97], v[50:65]
	s_waitcnt vmcnt(7)
	ds_write_b128 v66, v[106:109] offset:27648
	s_waitcnt vmcnt(6)
	ds_write_b128 v66, v[110:113] offset:32256
	global_load_dwordx4 v[106:109], v[74:75], off offset:768
	global_load_dwordx4 v[110:113], v[78:79], off offset:768
	ds_read_b128 v[86:89], v68 offset:4640
	v_mfma_f32_32x32x16_bf16 v[2:17], v[98:101], v[126:129], v[2:17]
	v_mfma_f32_32x32x16_bf16 v[18:33], v[98:101], v[130:133], v[18:33]
	ds_read_b128 v[98:101], v68 offset:4704
	s_waitcnt lgkmcnt(1)
	v_mfma_f32_32x32x16_bf16 v[2:17], v[86:89], v[90:93], v[2:17]
	s_waitcnt vmcnt(7)
	ds_write_b128 v66, v[144:147] offset:55296
	s_waitcnt vmcnt(6)
	ds_write_b128 v66, v[122:125] offset:59904
	global_load_dwordx4 v[144:147], v[76:77], off offset:768
	global_load_dwordx4 v[122:125], v[80:81], off offset:768
	ds_read_b128 v[90:93], v1 offset:36928
	v_mfma_f32_32x32x16_bf16 v[18:33], v[86:89], v[94:97], v[18:33]
	ds_read_b128 v[86:89], v68 offset:64
	ds_read_b128 v[94:97], v1 offset:41536
	s_waitcnt lgkmcnt(1)
	v_mfma_f32_32x32x16_bf16 v[34:49], v[86:89], v[90:93], v[34:49]
	s_waitcnt lgkmcnt(0)
	v_mfma_f32_32x32x16_bf16 v[50:65], v[86:89], v[94:97], v[50:65]
	s_waitcnt vmcnt(7)
	ds_write_b128 v66, v[118:121] offset:64512
	s_waitcnt vmcnt(6)
	ds_write_b128 v69, v[114:117] offset:32256
	global_load_dwordx4 v[118:121], v[82:83], off offset:768
	global_load_dwordx4 v[114:117], v[84:85], off offset:768
	ds_read_b128 v[86:89], v68 offset:4672
	s_waitcnt lgkmcnt(0)
	v_mfma_f32_32x32x16_bf16 v[2:17], v[86:89], v[90:93], v[2:17]
	ds_read_b128 v[90:93], v1 offset:36960
	v_mfma_f32_32x32x16_bf16 v[18:33], v[86:89], v[94:97], v[18:33]
	ds_read_b128 v[86:89], v68 offset:96
	ds_read_b128 v[94:97], v1 offset:41568
	s_waitcnt lgkmcnt(1)
	v_mfma_f32_32x32x16_bf16 v[34:49], v[86:89], v[90:93], v[34:49]
	s_waitcnt lgkmcnt(0)
	v_mfma_f32_32x32x16_bf16 v[50:65], v[86:89], v[94:97], v[50:65]
	v_mfma_f32_32x32x16_bf16 v[2:17], v[98:101], v[90:93], v[2:17]
	v_mfma_f32_32x32x16_bf16 v[18:33], v[98:101], v[94:97], v[18:33]
	s_setprio 0
	s_barrier
; #define MFMA(a, b, c) __builtin_amdgcn_mfma_f32_32x32x16_bf16((a), (b), (c), 0, 0, 0)
; template <int TM, int TN>
; DI void gemm_mainloop(const u16* __restrict__ A, long lda, const u16* __restrict__ Bt, long ldb, int K, char* smem,
;                       f32x16 (&acc)[TM][TN]) {
;     ...
;   for (int kt = 0; kt < nk; kt++) {
;     const int buf = kt & 1;
;     const u16* cA = sA + buf * BM * LD + (wm * 32 * TM + r) * LD + h * 8;
;     const u16* cB = sB + buf * BN * LD + (wn * 32 * TN + r) * LD + h * 8;
;     bf16x8 af[TM], bfr[TN];
; #pragma unroll
;     for (int tm = 0; tm < TM; tm++) af[tm] = *(const bf16x8*)(cA + tm * 32 * LD);
; #pragma unroll
;     for (int tn = 0; tn < TN; tn++) bfr[tn] = *(const bf16x8*)(cB + tn * 32 * LD);
;     if (kt + 1 < nk) GEMM_SSTORE(buf ^ 1)
;     __builtin_amdgcn_sched_barrier(0);
;     __builtin_amdgcn_s_setprio(1);
; #pragma unroll
;     for (int tm = 0; tm < TM; tm++)
; #pragma unroll
;       for (int tn = 0; tn < TN; tn++) acc[tm][tn] = MFMA(af[tm], bfr[tn], acc[tm][tn]);
; #pragma unroll
;     for (int tm = 0; tm < TM; tm++) af[tm] = *(const bf16x8*)(cA + tm * 32 * LD + 16);
; #pragma unroll
;     for (int tn = 0; tn < TN; tn++) bfr[tn] = *(const bf16x8*)(cB + tn * 32 * LD + 16);
; #pragma unroll
;     for (int tm = 0; tm < TM; tm++)
; #pragma unroll
;       for (int tn = 0; tn < TN; tn++) acc[tm][tn] = MFMA(af[tm], bfr[tn], acc[tm][tn]);
;     __builtin_amdgcn_sched_group_barrier(0x8, 4, 0);
;     if (kt + 2 < nk) GEMM_GLOAD((kt + 2) * 64)
; #pragma unroll
;     for (int ks = 2; ks < 4; ks++) {
; #pragma unroll
;       for (int tm = 0; tm < TM; tm++) af[tm] = *(const bf16x8*)(cA + tm * 32 * LD + ks * 16);
; #pragma unroll
;       for (int tn = 0; tn < TN; tn++) bfr[tn] = *(const bf16x8*)(cB + tn * 32 * LD + ks * 16);
; #pragma unroll
;       for (int tm = 0; tm < TM; tm++)
; #pragma unroll
;         for (int tn = 0; tn < TN; tn++) acc[tm][tn] = MFMA(af[tm], bfr[tn], acc[tm][tn]);
;     }
;     __builtin_amdgcn_s_setprio(0);
;     __syncthreads();
;   }
	ds_read_b128 v[94:97], v68 offset:18432
	ds_read_b128 v[98:101], v68 offset:23040
	ds_read_b128 v[126:129], v1 offset:55296
	ds_read_b128 v[130:133], v1 offset:59904
	s_setprio 1
	ds_read_b128 v[86:89], v68 offset:18464
	s_waitcnt lgkmcnt(2)
	v_mfma_f32_32x32x16_bf16 v[34:49], v[94:97], v[126:129], v[34:49]
	s_waitcnt vmcnt(7)
	ds_write_b128 v66, v[140:143]
	s_waitcnt vmcnt(6)
	ds_write_b128 v66, v[102:105] offset:4608
	global_load_dwordx4 v[140:143], v[72:73], off offset:896
	global_load_dwordx4 v[102:105], v[70:71], off offset:896
	ds_read_b128 v[90:93], v1 offset:55328
	s_waitcnt lgkmcnt(4)
	v_mfma_f32_32x32x16_bf16 v[50:65], v[94:97], v[130:133], v[50:65]
	ds_read_b128 v[94:97], v1 offset:59936
	s_waitcnt lgkmcnt(1)
	v_mfma_f32_32x32x16_bf16 v[34:49], v[86:89], v[90:93], v[34:49]
	s_waitcnt lgkmcnt(0)
	v_mfma_f32_32x32x16_bf16 v[50:65], v[86:89], v[94:97], v[50:65]
	s_waitcnt vmcnt(7)
	ds_write_b128 v66, v[106:109] offset:9216
	s_waitcnt vmcnt(6)
	ds_write_b128 v66, v[110:113] offset:13824
	global_load_dwordx4 v[106:109], v[74:75], off offset:896
	global_load_dwordx4 v[110:113], v[78:79], off offset:896
	ds_read_b128 v[86:89], v68 offset:23072
	v_mfma_f32_32x32x16_bf16 v[2:17], v[98:101], v[126:129], v[2:17]
	v_mfma_f32_32x32x16_bf16 v[18:33], v[98:101], v[130:133], v[18:33]
	ds_read_b128 v[98:101], v68 offset:23136
	s_waitcnt lgkmcnt(1)
	v_mfma_f32_32x32x16_bf16 v[2:17], v[86:89], v[90:93], v[2:17]
	s_waitcnt vmcnt(7)
	ds_write_b128 v66, v[144:147] offset:36864
	s_waitcnt vmcnt(6)
	ds_write_b128 v66, v[122:125] offset:41472
	global_load_dwordx4 v[144:147], v[76:77], off offset:896
	global_load_dwordx4 v[122:125], v[80:81], off offset:896
	ds_read_b128 v[90:93], v1 offset:55360
	v_mfma_f32_32x32x16_bf16 v[18:33], v[86:89], v[94:97], v[18:33]
	ds_read_b128 v[86:89], v68 offset:18496
	ds_read_b128 v[94:97], v1 offset:59968
	s_waitcnt lgkmcnt(1)
	v_mfma_f32_32x32x16_bf16 v[34:49], v[86:89], v[90:93], v[34:49]
	s_waitcnt lgkmcnt(0)
	v_mfma_f32_32x32x16_bf16 v[50:65], v[86:89], v[94:97], v[50:65]
	s_waitcnt vmcnt(7)
	ds_write_b128 v66, v[118:121] offset:46080
	s_waitcnt vmcnt(6)
	ds_write_b128 v66, v[114:117] offset:50688
	global_load_dwordx4 v[118:121], v[82:83], off offset:896
	global_load_dwordx4 v[114:117], v[84:85], off offset:896
	ds_read_b128 v[86:89], v68 offset:23104
	s_waitcnt lgkmcnt(0)
	v_mfma_f32_32x32x16_bf16 v[2:17], v[86:89], v[90:93], v[2:17]
	ds_read_b128 v[90:93], v1 offset:55392
	v_mfma_f32_32x32x16_bf16 v[18:33], v[86:89], v[94:97], v[18:33]
	ds_read_b128 v[86:89], v68 offset:18528
	ds_read_b128 v[94:97], v1 offset:60000
	s_waitcnt lgkmcnt(1)
	v_mfma_f32_32x32x16_bf16 v[34:49], v[86:89], v[90:93], v[34:49]
	s_waitcnt lgkmcnt(0)
	v_mfma_f32_32x32x16_bf16 v[50:65], v[86:89], v[94:97], v[50:65]
	v_mfma_f32_32x32x16_bf16 v[2:17], v[98:101], v[90:93], v[2:17]
	v_mfma_f32_32x32x16_bf16 v[18:33], v[98:101], v[94:97], v[18:33]
	s_setprio 0
	s_barrier
	ds_read_b128 v[94:97], v68
	ds_read_b128 v[98:101], v68 offset:4608
	ds_read_b128 v[126:129], v1 offset:36864
	ds_read_b128 v[130:133], v1 offset:41472
	s_setprio 1
	ds_read_b128 v[86:89], v68 offset:32
	s_waitcnt lgkmcnt(2)
	v_mfma_f32_32x32x16_bf16 v[34:49], v[94:97], v[126:129], v[34:49]
	s_waitcnt vmcnt(7)
	ds_write_b128 v66, v[140:143] offset:18432
	s_waitcnt vmcnt(6)
	ds_write_b128 v66, v[102:105] offset:23040
	global_load_dwordx4 v[140:143], v[72:73], off offset:1024
	global_load_dwordx4 v[102:105], v[70:71], off offset:1024
	ds_read_b128 v[90:93], v1 offset:36896
	s_waitcnt lgkmcnt(4)
	v_mfma_f32_32x32x16_bf16 v[50:65], v[94:97], v[130:133], v[50:65]
	ds_read_b128 v[94:97], v1 offset:41504
	s_waitcnt lgkmcnt(1)
	v_mfma_f32_32x32x16_bf16 v[34:49], v[86:89], v[90:93], v[34:49]
	s_waitcnt lgkmcnt(0)
	v_mfma_f32_32x32x16_bf16 v[50:65], v[86:89], v[94:97], v[50:65]
	s_waitcnt vmcnt(7)
	ds_write_b128 v66, v[106:109] offset:27648
	s_waitcnt vmcnt(6)
	ds_write_b128 v66, v[110:113] offset:32256
	global_load_dwordx4 v[106:109], v[74:75], off offset:1024
	global_load_dwordx4 v[110:113], v[78:79], off offset:1024
	ds_read_b128 v[86:89], v68 offset:4640
	v_mfma_f32_32x32x16_bf16 v[2:17], v[98:101], v[126:129], v[2:17]
	v_mfma_f32_32x32x16_bf16 v[18:33], v[98:101], v[130:133], v[18:33]
	ds_read_b128 v[98:101], v68 offset:4704
	s_waitcnt lgkmcnt(1)
	v_mfma_f32_32x32x16_bf16 v[2:17], v[86:89], v[90:93], v[2:17]
	s_waitcnt vmcnt(7)
	ds_write_b128 v66, v[144:147] offset:55296
	s_waitcnt vmcnt(6)
	ds_write_b128 v66, v[122:125] offset:59904
	global_load_dwordx4 v[144:147], v[76:77], off offset:1024
	global_load_dwordx4 v[122:125], v[80:81], off offset:1024
	ds_read_b128 v[90:93], v1 offset:36928
	v_mfma_f32_32x32x16_bf16 v[18:33], v[86:89], v[94:97], v[18:33]
	ds_read_b128 v[86:89], v68 offset:64
	ds_read_b128 v[94:97], v1 offset:41536
	s_waitcnt lgkmcnt(1)
	v_mfma_f32_32x32x16_bf16 v[34:49], v[86:89], v[90:93], v[34:49]
	s_waitcnt lgkmcnt(0)
	v_mfma_f32_32x32x16_bf16 v[50:65], v[86:89], v[94:97], v[50:65]
	s_waitcnt vmcnt(7)
	ds_write_b128 v66, v[118:121] offset:64512
	s_waitcnt vmcnt(6)
	ds_write_b128 v69, v[114:117] offset:32256
	global_load_dwordx4 v[118:121], v[82:83], off offset:1024
	global_load_dwordx4 v[114:117], v[84:85], off offset:1024
	ds_read_b128 v[86:89], v68 offset:4672
	s_waitcnt lgkmcnt(0)
	v_mfma_f32_32x32x16_bf16 v[2:17], v[86:89], v[90:93], v[2:17]
	ds_read_b128 v[90:93], v1 offset:36960
	v_mfma_f32_32x32x16_bf16 v[18:33], v[86:89], v[94:97], v[18:33]
	ds_read_b128 v[86:89], v68 offset:96
	ds_read_b128 v[94:97], v1 offset:41568
	s_waitcnt lgkmcnt(1)
	v_mfma_f32_32x32x16_bf16 v[34:49], v[86:89], v[90:93], v[34:49]
	s_waitcnt lgkmcnt(0)
	v_mfma_f32_32x32x16_bf16 v[50:65], v[86:89], v[94:97], v[50:65]
	v_mfma_f32_32x32x16_bf16 v[2:17], v[98:101], v[90:93], v[2:17]
	v_mfma_f32_32x32x16_bf16 v[18:33], v[98:101], v[94:97], v[18:33]
	s_setprio 0
	s_barrier
; #define MFMA(a, b, c) __builtin_amdgcn_mfma_f32_32x32x16_bf16((a), (b), (c), 0, 0, 0)
; template <int TM, int TN>
; DI void gemm_mainloop(const u16* __restrict__ A, long lda, const u16* __restrict__ Bt, long ldb, int K, char* smem,
;                       f32x16 (&acc)[TM][TN]) {
;     ...
;   for (int kt = 0; kt < nk; kt++) {
;     const int buf = kt & 1;
;     const u16* cA = sA + buf * BM * LD + (wm * 32 * TM + r) * LD + h * 8;
;     const u16* cB = sB + buf * BN * LD + (wn * 32 * TN + r) * LD + h * 8;
;     bf16x8 af[TM], bfr[TN];
; #pragma unroll
;     for (int tm = 0; tm < TM; tm++) af[tm] = *(const bf16x8*)(cA + tm * 32 * LD);
; #pragma unroll
;     for (int tn = 0; tn < TN; tn++) bfr[tn] = *(const bf16x8*)(cB + tn * 32 * LD);
;     if (kt + 1 < nk) GEMM_SSTORE(buf ^ 1)
;     __builtin_amdgcn_sched_barrier(0);
;     __builtin_amdgcn_s_setprio(1);
; #pragma unroll
;     for (int tm = 0; tm < TM; tm++)
; #pragma unroll
;       for (int tn = 0; tn < TN; tn++) acc[tm][tn] = MFMA(af[tm], bfr[tn], acc[tm][tn]);
; #pragma unroll
;     for (int tm = 0; tm < TM; tm++) af[tm] = *(const bf16x8*)(cA + tm * 32 * LD + 16);
; #pragma unroll
;     for (int tn = 0; tn < TN; tn++) bfr[tn] = *(const bf16x8*)(cB + tn * 32 * LD + 16);
; #pragma unroll
;     for (int tm = 0; tm < TM; tm++)
; #pragma unroll
;       for (int tn = 0; tn < TN; tn++) acc[tm][tn] = MFMA(af[tm], bfr[tn], acc[tm][tn]);
;     __builtin_amdgcn_sched_group_barrier(0x8, 4, 0);
;     if (kt + 2 < nk) GEMM_GLOAD((kt + 2) * 64)
; #pragma unroll
;     for (int ks = 2; ks < 4; ks++) {
; #pragma unroll
;       for (int tm = 0; tm < TM; tm++) af[tm] = *(const bf16x8*)(cA + tm * 32 * LD + ks * 16);
; #pragma unroll
;       for (int tn = 0; tn < TN; tn++) bfr[tn] = *(const bf16x8*)(cB + tn * 32 * LD + ks * 16);
; #pragma unroll
;       for (int tm = 0; tm < TM; tm++)
; #pragma unroll
;         for (int tn = 0; tn < TN; tn++) acc[tm][tn] = MFMA(af[tm], bfr[tn], acc[tm][tn]);
;     }
;     __builtin_amdgcn_s_setprio(0);
;     __syncthreads();
;   }
	ds_read_b128 v[94:97], v68 offset:18432
	ds_read_b128 v[98:101], v68 offset:23040
	ds_read_b128 v[126:129], v1 offset:55296
	ds_read_b128 v[130:133], v1 offset:59904
	s_setprio 1
	ds_read_b128 v[86:89], v68 offset:18464
	s_waitcnt lgkmcnt(2)
	v_mfma_f32_32x32x16_bf16 v[34:49], v[94:97], v[126:129], v[34:49]
	s_waitcnt vmcnt(7)
	ds_write_b128 v66, v[140:143]
	s_waitcnt vmcnt(6)
	ds_write_b128 v66, v[102:105] offset:4608
	global_load_dwordx4 v[140:143], v[72:73], off offset:1152
	global_load_dwordx4 v[102:105], v[70:71], off offset:1152
	ds_read_b128 v[90:93], v1 offset:55328
	s_waitcnt lgkmcnt(4)
	v_mfma_f32_32x32x16_bf16 v[50:65], v[94:97], v[130:133], v[50:65]
	ds_read_b128 v[94:97], v1 offset:59936
	s_waitcnt lgkmcnt(1)
	v_mfma_f32_32x32x16_bf16 v[34:49], v[86:89], v[90:93], v[34:49]
	s_waitcnt lgkmcnt(0)
	v_mfma_f32_32x32x16_bf16 v[50:65], v[86:89], v[94:97], v[50:65]
	s_waitcnt vmcnt(7)
	ds_write_b128 v66, v[106:109] offset:9216
	s_waitcnt vmcnt(6)
	ds_write_b128 v66, v[110:113] offset:13824
	global_load_dwordx4 v[106:109], v[74:75], off offset:1152
	global_load_dwordx4 v[110:113], v[78:79], off offset:1152
	ds_read_b128 v[86:89], v68 offset:23072
	v_mfma_f32_32x32x16_bf16 v[2:17], v[98:101], v[126:129], v[2:17]
	v_mfma_f32_32x32x16_bf16 v[18:33], v[98:101], v[130:133], v[18:33]
	ds_read_b128 v[98:101], v68 offset:23136
	s_waitcnt lgkmcnt(1)
	v_mfma_f32_32x32x16_bf16 v[2:17], v[86:89], v[90:93], v[2:17]
	s_waitcnt vmcnt(7)
	ds_write_b128 v66, v[144:147] offset:36864
	s_waitcnt vmcnt(6)
	ds_write_b128 v66, v[122:125] offset:41472
	global_load_dwordx4 v[144:147], v[76:77], off offset:1152
	global_load_dwordx4 v[122:125], v[80:81], off offset:1152
	ds_read_b128 v[90:93], v1 offset:55360
	v_mfma_f32_32x32x16_bf16 v[18:33], v[86:89], v[94:97], v[18:33]
	ds_read_b128 v[86:89], v68 offset:18496
	ds_read_b128 v[94:97], v1 offset:59968
	s_waitcnt lgkmcnt(1)
	v_mfma_f32_32x32x16_bf16 v[34:49], v[86:89], v[90:93], v[34:49]
	s_waitcnt lgkmcnt(0)
	v_mfma_f32_32x32x16_bf16 v[50:65], v[86:89], v[94:97], v[50:65]
	s_waitcnt vmcnt(7)
	ds_write_b128 v66, v[118:121] offset:46080
	s_waitcnt vmcnt(6)
	ds_write_b128 v66, v[114:117] offset:50688
	global_load_dwordx4 v[118:121], v[82:83], off offset:1152
	global_load_dwordx4 v[114:117], v[84:85], off offset:1152
	ds_read_b128 v[86:89], v68 offset:23104
	s_waitcnt lgkmcnt(0)
	v_mfma_f32_32x32x16_bf16 v[2:17], v[86:89], v[90:93], v[2:17]
	ds_read_b128 v[90:93], v1 offset:55392
	v_mfma_f32_32x32x16_bf16 v[18:33], v[86:89], v[94:97], v[18:33]
	ds_read_b128 v[86:89], v68 offset:18528
	ds_read_b128 v[94:97], v1 offset:60000
	s_waitcnt lgkmcnt(1)
	v_mfma_f32_32x32x16_bf16 v[34:49], v[86:89], v[90:93], v[34:49]
	s_waitcnt lgkmcnt(0)
	v_mfma_f32_32x32x16_bf16 v[50:65], v[86:89], v[94:97], v[50:65]
	v_mfma_f32_32x32x16_bf16 v[2:17], v[98:101], v[90:93], v[2:17]
	v_mfma_f32_32x32x16_bf16 v[18:33], v[98:101], v[94:97], v[18:33]
	s_setprio 0
	s_barrier
	ds_read_b128 v[94:97], v68
	ds_read_b128 v[98:101], v68 offset:4608
	ds_read_b128 v[126:129], v1 offset:36864
	ds_read_b128 v[130:133], v1 offset:41472
	s_setprio 1
	ds_read_b128 v[86:89], v68 offset:32
	s_waitcnt lgkmcnt(2)
	v_mfma_f32_32x32x16_bf16 v[34:49], v[94:97], v[126:129], v[34:49]
	s_waitcnt vmcnt(7)
	ds_write_b128 v66, v[140:143] offset:18432
	s_waitcnt vmcnt(6)
	ds_write_b128 v66, v[102:105] offset:23040
	global_load_dwordx4 v[140:143], v[72:73], off offset:1280
	global_load_dwordx4 v[102:105], v[70:71], off offset:1280
	ds_read_b128 v[90:93], v1 offset:36896
	s_waitcnt lgkmcnt(4)
	v_mfma_f32_32x32x16_bf16 v[50:65], v[94:97], v[130:133], v[50:65]
	ds_read_b128 v[94:97], v1 offset:41504
	s_waitcnt lgkmcnt(1)
	v_mfma_f32_32x32x16_bf16 v[34:49], v[86:89], v[90:93], v[34:49]
	s_waitcnt lgkmcnt(0)
	v_mfma_f32_32x32x16_bf16 v[50:65], v[86:89], v[94:97], v[50:65]
	s_waitcnt vmcnt(7)
	ds_write_b128 v66, v[106:109] offset:27648
	s_waitcnt vmcnt(6)
	ds_write_b128 v66, v[110:113] offset:32256
	global_load_dwordx4 v[106:109], v[74:75], off offset:1280
	global_load_dwordx4 v[110:113], v[78:79], off offset:1280
	ds_read_b128 v[86:89], v68 offset:4640
	v_mfma_f32_32x32x16_bf16 v[2:17], v[98:101], v[126:129], v[2:17]
	v_mfma_f32_32x32x16_bf16 v[18:33], v[98:101], v[130:133], v[18:33]
	ds_read_b128 v[98:101], v68 offset:4704
	s_waitcnt lgkmcnt(1)
	v_mfma_f32_32x32x16_bf16 v[2:17], v[86:89], v[90:93], v[2:17]
	s_waitcnt vmcnt(7)
	ds_write_b128 v66, v[144:147] offset:55296
	s_waitcnt vmcnt(6)
	ds_write_b128 v66, v[122:125] offset:59904
	global_load_dwordx4 v[144:147], v[76:77], off offset:1280
	global_load_dwordx4 v[122:125], v[80:81], off offset:1280
	ds_read_b128 v[90:93], v1 offset:36928
	v_mfma_f32_32x32x16_bf16 v[18:33], v[86:89], v[94:97], v[18:33]
	ds_read_b128 v[86:89], v68 offset:64
	ds_read_b128 v[94:97], v1 offset:41536
	s_waitcnt lgkmcnt(1)
	v_mfma_f32_32x32x16_bf16 v[34:49], v[86:89], v[90:93], v[34:49]
	s_waitcnt lgkmcnt(0)
	v_mfma_f32_32x32x16_bf16 v[50:65], v[86:89], v[94:97], v[50:65]
	s_waitcnt vmcnt(7)
	ds_write_b128 v66, v[118:121] offset:64512
	s_waitcnt vmcnt(6)
	ds_write_b128 v69, v[114:117] offset:32256
	global_load_dwordx4 v[118:121], v[82:83], off offset:1280
	global_load_dwordx4 v[114:117], v[84:85], off offset:1280
	ds_read_b128 v[86:89], v68 offset:4672
	s_waitcnt lgkmcnt(0)
	v_mfma_f32_32x32x16_bf16 v[2:17], v[86:89], v[90:93], v[2:17]
	ds_read_b128 v[90:93], v1 offset:36960
	v_mfma_f32_32x32x16_bf16 v[18:33], v[86:89], v[94:97], v[18:33]
	ds_read_b128 v[86:89], v68 offset:96
	ds_read_b128 v[94:97], v1 offset:41568
	s_waitcnt lgkmcnt(1)
	v_mfma_f32_32x32x16_bf16 v[34:49], v[86:89], v[90:93], v[34:49]
	s_waitcnt lgkmcnt(0)
	v_mfma_f32_32x32x16_bf16 v[50:65], v[86:89], v[94:97], v[50:65]
	v_mfma_f32_32x32x16_bf16 v[2:17], v[98:101], v[90:93], v[2:17]
	v_mfma_f32_32x32x16_bf16 v[18:33], v[98:101], v[94:97], v[18:33]
	s_setprio 0
	s_barrier
; #define MFMA(a, b, c) __builtin_amdgcn_mfma_f32_32x32x16_bf16((a), (b), (c), 0, 0, 0)
; template <int TM, int TN>
; DI void gemm_mainloop(const u16* __restrict__ A, long lda, const u16* __restrict__ Bt, long ldb, int K, char* smem,
;                       f32x16 (&acc)[TM][TN]) {
;     ...
;   for (int kt = 0; kt < nk; kt++) {
;     const int buf = kt & 1;
;     const u16* cA = sA + buf * BM * LD + (wm * 32 * TM + r) * LD + h * 8;
;     const u16* cB = sB + buf * BN * LD + (wn * 32 * TN + r) * LD + h * 8;
;     bf16x8 af[TM], bfr[TN];
; #pragma unroll
;     for (int tm = 0; tm < TM; tm++) af[tm] = *(const bf16x8*)(cA + tm * 32 * LD);
; #pragma unroll
;     for (int tn = 0; tn < TN; tn++) bfr[tn] = *(const bf16x8*)(cB + tn * 32 * LD);
;     if (kt + 1 < nk) GEMM_SSTORE(buf ^ 1)
;     __builtin_amdgcn_sched_barrier(0);
;     __builtin_amdgcn_s_setprio(1);
; #pragma unroll
;     for (int tm = 0; tm < TM; tm++)
; #pragma unroll
;       for (int tn = 0; tn < TN; tn++) acc[tm][tn] = MFMA(af[tm], bfr[tn], acc[tm][tn]);
; #pragma unroll
;     for (int tm = 0; tm < TM; tm++) af[tm] = *(const bf16x8*)(cA + tm * 32 * LD + 16);
; #pragma unroll
;     for (int tn = 0; tn < TN; tn++) bfr[tn] = *(const bf16x8*)(cB + tn * 32 * LD + 16);
; #pragma unroll
;     for (int tm = 0; tm < TM; tm++)
; #pragma unroll
;       for (int tn = 0; tn < TN; tn++) acc[tm][tn] = MFMA(af[tm], bfr[tn], acc[tm][tn]);
;     __builtin_amdgcn_sched_group_barrier(0x8, 4, 0);
;     if (kt + 2 < nk) GEMM_GLOAD((kt + 2) * 64)
; #pragma unroll
;     for (int ks = 2; ks < 4; ks++) {
; #pragma unroll
;       for (int tm = 0; tm < TM; tm++) af[tm] = *(const bf16x8*)(cA + tm * 32 * LD + ks * 16);
; #pragma unroll
;       for (int tn = 0; tn < TN; tn++) bfr[tn] = *(const bf16x8*)(cB + tn * 32 * LD + ks * 16);
; #pragma unroll
;       for (int tm = 0; tm < TM; tm++)
; #pragma unroll
;         for (int tn = 0; tn < TN; tn++) acc[tm][tn] = MFMA(af[tm], bfr[tn], acc[tm][tn]);
;     }
;     __builtin_amdgcn_s_setprio(0);
;     __syncthreads();
;   }
	ds_read_b128 v[94:97], v68 offset:18432
	ds_read_b128 v[98:101], v68 offset:23040
	ds_read_b128 v[126:129], v1 offset:55296
	ds_read_b128 v[130:133], v1 offset:59904
	s_setprio 1
	ds_read_b128 v[86:89], v68 offset:18464
	s_waitcnt lgkmcnt(2)
	v_mfma_f32_32x32x16_bf16 v[34:49], v[94:97], v[126:129], v[34:49]
	s_waitcnt vmcnt(7)
	ds_write_b128 v66, v[140:143]
	s_waitcnt vmcnt(6)
	ds_write_b128 v66, v[102:105] offset:4608
	global_load_dwordx4 v[140:143], v[72:73], off offset:1408
	global_load_dwordx4 v[102:105], v[70:71], off offset:1408
	ds_read_b128 v[90:93], v1 offset:55328
	s_waitcnt lgkmcnt(4)
	v_mfma_f32_32x32x16_bf16 v[50:65], v[94:97], v[130:133], v[50:65]
	ds_read_b128 v[94:97], v1 offset:59936
	s_waitcnt lgkmcnt(1)
	v_mfma_f32_32x32x16_bf16 v[34:49], v[86:89], v[90:93], v[34:49]
	s_waitcnt lgkmcnt(0)
	v_mfma_f32_32x32x16_bf16 v[50:65], v[86:89], v[94:97], v[50:65]
	s_waitcnt vmcnt(7)
	ds_write_b128 v66, v[106:109] offset:9216
	s_waitcnt vmcnt(6)
	ds_write_b128 v66, v[110:113] offset:13824
	global_load_dwordx4 v[106:109], v[74:75], off offset:1408
	global_load_dwordx4 v[110:113], v[78:79], off offset:1408
	ds_read_b128 v[86:89], v68 offset:23072
	v_mfma_f32_32x32x16_bf16 v[2:17], v[98:101], v[126:129], v[2:17]
	v_mfma_f32_32x32x16_bf16 v[18:33], v[98:101], v[130:133], v[18:33]
	ds_read_b128 v[98:101], v68 offset:23136
	s_waitcnt lgkmcnt(1)
	v_mfma_f32_32x32x16_bf16 v[2:17], v[86:89], v[90:93], v[2:17]
	s_waitcnt vmcnt(7)
	ds_write_b128 v66, v[144:147] offset:36864
	s_waitcnt vmcnt(6)
	ds_write_b128 v66, v[122:125] offset:41472
	global_load_dwordx4 v[144:147], v[76:77], off offset:1408
	global_load_dwordx4 v[122:125], v[80:81], off offset:1408
	ds_read_b128 v[90:93], v1 offset:55360
	v_mfma_f32_32x32x16_bf16 v[18:33], v[86:89], v[94:97], v[18:33]
	ds_read_b128 v[86:89], v68 offset:18496
	ds_read_b128 v[94:97], v1 offset:59968
	s_waitcnt lgkmcnt(1)
	v_mfma_f32_32x32x16_bf16 v[34:49], v[86:89], v[90:93], v[34:49]
	s_waitcnt lgkmcnt(0)
	v_mfma_f32_32x32x16_bf16 v[50:65], v[86:89], v[94:97], v[50:65]
	s_waitcnt vmcnt(7)
	ds_write_b128 v66, v[118:121] offset:46080
	s_waitcnt vmcnt(6)
	ds_write_b128 v66, v[114:117] offset:50688
	global_load_dwordx4 v[118:121], v[82:83], off offset:1408
	global_load_dwordx4 v[114:117], v[84:85], off offset:1408
	ds_read_b128 v[86:89], v68 offset:23104
	s_waitcnt lgkmcnt(0)
	v_mfma_f32_32x32x16_bf16 v[2:17], v[86:89], v[90:93], v[2:17]
	ds_read_b128 v[90:93], v1 offset:55392
	v_mfma_f32_32x32x16_bf16 v[18:33], v[86:89], v[94:97], v[18:33]
	ds_read_b128 v[86:89], v68 offset:18528
	ds_read_b128 v[94:97], v1 offset:60000
	s_waitcnt lgkmcnt(1)
	v_mfma_f32_32x32x16_bf16 v[34:49], v[86:89], v[90:93], v[34:49]
	s_waitcnt lgkmcnt(0)
	v_mfma_f32_32x32x16_bf16 v[50:65], v[86:89], v[94:97], v[50:65]
	v_mfma_f32_32x32x16_bf16 v[2:17], v[98:101], v[90:93], v[2:17]
	v_mfma_f32_32x32x16_bf16 v[18:33], v[98:101], v[94:97], v[18:33]
	s_setprio 0
	s_barrier
	ds_read_b128 v[94:97], v68
	ds_read_b128 v[98:101], v68 offset:4608
	ds_read_b128 v[126:129], v1 offset:36864
	ds_read_b128 v[130:133], v1 offset:41472
	s_setprio 1
	ds_read_b128 v[86:89], v68 offset:32
	s_waitcnt lgkmcnt(2)
	v_mfma_f32_32x32x16_bf16 v[34:49], v[94:97], v[126:129], v[34:49]
	s_waitcnt vmcnt(7)
	ds_write_b128 v66, v[140:143] offset:18432
	s_waitcnt vmcnt(6)
	ds_write_b128 v66, v[102:105] offset:23040
	global_load_dwordx4 v[140:143], v[72:73], off offset:1536
	global_load_dwordx4 v[102:105], v[70:71], off offset:1536
	ds_read_b128 v[90:93], v1 offset:36896
	s_waitcnt lgkmcnt(4)
	v_mfma_f32_32x32x16_bf16 v[50:65], v[94:97], v[130:133], v[50:65]
	ds_read_b128 v[94:97], v1 offset:41504
	s_waitcnt lgkmcnt(1)
	v_mfma_f32_32x32x16_bf16 v[34:49], v[86:89], v[90:93], v[34:49]
	s_waitcnt lgkmcnt(0)
	v_mfma_f32_32x32x16_bf16 v[50:65], v[86:89], v[94:97], v[50:65]
	s_waitcnt vmcnt(7)
	ds_write_b128 v66, v[106:109] offset:27648
	s_waitcnt vmcnt(6)
	ds_write_b128 v66, v[110:113] offset:32256
	global_load_dwordx4 v[106:109], v[74:75], off offset:1536
	global_load_dwordx4 v[110:113], v[78:79], off offset:1536
	ds_read_b128 v[86:89], v68 offset:4640
	v_mfma_f32_32x32x16_bf16 v[2:17], v[98:101], v[126:129], v[2:17]
	v_mfma_f32_32x32x16_bf16 v[18:33], v[98:101], v[130:133], v[18:33]
	ds_read_b128 v[98:101], v68 offset:4704
	s_waitcnt lgkmcnt(1)
	v_mfma_f32_32x32x16_bf16 v[2:17], v[86:89], v[90:93], v[2:17]
	s_waitcnt vmcnt(7)
	ds_write_b128 v66, v[144:147] offset:55296
	s_waitcnt vmcnt(6)
	ds_write_b128 v66, v[122:125] offset:59904
	global_load_dwordx4 v[144:147], v[76:77], off offset:1536
	global_load_dwordx4 v[122:125], v[80:81], off offset:1536
	ds_read_b128 v[90:93], v1 offset:36928
	v_mfma_f32_32x32x16_bf16 v[18:33], v[86:89], v[94:97], v[18:33]
	ds_read_b128 v[86:89], v68 offset:64
	ds_read_b128 v[94:97], v1 offset:41536
	s_waitcnt lgkmcnt(1)
	v_mfma_f32_32x32x16_bf16 v[34:49], v[86:89], v[90:93], v[34:49]
	s_waitcnt lgkmcnt(0)
	v_mfma_f32_32x32x16_bf16 v[50:65], v[86:89], v[94:97], v[50:65]
	s_waitcnt vmcnt(7)
	ds_write_b128 v66, v[118:121] offset:64512
	s_waitcnt vmcnt(6)
	ds_write_b128 v69, v[114:117] offset:32256
	global_load_dwordx4 v[118:121], v[82:83], off offset:1536
	global_load_dwordx4 v[114:117], v[84:85], off offset:1536
	ds_read_b128 v[86:89], v68 offset:4672
	s_waitcnt lgkmcnt(0)
	v_mfma_f32_32x32x16_bf16 v[2:17], v[86:89], v[90:93], v[2:17]
	ds_read_b128 v[90:93], v1 offset:36960
	v_mfma_f32_32x32x16_bf16 v[18:33], v[86:89], v[94:97], v[18:33]
	ds_read_b128 v[86:89], v68 offset:96
	ds_read_b128 v[94:97], v1 offset:41568
	s_waitcnt lgkmcnt(1)
	v_mfma_f32_32x32x16_bf16 v[34:49], v[86:89], v[90:93], v[34:49]
	s_waitcnt lgkmcnt(0)
	v_mfma_f32_32x32x16_bf16 v[50:65], v[86:89], v[94:97], v[50:65]
	v_mfma_f32_32x32x16_bf16 v[2:17], v[98:101], v[90:93], v[2:17]
	v_mfma_f32_32x32x16_bf16 v[18:33], v[98:101], v[94:97], v[18:33]
	s_setprio 0
	s_barrier
; #define MFMA(a, b, c) __builtin_amdgcn_mfma_f32_32x32x16_bf16((a), (b), (c), 0, 0, 0)
; template <int TM, int TN>
; DI void gemm_mainloop(const u16* __restrict__ A, long lda, const u16* __restrict__ Bt, long ldb, int K, char* smem,
;                       f32x16 (&acc)[TM][TN]) {
;     ...
;   for (int kt = 0; kt < nk; kt++) {
;     const int buf = kt & 1;
;     const u16* cA = sA + buf * BM * LD + (wm * 32 * TM + r) * LD + h * 8;
;     const u16* cB = sB + buf * BN * LD + (wn * 32 * TN + r) * LD + h * 8;
;     bf16x8 af[TM], bfr[TN];
; #pragma unroll
;     for (int tm = 0; tm < TM; tm++) af[tm] = *(const bf16x8*)(cA + tm * 32 * LD);
; #pragma unroll
;     for (int tn = 0; tn < TN; tn++) bfr[tn] = *(const bf16x8*)(cB + tn * 32 * LD);
;     if (kt + 1 < nk) GEMM_SSTORE(buf ^ 1)
;     __builtin_amdgcn_sched_barrier(0);
;     __builtin_amdgcn_s_setprio(1);
; #pragma unroll
;     for (int tm = 0; tm < TM; tm++)
; #pragma unroll
;       for (int tn = 0; tn < TN; tn++) acc[tm][tn] = MFMA(af[tm], bfr[tn], acc[tm][tn]);
; #pragma unroll
;     for (int tm = 0; tm < TM; tm++) af[tm] = *(const bf16x8*)(cA + tm * 32 * LD + 16);
; #pragma unroll
;     for (int tn = 0; tn < TN; tn++) bfr[tn] = *(const bf16x8*)(cB + tn * 32 * LD + 16);
; #pragma unroll
;     for (int tm = 0; tm < TM; tm++)
; #pragma unroll
;       for (int tn = 0; tn < TN; tn++) acc[tm][tn] = MFMA(af[tm], bfr[tn], acc[tm][tn]);
;     __builtin_amdgcn_sched_group_barrier(0x8, 4, 0);
;     if (kt + 2 < nk) GEMM_GLOAD((kt + 2) * 64)
; #pragma unroll
;     for (int ks = 2; ks < 4; ks++) {
; #pragma unroll
;       for (int tm = 0; tm < TM; tm++) af[tm] = *(const bf16x8*)(cA + tm * 32 * LD + ks * 16);
; #pragma unroll
;       for (int tn = 0; tn < TN; tn++) bfr[tn] = *(const bf16x8*)(cB + tn * 32 * LD + ks * 16);
; #pragma unroll
;       for (int tm = 0; tm < TM; tm++)
; #pragma unroll
;         for (int tn = 0; tn < TN; tn++) acc[tm][tn] = MFMA(af[tm], bfr[tn], acc[tm][tn]);
;     }
;     __builtin_amdgcn_s_setprio(0);
;     __syncthreads();
;   }
	ds_read_b128 v[94:97], v68 offset:18432
	ds_read_b128 v[98:101], v68 offset:23040
	ds_read_b128 v[126:129], v1 offset:55296
	ds_read_b128 v[130:133], v1 offset:59904
	s_setprio 1
	ds_read_b128 v[86:89], v68 offset:18464
	s_waitcnt lgkmcnt(2)
	v_mfma_f32_32x32x16_bf16 v[34:49], v[94:97], v[126:129], v[34:49]
	s_waitcnt vmcnt(7)
	ds_write_b128 v66, v[140:143]
	s_waitcnt vmcnt(6)
	ds_write_b128 v66, v[102:105] offset:4608
	global_load_dwordx4 v[140:143], v[72:73], off offset:1664
	global_load_dwordx4 v[102:105], v[70:71], off offset:1664
	ds_read_b128 v[90:93], v1 offset:55328
	s_waitcnt lgkmcnt(4)
	v_mfma_f32_32x32x16_bf16 v[50:65], v[94:97], v[130:133], v[50:65]
	ds_read_b128 v[94:97], v1 offset:59936
	s_waitcnt lgkmcnt(1)
	v_mfma_f32_32x32x16_bf16 v[34:49], v[86:89], v[90:93], v[34:49]
	s_waitcnt lgkmcnt(0)
	v_mfma_f32_32x32x16_bf16 v[50:65], v[86:89], v[94:97], v[50:65]
	s_waitcnt vmcnt(7)
	ds_write_b128 v66, v[106:109] offset:9216
	s_waitcnt vmcnt(6)
	ds_write_b128 v66, v[110:113] offset:13824
	global_load_dwordx4 v[106:109], v[74:75], off offset:1664
	global_load_dwordx4 v[110:113], v[78:79], off offset:1664
	ds_read_b128 v[86:89], v68 offset:23072
	v_mfma_f32_32x32x16_bf16 v[2:17], v[98:101], v[126:129], v[2:17]
	v_mfma_f32_32x32x16_bf16 v[18:33], v[98:101], v[130:133], v[18:33]
	ds_read_b128 v[98:101], v68 offset:23136
	s_waitcnt lgkmcnt(1)
	v_mfma_f32_32x32x16_bf16 v[2:17], v[86:89], v[90:93], v[2:17]
	s_waitcnt vmcnt(7)
	ds_write_b128 v66, v[144:147] offset:36864
	s_waitcnt vmcnt(6)
	ds_write_b128 v66, v[122:125] offset:41472
	global_load_dwordx4 v[144:147], v[76:77], off offset:1664
	global_load_dwordx4 v[122:125], v[80:81], off offset:1664
	ds_read_b128 v[90:93], v1 offset:55360
	v_mfma_f32_32x32x16_bf16 v[18:33], v[86:89], v[94:97], v[18:33]
	ds_read_b128 v[86:89], v68 offset:18496
	ds_read_b128 v[94:97], v1 offset:59968
	s_waitcnt lgkmcnt(1)
	v_mfma_f32_32x32x16_bf16 v[34:49], v[86:89], v[90:93], v[34:49]
	s_waitcnt lgkmcnt(0)
	v_mfma_f32_32x32x16_bf16 v[50:65], v[86:89], v[94:97], v[50:65]
	s_waitcnt vmcnt(7)
	ds_write_b128 v66, v[118:121] offset:46080
	s_waitcnt vmcnt(6)
	ds_write_b128 v66, v[114:117] offset:50688
	global_load_dwordx4 v[118:121], v[82:83], off offset:1664
	global_load_dwordx4 v[114:117], v[84:85], off offset:1664
	ds_read_b128 v[86:89], v68 offset:23104
	s_waitcnt lgkmcnt(0)
	v_mfma_f32_32x32x16_bf16 v[2:17], v[86:89], v[90:93], v[2:17]
	ds_read_b128 v[90:93], v1 offset:55392
	v_mfma_f32_32x32x16_bf16 v[18:33], v[86:89], v[94:97], v[18:33]
	ds_read_b128 v[86:89], v68 offset:18528
	ds_read_b128 v[94:97], v1 offset:60000
	s_waitcnt lgkmcnt(1)
	v_mfma_f32_32x32x16_bf16 v[34:49], v[86:89], v[90:93], v[34:49]
	s_waitcnt lgkmcnt(0)
	v_mfma_f32_32x32x16_bf16 v[50:65], v[86:89], v[94:97], v[50:65]
	v_mfma_f32_32x32x16_bf16 v[2:17], v[98:101], v[90:93], v[2:17]
	v_mfma_f32_32x32x16_bf16 v[18:33], v[98:101], v[94:97], v[18:33]
	s_setprio 0
	s_barrier
	ds_read_b128 v[94:97], v68
	ds_read_b128 v[98:101], v68 offset:4608
	ds_read_b128 v[126:129], v1 offset:36864
	ds_read_b128 v[130:133], v1 offset:41472
	s_setprio 1
	ds_read_b128 v[86:89], v68 offset:32
	s_waitcnt lgkmcnt(2)
	v_mfma_f32_32x32x16_bf16 v[34:49], v[94:97], v[126:129], v[34:49]
	s_waitcnt vmcnt(7)
	ds_write_b128 v66, v[140:143] offset:18432
	s_waitcnt vmcnt(6)
	ds_write_b128 v66, v[102:105] offset:23040
	global_load_dwordx4 v[140:143], v[72:73], off offset:1792
	global_load_dwordx4 v[102:105], v[70:71], off offset:1792
	ds_read_b128 v[90:93], v1 offset:36896
	s_waitcnt lgkmcnt(4)
	v_mfma_f32_32x32x16_bf16 v[50:65], v[94:97], v[130:133], v[50:65]
	ds_read_b128 v[94:97], v1 offset:41504
	s_waitcnt lgkmcnt(1)
	v_mfma_f32_32x32x16_bf16 v[34:49], v[86:89], v[90:93], v[34:49]
	s_waitcnt lgkmcnt(0)
	v_mfma_f32_32x32x16_bf16 v[50:65], v[86:89], v[94:97], v[50:65]
	s_waitcnt vmcnt(7)
	ds_write_b128 v66, v[106:109] offset:27648
	s_waitcnt vmcnt(6)
	ds_write_b128 v66, v[110:113] offset:32256
	global_load_dwordx4 v[106:109], v[74:75], off offset:1792
	global_load_dwordx4 v[110:113], v[78:79], off offset:1792
	ds_read_b128 v[86:89], v68 offset:4640
	v_mfma_f32_32x32x16_bf16 v[2:17], v[98:101], v[126:129], v[2:17]
	v_mfma_f32_32x32x16_bf16 v[18:33], v[98:101], v[130:133], v[18:33]
	ds_read_b128 v[98:101], v68 offset:4704
	s_waitcnt lgkmcnt(1)
	v_mfma_f32_32x32x16_bf16 v[2:17], v[86:89], v[90:93], v[2:17]
	s_waitcnt vmcnt(7)
	ds_write_b128 v66, v[144:147] offset:55296
	s_waitcnt vmcnt(6)
	ds_write_b128 v66, v[122:125] offset:59904
	global_load_dwordx4 v[144:147], v[76:77], off offset:1792
	global_load_dwordx4 v[122:125], v[80:81], off offset:1792
	ds_read_b128 v[90:93], v1 offset:36928
	v_mfma_f32_32x32x16_bf16 v[18:33], v[86:89], v[94:97], v[18:33]
	ds_read_b128 v[86:89], v68 offset:64
	ds_read_b128 v[94:97], v1 offset:41536
	s_waitcnt lgkmcnt(1)
	v_mfma_f32_32x32x16_bf16 v[34:49], v[86:89], v[90:93], v[34:49]
	s_waitcnt lgkmcnt(0)
	v_mfma_f32_32x32x16_bf16 v[50:65], v[86:89], v[94:97], v[50:65]
	s_waitcnt vmcnt(7)
	ds_write_b128 v66, v[118:121] offset:64512
	s_waitcnt vmcnt(6)
	ds_write_b128 v69, v[114:117] offset:32256
	global_load_dwordx4 v[118:121], v[82:83], off offset:1792
	global_load_dwordx4 v[114:117], v[84:85], off offset:1792
	ds_read_b128 v[86:89], v68 offset:4672
	s_waitcnt lgkmcnt(0)
	v_mfma_f32_32x32x16_bf16 v[2:17], v[86:89], v[90:93], v[2:17]
	ds_read_b128 v[90:93], v1 offset:36960
	v_mfma_f32_32x32x16_bf16 v[18:33], v[86:89], v[94:97], v[18:33]
	ds_read_b128 v[86:89], v68 offset:96
	ds_read_b128 v[94:97], v1 offset:41568
	s_waitcnt lgkmcnt(1)
	v_mfma_f32_32x32x16_bf16 v[34:49], v[86:89], v[90:93], v[34:49]
	s_waitcnt lgkmcnt(0)
	v_mfma_f32_32x32x16_bf16 v[50:65], v[86:89], v[94:97], v[50:65]
	v_mfma_f32_32x32x16_bf16 v[2:17], v[98:101], v[90:93], v[2:17]
	v_mfma_f32_32x32x16_bf16 v[18:33], v[98:101], v[94:97], v[18:33]
	s_setprio 0
	s_barrier
; #define MFMA(a, b, c) __builtin_amdgcn_mfma_f32_32x32x16_bf16((a), (b), (c), 0, 0, 0)
; template <int TM, int TN>
; DI void gemm_mainloop(const u16* __restrict__ A, long lda, const u16* __restrict__ Bt, long ldb, int K, char* smem,
;                       f32x16 (&acc)[TM][TN]) {
;     ...
;   for (int kt = 0; kt < nk; kt++) {
;     const int buf = kt & 1;
;     const u16* cA = sA + buf * BM * LD + (wm * 32 * TM + r) * LD + h * 8;
;     const u16* cB = sB + buf * BN * LD + (wn * 32 * TN + r) * LD + h * 8;
;     bf16x8 af[TM], bfr[TN];
; #pragma unroll
;     for (int tm = 0; tm < TM; tm++) af[tm] = *(const bf16x8*)(cA + tm * 32 * LD);
; #pragma unroll
;     for (int tn = 0; tn < TN; tn++) bfr[tn] = *(const bf16x8*)(cB + tn * 32 * LD);
;     if (kt + 1 < nk) GEMM_SSTORE(buf ^ 1)
;     __builtin_amdgcn_sched_barrier(0);
;     __builtin_amdgcn_s_setprio(1);
; #pragma unroll
;     for (int tm = 0; tm < TM; tm++)
; #pragma unroll
;       for (int tn = 0; tn < TN; tn++) acc[tm][tn] = MFMA(af[tm], bfr[tn], acc[tm][tn]);
; #pragma unroll
;     for (int tm = 0; tm < TM; tm++) af[tm] = *(const bf16x8*)(cA + tm * 32 * LD + 16);
; #pragma unroll
;     for (int tn = 0; tn < TN; tn++) bfr[tn] = *(const bf16x8*)(cB + tn * 32 * LD + 16);
; #pragma unroll
;     for (int tm = 0; tm < TM; tm++)
; #pragma unroll
;       for (int tn = 0; tn < TN; tn++) acc[tm][tn] = MFMA(af[tm], bfr[tn], acc[tm][tn]);
;     __builtin_amdgcn_sched_group_barrier(0x8, 4, 0);
;     if (kt + 2 < nk) GEMM_GLOAD((kt + 2) * 64)
; #pragma unroll
;     for (int ks = 2; ks < 4; ks++) {
; #pragma unroll
;       for (int tm = 0; tm < TM; tm++) af[tm] = *(const bf16x8*)(cA + tm * 32 * LD + ks * 16);
; #pragma unroll
;       for (int tn = 0; tn < TN; tn++) bfr[tn] = *(const bf16x8*)(cB + tn * 32 * LD + ks * 16);
; #pragma unroll
;       for (int tm = 0; tm < TM; tm++)
; #pragma unroll
;         for (int tn = 0; tn < TN; tn++) acc[tm][tn] = MFMA(af[tm], bfr[tn], acc[tm][tn]);
;     }
;     __builtin_amdgcn_s_setprio(0);
;     __syncthreads();
;   }
	ds_read_b128 v[94:97], v68 offset:18432
	ds_read_b128 v[98:101], v68 offset:23040
	ds_read_b128 v[126:129], v1 offset:55296
	ds_read_b128 v[130:133], v1 offset:59904
	s_setprio 1
	ds_read_b128 v[86:89], v68 offset:18464
	s_waitcnt lgkmcnt(2)
	v_mfma_f32_32x32x16_bf16 v[34:49], v[94:97], v[126:129], v[34:49]
	s_waitcnt vmcnt(7)
	ds_write_b128 v66, v[140:143]
	s_waitcnt vmcnt(6)
	ds_write_b128 v66, v[102:105] offset:4608
	global_load_dwordx4 v[140:143], v[72:73], off offset:1920
	global_load_dwordx4 v[102:105], v[70:71], off offset:1920
	ds_read_b128 v[90:93], v1 offset:55328
	s_waitcnt lgkmcnt(4)
	v_mfma_f32_32x32x16_bf16 v[50:65], v[94:97], v[130:133], v[50:65]
	ds_read_b128 v[94:97], v1 offset:59936
	s_waitcnt lgkmcnt(1)
	v_mfma_f32_32x32x16_bf16 v[34:49], v[86:89], v[90:93], v[34:49]
	s_waitcnt lgkmcnt(0)
	v_mfma_f32_32x32x16_bf16 v[50:65], v[86:89], v[94:97], v[50:65]
	s_waitcnt vmcnt(7)
	ds_write_b128 v66, v[106:109] offset:9216
	s_waitcnt vmcnt(6)
	ds_write_b128 v66, v[110:113] offset:13824
	global_load_dwordx4 v[106:109], v[74:75], off offset:1920
	global_load_dwordx4 v[110:113], v[78:79], off offset:1920
	ds_read_b128 v[86:89], v68 offset:23072
	v_mfma_f32_32x32x16_bf16 v[2:17], v[98:101], v[126:129], v[2:17]
	v_mfma_f32_32x32x16_bf16 v[18:33], v[98:101], v[130:133], v[18:33]
	ds_read_b128 v[98:101], v68 offset:23136
	s_waitcnt lgkmcnt(1)
	v_mfma_f32_32x32x16_bf16 v[2:17], v[86:89], v[90:93], v[2:17]
	s_waitcnt vmcnt(7)
	ds_write_b128 v66, v[144:147] offset:36864
	s_waitcnt vmcnt(6)
	ds_write_b128 v66, v[122:125] offset:41472
	global_load_dwordx4 v[144:147], v[76:77], off offset:1920
	global_load_dwordx4 v[122:125], v[80:81], off offset:1920
	ds_read_b128 v[90:93], v1 offset:55360
	v_mfma_f32_32x32x16_bf16 v[18:33], v[86:89], v[94:97], v[18:33]
	ds_read_b128 v[86:89], v68 offset:18496
	ds_read_b128 v[94:97], v1 offset:59968
	s_waitcnt lgkmcnt(1)
	v_mfma_f32_32x32x16_bf16 v[34:49], v[86:89], v[90:93], v[34:49]
	s_waitcnt lgkmcnt(0)
	v_mfma_f32_32x32x16_bf16 v[50:65], v[86:89], v[94:97], v[50:65]
	s_waitcnt vmcnt(7)
	ds_write_b128 v66, v[118:121] offset:46080
	s_waitcnt vmcnt(6)
	ds_write_b128 v66, v[114:117] offset:50688
	global_load_dwordx4 v[118:121], v[82:83], off offset:1920
	global_load_dwordx4 v[114:117], v[84:85], off offset:1920
	ds_read_b128 v[86:89], v68 offset:23104
	s_waitcnt lgkmcnt(0)
	v_mfma_f32_32x32x16_bf16 v[2:17], v[86:89], v[90:93], v[2:17]
	ds_read_b128 v[90:93], v1 offset:55392
	v_mfma_f32_32x32x16_bf16 v[18:33], v[86:89], v[94:97], v[18:33]
	ds_read_b128 v[86:89], v68 offset:18528
	ds_read_b128 v[94:97], v1 offset:60000
	s_waitcnt lgkmcnt(1)
	v_mfma_f32_32x32x16_bf16 v[34:49], v[86:89], v[90:93], v[34:49]
	s_waitcnt lgkmcnt(0)
	v_mfma_f32_32x32x16_bf16 v[50:65], v[86:89], v[94:97], v[50:65]
	s_nop 0
	v_mfma_f32_32x32x16_bf16 v[2:17], v[98:101], v[90:93], v[2:17]
	v_mfma_f32_32x32x16_bf16 v[18:33], v[98:101], v[94:97], v[18:33]
	s_setprio 0
	s_barrier
	ds_read_b128 v[74:77], v68
	ds_read_b128 v[78:81], v68 offset:4608
	ds_read_b128 v[82:85], v1 offset:36864
	ds_read_b128 v[90:93], v1 offset:41472
	s_setprio 1
	ds_read_b128 v[70:73], v68 offset:32
	s_waitcnt lgkmcnt(2)
	v_mfma_f32_32x32x16_bf16 v[34:49], v[74:77], v[82:85], v[34:49]
	s_waitcnt vmcnt(7)
	ds_write_b128 v66, v[140:143] offset:18432
	s_waitcnt vmcnt(6)
	ds_write_b128 v66, v[102:105] offset:23040
	s_waitcnt lgkmcnt(3)
	v_mfma_f32_32x32x16_bf16 v[50:65], v[74:77], v[90:93], v[50:65]
	ds_read_b128 v[74:77], v1 offset:36896
	v_mfma_f32_32x32x16_bf16 v[2:17], v[78:81], v[82:85], v[2:17]
	v_mfma_f32_32x32x16_bf16 v[18:33], v[78:81], v[90:93], v[18:33]
	s_waitcnt vmcnt(5)
	ds_write_b128 v66, v[106:109] offset:27648
	s_waitcnt vmcnt(4)
	ds_write_b128 v66, v[110:113] offset:32256
	ds_read_b128 v[78:81], v1 offset:41504
	s_waitcnt lgkmcnt(3)
	v_mfma_f32_32x32x16_bf16 v[34:49], v[70:73], v[74:77], v[34:49]
	s_waitcnt lgkmcnt(0)
	v_mfma_f32_32x32x16_bf16 v[50:65], v[70:73], v[78:81], v[50:65]
	ds_read_b128 v[70:73], v68 offset:4640
	s_waitcnt lgkmcnt(0)
	v_mfma_f32_32x32x16_bf16 v[2:17], v[70:73], v[74:77], v[2:17]
	s_waitcnt vmcnt(3)
	ds_write_b128 v66, v[144:147] offset:55296
	s_waitcnt vmcnt(2)
	ds_write_b128 v66, v[122:125] offset:59904
	ds_read_b128 v[74:77], v1 offset:36928
	v_mfma_f32_32x32x16_bf16 v[18:33], v[70:73], v[78:81], v[18:33]
	ds_read_b128 v[70:73], v68 offset:64
	ds_read_b128 v[78:81], v1 offset:41536
	s_waitcnt lgkmcnt(1)
	v_mfma_f32_32x32x16_bf16 v[34:49], v[70:73], v[74:77], v[34:49]
	s_waitcnt lgkmcnt(0)
	v_mfma_f32_32x32x16_bf16 v[50:65], v[70:73], v[78:81], v[50:65]
	s_waitcnt vmcnt(1)
	ds_write_b128 v66, v[118:121] offset:64512
	s_waitcnt vmcnt(0)
	ds_write_b128 v69, v[114:117] offset:32256
	ds_read_b128 v[70:73], v68 offset:4672
	s_waitcnt lgkmcnt(0)
	v_mfma_f32_32x32x16_bf16 v[2:17], v[70:73], v[74:77], v[2:17]
	ds_read_b128 v[74:77], v1 offset:36960
	v_mfma_f32_32x32x16_bf16 v[18:33], v[70:73], v[78:81], v[18:33]
	ds_read_b128 v[70:73], v68 offset:96
	ds_read_b128 v[78:81], v1 offset:41568
	s_waitcnt lgkmcnt(1)
	v_mfma_f32_32x32x16_bf16 v[34:49], v[70:73], v[74:77], v[34:49]
	s_waitcnt lgkmcnt(0)
	v_mfma_f32_32x32x16_bf16 v[50:65], v[70:73], v[78:81], v[50:65]
	ds_read_b128 v[70:73], v68 offset:4704
	s_waitcnt lgkmcnt(0)
	v_mfma_f32_32x32x16_bf16 v[2:17], v[70:73], v[74:77], v[2:17]
	v_mfma_f32_32x32x16_bf16 v[18:33], v[70:73], v[78:81], v[18:33]
	s_setprio 0
	s_barrier
; #define MFMA(a, b, c) __builtin_amdgcn_mfma_f32_32x32x16_bf16((a), (b), (c), 0, 0, 0)
; DI int crow(int i, int h) { return (i & 3) + 8 * (i >> 2) + 4 * h; }
; template <int TM, int TN>
; DI void gemm_mainloop(const u16* __restrict__ A, long lda, const u16* __restrict__ Bt, long ldb, int K, char* smem,
;                       f32x16 (&acc)[TM][TN]) {
;     ...
;     for (int ks = 2; ks < 4; ks++) {
; #pragma unroll
;       for (int tm = 0; tm < TM; tm++) af[tm] = *(const bf16x8*)(cA + tm * 32 * LD + ks * 16);
; #pragma unroll
;       for (int tn = 0; tn < TN; tn++) bfr[tn] = *(const bf16x8*)(cB + tn * 32 * LD + ks * 16);
; #pragma unroll
;       for (int tm = 0; tm < TM; tm++)
; #pragma unroll
;         for (int tn = 0; tn < TN; tn++) acc[tm][tn] = MFMA(af[tm], bfr[tn], acc[tm][tn]);
;     }
;     __builtin_amdgcn_s_setprio(0);
;     __syncthreads();
;   }
; template <int TM, int TN, class Epi>
; DI void gemm_tile(const u16* A, long lda, const u16* Bt, long ldb, int K, int m0, int n0, char* smem, const Epi& epi) {
;     ...
; #pragma unroll
;   for (int tm = 0; tm < TM; tm++)
; #pragma unroll
;     for (int tn = 0; tn < TN; tn++)
; #pragma unroll
;       for (int i = 0; i < 16; i++)
;         Ct[(wm * 32 * TM + tm * 32 + crow(i, h)) * LDC + wn * 32 * TN + tn * 32 + r] = acc[tm][tn][i];
;   __syncthreads();
	ds_read_b128 v[70:73], v68 offset:18432
	ds_read_b128 v[74:77], v68 offset:23040
	ds_read_b128 v[78:81], v1 offset:55296
	ds_read_b128 v[82:85], v1 offset:59904
	s_setprio 1
	s_waitcnt lgkmcnt(1)
	v_mfma_f32_32x32x16_bf16 v[34:49], v[70:73], v[78:81], v[34:49]
	s_waitcnt lgkmcnt(0)
	v_mfma_f32_32x32x16_bf16 v[50:65], v[70:73], v[82:85], v[50:65]
	ds_read_b128 v[70:73], v68 offset:18464
	v_mfma_f32_32x32x16_bf16 v[2:17], v[74:77], v[78:81], v[2:17]
	ds_read_b128 v[78:81], v1 offset:59936
	v_mfma_f32_32x32x16_bf16 v[18:33], v[74:77], v[82:85], v[18:33]
	ds_read_b128 v[74:77], v1 offset:55328
	s_waitcnt lgkmcnt(0)
	v_mfma_f32_32x32x16_bf16 v[34:49], v[70:73], v[74:77], v[34:49]
	v_mfma_f32_32x32x16_bf16 v[50:65], v[70:73], v[78:81], v[50:65]
	ds_read_b128 v[70:73], v68 offset:23072
	s_waitcnt lgkmcnt(0)
	v_mfma_f32_32x32x16_bf16 v[2:17], v[70:73], v[74:77], v[2:17]
	ds_read_b128 v[74:77], v1 offset:55360
	v_mfma_f32_32x32x16_bf16 v[18:33], v[70:73], v[78:81], v[18:33]
	ds_read_b128 v[70:73], v68 offset:18496
	ds_read_b128 v[78:81], v1 offset:59968
	s_waitcnt lgkmcnt(1)
	v_mfma_f32_32x32x16_bf16 v[34:49], v[70:73], v[74:77], v[34:49]
	s_waitcnt lgkmcnt(0)
	v_mfma_f32_32x32x16_bf16 v[50:65], v[70:73], v[78:81], v[50:65]
	ds_read_b128 v[70:73], v68 offset:23104
	s_waitcnt lgkmcnt(0)
	v_mfma_f32_32x32x16_bf16 v[2:17], v[70:73], v[74:77], v[2:17]
	ds_read_b128 v[74:77], v1 offset:55392
	v_mfma_f32_32x32x16_bf16 v[18:33], v[70:73], v[78:81], v[18:33]
	ds_read_b128 v[70:73], v68 offset:18528
	ds_read_b128 v[78:81], v1 offset:60000
	s_waitcnt lgkmcnt(1)
	v_mfma_f32_32x32x16_bf16 v[34:49], v[70:73], v[74:77], v[34:49]
	s_waitcnt lgkmcnt(0)
	v_mfma_f32_32x32x16_bf16 v[50:65], v[70:73], v[78:81], v[50:65]
	ds_read_b128 v[68:71], v68 offset:23136
	s_waitcnt lgkmcnt(0)
	v_mfma_f32_32x32x16_bf16 v[2:17], v[68:71], v[74:77], v[2:17]
	v_mfma_f32_32x32x16_bf16 v[18:33], v[68:71], v[78:81], v[18:33]
	s_setprio 0
	v_mov_b32_e32 v1, v0
	s_barrier
	s_lshl_b32 s25, s25, 2
	v_lshrrev_b32_e32 v66, 1, v1
	v_and_b32_e32 v66, 0xfffffc0, v66
	v_lshrrev_b32_e32 v68, 3, v1
	v_and_or_b32 v66, v68, 4, v66
	v_and_b32_e32 v68, 0x5f, v1
	v_mul_lo_u32 v66, v66, s20
	v_lshl_add_u32 v66, v68, 2, v66
	ds_write2_b32 v66, v34, v50 offset1:32
	v_add_u32_e32 v34, 0x400, v66
	ds_write2_b32 v34, v36, v52 offset0:8 offset1:40
	ds_write2_b32 v34, v37, v53 offset0:140 offset1:172
	v_add_u32_e32 v34, 0x1000, v66
	ds_write2_b32 v34, v38, v54 offset0:32 offset1:64
	ds_write2_b32 v34, v39, v55 offset0:164 offset1:196
	v_add_u32_e32 v34, 0x1400, v66
	ds_write2_b32 v34, v40, v56 offset0:40 offset1:72
	ds_write2_b32 v34, v41, v57 offset0:172 offset1:204
	v_add_u32_e32 v34, 0x2000, v66
	ds_write2_b32 v34, v42, v58 offset0:64 offset1:96
	ds_write2_b32 v34, v43, v59 offset0:196 offset1:228
	v_add_u32_e32 v34, 0x2400, v66
	ds_write2_b32 v34, v44, v60 offset0:72 offset1:104
	ds_write2_b32 v34, v45, v61 offset0:204 offset1:236
	v_add_u32_e32 v34, 0x3000, v66
	ds_write2_b32 v34, v46, v62 offset0:96 offset1:128
	v_add_u32_e32 v34, 0x3200, v66
	ds_write2_b32 v34, v47, v63 offset0:100 offset1:132
	v_add_u32_e32 v34, 0x3400, v66
	ds_write2_b32 v34, v48, v64 offset0:104 offset1:136
	v_add_u32_e32 v34, 0x3600, v66
	ds_write2_b32 v34, v49, v65 offset0:108 offset1:140
	v_add_u32_e32 v34, 0x4000, v66
	ds_write2_b32 v34, v2, v18 offset0:128 offset1:160
	v_add_u32_e32 v2, 0x4400, v66
	ds_write2_b32 v2, v3, v19 offset0:4 offset1:36
	ds_write2_b32 v2, v4, v20 offset0:136 offset1:168
	v_add_u32_e32 v2, 0x4800, v66
	ds_write2_b32 v2, v5, v21 offset0:12 offset1:44
	v_add_u32_e32 v2, 0x5000, v66
	ds_write2_b32 v2, v6, v22 offset0:160 offset1:192
	v_add_u32_e32 v2, 0x5400, v66
	ds_write2_b32 v2, v7, v23 offset0:36 offset1:68
	ds_write2_b32 v2, v8, v24 offset0:168 offset1:200
	v_add_u32_e32 v2, 0x5800, v66
	ds_write2_b32 v2, v9, v25 offset0:44 offset1:76
	v_add_u32_e32 v2, 0x6000, v66
	ds_write2_b32 v2, v10, v26 offset0:192 offset1:224
	v_add_u32_e32 v2, 0x6400, v66
	ds_write2_b32 v2, v11, v27 offset0:68 offset1:100
	ds_write2_b32 v2, v12, v28 offset0:200 offset1:232
	v_add_u32_e32 v2, 0x6800, v66
	ds_write2_b32 v2, v13, v29 offset0:76 offset1:108
	v_add_u32_e32 v2, 0x7200, v66
	ds_write2_b32 v2, v14, v30 offset0:96 offset1:128
	v_add_u32_e32 v2, 0x7400, v66
	ds_write2_b32 v2, v15, v31 offset0:100 offset1:132
	v_add_u32_e32 v2, 0x7600, v66
	ds_write2_b32 v2, v16, v32 offset0:104 offset1:136
	v_add_u32_e32 v2, 0x7800, v66
	ds_write2_b32 v2, v17, v33 offset0:108 offset1:140
	v_lshlrev_b32_e32 v2, 5, v1
	s_add_u32 s26, s23, s25
	ds_write2_b32 v66, v35, v51 offset0:132 offset1:164
	v_and_b32_e32 v66, 0x1e0, v2
	s_addc_u32 s27, s24, 0
	v_lshl_add_u64 v[2:3], s[26:27], 0, v[66:67]
	s_mov_b32 s23, 0
	s_waitcnt lgkmcnt(0)
	s_barrier

; #define MFMA(a, b, c) __builtin_amdgcn_mfma_f32_32x32x16_bf16((a), (b), (c), 0, 0, 0)
; template <int TM, int TN>
; DI void gemm_mainloop(const u16* __restrict__ A, long lda, const u16* __restrict__ Bt, long ldb, int K, char* smem,
;                       f32x16 (&acc)[TM][TN]) {
;     ...
;   const int nk = K / 64;
;   const int lrow = tid >> 3, lch = (tid & 7) * 8;
;   const u16* gA = A + (long)lrow * lda + lch;
;   const u16* gB = Bt + (long)lrow * ldb + lch;
;   const int soff = lrow * LD + lch;
;     ...
;   GEMM_GLOAD(0)
;   __syncthreads();
;   GEMM_SSTORE(0)
;   if (nk > 1) GEMM_GLOAD(64)
;   __syncthreads();
;   for (int kt = 0; kt < nk; kt++) {
;     const int buf = kt & 1;
;     const u16* cA = sA + buf * BM * LD + (wm * 32 * TM + r) * LD + h * 8;
;     const u16* cB = sB + buf * BN * LD + (wn * 32 * TN + r) * LD + h * 8;
;     bf16x8 af[TM], bfr[TN];
; #pragma unroll
;     for (int tm = 0; tm < TM; tm++) af[tm] = *(const bf16x8*)(cA + tm * 32 * LD);
; #pragma unroll
;     for (int tn = 0; tn < TN; tn++) bfr[tn] = *(const bf16x8*)(cB + tn * 32 * LD);
;     if (kt + 1 < nk) GEMM_SSTORE(buf ^ 1)
;     __builtin_amdgcn_sched_barrier(0);
;     __builtin_amdgcn_s_setprio(1);
; #pragma unroll
;     for (int tm = 0; tm < TM; tm++)
; #pragma unroll
;       for (int tn = 0; tn < TN; tn++) acc[tm][tn] = MFMA(af[tm], bfr[tn], acc[tm][tn]);
; #pragma unroll
;     for (int tm = 0; tm < TM; tm++) af[tm] = *(const bf16x8*)(cA + tm * 32 * LD + 16);
; #pragma unroll
;     for (int tn = 0; tn < TN; tn++) bfr[tn] = *(const bf16x8*)(cB + tn * 32 * LD + 16);
; #pragma unroll
;     for (int tm = 0; tm < TM; tm++)
; #pragma unroll
;       for (int tn = 0; tn < TN; tn++) acc[tm][tn] = MFMA(af[tm], bfr[tn], acc[tm][tn]);
;     __builtin_amdgcn_sched_group_barrier(0x8, 4, 0);
;     if (kt + 2 < nk) GEMM_GLOAD((kt + 2) * 64)
; #pragma unroll
;     for (int ks = 2; ks < 4; ks++) {
; #pragma unroll
;       for (int tm = 0; tm < TM; tm++) af[tm] = *(const bf16x8*)(cA + tm * 32 * LD + ks * 16);
; #pragma unroll
;       for (int tn = 0; tn < TN; tn++) bfr[tn] = *(const bf16x8*)(cB + tn * 32 * LD + ks * 16);
; #pragma unroll
;       for (int tm = 0; tm < TM; tm++)
; #pragma unroll
;         for (int tn = 0; tn < TN; tn++) acc[tm][tn] = MFMA(af[tm], bfr[tn], acc[tm][tn]);
;     }
;     __builtin_amdgcn_s_setprio(0);
;     __syncthreads();
;   }
.LBB0_1072:
	s_lshl_b32 s27, s26, 10
	s_add_i32 s27, s27, s14
	s_mul_i32 s4, s27, 0x880
	s_mul_hi_i32 s5, s27, 0x880
	s_add_u32 s4, s8, s4
	v_mov_b32_e32 v1, v0
	s_addc_u32 s5, s9, s5
	s_nop 0
	v_lshlrev_b32_e32 v2, 3, v1
	v_ashrrev_i32_e32 v70, 3, v1
	v_and_b32_e32 v71, 56, v2
	v_mov_b64_e32 v[2:3], s[4:5]
	v_mad_i64_i32 v[2:3], s[4:5], v70, s17, v[2:3]
	v_lshlrev_b32_e32 v66, 1, v71
	v_lshl_add_u64 v[74:75], v[2:3], 0, v[66:67]
	v_add_co_u32_e32 v72, vcc, s19, v74
	v_mad_i64_i32 v[10:11], s[4:5], v70, s17, v[68:69]
	s_nop 0
	v_addc_co_u32_e32 v73, vcc, 0, v75, vcc
	v_add_co_u32_e32 v76, vcc, s20, v74
	v_lshl_add_u64 v[78:79], v[10:11], 0, v[66:67]
	s_nop 0
	v_addc_co_u32_e32 v77, vcc, 0, v75, vcc
	v_add_co_u32_e32 v80, vcc, s19, v78
	global_load_dwordx4 v[2:5], v[74:75], off
	s_nop 0
	v_addc_co_u32_e32 v81, vcc, 0, v79, vcc
	v_add_co_u32_e32 v82, vcc, s20, v78
	global_load_dwordx4 v[6:9], v[72:73], off
	s_nop 0
	v_addc_co_u32_e32 v83, vcc, 0, v79, vcc
	v_add_co_u32_e32 v84, vcc, s21, v78
	global_load_dwordx4 v[10:13], v[78:79], off
	s_nop 0
	v_addc_co_u32_e32 v85, vcc, 0, v79, vcc
	v_add_co_u32_e32 v86, vcc, s21, v74
	global_load_dwordx4 v[14:17], v[80:81], off
	s_nop 0
	v_addc_co_u32_e32 v87, vcc, 0, v75, vcc
	global_load_dwordx4 v[18:21], v[82:83], off
	global_load_dwordx4 v[22:25], v[84:85], off
	global_load_dwordx4 v[26:29], v[76:77], off
	global_load_dwordx4 v[30:33], v[86:87], off
	s_barrier
	global_load_dwordx4 v[34:37], v[74:75], off offset:128
	global_load_dwordx4 v[38:41], v[72:73], off offset:128
	global_load_dwordx4 v[42:45], v[76:77], off offset:128
	global_load_dwordx4 v[46:49], v[86:87], off offset:128
	global_load_dwordx4 v[50:53], v[78:79], off offset:128
	global_load_dwordx4 v[54:57], v[80:81], off offset:128
	global_load_dwordx4 v[58:61], v[82:83], off offset:128
	global_load_dwordx4 v[62:65], v[84:85], off offset:128
	v_and_b32_e32 v66, 31, v1
	v_lshrrev_b32_e32 v88, 1, v1
	v_mul_lo_u32 v70, v70, s18
	v_and_or_b32 v89, v88, s22, v66
	v_and_b32_e32 v88, 16, v88
	v_and_b32_e32 v1, 0x5f, v1
	v_add_lshl_u32 v66, v70, v71, 1
	v_mad_u64_u32 v[70:71], s[4:5], v89, s23, v[88:89]
	v_mad_u32_u24 v1, v1, s23, v88
	v_add_u32_e32 v71, 0x9000, v66
	s_waitcnt vmcnt(15)
	ds_write_b128 v66, v[2:5]
	s_waitcnt vmcnt(14)
	ds_write_b128 v66, v[6:9] offset:4608
	s_waitcnt vmcnt(13)
	ds_write_b128 v66, v[10:13] offset:36864
	s_waitcnt vmcnt(12)
	ds_write_b128 v66, v[14:17] offset:41472
	s_waitcnt vmcnt(11)
	ds_write_b128 v66, v[18:21] offset:46080
	s_waitcnt vmcnt(10)
	ds_write_b128 v66, v[22:25] offset:50688
	s_waitcnt vmcnt(9)
	ds_write_b128 v66, v[26:29] offset:9216
	s_waitcnt vmcnt(8)
	ds_write_b128 v66, v[30:33] offset:13824
	s_waitcnt lgkmcnt(0)
	s_barrier
	ds_read_b128 v[2:5], v70
	ds_read_b128 v[18:21], v70 offset:4608
	ds_read_b128 v[6:9], v1 offset:36864
	ds_read_b128 v[22:25], v1 offset:41472
	s_waitcnt vmcnt(7)
	ds_write_b128 v66, v[34:37] offset:18432
	s_waitcnt vmcnt(6)
	ds_write_b128 v66, v[38:41] offset:23040
	s_waitcnt vmcnt(5)
	ds_write_b128 v66, v[42:45] offset:27648
	s_waitcnt vmcnt(4)
	ds_write_b128 v66, v[46:49] offset:32256
	s_waitcnt vmcnt(3)
	ds_write_b128 v66, v[50:53] offset:55296
	s_waitcnt vmcnt(2)
	ds_write_b128 v66, v[54:57] offset:59904
	s_waitcnt vmcnt(1)
	ds_write_b128 v66, v[58:61] offset:64512
	s_waitcnt vmcnt(0)
	ds_write_b128 v71, v[62:65] offset:32256
	s_setprio 1
	ds_read_b128 v[88:91], v70 offset:32
	s_waitcnt lgkmcnt(10)
	v_mfma_f32_32x32x16_bf16 v[34:49], v[2:5], v[6:9], 0
	ds_read_b128 v[92:95], v1 offset:36896
	ds_read_b128 v[96:99], v1 offset:41504
	ds_read_b128 v[100:103], v70 offset:4704
	global_load_dwordx4 v[104:107], v[72:73], off offset:256
	global_load_dwordx4 v[108:111], v[76:77], off offset:256
	global_load_dwordx4 v[112:115], v[86:87], off offset:256
	global_load_dwordx4 v[116:119], v[84:85], off offset:256
	s_waitcnt lgkmcnt(12)
	v_mfma_f32_32x32x16_bf16 v[50:65], v[2:5], v[22:25], 0
	global_load_dwordx4 v[120:123], v[82:83], off offset:256
	global_load_dwordx4 v[124:127], v[80:81], off offset:256
	global_load_dwordx4 v[140:143], v[74:75], off offset:256
	global_load_dwordx4 v[144:147], v[78:79], off offset:256
	s_waitcnt lgkmcnt(2)
	v_mfma_f32_32x32x16_bf16 v[34:49], v[88:91], v[92:95], v[34:49]
	s_waitcnt lgkmcnt(1)
	v_mfma_f32_32x32x16_bf16 v[50:65], v[88:91], v[96:99], v[50:65]
	ds_read_b128 v[88:91], v70 offset:4640
	v_mfma_f32_32x32x16_bf16 v[2:17], v[18:21], v[6:9], 0
	v_mfma_f32_32x32x16_bf16 v[18:33], v[18:21], v[22:25], 0
	s_waitcnt lgkmcnt(0)
	v_mfma_f32_32x32x16_bf16 v[2:17], v[88:91], v[92:95], v[2:17]
	ds_read_b128 v[92:95], v1 offset:36928
	v_mfma_f32_32x32x16_bf16 v[18:33], v[88:91], v[96:99], v[18:33]
	ds_read_b128 v[88:91], v70 offset:64
	ds_read_b128 v[96:99], v1 offset:41536
	s_waitcnt lgkmcnt(1)
	v_mfma_f32_32x32x16_bf16 v[34:49], v[88:91], v[92:95], v[34:49]
	s_waitcnt lgkmcnt(0)
	v_mfma_f32_32x32x16_bf16 v[50:65], v[88:91], v[96:99], v[50:65]
	ds_read_b128 v[88:91], v70 offset:4672
	s_waitcnt lgkmcnt(0)
	v_mfma_f32_32x32x16_bf16 v[2:17], v[88:91], v[92:95], v[2:17]
	ds_read_b128 v[92:95], v1 offset:36960
	v_mfma_f32_32x32x16_bf16 v[18:33], v[88:91], v[96:99], v[18:33]
	ds_read_b128 v[88:91], v70 offset:96
	ds_read_b128 v[96:99], v1 offset:41568
	s_waitcnt lgkmcnt(1)
	v_mfma_f32_32x32x16_bf16 v[34:49], v[88:91], v[92:95], v[34:49]
	s_waitcnt lgkmcnt(0)
	v_mfma_f32_32x32x16_bf16 v[50:65], v[88:91], v[96:99], v[50:65]
	v_mfma_f32_32x32x16_bf16 v[2:17], v[100:103], v[92:95], v[2:17]
	v_mfma_f32_32x32x16_bf16 v[18:33], v[100:103], v[96:99], v[18:33]
	s_setprio 0
	s_barrier
; #define MFMA(a, b, c) __builtin_amdgcn_mfma_f32_32x32x16_bf16((a), (b), (c), 0, 0, 0)
; template <int TM, int TN>
; DI void gemm_mainloop(const u16* __restrict__ A, long lda, const u16* __restrict__ Bt, long ldb, int K, char* smem,
;                       f32x16 (&acc)[TM][TN]) {
;     ...
;   for (int kt = 0; kt < nk; kt++) {
;     const int buf = kt & 1;
;     const u16* cA = sA + buf * BM * LD + (wm * 32 * TM + r) * LD + h * 8;
;     const u16* cB = sB + buf * BN * LD + (wn * 32 * TN + r) * LD + h * 8;
;     bf16x8 af[TM], bfr[TN];
; #pragma unroll
;     for (int tm = 0; tm < TM; tm++) af[tm] = *(const bf16x8*)(cA + tm * 32 * LD);
; #pragma unroll
;     for (int tn = 0; tn < TN; tn++) bfr[tn] = *(const bf16x8*)(cB + tn * 32 * LD);
;     if (kt + 1 < nk) GEMM_SSTORE(buf ^ 1)
;     __builtin_amdgcn_sched_barrier(0);
;     __builtin_amdgcn_s_setprio(1);
; #pragma unroll
;     for (int tm = 0; tm < TM; tm++)
; #pragma unroll
;       for (int tn = 0; tn < TN; tn++) acc[tm][tn] = MFMA(af[tm], bfr[tn], acc[tm][tn]);
; #pragma unroll
;     for (int tm = 0; tm < TM; tm++) af[tm] = *(const bf16x8*)(cA + tm * 32 * LD + 16);
; #pragma unroll
;     for (int tn = 0; tn < TN; tn++) bfr[tn] = *(const bf16x8*)(cB + tn * 32 * LD + 16);
; #pragma unroll
;     for (int tm = 0; tm < TM; tm++)
; #pragma unroll
;       for (int tn = 0; tn < TN; tn++) acc[tm][tn] = MFMA(af[tm], bfr[tn], acc[tm][tn]);
;     __builtin_amdgcn_sched_group_barrier(0x8, 4, 0);
;     if (kt + 2 < nk) GEMM_GLOAD((kt + 2) * 64)
; #pragma unroll
;     for (int ks = 2; ks < 4; ks++) {
; #pragma unroll
;       for (int tm = 0; tm < TM; tm++) af[tm] = *(const bf16x8*)(cA + tm * 32 * LD + ks * 16);
; #pragma unroll
;       for (int tn = 0; tn < TN; tn++) bfr[tn] = *(const bf16x8*)(cB + tn * 32 * LD + ks * 16);
; #pragma unroll
;       for (int tm = 0; tm < TM; tm++)
; #pragma unroll
;         for (int tn = 0; tn < TN; tn++) acc[tm][tn] = MFMA(af[tm], bfr[tn], acc[tm][tn]);
;     }
;     __builtin_amdgcn_s_setprio(0);
;     __syncthreads();
;   }
	ds_read_b128 v[96:99], v70 offset:18432
	ds_read_b128 v[100:103], v70 offset:23040
	ds_read_b128 v[128:131], v1 offset:55296
	ds_read_b128 v[132:135], v1 offset:59904
	s_setprio 1
	ds_read_b128 v[88:91], v70 offset:18464
	s_waitcnt lgkmcnt(2)
	v_mfma_f32_32x32x16_bf16 v[34:49], v[96:99], v[128:131], v[34:49]
	s_waitcnt vmcnt(1)
	ds_write_b128 v66, v[140:143]
	ds_write_b128 v66, v[104:107] offset:4608
	global_load_dwordx4 v[140:143], v[74:75], off offset:384
	global_load_dwordx4 v[104:107], v[72:73], off offset:384
	ds_read_b128 v[92:95], v1 offset:55328
	s_waitcnt lgkmcnt(4)
	v_mfma_f32_32x32x16_bf16 v[50:65], v[96:99], v[132:135], v[50:65]
	ds_read_b128 v[96:99], v1 offset:59936
	s_waitcnt lgkmcnt(1)
	v_mfma_f32_32x32x16_bf16 v[34:49], v[88:91], v[92:95], v[34:49]
	s_waitcnt lgkmcnt(0)
	v_mfma_f32_32x32x16_bf16 v[50:65], v[88:91], v[96:99], v[50:65]
	ds_write_b128 v66, v[108:111] offset:9216
	ds_write_b128 v66, v[112:115] offset:13824
	global_load_dwordx4 v[108:111], v[76:77], off offset:384
	global_load_dwordx4 v[112:115], v[86:87], off offset:384
	ds_read_b128 v[88:91], v70 offset:23072
	v_mfma_f32_32x32x16_bf16 v[2:17], v[100:103], v[128:131], v[2:17]
	v_mfma_f32_32x32x16_bf16 v[18:33], v[100:103], v[132:135], v[18:33]
	ds_read_b128 v[100:103], v70 offset:23136
	s_waitcnt lgkmcnt(1)
	v_mfma_f32_32x32x16_bf16 v[2:17], v[88:91], v[92:95], v[2:17]
	s_waitcnt vmcnt(4)
	ds_write_b128 v66, v[144:147] offset:36864
	ds_write_b128 v66, v[124:127] offset:41472
	global_load_dwordx4 v[144:147], v[78:79], off offset:384
	global_load_dwordx4 v[124:127], v[80:81], off offset:384
	ds_read_b128 v[92:95], v1 offset:55360
	v_mfma_f32_32x32x16_bf16 v[18:33], v[88:91], v[96:99], v[18:33]
	ds_read_b128 v[88:91], v70 offset:18496
	ds_read_b128 v[96:99], v1 offset:59968
	s_waitcnt lgkmcnt(1)
	v_mfma_f32_32x32x16_bf16 v[34:49], v[88:91], v[92:95], v[34:49]
	s_waitcnt lgkmcnt(0)
	v_mfma_f32_32x32x16_bf16 v[50:65], v[88:91], v[96:99], v[50:65]
	ds_write_b128 v66, v[120:123] offset:46080
	ds_write_b128 v66, v[116:119] offset:50688
	global_load_dwordx4 v[120:123], v[82:83], off offset:384
	global_load_dwordx4 v[116:119], v[84:85], off offset:384
	ds_read_b128 v[88:91], v70 offset:23104
	s_waitcnt lgkmcnt(0)
	v_mfma_f32_32x32x16_bf16 v[2:17], v[88:91], v[92:95], v[2:17]
	ds_read_b128 v[92:95], v1 offset:55392
	v_mfma_f32_32x32x16_bf16 v[18:33], v[88:91], v[96:99], v[18:33]
	ds_read_b128 v[88:91], v70 offset:18528
	ds_read_b128 v[96:99], v1 offset:60000
	s_waitcnt lgkmcnt(1)
	v_mfma_f32_32x32x16_bf16 v[34:49], v[88:91], v[92:95], v[34:49]
	s_waitcnt lgkmcnt(0)
	v_mfma_f32_32x32x16_bf16 v[50:65], v[88:91], v[96:99], v[50:65]
	v_mfma_f32_32x32x16_bf16 v[2:17], v[100:103], v[92:95], v[2:17]
	v_mfma_f32_32x32x16_bf16 v[18:33], v[100:103], v[96:99], v[18:33]
	s_setprio 0
	s_barrier
	ds_read_b128 v[96:99], v70
	ds_read_b128 v[100:103], v70 offset:4608
	ds_read_b128 v[128:131], v1 offset:36864
	ds_read_b128 v[132:135], v1 offset:41472
	s_setprio 1
	ds_read_b128 v[88:91], v70 offset:32
	s_waitcnt lgkmcnt(2)
	v_mfma_f32_32x32x16_bf16 v[34:49], v[96:99], v[128:131], v[34:49]
	s_waitcnt vmcnt(7)
	ds_write_b128 v66, v[140:143] offset:18432
	s_waitcnt vmcnt(6)
	ds_write_b128 v66, v[104:107] offset:23040
	global_load_dwordx4 v[140:143], v[74:75], off offset:512
	global_load_dwordx4 v[104:107], v[72:73], off offset:512
	ds_read_b128 v[92:95], v1 offset:36896
	s_waitcnt lgkmcnt(4)
	v_mfma_f32_32x32x16_bf16 v[50:65], v[96:99], v[132:135], v[50:65]
	ds_read_b128 v[96:99], v1 offset:41504
	s_waitcnt lgkmcnt(1)
	v_mfma_f32_32x32x16_bf16 v[34:49], v[88:91], v[92:95], v[34:49]
	s_waitcnt lgkmcnt(0)
	v_mfma_f32_32x32x16_bf16 v[50:65], v[88:91], v[96:99], v[50:65]
	s_waitcnt vmcnt(7)
	ds_write_b128 v66, v[108:111] offset:27648
	s_waitcnt vmcnt(6)
	ds_write_b128 v66, v[112:115] offset:32256
	global_load_dwordx4 v[108:111], v[76:77], off offset:512
	global_load_dwordx4 v[112:115], v[86:87], off offset:512
	ds_read_b128 v[88:91], v70 offset:4640
	v_mfma_f32_32x32x16_bf16 v[2:17], v[100:103], v[128:131], v[2:17]
	v_mfma_f32_32x32x16_bf16 v[18:33], v[100:103], v[132:135], v[18:33]
	ds_read_b128 v[100:103], v70 offset:4704
	s_waitcnt lgkmcnt(1)
	v_mfma_f32_32x32x16_bf16 v[2:17], v[88:91], v[92:95], v[2:17]
	s_waitcnt vmcnt(7)
	ds_write_b128 v66, v[144:147] offset:55296
	s_waitcnt vmcnt(6)
	ds_write_b128 v66, v[124:127] offset:59904
	global_load_dwordx4 v[144:147], v[78:79], off offset:512
	global_load_dwordx4 v[124:127], v[80:81], off offset:512
	ds_read_b128 v[92:95], v1 offset:36928
	v_mfma_f32_32x32x16_bf16 v[18:33], v[88:91], v[96:99], v[18:33]
	ds_read_b128 v[88:91], v70 offset:64
	ds_read_b128 v[96:99], v1 offset:41536
	s_waitcnt lgkmcnt(1)
	v_mfma_f32_32x32x16_bf16 v[34:49], v[88:91], v[92:95], v[34:49]
	s_waitcnt lgkmcnt(0)
	v_mfma_f32_32x32x16_bf16 v[50:65], v[88:91], v[96:99], v[50:65]
	s_waitcnt vmcnt(7)
	ds_write_b128 v66, v[120:123] offset:64512
	s_waitcnt vmcnt(6)
	ds_write_b128 v71, v[116:119] offset:32256
	global_load_dwordx4 v[120:123], v[82:83], off offset:512
	global_load_dwordx4 v[116:119], v[84:85], off offset:512
	ds_read_b128 v[88:91], v70 offset:4672
	s_waitcnt lgkmcnt(0)
	v_mfma_f32_32x32x16_bf16 v[2:17], v[88:91], v[92:95], v[2:17]
	ds_read_b128 v[92:95], v1 offset:36960
	v_mfma_f32_32x32x16_bf16 v[18:33], v[88:91], v[96:99], v[18:33]
	ds_read_b128 v[88:91], v70 offset:96
	ds_read_b128 v[96:99], v1 offset:41568
	s_waitcnt lgkmcnt(1)
	v_mfma_f32_32x32x16_bf16 v[34:49], v[88:91], v[92:95], v[34:49]
	s_waitcnt lgkmcnt(0)
	v_mfma_f32_32x32x16_bf16 v[50:65], v[88:91], v[96:99], v[50:65]
	v_mfma_f32_32x32x16_bf16 v[2:17], v[100:103], v[92:95], v[2:17]
	v_mfma_f32_32x32x16_bf16 v[18:33], v[100:103], v[96:99], v[18:33]
	s_setprio 0
	s_barrier
; #define MFMA(a, b, c) __builtin_amdgcn_mfma_f32_32x32x16_bf16((a), (b), (c), 0, 0, 0)
; template <int TM, int TN>
; DI void gemm_mainloop(const u16* __restrict__ A, long lda, const u16* __restrict__ Bt, long ldb, int K, char* smem,
;                       f32x16 (&acc)[TM][TN]) {
;     ...
;   for (int kt = 0; kt < nk; kt++) {
;     const int buf = kt & 1;
;     const u16* cA = sA + buf * BM * LD + (wm * 32 * TM + r) * LD + h * 8;
;     const u16* cB = sB + buf * BN * LD + (wn * 32 * TN + r) * LD + h * 8;
;     bf16x8 af[TM], bfr[TN];
; #pragma unroll
;     for (int tm = 0; tm < TM; tm++) af[tm] = *(const bf16x8*)(cA + tm * 32 * LD);
; #pragma unroll
;     for (int tn = 0; tn < TN; tn++) bfr[tn] = *(const bf16x8*)(cB + tn * 32 * LD);
;     if (kt + 1 < nk) GEMM_SSTORE(buf ^ 1)
;     __builtin_amdgcn_sched_barrier(0);
;     __builtin_amdgcn_s_setprio(1);
; #pragma unroll
;     for (int tm = 0; tm < TM; tm++)
; #pragma unroll
;       for (int tn = 0; tn < TN; tn++) acc[tm][tn] = MFMA(af[tm], bfr[tn], acc[tm][tn]);
; #pragma unroll
;     for (int tm = 0; tm < TM; tm++) af[tm] = *(const bf16x8*)(cA + tm * 32 * LD + 16);
; #pragma unroll
;     for (int tn = 0; tn < TN; tn++) bfr[tn] = *(const bf16x8*)(cB + tn * 32 * LD + 16);
; #pragma unroll
;     for (int tm = 0; tm < TM; tm++)
; #pragma unroll
;       for (int tn = 0; tn < TN; tn++) acc[tm][tn] = MFMA(af[tm], bfr[tn], acc[tm][tn]);
;     __builtin_amdgcn_sched_group_barrier(0x8, 4, 0);
;     if (kt + 2 < nk) GEMM_GLOAD((kt + 2) * 64)
; #pragma unroll
;     for (int ks = 2; ks < 4; ks++) {
; #pragma unroll
;       for (int tm = 0; tm < TM; tm++) af[tm] = *(const bf16x8*)(cA + tm * 32 * LD + ks * 16);
; #pragma unroll
;       for (int tn = 0; tn < TN; tn++) bfr[tn] = *(const bf16x8*)(cB + tn * 32 * LD + ks * 16);
; #pragma unroll
;       for (int tm = 0; tm < TM; tm++)
; #pragma unroll
;         for (int tn = 0; tn < TN; tn++) acc[tm][tn] = MFMA(af[tm], bfr[tn], acc[tm][tn]);
;     }
;     __builtin_amdgcn_s_setprio(0);
;     __syncthreads();
;   }
	ds_read_b128 v[96:99], v70 offset:18432
	ds_read_b128 v[100:103], v70 offset:23040
	ds_read_b128 v[128:131], v1 offset:55296
	ds_read_b128 v[132:135], v1 offset:59904
	s_setprio 1
	ds_read_b128 v[88:91], v70 offset:18464
	s_waitcnt lgkmcnt(2)
	v_mfma_f32_32x32x16_bf16 v[34:49], v[96:99], v[128:131], v[34:49]
	s_waitcnt vmcnt(7)
	ds_write_b128 v66, v[140:143]
	s_waitcnt vmcnt(6)
	ds_write_b128 v66, v[104:107] offset:4608
	global_load_dwordx4 v[140:143], v[74:75], off offset:640
	global_load_dwordx4 v[104:107], v[72:73], off offset:640
	ds_read_b128 v[92:95], v1 offset:55328
	s_waitcnt lgkmcnt(4)
	v_mfma_f32_32x32x16_bf16 v[50:65], v[96:99], v[132:135], v[50:65]
	ds_read_b128 v[96:99], v1 offset:59936
	s_waitcnt lgkmcnt(1)
	v_mfma_f32_32x32x16_bf16 v[34:49], v[88:91], v[92:95], v[34:49]
	s_waitcnt lgkmcnt(0)
	v_mfma_f32_32x32x16_bf16 v[50:65], v[88:91], v[96:99], v[50:65]
	s_waitcnt vmcnt(7)
	ds_write_b128 v66, v[108:111] offset:9216
	s_waitcnt vmcnt(6)
	ds_write_b128 v66, v[112:115] offset:13824
	global_load_dwordx4 v[108:111], v[76:77], off offset:640
	global_load_dwordx4 v[112:115], v[86:87], off offset:640
	ds_read_b128 v[88:91], v70 offset:23072
	v_mfma_f32_32x32x16_bf16 v[2:17], v[100:103], v[128:131], v[2:17]
	v_mfma_f32_32x32x16_bf16 v[18:33], v[100:103], v[132:135], v[18:33]
	ds_read_b128 v[100:103], v70 offset:23136
	s_waitcnt lgkmcnt(1)
	v_mfma_f32_32x32x16_bf16 v[2:17], v[88:91], v[92:95], v[2:17]
	s_waitcnt vmcnt(7)
	ds_write_b128 v66, v[144:147] offset:36864
	s_waitcnt vmcnt(6)
	ds_write_b128 v66, v[124:127] offset:41472
	global_load_dwordx4 v[144:147], v[78:79], off offset:640
	global_load_dwordx4 v[124:127], v[80:81], off offset:640
	ds_read_b128 v[92:95], v1 offset:55360
	v_mfma_f32_32x32x16_bf16 v[18:33], v[88:91], v[96:99], v[18:33]
	ds_read_b128 v[88:91], v70 offset:18496
	ds_read_b128 v[96:99], v1 offset:59968
	s_waitcnt lgkmcnt(1)
	v_mfma_f32_32x32x16_bf16 v[34:49], v[88:91], v[92:95], v[34:49]
	s_waitcnt lgkmcnt(0)
	v_mfma_f32_32x32x16_bf16 v[50:65], v[88:91], v[96:99], v[50:65]
	s_waitcnt vmcnt(7)
	ds_write_b128 v66, v[120:123] offset:46080
	s_waitcnt vmcnt(6)
	ds_write_b128 v66, v[116:119] offset:50688
	global_load_dwordx4 v[120:123], v[82:83], off offset:640
	global_load_dwordx4 v[116:119], v[84:85], off offset:640
	ds_read_b128 v[88:91], v70 offset:23104
	s_waitcnt lgkmcnt(0)
	v_mfma_f32_32x32x16_bf16 v[2:17], v[88:91], v[92:95], v[2:17]
	ds_read_b128 v[92:95], v1 offset:55392
	v_mfma_f32_32x32x16_bf16 v[18:33], v[88:91], v[96:99], v[18:33]
	ds_read_b128 v[88:91], v70 offset:18528
	ds_read_b128 v[96:99], v1 offset:60000
	s_waitcnt lgkmcnt(1)
	v_mfma_f32_32x32x16_bf16 v[34:49], v[88:91], v[92:95], v[34:49]
	s_waitcnt lgkmcnt(0)
	v_mfma_f32_32x32x16_bf16 v[50:65], v[88:91], v[96:99], v[50:65]
	v_mfma_f32_32x32x16_bf16 v[2:17], v[100:103], v[92:95], v[2:17]
	v_mfma_f32_32x32x16_bf16 v[18:33], v[100:103], v[96:99], v[18:33]
	s_setprio 0
	s_barrier
	ds_read_b128 v[96:99], v70
	ds_read_b128 v[100:103], v70 offset:4608
	ds_read_b128 v[128:131], v1 offset:36864
	ds_read_b128 v[132:135], v1 offset:41472
	s_setprio 1
	ds_read_b128 v[88:91], v70 offset:32
	s_waitcnt lgkmcnt(2)
	v_mfma_f32_32x32x16_bf16 v[34:49], v[96:99], v[128:131], v[34:49]
	s_waitcnt vmcnt(7)
	ds_write_b128 v66, v[140:143] offset:18432
	s_waitcnt vmcnt(6)
	ds_write_b128 v66, v[104:107] offset:23040
	global_load_dwordx4 v[140:143], v[74:75], off offset:768
	global_load_dwordx4 v[104:107], v[72:73], off offset:768
	ds_read_b128 v[92:95], v1 offset:36896
	s_waitcnt lgkmcnt(4)
	v_mfma_f32_32x32x16_bf16 v[50:65], v[96:99], v[132:135], v[50:65]
	ds_read_b128 v[96:99], v1 offset:41504
	s_waitcnt lgkmcnt(1)
	v_mfma_f32_32x32x16_bf16 v[34:49], v[88:91], v[92:95], v[34:49]
	s_waitcnt lgkmcnt(0)
	v_mfma_f32_32x32x16_bf16 v[50:65], v[88:91], v[96:99], v[50:65]
	s_waitcnt vmcnt(7)
	ds_write_b128 v66, v[108:111] offset:27648
	s_waitcnt vmcnt(6)
	ds_write_b128 v66, v[112:115] offset:32256
	global_load_dwordx4 v[108:111], v[76:77], off offset:768
	global_load_dwordx4 v[112:115], v[86:87], off offset:768
	ds_read_b128 v[88:91], v70 offset:4640
	v_mfma_f32_32x32x16_bf16 v[2:17], v[100:103], v[128:131], v[2:17]
	v_mfma_f32_32x32x16_bf16 v[18:33], v[100:103], v[132:135], v[18:33]
	ds_read_b128 v[100:103], v70 offset:4704
	s_waitcnt lgkmcnt(1)
	v_mfma_f32_32x32x16_bf16 v[2:17], v[88:91], v[92:95], v[2:17]
	s_waitcnt vmcnt(7)
	ds_write_b128 v66, v[144:147] offset:55296
	s_waitcnt vmcnt(6)
	ds_write_b128 v66, v[124:127] offset:59904
	global_load_dwordx4 v[144:147], v[78:79], off offset:768
	global_load_dwordx4 v[124:127], v[80:81], off offset:768
	ds_read_b128 v[92:95], v1 offset:36928
	v_mfma_f32_32x32x16_bf16 v[18:33], v[88:91], v[96:99], v[18:33]
	ds_read_b128 v[88:91], v70 offset:64
	ds_read_b128 v[96:99], v1 offset:41536
	s_waitcnt lgkmcnt(1)
	v_mfma_f32_32x32x16_bf16 v[34:49], v[88:91], v[92:95], v[34:49]
	s_waitcnt lgkmcnt(0)
	v_mfma_f32_32x32x16_bf16 v[50:65], v[88:91], v[96:99], v[50:65]
	s_waitcnt vmcnt(7)
	ds_write_b128 v66, v[120:123] offset:64512
	s_waitcnt vmcnt(6)
	ds_write_b128 v71, v[116:119] offset:32256
	global_load_dwordx4 v[120:123], v[82:83], off offset:768
	global_load_dwordx4 v[116:119], v[84:85], off offset:768
	ds_read_b128 v[88:91], v70 offset:4672
	s_waitcnt lgkmcnt(0)
	v_mfma_f32_32x32x16_bf16 v[2:17], v[88:91], v[92:95], v[2:17]
	ds_read_b128 v[92:95], v1 offset:36960
	v_mfma_f32_32x32x16_bf16 v[18:33], v[88:91], v[96:99], v[18:33]
	ds_read_b128 v[88:91], v70 offset:96
	ds_read_b128 v[96:99], v1 offset:41568
	s_waitcnt lgkmcnt(1)
	v_mfma_f32_32x32x16_bf16 v[34:49], v[88:91], v[92:95], v[34:49]
	s_waitcnt lgkmcnt(0)
	v_mfma_f32_32x32x16_bf16 v[50:65], v[88:91], v[96:99], v[50:65]
	v_mfma_f32_32x32x16_bf16 v[2:17], v[100:103], v[92:95], v[2:17]
	v_mfma_f32_32x32x16_bf16 v[18:33], v[100:103], v[96:99], v[18:33]
	s_setprio 0
	s_barrier
; #define MFMA(a, b, c) __builtin_amdgcn_mfma_f32_32x32x16_bf16((a), (b), (c), 0, 0, 0)
; template <int TM, int TN>
; DI void gemm_mainloop(const u16* __restrict__ A, long lda, const u16* __restrict__ Bt, long ldb, int K, char* smem,
;                       f32x16 (&acc)[TM][TN]) {
;     ...
;   for (int kt = 0; kt < nk; kt++) {
;     const int buf = kt & 1;
;     const u16* cA = sA + buf * BM * LD + (wm * 32 * TM + r) * LD + h * 8;
;     const u16* cB = sB + buf * BN * LD + (wn * 32 * TN + r) * LD + h * 8;
;     bf16x8 af[TM], bfr[TN];
; #pragma unroll
;     for (int tm = 0; tm < TM; tm++) af[tm] = *(const bf16x8*)(cA + tm * 32 * LD);
; #pragma unroll
;     for (int tn = 0; tn < TN; tn++) bfr[tn] = *(const bf16x8*)(cB + tn * 32 * LD);
;     if (kt + 1 < nk) GEMM_SSTORE(buf ^ 1)
;     __builtin_amdgcn_sched_barrier(0);
;     __builtin_amdgcn_s_setprio(1);
; #pragma unroll
;     for (int tm = 0; tm < TM; tm++)
; #pragma unroll
;       for (int tn = 0; tn < TN; tn++) acc[tm][tn] = MFMA(af[tm], bfr[tn], acc[tm][tn]);
; #pragma unroll
;     for (int tm = 0; tm < TM; tm++) af[tm] = *(const bf16x8*)(cA + tm * 32 * LD + 16);
; #pragma unroll
;     for (int tn = 0; tn < TN; tn++) bfr[tn] = *(const bf16x8*)(cB + tn * 32 * LD + 16);
; #pragma unroll
;     for (int tm = 0; tm < TM; tm++)
; #pragma unroll
;       for (int tn = 0; tn < TN; tn++) acc[tm][tn] = MFMA(af[tm], bfr[tn], acc[tm][tn]);
;     __builtin_amdgcn_sched_group_barrier(0x8, 4, 0);
;     if (kt + 2 < nk) GEMM_GLOAD((kt + 2) * 64)
; #pragma unroll
;     for (int ks = 2; ks < 4; ks++) {
; #pragma unroll
;       for (int tm = 0; tm < TM; tm++) af[tm] = *(const bf16x8*)(cA + tm * 32 * LD + ks * 16);
; #pragma unroll
;       for (int tn = 0; tn < TN; tn++) bfr[tn] = *(const bf16x8*)(cB + tn * 32 * LD + ks * 16);
; #pragma unroll
;       for (int tm = 0; tm < TM; tm++)
; #pragma unroll
;         for (int tn = 0; tn < TN; tn++) acc[tm][tn] = MFMA(af[tm], bfr[tn], acc[tm][tn]);
;     }
;     __builtin_amdgcn_s_setprio(0);
;     __syncthreads();
;   }
	ds_read_b128 v[96:99], v70 offset:18432
	ds_read_b128 v[100:103], v70 offset:23040
	ds_read_b128 v[128:131], v1 offset:55296
	ds_read_b128 v[132:135], v1 offset:59904
	s_setprio 1
	ds_read_b128 v[88:91], v70 offset:18464
	s_waitcnt lgkmcnt(2)
	v_mfma_f32_32x32x16_bf16 v[34:49], v[96:99], v[128:131], v[34:49]
	s_waitcnt vmcnt(7)
	ds_write_b128 v66, v[140:143]
	s_waitcnt vmcnt(6)
	ds_write_b128 v66, v[104:107] offset:4608
	global_load_dwordx4 v[140:143], v[74:75], off offset:896
	global_load_dwordx4 v[104:107], v[72:73], off offset:896
	ds_read_b128 v[92:95], v1 offset:55328
	s_waitcnt lgkmcnt(4)
	v_mfma_f32_32x32x16_bf16 v[50:65], v[96:99], v[132:135], v[50:65]
	ds_read_b128 v[96:99], v1 offset:59936
	s_waitcnt lgkmcnt(1)
	v_mfma_f32_32x32x16_bf16 v[34:49], v[88:91], v[92:95], v[34:49]
	s_waitcnt lgkmcnt(0)
	v_mfma_f32_32x32x16_bf16 v[50:65], v[88:91], v[96:99], v[50:65]
	s_waitcnt vmcnt(7)
	ds_write_b128 v66, v[108:111] offset:9216
	s_waitcnt vmcnt(6)
	ds_write_b128 v66, v[112:115] offset:13824
	global_load_dwordx4 v[108:111], v[76:77], off offset:896
	global_load_dwordx4 v[112:115], v[86:87], off offset:896
	ds_read_b128 v[88:91], v70 offset:23072
	v_mfma_f32_32x32x16_bf16 v[2:17], v[100:103], v[128:131], v[2:17]
	v_mfma_f32_32x32x16_bf16 v[18:33], v[100:103], v[132:135], v[18:33]
	ds_read_b128 v[100:103], v70 offset:23136
	s_waitcnt lgkmcnt(1)
	v_mfma_f32_32x32x16_bf16 v[2:17], v[88:91], v[92:95], v[2:17]
	s_waitcnt vmcnt(7)
	ds_write_b128 v66, v[144:147] offset:36864
	s_waitcnt vmcnt(6)
	ds_write_b128 v66, v[124:127] offset:41472
	global_load_dwordx4 v[144:147], v[78:79], off offset:896
	global_load_dwordx4 v[124:127], v[80:81], off offset:896
	ds_read_b128 v[92:95], v1 offset:55360
	v_mfma_f32_32x32x16_bf16 v[18:33], v[88:91], v[96:99], v[18:33]
	ds_read_b128 v[88:91], v70 offset:18496
	ds_read_b128 v[96:99], v1 offset:59968
	s_waitcnt lgkmcnt(1)
	v_mfma_f32_32x32x16_bf16 v[34:49], v[88:91], v[92:95], v[34:49]
	s_waitcnt lgkmcnt(0)
	v_mfma_f32_32x32x16_bf16 v[50:65], v[88:91], v[96:99], v[50:65]
	s_waitcnt vmcnt(7)
	ds_write_b128 v66, v[120:123] offset:46080
	s_waitcnt vmcnt(6)
	ds_write_b128 v66, v[116:119] offset:50688
	global_load_dwordx4 v[120:123], v[82:83], off offset:896
	global_load_dwordx4 v[116:119], v[84:85], off offset:896
	ds_read_b128 v[88:91], v70 offset:23104
	s_waitcnt lgkmcnt(0)
	v_mfma_f32_32x32x16_bf16 v[2:17], v[88:91], v[92:95], v[2:17]
	ds_read_b128 v[92:95], v1 offset:55392
	v_mfma_f32_32x32x16_bf16 v[18:33], v[88:91], v[96:99], v[18:33]
	ds_read_b128 v[88:91], v70 offset:18528
	ds_read_b128 v[96:99], v1 offset:60000
	s_waitcnt lgkmcnt(1)
	v_mfma_f32_32x32x16_bf16 v[34:49], v[88:91], v[92:95], v[34:49]
	s_waitcnt lgkmcnt(0)
	v_mfma_f32_32x32x16_bf16 v[50:65], v[88:91], v[96:99], v[50:65]
	v_mfma_f32_32x32x16_bf16 v[2:17], v[100:103], v[92:95], v[2:17]
	v_mfma_f32_32x32x16_bf16 v[18:33], v[100:103], v[96:99], v[18:33]
	s_setprio 0
	s_barrier
	ds_read_b128 v[96:99], v70
	ds_read_b128 v[100:103], v70 offset:4608
	ds_read_b128 v[128:131], v1 offset:36864
	ds_read_b128 v[132:135], v1 offset:41472
	s_setprio 1
	ds_read_b128 v[88:91], v70 offset:32
	s_waitcnt lgkmcnt(2)
	v_mfma_f32_32x32x16_bf16 v[34:49], v[96:99], v[128:131], v[34:49]
	s_waitcnt vmcnt(7)
	ds_write_b128 v66, v[140:143] offset:18432
	s_waitcnt vmcnt(6)
	ds_write_b128 v66, v[104:107] offset:23040
	global_load_dwordx4 v[140:143], v[74:75], off offset:1024
	global_load_dwordx4 v[104:107], v[72:73], off offset:1024
	ds_read_b128 v[92:95], v1 offset:36896
	s_waitcnt lgkmcnt(4)
	v_mfma_f32_32x32x16_bf16 v[50:65], v[96:99], v[132:135], v[50:65]
	ds_read_b128 v[96:99], v1 offset:41504
	s_waitcnt lgkmcnt(1)
	v_mfma_f32_32x32x16_bf16 v[34:49], v[88:91], v[92:95], v[34:49]
	s_waitcnt lgkmcnt(0)
	v_mfma_f32_32x32x16_bf16 v[50:65], v[88:91], v[96:99], v[50:65]
	s_waitcnt vmcnt(7)
	ds_write_b128 v66, v[108:111] offset:27648
	s_waitcnt vmcnt(6)
	ds_write_b128 v66, v[112:115] offset:32256
	global_load_dwordx4 v[108:111], v[76:77], off offset:1024
	global_load_dwordx4 v[112:115], v[86:87], off offset:1024
	ds_read_b128 v[88:91], v70 offset:4640
	v_mfma_f32_32x32x16_bf16 v[2:17], v[100:103], v[128:131], v[2:17]
	v_mfma_f32_32x32x16_bf16 v[18:33], v[100:103], v[132:135], v[18:33]
	ds_read_b128 v[100:103], v70 offset:4704
	s_waitcnt lgkmcnt(1)
	v_mfma_f32_32x32x16_bf16 v[2:17], v[88:91], v[92:95], v[2:17]
	s_waitcnt vmcnt(7)
	ds_write_b128 v66, v[144:147] offset:55296
	s_waitcnt vmcnt(6)
	ds_write_b128 v66, v[124:127] offset:59904
	global_load_dwordx4 v[144:147], v[78:79], off offset:1024
	global_load_dwordx4 v[124:127], v[80:81], off offset:1024
	ds_read_b128 v[92:95], v1 offset:36928
	v_mfma_f32_32x32x16_bf16 v[18:33], v[88:91], v[96:99], v[18:33]
	ds_read_b128 v[88:91], v70 offset:64
	ds_read_b128 v[96:99], v1 offset:41536
	s_waitcnt lgkmcnt(1)
	v_mfma_f32_32x32x16_bf16 v[34:49], v[88:91], v[92:95], v[34:49]
	s_waitcnt lgkmcnt(0)
	v_mfma_f32_32x32x16_bf16 v[50:65], v[88:91], v[96:99], v[50:65]
	s_waitcnt vmcnt(7)
	ds_write_b128 v66, v[120:123] offset:64512
	s_waitcnt vmcnt(6)
	ds_write_b128 v71, v[116:119] offset:32256
	global_load_dwordx4 v[120:123], v[82:83], off offset:1024
	global_load_dwordx4 v[116:119], v[84:85], off offset:1024
	ds_read_b128 v[88:91], v70 offset:4672
	s_waitcnt lgkmcnt(0)
	v_mfma_f32_32x32x16_bf16 v[2:17], v[88:91], v[92:95], v[2:17]
	ds_read_b128 v[92:95], v1 offset:36960
	v_mfma_f32_32x32x16_bf16 v[18:33], v[88:91], v[96:99], v[18:33]
	ds_read_b128 v[88:91], v70 offset:96
	ds_read_b128 v[96:99], v1 offset:41568
	s_waitcnt lgkmcnt(1)
	v_mfma_f32_32x32x16_bf16 v[34:49], v[88:91], v[92:95], v[34:49]
	s_waitcnt lgkmcnt(0)
	v_mfma_f32_32x32x16_bf16 v[50:65], v[88:91], v[96:99], v[50:65]
	v_mfma_f32_32x32x16_bf16 v[2:17], v[100:103], v[92:95], v[2:17]
	v_mfma_f32_32x32x16_bf16 v[18:33], v[100:103], v[96:99], v[18:33]
	s_setprio 0
	s_barrier
; #define MFMA(a, b, c) __builtin_amdgcn_mfma_f32_32x32x16_bf16((a), (b), (c), 0, 0, 0)
; template <int TM, int TN>
; DI void gemm_mainloop(const u16* __restrict__ A, long lda, const u16* __restrict__ Bt, long ldb, int K, char* smem,
;                       f32x16 (&acc)[TM][TN]) {
;     ...
;   for (int kt = 0; kt < nk; kt++) {
;     const int buf = kt & 1;
;     const u16* cA = sA + buf * BM * LD + (wm * 32 * TM + r) * LD + h * 8;
;     const u16* cB = sB + buf * BN * LD + (wn * 32 * TN + r) * LD + h * 8;
;     bf16x8 af[TM], bfr[TN];
; #pragma unroll
;     for (int tm = 0; tm < TM; tm++) af[tm] = *(const bf16x8*)(cA + tm * 32 * LD);
; #pragma unroll
;     for (int tn = 0; tn < TN; tn++) bfr[tn] = *(const bf16x8*)(cB + tn * 32 * LD);
;     if (kt + 1 < nk) GEMM_SSTORE(buf ^ 1)
;     __builtin_amdgcn_sched_barrier(0);
;     __builtin_amdgcn_s_setprio(1);
; #pragma unroll
;     for (int tm = 0; tm < TM; tm++)
; #pragma unroll
;       for (int tn = 0; tn < TN; tn++) acc[tm][tn] = MFMA(af[tm], bfr[tn], acc[tm][tn]);
; #pragma unroll
;     for (int tm = 0; tm < TM; tm++) af[tm] = *(const bf16x8*)(cA + tm * 32 * LD + 16);
; #pragma unroll
;     for (int tn = 0; tn < TN; tn++) bfr[tn] = *(const bf16x8*)(cB + tn * 32 * LD + 16);
; #pragma unroll
;     for (int tm = 0; tm < TM; tm++)
; #pragma unroll
;       for (int tn = 0; tn < TN; tn++) acc[tm][tn] = MFMA(af[tm], bfr[tn], acc[tm][tn]);
;     __builtin_amdgcn_sched_group_barrier(0x8, 4, 0);
;     if (kt + 2 < nk) GEMM_GLOAD((kt + 2) * 64)
; #pragma unroll
;     for (int ks = 2; ks < 4; ks++) {
; #pragma unroll
;       for (int tm = 0; tm < TM; tm++) af[tm] = *(const bf16x8*)(cA + tm * 32 * LD + ks * 16);
; #pragma unroll
;       for (int tn = 0; tn < TN; tn++) bfr[tn] = *(const bf16x8*)(cB + tn * 32 * LD + ks * 16);
; #pragma unroll
;       for (int tm = 0; tm < TM; tm++)
; #pragma unroll
;         for (int tn = 0; tn < TN; tn++) acc[tm][tn] = MFMA(af[tm], bfr[tn], acc[tm][tn]);
;     }
;     __builtin_amdgcn_s_setprio(0);
;     __syncthreads();
;   }
	ds_read_b128 v[96:99], v70 offset:18432
	ds_read_b128 v[100:103], v70 offset:23040
	ds_read_b128 v[128:131], v1 offset:55296
	ds_read_b128 v[132:135], v1 offset:59904
	s_setprio 1
	ds_read_b128 v[88:91], v70 offset:18464
	s_waitcnt lgkmcnt(2)
	v_mfma_f32_32x32x16_bf16 v[34:49], v[96:99], v[128:131], v[34:49]
	s_waitcnt vmcnt(7)
	ds_write_b128 v66, v[140:143]
	s_waitcnt vmcnt(6)
	ds_write_b128 v66, v[104:107] offset:4608
	global_load_dwordx4 v[140:143], v[74:75], off offset:1152
	global_load_dwordx4 v[104:107], v[72:73], off offset:1152
	ds_read_b128 v[92:95], v1 offset:55328
	s_waitcnt lgkmcnt(4)
	v_mfma_f32_32x32x16_bf16 v[50:65], v[96:99], v[132:135], v[50:65]
	ds_read_b128 v[96:99], v1 offset:59936
	s_waitcnt lgkmcnt(1)
	v_mfma_f32_32x32x16_bf16 v[34:49], v[88:91], v[92:95], v[34:49]
	s_waitcnt lgkmcnt(0)
	v_mfma_f32_32x32x16_bf16 v[50:65], v[88:91], v[96:99], v[50:65]
	s_waitcnt vmcnt(7)
	ds_write_b128 v66, v[108:111] offset:9216
	s_waitcnt vmcnt(6)
	ds_write_b128 v66, v[112:115] offset:13824
	global_load_dwordx4 v[108:111], v[76:77], off offset:1152
	global_load_dwordx4 v[112:115], v[86:87], off offset:1152
	ds_read_b128 v[88:91], v70 offset:23072
	v_mfma_f32_32x32x16_bf16 v[2:17], v[100:103], v[128:131], v[2:17]
	v_mfma_f32_32x32x16_bf16 v[18:33], v[100:103], v[132:135], v[18:33]
	ds_read_b128 v[100:103], v70 offset:23136
	s_waitcnt lgkmcnt(1)
	v_mfma_f32_32x32x16_bf16 v[2:17], v[88:91], v[92:95], v[2:17]
	s_waitcnt vmcnt(7)
	ds_write_b128 v66, v[144:147] offset:36864
	s_waitcnt vmcnt(6)
	ds_write_b128 v66, v[124:127] offset:41472
	global_load_dwordx4 v[144:147], v[78:79], off offset:1152
	global_load_dwordx4 v[124:127], v[80:81], off offset:1152
	ds_read_b128 v[92:95], v1 offset:55360
	v_mfma_f32_32x32x16_bf16 v[18:33], v[88:91], v[96:99], v[18:33]
	ds_read_b128 v[88:91], v70 offset:18496
	ds_read_b128 v[96:99], v1 offset:59968
	s_waitcnt lgkmcnt(1)
	v_mfma_f32_32x32x16_bf16 v[34:49], v[88:91], v[92:95], v[34:49]
	s_waitcnt lgkmcnt(0)
	v_mfma_f32_32x32x16_bf16 v[50:65], v[88:91], v[96:99], v[50:65]
	s_waitcnt vmcnt(7)
	ds_write_b128 v66, v[120:123] offset:46080
	s_waitcnt vmcnt(6)
	ds_write_b128 v66, v[116:119] offset:50688
	global_load_dwordx4 v[120:123], v[82:83], off offset:1152
	global_load_dwordx4 v[116:119], v[84:85], off offset:1152
	ds_read_b128 v[88:91], v70 offset:23104
	s_waitcnt lgkmcnt(0)
	v_mfma_f32_32x32x16_bf16 v[2:17], v[88:91], v[92:95], v[2:17]
	ds_read_b128 v[92:95], v1 offset:55392
	v_mfma_f32_32x32x16_bf16 v[18:33], v[88:91], v[96:99], v[18:33]
	ds_read_b128 v[88:91], v70 offset:18528
	ds_read_b128 v[96:99], v1 offset:60000
	s_waitcnt lgkmcnt(1)
	v_mfma_f32_32x32x16_bf16 v[34:49], v[88:91], v[92:95], v[34:49]
	s_waitcnt lgkmcnt(0)
	v_mfma_f32_32x32x16_bf16 v[50:65], v[88:91], v[96:99], v[50:65]
	v_mfma_f32_32x32x16_bf16 v[2:17], v[100:103], v[92:95], v[2:17]
	v_mfma_f32_32x32x16_bf16 v[18:33], v[100:103], v[96:99], v[18:33]
	s_setprio 0
	s_barrier
	ds_read_b128 v[96:99], v70
	ds_read_b128 v[100:103], v70 offset:4608
	ds_read_b128 v[128:131], v1 offset:36864
	ds_read_b128 v[132:135], v1 offset:41472
	s_setprio 1
	ds_read_b128 v[88:91], v70 offset:32
	s_waitcnt lgkmcnt(2)
	v_mfma_f32_32x32x16_bf16 v[34:49], v[96:99], v[128:131], v[34:49]
	s_waitcnt vmcnt(7)
	ds_write_b128 v66, v[140:143] offset:18432
	s_waitcnt vmcnt(6)
	ds_write_b128 v66, v[104:107] offset:23040
	global_load_dwordx4 v[140:143], v[74:75], off offset:1280
	global_load_dwordx4 v[104:107], v[72:73], off offset:1280
	ds_read_b128 v[92:95], v1 offset:36896
	s_waitcnt lgkmcnt(4)
	v_mfma_f32_32x32x16_bf16 v[50:65], v[96:99], v[132:135], v[50:65]
	ds_read_b128 v[96:99], v1 offset:41504
	s_waitcnt lgkmcnt(1)
	v_mfma_f32_32x32x16_bf16 v[34:49], v[88:91], v[92:95], v[34:49]
	s_waitcnt lgkmcnt(0)
	v_mfma_f32_32x32x16_bf16 v[50:65], v[88:91], v[96:99], v[50:65]
	s_waitcnt vmcnt(7)
	ds_write_b128 v66, v[108:111] offset:27648
	s_waitcnt vmcnt(6)
	ds_write_b128 v66, v[112:115] offset:32256
	global_load_dwordx4 v[108:111], v[76:77], off offset:1280
	global_load_dwordx4 v[112:115], v[86:87], off offset:1280
	ds_read_b128 v[88:91], v70 offset:4640
	v_mfma_f32_32x32x16_bf16 v[2:17], v[100:103], v[128:131], v[2:17]
	v_mfma_f32_32x32x16_bf16 v[18:33], v[100:103], v[132:135], v[18:33]
	ds_read_b128 v[100:103], v70 offset:4704
	s_waitcnt lgkmcnt(1)
	v_mfma_f32_32x32x16_bf16 v[2:17], v[88:91], v[92:95], v[2:17]
	s_waitcnt vmcnt(7)
	ds_write_b128 v66, v[144:147] offset:55296
	s_waitcnt vmcnt(6)
	ds_write_b128 v66, v[124:127] offset:59904
	global_load_dwordx4 v[144:147], v[78:79], off offset:1280
	global_load_dwordx4 v[124:127], v[80:81], off offset:1280
	ds_read_b128 v[92:95], v1 offset:36928
	v_mfma_f32_32x32x16_bf16 v[18:33], v[88:91], v[96:99], v[18:33]
	ds_read_b128 v[88:91], v70 offset:64
	ds_read_b128 v[96:99], v1 offset:41536
	s_waitcnt lgkmcnt(1)
	v_mfma_f32_32x32x16_bf16 v[34:49], v[88:91], v[92:95], v[34:49]
	s_waitcnt lgkmcnt(0)
	v_mfma_f32_32x32x16_bf16 v[50:65], v[88:91], v[96:99], v[50:65]
	s_waitcnt vmcnt(7)
	ds_write_b128 v66, v[120:123] offset:64512
	s_waitcnt vmcnt(6)
	ds_write_b128 v71, v[116:119] offset:32256
	global_load_dwordx4 v[120:123], v[82:83], off offset:1280
	global_load_dwordx4 v[116:119], v[84:85], off offset:1280
	ds_read_b128 v[88:91], v70 offset:4672
	s_waitcnt lgkmcnt(0)
	v_mfma_f32_32x32x16_bf16 v[2:17], v[88:91], v[92:95], v[2:17]
	ds_read_b128 v[92:95], v1 offset:36960
	v_mfma_f32_32x32x16_bf16 v[18:33], v[88:91], v[96:99], v[18:33]
	ds_read_b128 v[88:91], v70 offset:96
	ds_read_b128 v[96:99], v1 offset:41568
	s_waitcnt lgkmcnt(1)
	v_mfma_f32_32x32x16_bf16 v[34:49], v[88:91], v[92:95], v[34:49]
	s_waitcnt lgkmcnt(0)
	v_mfma_f32_32x32x16_bf16 v[50:65], v[88:91], v[96:99], v[50:65]
	v_mfma_f32_32x32x16_bf16 v[2:17], v[100:103], v[92:95], v[2:17]
	v_mfma_f32_32x32x16_bf16 v[18:33], v[100:103], v[96:99], v[18:33]
	s_setprio 0
	s_barrier
; #define MFMA(a, b, c) __builtin_amdgcn_mfma_f32_32x32x16_bf16((a), (b), (c), 0, 0, 0)
; template <int TM, int TN>
; DI void gemm_mainloop(const u16* __restrict__ A, long lda, const u16* __restrict__ Bt, long ldb, int K, char* smem,
;                       f32x16 (&acc)[TM][TN]) {
;     ...
;   for (int kt = 0; kt < nk; kt++) {
;     const int buf = kt & 1;
;     const u16* cA = sA + buf * BM * LD + (wm * 32 * TM + r) * LD + h * 8;
;     const u16* cB = sB + buf * BN * LD + (wn * 32 * TN + r) * LD + h * 8;
;     bf16x8 af[TM], bfr[TN];
; #pragma unroll
;     for (int tm = 0; tm < TM; tm++) af[tm] = *(const bf16x8*)(cA + tm * 32 * LD);
; #pragma unroll
;     for (int tn = 0; tn < TN; tn++) bfr[tn] = *(const bf16x8*)(cB + tn * 32 * LD);
;     if (kt + 1 < nk) GEMM_SSTORE(buf ^ 1)
;     __builtin_amdgcn_sched_barrier(0);
;     __builtin_amdgcn_s_setprio(1);
; #pragma unroll
;     for (int tm = 0; tm < TM; tm++)
; #pragma unroll
;       for (int tn = 0; tn < TN; tn++) acc[tm][tn] = MFMA(af[tm], bfr[tn], acc[tm][tn]);
; #pragma unroll
;     for (int tm = 0; tm < TM; tm++) af[tm] = *(const bf16x8*)(cA + tm * 32 * LD + 16);
; #pragma unroll
;     for (int tn = 0; tn < TN; tn++) bfr[tn] = *(const bf16x8*)(cB + tn * 32 * LD + 16);
; #pragma unroll
;     for (int tm = 0; tm < TM; tm++)
; #pragma unroll
;       for (int tn = 0; tn < TN; tn++) acc[tm][tn] = MFMA(af[tm], bfr[tn], acc[tm][tn]);
;     __builtin_amdgcn_sched_group_barrier(0x8, 4, 0);
;     if (kt + 2 < nk) GEMM_GLOAD((kt + 2) * 64)
; #pragma unroll
;     for (int ks = 2; ks < 4; ks++) {
; #pragma unroll
;       for (int tm = 0; tm < TM; tm++) af[tm] = *(const bf16x8*)(cA + tm * 32 * LD + ks * 16);
; #pragma unroll
;       for (int tn = 0; tn < TN; tn++) bfr[tn] = *(const bf16x8*)(cB + tn * 32 * LD + ks * 16);
; #pragma unroll
;       for (int tm = 0; tm < TM; tm++)
; #pragma unroll
;         for (int tn = 0; tn < TN; tn++) acc[tm][tn] = MFMA(af[tm], bfr[tn], acc[tm][tn]);
;     }
;     __builtin_amdgcn_s_setprio(0);
;     __syncthreads();
;   }
	ds_read_b128 v[96:99], v70 offset:18432
	ds_read_b128 v[100:103], v70 offset:23040
	ds_read_b128 v[128:131], v1 offset:55296
	ds_read_b128 v[132:135], v1 offset:59904
	s_setprio 1
	ds_read_b128 v[88:91], v70 offset:18464
	s_waitcnt lgkmcnt(2)
	v_mfma_f32_32x32x16_bf16 v[34:49], v[96:99], v[128:131], v[34:49]
	s_waitcnt vmcnt(7)
	ds_write_b128 v66, v[140:143]
	s_waitcnt vmcnt(6)
	ds_write_b128 v66, v[104:107] offset:4608
	global_load_dwordx4 v[140:143], v[74:75], off offset:1408
	global_load_dwordx4 v[104:107], v[72:73], off offset:1408
	ds_read_b128 v[92:95], v1 offset:55328
	s_waitcnt lgkmcnt(4)
	v_mfma_f32_32x32x16_bf16 v[50:65], v[96:99], v[132:135], v[50:65]
	ds_read_b128 v[96:99], v1 offset:59936
	s_waitcnt lgkmcnt(1)
	v_mfma_f32_32x32x16_bf16 v[34:49], v[88:91], v[92:95], v[34:49]
	s_waitcnt lgkmcnt(0)
	v_mfma_f32_32x32x16_bf16 v[50:65], v[88:91], v[96:99], v[50:65]
	s_waitcnt vmcnt(7)
	ds_write_b128 v66, v[108:111] offset:9216
	s_waitcnt vmcnt(6)
	ds_write_b128 v66, v[112:115] offset:13824
	global_load_dwordx4 v[108:111], v[76:77], off offset:1408
	global_load_dwordx4 v[112:115], v[86:87], off offset:1408
	ds_read_b128 v[88:91], v70 offset:23072
	v_mfma_f32_32x32x16_bf16 v[2:17], v[100:103], v[128:131], v[2:17]
	v_mfma_f32_32x32x16_bf16 v[18:33], v[100:103], v[132:135], v[18:33]
	ds_read_b128 v[100:103], v70 offset:23136
	s_waitcnt lgkmcnt(1)
	v_mfma_f32_32x32x16_bf16 v[2:17], v[88:91], v[92:95], v[2:17]
	s_waitcnt vmcnt(7)
	ds_write_b128 v66, v[144:147] offset:36864
	s_waitcnt vmcnt(6)
	ds_write_b128 v66, v[124:127] offset:41472
	global_load_dwordx4 v[144:147], v[78:79], off offset:1408
	global_load_dwordx4 v[124:127], v[80:81], off offset:1408
	ds_read_b128 v[92:95], v1 offset:55360
	v_mfma_f32_32x32x16_bf16 v[18:33], v[88:91], v[96:99], v[18:33]
	ds_read_b128 v[88:91], v70 offset:18496
	ds_read_b128 v[96:99], v1 offset:59968
	s_waitcnt lgkmcnt(1)
	v_mfma_f32_32x32x16_bf16 v[34:49], v[88:91], v[92:95], v[34:49]
	s_waitcnt lgkmcnt(0)
	v_mfma_f32_32x32x16_bf16 v[50:65], v[88:91], v[96:99], v[50:65]
	s_waitcnt vmcnt(7)
	ds_write_b128 v66, v[120:123] offset:46080
	s_waitcnt vmcnt(6)
	ds_write_b128 v66, v[116:119] offset:50688
	global_load_dwordx4 v[120:123], v[82:83], off offset:1408
	global_load_dwordx4 v[116:119], v[84:85], off offset:1408
	ds_read_b128 v[88:91], v70 offset:23104
	s_waitcnt lgkmcnt(0)
	v_mfma_f32_32x32x16_bf16 v[2:17], v[88:91], v[92:95], v[2:17]
	ds_read_b128 v[92:95], v1 offset:55392
	v_mfma_f32_32x32x16_bf16 v[18:33], v[88:91], v[96:99], v[18:33]
	ds_read_b128 v[88:91], v70 offset:18528
	ds_read_b128 v[96:99], v1 offset:60000
	s_waitcnt lgkmcnt(1)
	v_mfma_f32_32x32x16_bf16 v[34:49], v[88:91], v[92:95], v[34:49]
	s_waitcnt lgkmcnt(0)
	v_mfma_f32_32x32x16_bf16 v[50:65], v[88:91], v[96:99], v[50:65]
	v_mfma_f32_32x32x16_bf16 v[2:17], v[100:103], v[92:95], v[2:17]
	v_mfma_f32_32x32x16_bf16 v[18:33], v[100:103], v[96:99], v[18:33]
	s_setprio 0
	s_barrier
	ds_read_b128 v[96:99], v70
	ds_read_b128 v[100:103], v70 offset:4608
	ds_read_b128 v[128:131], v1 offset:36864
	ds_read_b128 v[132:135], v1 offset:41472
	s_setprio 1
	ds_read_b128 v[88:91], v70 offset:32
	s_waitcnt lgkmcnt(2)
	v_mfma_f32_32x32x16_bf16 v[34:49], v[96:99], v[128:131], v[34:49]
	s_waitcnt vmcnt(7)
	ds_write_b128 v66, v[140:143] offset:18432
	s_waitcnt vmcnt(6)
	ds_write_b128 v66, v[104:107] offset:23040
	global_load_dwordx4 v[140:143], v[74:75], off offset:1536
	global_load_dwordx4 v[104:107], v[72:73], off offset:1536
	ds_read_b128 v[92:95], v1 offset:36896
	s_waitcnt lgkmcnt(4)
	v_mfma_f32_32x32x16_bf16 v[50:65], v[96:99], v[132:135], v[50:65]
	ds_read_b128 v[96:99], v1 offset:41504
	s_waitcnt lgkmcnt(1)
	v_mfma_f32_32x32x16_bf16 v[34:49], v[88:91], v[92:95], v[34:49]
	s_waitcnt lgkmcnt(0)
	v_mfma_f32_32x32x16_bf16 v[50:65], v[88:91], v[96:99], v[50:65]
	s_waitcnt vmcnt(7)
	ds_write_b128 v66, v[108:111] offset:27648
	s_waitcnt vmcnt(6)
	ds_write_b128 v66, v[112:115] offset:32256
	global_load_dwordx4 v[108:111], v[76:77], off offset:1536
	global_load_dwordx4 v[112:115], v[86:87], off offset:1536
	ds_read_b128 v[88:91], v70 offset:4640
	v_mfma_f32_32x32x16_bf16 v[2:17], v[100:103], v[128:131], v[2:17]
	v_mfma_f32_32x32x16_bf16 v[18:33], v[100:103], v[132:135], v[18:33]
	ds_read_b128 v[100:103], v70 offset:4704
	s_waitcnt lgkmcnt(1)
	v_mfma_f32_32x32x16_bf16 v[2:17], v[88:91], v[92:95], v[2:17]
	s_waitcnt vmcnt(7)
	ds_write_b128 v66, v[144:147] offset:55296
	s_waitcnt vmcnt(6)
	ds_write_b128 v66, v[124:127] offset:59904
	global_load_dwordx4 v[144:147], v[78:79], off offset:1536
	global_load_dwordx4 v[124:127], v[80:81], off offset:1536
	ds_read_b128 v[92:95], v1 offset:36928
	v_mfma_f32_32x32x16_bf16 v[18:33], v[88:91], v[96:99], v[18:33]
	ds_read_b128 v[88:91], v70 offset:64
	ds_read_b128 v[96:99], v1 offset:41536
	s_waitcnt lgkmcnt(1)
	v_mfma_f32_32x32x16_bf16 v[34:49], v[88:91], v[92:95], v[34:49]
	s_waitcnt lgkmcnt(0)
	v_mfma_f32_32x32x16_bf16 v[50:65], v[88:91], v[96:99], v[50:65]
	s_waitcnt vmcnt(7)
	ds_write_b128 v66, v[120:123] offset:64512
	s_waitcnt vmcnt(6)
	ds_write_b128 v71, v[116:119] offset:32256
	global_load_dwordx4 v[120:123], v[82:83], off offset:1536
	global_load_dwordx4 v[116:119], v[84:85], off offset:1536
	ds_read_b128 v[88:91], v70 offset:4672
	s_waitcnt lgkmcnt(0)
	v_mfma_f32_32x32x16_bf16 v[2:17], v[88:91], v[92:95], v[2:17]
	ds_read_b128 v[92:95], v1 offset:36960
	v_mfma_f32_32x32x16_bf16 v[18:33], v[88:91], v[96:99], v[18:33]
	ds_read_b128 v[88:91], v70 offset:96
	ds_read_b128 v[96:99], v1 offset:41568
	s_waitcnt lgkmcnt(1)
	v_mfma_f32_32x32x16_bf16 v[34:49], v[88:91], v[92:95], v[34:49]
	s_waitcnt lgkmcnt(0)
	v_mfma_f32_32x32x16_bf16 v[50:65], v[88:91], v[96:99], v[50:65]
	v_mfma_f32_32x32x16_bf16 v[2:17], v[100:103], v[92:95], v[2:17]
	v_mfma_f32_32x32x16_bf16 v[18:33], v[100:103], v[96:99], v[18:33]
	s_setprio 0
	s_barrier
; #define MFMA(a, b, c) __builtin_amdgcn_mfma_f32_32x32x16_bf16((a), (b), (c), 0, 0, 0)
; template <int TM, int TN>
; DI void gemm_mainloop(const u16* __restrict__ A, long lda, const u16* __restrict__ Bt, long ldb, int K, char* smem,
;                       f32x16 (&acc)[TM][TN]) {
;     ...
;   for (int kt = 0; kt < nk; kt++) {
;     const int buf = kt & 1;
;     const u16* cA = sA + buf * BM * LD + (wm * 32 * TM + r) * LD + h * 8;
;     const u16* cB = sB + buf * BN * LD + (wn * 32 * TN + r) * LD + h * 8;
;     bf16x8 af[TM], bfr[TN];
; #pragma unroll
;     for (int tm = 0; tm < TM; tm++) af[tm] = *(const bf16x8*)(cA + tm * 32 * LD);
; #pragma unroll
;     for (int tn = 0; tn < TN; tn++) bfr[tn] = *(const bf16x8*)(cB + tn * 32 * LD);
;     if (kt + 1 < nk) GEMM_SSTORE(buf ^ 1)
;     __builtin_amdgcn_sched_barrier(0);
;     __builtin_amdgcn_s_setprio(1);
; #pragma unroll
;     for (int tm = 0; tm < TM; tm++)
; #pragma unroll
;       for (int tn = 0; tn < TN; tn++) acc[tm][tn] = MFMA(af[tm], bfr[tn], acc[tm][tn]);
; #pragma unroll
;     for (int tm = 0; tm < TM; tm++) af[tm] = *(const bf16x8*)(cA + tm * 32 * LD + 16);
; #pragma unroll
;     for (int tn = 0; tn < TN; tn++) bfr[tn] = *(const bf16x8*)(cB + tn * 32 * LD + 16);
; #pragma unroll
;     for (int tm = 0; tm < TM; tm++)
; #pragma unroll
;       for (int tn = 0; tn < TN; tn++) acc[tm][tn] = MFMA(af[tm], bfr[tn], acc[tm][tn]);
;     __builtin_amdgcn_sched_group_barrier(0x8, 4, 0);
;     if (kt + 2 < nk) GEMM_GLOAD((kt + 2) * 64)
; #pragma unroll
;     for (int ks = 2; ks < 4; ks++) {
; #pragma unroll
;       for (int tm = 0; tm < TM; tm++) af[tm] = *(const bf16x8*)(cA + tm * 32 * LD + ks * 16);
; #pragma unroll
;       for (int tn = 0; tn < TN; tn++) bfr[tn] = *(const bf16x8*)(cB + tn * 32 * LD + ks * 16);
; #pragma unroll
;       for (int tm = 0; tm < TM; tm++)
; #pragma unroll
;         for (int tn = 0; tn < TN; tn++) acc[tm][tn] = MFMA(af[tm], bfr[tn], acc[tm][tn]);
;     }
;     __builtin_amdgcn_s_setprio(0);
;     __syncthreads();
;   }
	ds_read_b128 v[96:99], v70 offset:18432
	ds_read_b128 v[100:103], v70 offset:23040
	ds_read_b128 v[128:131], v1 offset:55296
	ds_read_b128 v[132:135], v1 offset:59904
	s_setprio 1
	ds_read_b128 v[88:91], v70 offset:18464
	s_waitcnt lgkmcnt(2)
	v_mfma_f32_32x32x16_bf16 v[34:49], v[96:99], v[128:131], v[34:49]
	s_waitcnt vmcnt(7)
	ds_write_b128 v66, v[140:143]
	s_waitcnt vmcnt(6)
	ds_write_b128 v66, v[104:107] offset:4608
	global_load_dwordx4 v[140:143], v[74:75], off offset:1664
	global_load_dwordx4 v[104:107], v[72:73], off offset:1664
	ds_read_b128 v[92:95], v1 offset:55328
	s_waitcnt lgkmcnt(4)
	v_mfma_f32_32x32x16_bf16 v[50:65], v[96:99], v[132:135], v[50:65]
	ds_read_b128 v[96:99], v1 offset:59936
	s_waitcnt lgkmcnt(1)
	v_mfma_f32_32x32x16_bf16 v[34:49], v[88:91], v[92:95], v[34:49]
	s_waitcnt lgkmcnt(0)
	v_mfma_f32_32x32x16_bf16 v[50:65], v[88:91], v[96:99], v[50:65]
	s_waitcnt vmcnt(7)
	ds_write_b128 v66, v[108:111] offset:9216
	s_waitcnt vmcnt(6)
	ds_write_b128 v66, v[112:115] offset:13824
	global_load_dwordx4 v[108:111], v[76:77], off offset:1664
	global_load_dwordx4 v[112:115], v[86:87], off offset:1664
	ds_read_b128 v[88:91], v70 offset:23072
	v_mfma_f32_32x32x16_bf16 v[2:17], v[100:103], v[128:131], v[2:17]
	v_mfma_f32_32x32x16_bf16 v[18:33], v[100:103], v[132:135], v[18:33]
	ds_read_b128 v[100:103], v70 offset:23136
	s_waitcnt lgkmcnt(1)
	v_mfma_f32_32x32x16_bf16 v[2:17], v[88:91], v[92:95], v[2:17]
	s_waitcnt vmcnt(7)
	ds_write_b128 v66, v[144:147] offset:36864
	s_waitcnt vmcnt(6)
	ds_write_b128 v66, v[124:127] offset:41472
	global_load_dwordx4 v[144:147], v[78:79], off offset:1664
	global_load_dwordx4 v[124:127], v[80:81], off offset:1664
	ds_read_b128 v[92:95], v1 offset:55360
	v_mfma_f32_32x32x16_bf16 v[18:33], v[88:91], v[96:99], v[18:33]
	ds_read_b128 v[88:91], v70 offset:18496
	ds_read_b128 v[96:99], v1 offset:59968
	s_waitcnt lgkmcnt(1)
	v_mfma_f32_32x32x16_bf16 v[34:49], v[88:91], v[92:95], v[34:49]
	s_waitcnt lgkmcnt(0)
	v_mfma_f32_32x32x16_bf16 v[50:65], v[88:91], v[96:99], v[50:65]
	s_waitcnt vmcnt(7)
	ds_write_b128 v66, v[120:123] offset:46080
	s_waitcnt vmcnt(6)
	ds_write_b128 v66, v[116:119] offset:50688
	global_load_dwordx4 v[120:123], v[82:83], off offset:1664
	global_load_dwordx4 v[116:119], v[84:85], off offset:1664
	ds_read_b128 v[88:91], v70 offset:23104
	s_waitcnt lgkmcnt(0)
	v_mfma_f32_32x32x16_bf16 v[2:17], v[88:91], v[92:95], v[2:17]
	ds_read_b128 v[92:95], v1 offset:55392
	v_mfma_f32_32x32x16_bf16 v[18:33], v[88:91], v[96:99], v[18:33]
	ds_read_b128 v[88:91], v70 offset:18528
	ds_read_b128 v[96:99], v1 offset:60000
	s_waitcnt lgkmcnt(1)
	v_mfma_f32_32x32x16_bf16 v[34:49], v[88:91], v[92:95], v[34:49]
	s_waitcnt lgkmcnt(0)
	v_mfma_f32_32x32x16_bf16 v[50:65], v[88:91], v[96:99], v[50:65]
	v_mfma_f32_32x32x16_bf16 v[2:17], v[100:103], v[92:95], v[2:17]
	v_mfma_f32_32x32x16_bf16 v[18:33], v[100:103], v[96:99], v[18:33]
	s_setprio 0
	s_barrier
	ds_read_b128 v[96:99], v70
	ds_read_b128 v[100:103], v70 offset:4608
	ds_read_b128 v[128:131], v1 offset:36864
	ds_read_b128 v[132:135], v1 offset:41472
	s_setprio 1
	ds_read_b128 v[88:91], v70 offset:32
	s_waitcnt lgkmcnt(2)
	v_mfma_f32_32x32x16_bf16 v[34:49], v[96:99], v[128:131], v[34:49]
	s_waitcnt vmcnt(7)
	ds_write_b128 v66, v[140:143] offset:18432
	s_waitcnt vmcnt(6)
	ds_write_b128 v66, v[104:107] offset:23040
	global_load_dwordx4 v[140:143], v[74:75], off offset:1792
	global_load_dwordx4 v[104:107], v[72:73], off offset:1792
	ds_read_b128 v[92:95], v1 offset:36896
	s_waitcnt lgkmcnt(4)
	v_mfma_f32_32x32x16_bf16 v[50:65], v[96:99], v[132:135], v[50:65]
	ds_read_b128 v[96:99], v1 offset:41504
	s_waitcnt lgkmcnt(1)
	v_mfma_f32_32x32x16_bf16 v[34:49], v[88:91], v[92:95], v[34:49]
	s_waitcnt lgkmcnt(0)
	v_mfma_f32_32x32x16_bf16 v[50:65], v[88:91], v[96:99], v[50:65]
	s_waitcnt vmcnt(7)
	ds_write_b128 v66, v[108:111] offset:27648
	s_waitcnt vmcnt(6)
	ds_write_b128 v66, v[112:115] offset:32256
	global_load_dwordx4 v[108:111], v[76:77], off offset:1792
	global_load_dwordx4 v[112:115], v[86:87], off offset:1792
	ds_read_b128 v[88:91], v70 offset:4640
	v_mfma_f32_32x32x16_bf16 v[2:17], v[100:103], v[128:131], v[2:17]
	v_mfma_f32_32x32x16_bf16 v[18:33], v[100:103], v[132:135], v[18:33]
	ds_read_b128 v[100:103], v70 offset:4704
	s_waitcnt lgkmcnt(1)
	v_mfma_f32_32x32x16_bf16 v[2:17], v[88:91], v[92:95], v[2:17]
	s_waitcnt vmcnt(7)
	ds_write_b128 v66, v[144:147] offset:55296
	s_waitcnt vmcnt(6)
	ds_write_b128 v66, v[124:127] offset:59904
	global_load_dwordx4 v[144:147], v[78:79], off offset:1792
	global_load_dwordx4 v[124:127], v[80:81], off offset:1792
	ds_read_b128 v[92:95], v1 offset:36928
	v_mfma_f32_32x32x16_bf16 v[18:33], v[88:91], v[96:99], v[18:33]
	ds_read_b128 v[88:91], v70 offset:64
	ds_read_b128 v[96:99], v1 offset:41536
	s_waitcnt lgkmcnt(1)
	v_mfma_f32_32x32x16_bf16 v[34:49], v[88:91], v[92:95], v[34:49]
	s_waitcnt lgkmcnt(0)
	v_mfma_f32_32x32x16_bf16 v[50:65], v[88:91], v[96:99], v[50:65]
	s_waitcnt vmcnt(7)
	ds_write_b128 v66, v[120:123] offset:64512
	s_waitcnt vmcnt(6)
	ds_write_b128 v71, v[116:119] offset:32256
	global_load_dwordx4 v[120:123], v[82:83], off offset:1792
	global_load_dwordx4 v[116:119], v[84:85], off offset:1792
	ds_read_b128 v[88:91], v70 offset:4672
	s_waitcnt lgkmcnt(0)
	v_mfma_f32_32x32x16_bf16 v[2:17], v[88:91], v[92:95], v[2:17]
	ds_read_b128 v[92:95], v1 offset:36960
	v_mfma_f32_32x32x16_bf16 v[18:33], v[88:91], v[96:99], v[18:33]
	ds_read_b128 v[88:91], v70 offset:96
	ds_read_b128 v[96:99], v1 offset:41568
	s_waitcnt lgkmcnt(1)
	v_mfma_f32_32x32x16_bf16 v[34:49], v[88:91], v[92:95], v[34:49]
	s_waitcnt lgkmcnt(0)
	v_mfma_f32_32x32x16_bf16 v[50:65], v[88:91], v[96:99], v[50:65]
	v_mfma_f32_32x32x16_bf16 v[2:17], v[100:103], v[92:95], v[2:17]
	v_mfma_f32_32x32x16_bf16 v[18:33], v[100:103], v[96:99], v[18:33]
	s_setprio 0
	s_barrier
; #define MFMA(a, b, c) __builtin_amdgcn_mfma_f32_32x32x16_bf16((a), (b), (c), 0, 0, 0)
; template <int TM, int TN>
; DI void gemm_mainloop(const u16* __restrict__ A, long lda, const u16* __restrict__ Bt, long ldb, int K, char* smem,
;                       f32x16 (&acc)[TM][TN]) {
;     ...
;   for (int kt = 0; kt < nk; kt++) {
;     const int buf = kt & 1;
;     const u16* cA = sA + buf * BM * LD + (wm * 32 * TM + r) * LD + h * 8;
;     const u16* cB = sB + buf * BN * LD + (wn * 32 * TN + r) * LD + h * 8;
;     bf16x8 af[TM], bfr[TN];
; #pragma unroll
;     for (int tm = 0; tm < TM; tm++) af[tm] = *(const bf16x8*)(cA + tm * 32 * LD);
; #pragma unroll
;     for (int tn = 0; tn < TN; tn++) bfr[tn] = *(const bf16x8*)(cB + tn * 32 * LD);
;     if (kt + 1 < nk) GEMM_SSTORE(buf ^ 1)
;     __builtin_amdgcn_sched_barrier(0);
;     __builtin_amdgcn_s_setprio(1);
; #pragma unroll
;     for (int tm = 0; tm < TM; tm++)
; #pragma unroll
;       for (int tn = 0; tn < TN; tn++) acc[tm][tn] = MFMA(af[tm], bfr[tn], acc[tm][tn]);
; #pragma unroll
;     for (int tm = 0; tm < TM; tm++) af[tm] = *(const bf16x8*)(cA + tm * 32 * LD + 16);
; #pragma unroll
;     for (int tn = 0; tn < TN; tn++) bfr[tn] = *(const bf16x8*)(cB + tn * 32 * LD + 16);
; #pragma unroll
;     for (int tm = 0; tm < TM; tm++)
; #pragma unroll
;       for (int tn = 0; tn < TN; tn++) acc[tm][tn] = MFMA(af[tm], bfr[tn], acc[tm][tn]);
;     __builtin_amdgcn_sched_group_barrier(0x8, 4, 0);
;     if (kt + 2 < nk) GEMM_GLOAD((kt + 2) * 64)
; #pragma unroll
;     for (int ks = 2; ks < 4; ks++) {
; #pragma unroll
;       for (int tm = 0; tm < TM; tm++) af[tm] = *(const bf16x8*)(cA + tm * 32 * LD + ks * 16);
; #pragma unroll
;       for (int tn = 0; tn < TN; tn++) bfr[tn] = *(const bf16x8*)(cB + tn * 32 * LD + ks * 16);
; #pragma unroll
;       for (int tm = 0; tm < TM; tm++)
; #pragma unroll
;         for (int tn = 0; tn < TN; tn++) acc[tm][tn] = MFMA(af[tm], bfr[tn], acc[tm][tn]);
;     }
;     __builtin_amdgcn_s_setprio(0);
;     __syncthreads();
;   }
	ds_read_b128 v[96:99], v70 offset:18432
	ds_read_b128 v[100:103], v70 offset:23040
	ds_read_b128 v[128:131], v1 offset:55296
	ds_read_b128 v[132:135], v1 offset:59904
	s_setprio 1
	ds_read_b128 v[88:91], v70 offset:18464
	s_waitcnt lgkmcnt(2)
	v_mfma_f32_32x32x16_bf16 v[34:49], v[96:99], v[128:131], v[34:49]
	s_waitcnt vmcnt(7)
	ds_write_b128 v66, v[140:143]
	s_waitcnt vmcnt(6)
	ds_write_b128 v66, v[104:107] offset:4608
	global_load_dwordx4 v[140:143], v[74:75], off offset:1920
	global_load_dwordx4 v[104:107], v[72:73], off offset:1920
	ds_read_b128 v[92:95], v1 offset:55328
	s_waitcnt lgkmcnt(4)
	v_mfma_f32_32x32x16_bf16 v[50:65], v[96:99], v[132:135], v[50:65]
	ds_read_b128 v[96:99], v1 offset:59936
	s_waitcnt lgkmcnt(1)
	v_mfma_f32_32x32x16_bf16 v[34:49], v[88:91], v[92:95], v[34:49]
	s_waitcnt lgkmcnt(0)
	v_mfma_f32_32x32x16_bf16 v[50:65], v[88:91], v[96:99], v[50:65]
	s_waitcnt vmcnt(7)
	ds_write_b128 v66, v[108:111] offset:9216
	s_waitcnt vmcnt(6)
	ds_write_b128 v66, v[112:115] offset:13824
	global_load_dwordx4 v[108:111], v[76:77], off offset:1920
	global_load_dwordx4 v[112:115], v[86:87], off offset:1920
	ds_read_b128 v[88:91], v70 offset:23072
	v_mfma_f32_32x32x16_bf16 v[2:17], v[100:103], v[128:131], v[2:17]
	v_mfma_f32_32x32x16_bf16 v[18:33], v[100:103], v[132:135], v[18:33]
	ds_read_b128 v[100:103], v70 offset:23136
	s_waitcnt lgkmcnt(1)
	v_mfma_f32_32x32x16_bf16 v[2:17], v[88:91], v[92:95], v[2:17]
	s_waitcnt vmcnt(7)
	ds_write_b128 v66, v[144:147] offset:36864
	s_waitcnt vmcnt(6)
	ds_write_b128 v66, v[124:127] offset:41472
	global_load_dwordx4 v[144:147], v[78:79], off offset:1920
	global_load_dwordx4 v[124:127], v[80:81], off offset:1920
	ds_read_b128 v[92:95], v1 offset:55360
	v_mfma_f32_32x32x16_bf16 v[18:33], v[88:91], v[96:99], v[18:33]
	ds_read_b128 v[88:91], v70 offset:18496
	ds_read_b128 v[96:99], v1 offset:59968
	s_waitcnt lgkmcnt(1)
	v_mfma_f32_32x32x16_bf16 v[34:49], v[88:91], v[92:95], v[34:49]
	s_waitcnt lgkmcnt(0)
	v_mfma_f32_32x32x16_bf16 v[50:65], v[88:91], v[96:99], v[50:65]
	s_waitcnt vmcnt(7)
	ds_write_b128 v66, v[120:123] offset:46080
	s_waitcnt vmcnt(6)
	ds_write_b128 v66, v[116:119] offset:50688
	global_load_dwordx4 v[120:123], v[82:83], off offset:1920
	global_load_dwordx4 v[116:119], v[84:85], off offset:1920
	ds_read_b128 v[88:91], v70 offset:23104
	s_waitcnt lgkmcnt(0)
	v_mfma_f32_32x32x16_bf16 v[2:17], v[88:91], v[92:95], v[2:17]
	ds_read_b128 v[92:95], v1 offset:55392
	v_mfma_f32_32x32x16_bf16 v[18:33], v[88:91], v[96:99], v[18:33]
	ds_read_b128 v[88:91], v70 offset:18528
	ds_read_b128 v[96:99], v1 offset:60000
	s_waitcnt lgkmcnt(1)
	v_mfma_f32_32x32x16_bf16 v[34:49], v[88:91], v[92:95], v[34:49]
	s_waitcnt lgkmcnt(0)
	v_mfma_f32_32x32x16_bf16 v[50:65], v[88:91], v[96:99], v[50:65]
	s_nop 0
	v_mfma_f32_32x32x16_bf16 v[2:17], v[100:103], v[92:95], v[2:17]
	v_mfma_f32_32x32x16_bf16 v[18:33], v[100:103], v[96:99], v[18:33]
	s_setprio 0
	s_barrier
	ds_read_b128 v[76:79], v70
	ds_read_b128 v[80:83], v70 offset:4608
	ds_read_b128 v[84:87], v1 offset:36864
	ds_read_b128 v[92:95], v1 offset:41472
	s_setprio 1
	ds_read_b128 v[72:75], v70 offset:32
	s_waitcnt lgkmcnt(2)
	v_mfma_f32_32x32x16_bf16 v[34:49], v[76:79], v[84:87], v[34:49]
	s_waitcnt vmcnt(7)
	ds_write_b128 v66, v[140:143] offset:18432
	s_waitcnt vmcnt(6)
	ds_write_b128 v66, v[104:107] offset:23040
	s_waitcnt lgkmcnt(3)
	v_mfma_f32_32x32x16_bf16 v[50:65], v[76:79], v[92:95], v[50:65]
	ds_read_b128 v[76:79], v1 offset:36896
	v_mfma_f32_32x32x16_bf16 v[2:17], v[80:83], v[84:87], v[2:17]
	v_mfma_f32_32x32x16_bf16 v[18:33], v[80:83], v[92:95], v[18:33]
	s_waitcnt vmcnt(5)
	ds_write_b128 v66, v[108:111] offset:27648
	s_waitcnt vmcnt(4)
	ds_write_b128 v66, v[112:115] offset:32256
	ds_read_b128 v[80:83], v1 offset:41504
	s_waitcnt lgkmcnt(3)
	v_mfma_f32_32x32x16_bf16 v[34:49], v[72:75], v[76:79], v[34:49]
	s_waitcnt lgkmcnt(0)
	v_mfma_f32_32x32x16_bf16 v[50:65], v[72:75], v[80:83], v[50:65]
	ds_read_b128 v[72:75], v70 offset:4640
	s_waitcnt lgkmcnt(0)
	v_mfma_f32_32x32x16_bf16 v[2:17], v[72:75], v[76:79], v[2:17]
	s_waitcnt vmcnt(3)
	ds_write_b128 v66, v[144:147] offset:55296
	s_waitcnt vmcnt(2)
	ds_write_b128 v66, v[124:127] offset:59904
	ds_read_b128 v[76:79], v1 offset:36928
	v_mfma_f32_32x32x16_bf16 v[18:33], v[72:75], v[80:83], v[18:33]
	ds_read_b128 v[72:75], v70 offset:64
	ds_read_b128 v[80:83], v1 offset:41536
	s_waitcnt lgkmcnt(1)
	v_mfma_f32_32x32x16_bf16 v[34:49], v[72:75], v[76:79], v[34:49]
	s_waitcnt lgkmcnt(0)
	v_mfma_f32_32x32x16_bf16 v[50:65], v[72:75], v[80:83], v[50:65]
	s_waitcnt vmcnt(1)
	ds_write_b128 v66, v[120:123] offset:64512
	s_waitcnt vmcnt(0)
	ds_write_b128 v71, v[116:119] offset:32256
	ds_read_b128 v[72:75], v70 offset:4672
	s_waitcnt lgkmcnt(0)
	v_mfma_f32_32x32x16_bf16 v[2:17], v[72:75], v[76:79], v[2:17]
	ds_read_b128 v[76:79], v1 offset:36960
	v_mfma_f32_32x32x16_bf16 v[18:33], v[72:75], v[80:83], v[18:33]
	ds_read_b128 v[72:75], v70 offset:96
	ds_read_b128 v[80:83], v1 offset:41568
	s_waitcnt lgkmcnt(1)
	v_mfma_f32_32x32x16_bf16 v[34:49], v[72:75], v[76:79], v[34:49]
	s_waitcnt lgkmcnt(0)
	v_mfma_f32_32x32x16_bf16 v[50:65], v[72:75], v[80:83], v[50:65]
	ds_read_b128 v[72:75], v70 offset:4704
	s_waitcnt lgkmcnt(0)
	v_mfma_f32_32x32x16_bf16 v[2:17], v[72:75], v[76:79], v[2:17]
	v_mfma_f32_32x32x16_bf16 v[18:33], v[72:75], v[80:83], v[18:33]
	s_setprio 0
	s_barrier
; #define MFMA(a, b, c) __builtin_amdgcn_mfma_f32_32x32x16_bf16((a), (b), (c), 0, 0, 0)
; DI int crow(int i, int h) { return (i & 3) + 8 * (i >> 2) + 4 * h; }
; template <int TM, int TN>
; DI void gemm_mainloop(const u16* __restrict__ A, long lda, const u16* __restrict__ Bt, long ldb, int K, char* smem,
;                       f32x16 (&acc)[TM][TN]) {
;     ...
;     for (int ks = 2; ks < 4; ks++) {
; #pragma unroll
;       for (int tm = 0; tm < TM; tm++) af[tm] = *(const bf16x8*)(cA + tm * 32 * LD + ks * 16);
; #pragma unroll
;       for (int tn = 0; tn < TN; tn++) bfr[tn] = *(const bf16x8*)(cB + tn * 32 * LD + ks * 16);
; #pragma unroll
;       for (int tm = 0; tm < TM; tm++)
; #pragma unroll
;         for (int tn = 0; tn < TN; tn++) acc[tm][tn] = MFMA(af[tm], bfr[tn], acc[tm][tn]);
;     }
;     __builtin_amdgcn_s_setprio(0);
;     __syncthreads();
;   }
; template <int TM, int TN, class Epi>
; DI void gemm_tile(const u16* A, long lda, const u16* Bt, long ldb, int K, int m0, int n0, char* smem, const Epi& epi) {
;     ...
; #pragma unroll
;   for (int tm = 0; tm < TM; tm++)
; #pragma unroll
;     for (int tn = 0; tn < TN; tn++)
; #pragma unroll
;       for (int i = 0; i < 16; i++)
;         Ct[(wm * 32 * TM + tm * 32 + crow(i, h)) * LDC + wn * 32 * TN + tn * 32 + r] = acc[tm][tn][i];
;   __syncthreads();
;   epi(Ct, LDC, m0, n0, tid, BM);
;   __syncthreads();
;   (void)BM;
; }
;   DI void operator()(const float* Ct, int ldc, int m0, int n0, int tid, int bm) const {
; #pragma unroll 4
;     for (int it = 0; it < bm / 16; it++) {
;       int id = tid + 256 * it; int row = id >> 4, c8 = (id & 15) * 8;
;       int n = n0 + c8;
;       if (n < nmax) {
	ds_read_b128 v[72:75], v70 offset:18432
	ds_read_b128 v[76:79], v70 offset:23040
	ds_read_b128 v[80:83], v1 offset:55296
	ds_read_b128 v[84:87], v1 offset:59904
	s_setprio 1
	s_waitcnt lgkmcnt(1)
	v_mfma_f32_32x32x16_bf16 v[34:49], v[72:75], v[80:83], v[34:49]
	s_waitcnt lgkmcnt(0)
	v_mfma_f32_32x32x16_bf16 v[50:65], v[72:75], v[84:87], v[50:65]
	ds_read_b128 v[72:75], v70 offset:18464
	v_mfma_f32_32x32x16_bf16 v[2:17], v[76:79], v[80:83], v[2:17]
	ds_read_b128 v[80:83], v1 offset:59936
	v_mfma_f32_32x32x16_bf16 v[18:33], v[76:79], v[84:87], v[18:33]
	ds_read_b128 v[76:79], v1 offset:55328
	s_waitcnt lgkmcnt(0)
	v_mfma_f32_32x32x16_bf16 v[34:49], v[72:75], v[76:79], v[34:49]
	v_mfma_f32_32x32x16_bf16 v[50:65], v[72:75], v[80:83], v[50:65]
	ds_read_b128 v[72:75], v70 offset:23072
	s_waitcnt lgkmcnt(0)
	v_mfma_f32_32x32x16_bf16 v[2:17], v[72:75], v[76:79], v[2:17]
	ds_read_b128 v[76:79], v1 offset:55360
	v_mfma_f32_32x32x16_bf16 v[18:33], v[72:75], v[80:83], v[18:33]
	ds_read_b128 v[72:75], v70 offset:18496
	ds_read_b128 v[80:83], v1 offset:59968
	s_waitcnt lgkmcnt(1)
	v_mfma_f32_32x32x16_bf16 v[34:49], v[72:75], v[76:79], v[34:49]
	s_waitcnt lgkmcnt(0)
	v_mfma_f32_32x32x16_bf16 v[50:65], v[72:75], v[80:83], v[50:65]
	ds_read_b128 v[72:75], v70 offset:23104
	s_waitcnt lgkmcnt(0)
	v_mfma_f32_32x32x16_bf16 v[2:17], v[72:75], v[76:79], v[2:17]
	ds_read_b128 v[76:79], v1 offset:55392
	v_mfma_f32_32x32x16_bf16 v[18:33], v[72:75], v[80:83], v[18:33]
	ds_read_b128 v[72:75], v70 offset:18528
	ds_read_b128 v[80:83], v1 offset:60000
	s_waitcnt lgkmcnt(1)
	v_mfma_f32_32x32x16_bf16 v[34:49], v[72:75], v[76:79], v[34:49]
	s_waitcnt lgkmcnt(0)
	v_mfma_f32_32x32x16_bf16 v[50:65], v[72:75], v[80:83], v[50:65]
	ds_read_b128 v[70:73], v70 offset:23136
	s_waitcnt lgkmcnt(0)
	v_mfma_f32_32x32x16_bf16 v[2:17], v[70:73], v[76:79], v[2:17]
	v_mfma_f32_32x32x16_bf16 v[18:33], v[70:73], v[80:83], v[18:33]
	s_setprio 0
	v_mov_b32_e32 v1, v0
	s_barrier
	s_mov_b32 s4, 0
	v_lshrrev_b32_e32 v66, 1, v1
	v_and_b32_e32 v66, 0xfffffc0, v66
	v_lshrrev_b32_e32 v70, 3, v1
	v_and_or_b32 v66, v70, 4, v66
	v_and_b32_e32 v70, 0x5f, v1
	v_mul_lo_u32 v66, v66, s24
	v_lshl_add_u32 v66, v70, 2, v66
	ds_write2_b32 v66, v34, v50 offset1:32
	v_add_u32_e32 v34, 0x400, v66
	ds_write2_b32 v34, v36, v52 offset0:8 offset1:40
	ds_write2_b32 v34, v37, v53 offset0:140 offset1:172
	v_add_u32_e32 v34, 0x1000, v66
	ds_write2_b32 v34, v38, v54 offset0:32 offset1:64
	ds_write2_b32 v34, v39, v55 offset0:164 offset1:196
	v_add_u32_e32 v34, 0x1400, v66
	ds_write2_b32 v34, v40, v56 offset0:40 offset1:72
	ds_write2_b32 v34, v41, v57 offset0:172 offset1:204
	v_add_u32_e32 v34, 0x2000, v66
	ds_write2_b32 v34, v42, v58 offset0:64 offset1:96
	ds_write2_b32 v34, v43, v59 offset0:196 offset1:228
	v_add_u32_e32 v34, 0x2400, v66
	ds_write2_b32 v34, v44, v60 offset0:72 offset1:104
	ds_write2_b32 v34, v45, v61 offset0:204 offset1:236
	v_add_u32_e32 v34, 0x3000, v66
	ds_write2_b32 v34, v46, v62 offset0:96 offset1:128
	v_add_u32_e32 v34, 0x3200, v66
	ds_write2_b32 v34, v47, v63 offset0:100 offset1:132
	v_add_u32_e32 v34, 0x3400, v66
	ds_write2_b32 v34, v48, v64 offset0:104 offset1:136
	v_add_u32_e32 v34, 0x3600, v66
	ds_write2_b32 v34, v49, v65 offset0:108 offset1:140
	v_add_u32_e32 v34, 0x4000, v66
	ds_write2_b32 v34, v2, v18 offset0:128 offset1:160
	v_add_u32_e32 v2, 0x4400, v66
	ds_write2_b32 v2, v3, v19 offset0:4 offset1:36
	ds_write2_b32 v2, v4, v20 offset0:136 offset1:168
	v_add_u32_e32 v2, 0x4800, v66
	ds_write2_b32 v2, v5, v21 offset0:12 offset1:44
	v_add_u32_e32 v2, 0x5000, v66
	ds_write2_b32 v2, v6, v22 offset0:160 offset1:192
	v_add_u32_e32 v2, 0x5400, v66
	ds_write2_b32 v2, v7, v23 offset0:36 offset1:68
	ds_write2_b32 v2, v8, v24 offset0:168 offset1:200
	v_add_u32_e32 v2, 0x5800, v66
	ds_write2_b32 v2, v9, v25 offset0:44 offset1:76
	v_add_u32_e32 v2, 0x6000, v66
	ds_write2_b32 v2, v10, v26 offset0:192 offset1:224
	v_add_u32_e32 v2, 0x6400, v66
	ds_write2_b32 v2, v11, v27 offset0:68 offset1:100
	ds_write2_b32 v2, v12, v28 offset0:200 offset1:232
	v_add_u32_e32 v2, 0x6800, v66
	ds_write2_b32 v2, v13, v29 offset0:76 offset1:108
	v_add_u32_e32 v2, 0x7200, v66
	ds_write2_b32 v2, v14, v30 offset0:96 offset1:128
	v_add_u32_e32 v2, 0x7400, v66
	ds_write2_b32 v2, v15, v31 offset0:100 offset1:132
	v_add_u32_e32 v2, 0x7600, v66
	ds_write2_b32 v2, v16, v32 offset0:104 offset1:136
	v_add_u32_e32 v2, 0x7800, v66
	ds_write2_b32 v2, v17, v33 offset0:108 offset1:140
	v_lshlrev_b32_e32 v2, 3, v1
	v_and_b32_e32 v2, 0x78, v2
	v_or_b32_e32 v4, s15, v2
	v_ashrrev_i32_e32 v5, 31, v4
	v_lshlrev_b32_e32 v2, 2, v2
	v_cmp_gt_i32_e32 vcc, s25, v4
	v_lshl_add_u64 v[4:5], v[4:5], 1, s[6:7]
	ds_write2_b32 v66, v35, v51 offset0:132 offset1:164
	s_waitcnt lgkmcnt(0)
	s_barrier
	s_branch .LBB0_1074

; #define MFMA(a, b, c) __builtin_amdgcn_mfma_f32_32x32x16_bf16((a), (b), (c), 0, 0, 0)
; template <int TM, int TN>
; DI void gemm_mainloop(const u16* __restrict__ A, long lda, const u16* __restrict__ Bt, long ldb, int K, char* smem,
;                       f32x16 (&acc)[TM][TN]) {
;     ...
;   const int nk = K / 64;
;   const int lrow = tid >> 3, lch = (tid & 7) * 8;
;   const u16* gA = A + (long)lrow * lda + lch;
;   const u16* gB = Bt + (long)lrow * ldb + lch;
;   const int soff = lrow * LD + lch;
;     ...
;   GEMM_GLOAD(0)
;   __syncthreads();
;   GEMM_SSTORE(0)
;   if (nk > 1) GEMM_GLOAD(64)
;   __syncthreads();
;   for (int kt = 0; kt < nk; kt++) {
;     const int buf = kt & 1;
;     const u16* cA = sA + buf * BM * LD + (wm * 32 * TM + r) * LD + h * 8;
;     const u16* cB = sB + buf * BN * LD + (wn * 32 * TN + r) * LD + h * 8;
;     bf16x8 af[TM], bfr[TN];
; #pragma unroll
;     for (int tm = 0; tm < TM; tm++) af[tm] = *(const bf16x8*)(cA + tm * 32 * LD);
; #pragma unroll
;     for (int tn = 0; tn < TN; tn++) bfr[tn] = *(const bf16x8*)(cB + tn * 32 * LD);
;     if (kt + 1 < nk) GEMM_SSTORE(buf ^ 1)
;     __builtin_amdgcn_sched_barrier(0);
;     __builtin_amdgcn_s_setprio(1);
; #pragma unroll
;     for (int tm = 0; tm < TM; tm++)
; #pragma unroll
;       for (int tn = 0; tn < TN; tn++) acc[tm][tn] = MFMA(af[tm], bfr[tn], acc[tm][tn]);
; #pragma unroll
;     for (int tm = 0; tm < TM; tm++) af[tm] = *(const bf16x8*)(cA + tm * 32 * LD + 16);
; #pragma unroll
;     for (int tn = 0; tn < TN; tn++) bfr[tn] = *(const bf16x8*)(cB + tn * 32 * LD + 16);
; #pragma unroll
;     for (int tm = 0; tm < TM; tm++)
; #pragma unroll
;       for (int tn = 0; tn < TN; tn++) acc[tm][tn] = MFMA(af[tm], bfr[tn], acc[tm][tn]);
;     __builtin_amdgcn_sched_group_barrier(0x8, 4, 0);
;     if (kt + 2 < nk) GEMM_GLOAD((kt + 2) * 64)
; template <class Epi>
; DI void phase_gemm128(const Sched& sc, const u16* A, long lda, const u16* Bt, long ldb, int K, int MT, int NT, int SN, char* smem, const Epi& epi) {
;     ...
;       int sm = st / sng, sn = st % sng;
;       int mt = sm * SM + xi / SN, nt = sn * SN + xi % SN;
;       gemm_tile<2, 2>(A, lda, Bt, ldb, K, mt * 128, nt * 128, smem, epi);
.LBB0_1343:
	s_lshl_b32 s4, s26, 8
	s_and_b32 s27, s4, 0xfffffe00
	s_lshl_b32 s4, s26, 11
	s_add_i32 s27, s27, s15
	s_and_b32 s4, s4, 0x800
	s_add_i32 s6, s4, s16
	s_mul_i32 s4, s27, 0x880
	s_mul_hi_i32 s5, s27, 0x880
	s_add_u32 s4, s8, s4
	v_mov_b32_e32 v1, v0
	s_addc_u32 s5, s9, s5
	s_ashr_i32 s7, s6, 31
	v_lshlrev_b32_e32 v2, 3, v1
	v_ashrrev_i32_e32 v68, 3, v1
	v_and_b32_e32 v69, 56, v2
	v_mov_b64_e32 v[2:3], s[4:5]
	v_mad_i64_i32 v[2:3], s[4:5], v68, s17, v[2:3]
	v_lshlrev_b32_e32 v66, 1, v69
	v_lshl_add_u64 v[72:73], v[2:3], 0, v[66:67]
	s_mul_i32 s28, s6, 0x880
	v_add_co_u32_e32 v70, vcc, s19, v72
	s_mul_hi_i32 s29, s6, 0x880
	s_add_u32 s28, s10, s28
	v_addc_co_u32_e32 v71, vcc, 0, v73, vcc
	s_addc_u32 s29, s11, s29
	v_add_co_u32_e32 v74, vcc, s20, v72
	v_mov_b64_e32 v[2:3], s[28:29]
	s_nop 0
	v_addc_co_u32_e32 v75, vcc, 0, v73, vcc
	v_mad_i64_i32 v[18:19], s[4:5], v68, s17, v[2:3]
	v_add_co_u32_e32 v78, vcc, s21, v72
	v_lshl_add_u64 v[76:77], v[18:19], 0, v[66:67]
	s_nop 0
	v_addc_co_u32_e32 v79, vcc, 0, v73, vcc
	v_add_co_u32_e32 v80, vcc, s19, v76
	global_load_dwordx4 v[2:5], v[72:73], off
	s_nop 0
	v_addc_co_u32_e32 v81, vcc, 0, v77, vcc
	v_add_co_u32_e32 v82, vcc, s20, v76
	global_load_dwordx4 v[6:9], v[70:71], off
	s_nop 0
	v_addc_co_u32_e32 v83, vcc, 0, v77, vcc
	v_add_co_u32_e32 v84, vcc, s21, v76
	global_load_dwordx4 v[10:13], v[74:75], off
	s_nop 0
	v_addc_co_u32_e32 v85, vcc, 0, v77, vcc
	global_load_dwordx4 v[14:17], v[78:79], off
	global_load_dwordx4 v[18:21], v[76:77], off
	global_load_dwordx4 v[22:25], v[80:81], off
	global_load_dwordx4 v[26:29], v[82:83], off
	global_load_dwordx4 v[30:33], v[84:85], off
	s_barrier
	global_load_dwordx4 v[34:37], v[72:73], off offset:128
	global_load_dwordx4 v[38:41], v[70:71], off offset:128
	global_load_dwordx4 v[42:45], v[74:75], off offset:128
	global_load_dwordx4 v[46:49], v[78:79], off offset:128
	global_load_dwordx4 v[50:53], v[76:77], off offset:128
	global_load_dwordx4 v[54:57], v[80:81], off offset:128
	global_load_dwordx4 v[58:61], v[82:83], off offset:128
	global_load_dwordx4 v[62:65], v[84:85], off offset:128
	v_and_b32_e32 v66, 31, v1
	v_lshrrev_b32_e32 v86, 1, v1
	v_mul_lo_u32 v68, v68, s18
	v_and_or_b32 v87, v86, s22, v66
	v_and_b32_e32 v86, 16, v86
	v_and_b32_e32 v1, 0x5f, v1
	v_add_lshl_u32 v66, v68, v69, 1
	v_mad_u64_u32 v[68:69], s[4:5], v87, s23, v[86:87]
	v_mad_u32_u24 v1, v1, s23, v86
	v_add_u32_e32 v69, 0x9000, v66
	s_waitcnt vmcnt(15)
	ds_write_b128 v66, v[2:5]
	s_waitcnt vmcnt(14)
	ds_write_b128 v66, v[6:9] offset:4608
	s_waitcnt vmcnt(13)
	ds_write_b128 v66, v[10:13] offset:9216
	s_waitcnt vmcnt(12)
	ds_write_b128 v66, v[14:17] offset:13824
	s_waitcnt vmcnt(11)
	ds_write_b128 v66, v[18:21] offset:36864
	s_waitcnt vmcnt(10)
	ds_write_b128 v66, v[22:25] offset:41472
	s_waitcnt vmcnt(9)
	ds_write_b128 v66, v[26:29] offset:46080
	s_waitcnt vmcnt(8)
	ds_write_b128 v66, v[30:33] offset:50688
	s_waitcnt lgkmcnt(0)
	s_barrier
	ds_read_b128 v[2:5], v68
	ds_read_b128 v[18:21], v68 offset:4608
	ds_read_b128 v[6:9], v1 offset:36864
	ds_read_b128 v[22:25], v1 offset:41472
	s_waitcnt vmcnt(7)
	ds_write_b128 v66, v[34:37] offset:18432
	s_waitcnt vmcnt(6)
	ds_write_b128 v66, v[38:41] offset:23040
	s_waitcnt vmcnt(5)
	ds_write_b128 v66, v[42:45] offset:27648
	s_waitcnt vmcnt(4)
	ds_write_b128 v66, v[46:49] offset:32256
	s_waitcnt vmcnt(3)
	ds_write_b128 v66, v[50:53] offset:55296
	s_waitcnt vmcnt(2)
	ds_write_b128 v66, v[54:57] offset:59904
	s_waitcnt vmcnt(1)
	ds_write_b128 v66, v[58:61] offset:64512
	s_waitcnt vmcnt(0)
	ds_write_b128 v69, v[62:65] offset:32256
	s_setprio 1
	ds_read_b128 v[86:89], v68 offset:32
	s_waitcnt lgkmcnt(10)
	v_mfma_f32_32x32x16_bf16 v[34:49], v[2:5], v[6:9], 0
	ds_read_b128 v[90:93], v1 offset:36896
	ds_read_b128 v[94:97], v1 offset:41504
	ds_read_b128 v[98:101], v68 offset:4704
	global_load_dwordx4 v[102:105], v[70:71], off offset:256
	global_load_dwordx4 v[106:109], v[74:75], off offset:256
	global_load_dwordx4 v[110:113], v[78:79], off offset:256
	global_load_dwordx4 v[114:117], v[84:85], off offset:256
	s_waitcnt lgkmcnt(12)
	v_mfma_f32_32x32x16_bf16 v[50:65], v[2:5], v[22:25], 0
	global_load_dwordx4 v[118:121], v[82:83], off offset:256
	global_load_dwordx4 v[122:125], v[80:81], off offset:256
	global_load_dwordx4 v[140:143], v[72:73], off offset:256
	global_load_dwordx4 v[144:147], v[76:77], off offset:256
	s_waitcnt lgkmcnt(2)
	v_mfma_f32_32x32x16_bf16 v[34:49], v[86:89], v[90:93], v[34:49]
	s_waitcnt lgkmcnt(1)
	v_mfma_f32_32x32x16_bf16 v[50:65], v[86:89], v[94:97], v[50:65]
	ds_read_b128 v[86:89], v68 offset:4640
	v_mfma_f32_32x32x16_bf16 v[2:17], v[18:21], v[6:9], 0
	v_mfma_f32_32x32x16_bf16 v[18:33], v[18:21], v[22:25], 0
	s_waitcnt lgkmcnt(0)
	v_mfma_f32_32x32x16_bf16 v[2:17], v[86:89], v[90:93], v[2:17]
	ds_read_b128 v[90:93], v1 offset:36928
	v_mfma_f32_32x32x16_bf16 v[18:33], v[86:89], v[94:97], v[18:33]
	ds_read_b128 v[86:89], v68 offset:64
	ds_read_b128 v[94:97], v1 offset:41536
	s_waitcnt lgkmcnt(1)
	v_mfma_f32_32x32x16_bf16 v[34:49], v[86:89], v[90:93], v[34:49]
	s_waitcnt lgkmcnt(0)
	v_mfma_f32_32x32x16_bf16 v[50:65], v[86:89], v[94:97], v[50:65]
	ds_read_b128 v[86:89], v68 offset:4672
	s_waitcnt lgkmcnt(0)
	v_mfma_f32_32x32x16_bf16 v[2:17], v[86:89], v[90:93], v[2:17]
	ds_read_b128 v[90:93], v1 offset:36960
	v_mfma_f32_32x32x16_bf16 v[18:33], v[86:89], v[94:97], v[18:33]
	ds_read_b128 v[86:89], v68 offset:96
	ds_read_b128 v[94:97], v1 offset:41568
	s_waitcnt lgkmcnt(1)
	v_mfma_f32_32x32x16_bf16 v[34:49], v[86:89], v[90:93], v[34:49]
	s_waitcnt lgkmcnt(0)
	v_mfma_f32_32x32x16_bf16 v[50:65], v[86:89], v[94:97], v[50:65]
	v_mfma_f32_32x32x16_bf16 v[2:17], v[98:101], v[90:93], v[2:17]
	v_mfma_f32_32x32x16_bf16 v[18:33], v[98:101], v[94:97], v[18:33]
	s_setprio 0
	s_barrier
; #define MFMA(a, b, c) __builtin_amdgcn_mfma_f32_32x32x16_bf16((a), (b), (c), 0, 0, 0)
; template <int TM, int TN>
; DI void gemm_mainloop(const u16* __restrict__ A, long lda, const u16* __restrict__ Bt, long ldb, int K, char* smem,
;                       f32x16 (&acc)[TM][TN]) {
;     ...
;   for (int kt = 0; kt < nk; kt++) {
;     const int buf = kt & 1;
;     const u16* cA = sA + buf * BM * LD + (wm * 32 * TM + r) * LD + h * 8;
;     const u16* cB = sB + buf * BN * LD + (wn * 32 * TN + r) * LD + h * 8;
;     bf16x8 af[TM], bfr[TN];
; #pragma unroll
;     for (int tm = 0; tm < TM; tm++) af[tm] = *(const bf16x8*)(cA + tm * 32 * LD);
; #pragma unroll
;     for (int tn = 0; tn < TN; tn++) bfr[tn] = *(const bf16x8*)(cB + tn * 32 * LD);
;     if (kt + 1 < nk) GEMM_SSTORE(buf ^ 1)
;     __builtin_amdgcn_sched_barrier(0);
;     __builtin_amdgcn_s_setprio(1);
; #pragma unroll
;     for (int tm = 0; tm < TM; tm++)
; #pragma unroll
;       for (int tn = 0; tn < TN; tn++) acc[tm][tn] = MFMA(af[tm], bfr[tn], acc[tm][tn]);
; #pragma unroll
;     for (int tm = 0; tm < TM; tm++) af[tm] = *(const bf16x8*)(cA + tm * 32 * LD + 16);
; #pragma unroll
;     for (int tn = 0; tn < TN; tn++) bfr[tn] = *(const bf16x8*)(cB + tn * 32 * LD + 16);
; #pragma unroll
;     for (int tm = 0; tm < TM; tm++)
; #pragma unroll
;       for (int tn = 0; tn < TN; tn++) acc[tm][tn] = MFMA(af[tm], bfr[tn], acc[tm][tn]);
;     __builtin_amdgcn_sched_group_barrier(0x8, 4, 0);
;     if (kt + 2 < nk) GEMM_GLOAD((kt + 2) * 64)
; #pragma unroll
;     for (int ks = 2; ks < 4; ks++) {
; #pragma unroll
;       for (int tm = 0; tm < TM; tm++) af[tm] = *(const bf16x8*)(cA + tm * 32 * LD + ks * 16);
; #pragma unroll
;       for (int tn = 0; tn < TN; tn++) bfr[tn] = *(const bf16x8*)(cB + tn * 32 * LD + ks * 16);
; #pragma unroll
;       for (int tm = 0; tm < TM; tm++)
; #pragma unroll
;         for (int tn = 0; tn < TN; tn++) acc[tm][tn] = MFMA(af[tm], bfr[tn], acc[tm][tn]);
;     }
;     __builtin_amdgcn_s_setprio(0);
;     __syncthreads();
;   }
	ds_read_b128 v[94:97], v68 offset:18432
	ds_read_b128 v[98:101], v68 offset:23040
	ds_read_b128 v[126:129], v1 offset:55296
	ds_read_b128 v[130:133], v1 offset:59904
	s_setprio 1
	ds_read_b128 v[86:89], v68 offset:18464
	s_waitcnt lgkmcnt(2)
	v_mfma_f32_32x32x16_bf16 v[34:49], v[94:97], v[126:129], v[34:49]
	s_waitcnt vmcnt(1)
	ds_write_b128 v66, v[140:143]
	ds_write_b128 v66, v[102:105] offset:4608
	global_load_dwordx4 v[140:143], v[72:73], off offset:384
	global_load_dwordx4 v[102:105], v[70:71], off offset:384
	ds_read_b128 v[90:93], v1 offset:55328
	s_waitcnt lgkmcnt(4)
	v_mfma_f32_32x32x16_bf16 v[50:65], v[94:97], v[130:133], v[50:65]
	ds_read_b128 v[94:97], v1 offset:59936
	s_waitcnt lgkmcnt(1)
	v_mfma_f32_32x32x16_bf16 v[34:49], v[86:89], v[90:93], v[34:49]
	s_waitcnt lgkmcnt(0)
	v_mfma_f32_32x32x16_bf16 v[50:65], v[86:89], v[94:97], v[50:65]
	ds_write_b128 v66, v[106:109] offset:9216
	ds_write_b128 v66, v[110:113] offset:13824
	global_load_dwordx4 v[106:109], v[74:75], off offset:384
	global_load_dwordx4 v[110:113], v[78:79], off offset:384
	ds_read_b128 v[86:89], v68 offset:23072
	v_mfma_f32_32x32x16_bf16 v[2:17], v[98:101], v[126:129], v[2:17]
	v_mfma_f32_32x32x16_bf16 v[18:33], v[98:101], v[130:133], v[18:33]
	ds_read_b128 v[98:101], v68 offset:23136
	s_waitcnt lgkmcnt(1)
	v_mfma_f32_32x32x16_bf16 v[2:17], v[86:89], v[90:93], v[2:17]
	s_waitcnt vmcnt(4)
	ds_write_b128 v66, v[144:147] offset:36864
	ds_write_b128 v66, v[122:125] offset:41472
	global_load_dwordx4 v[144:147], v[76:77], off offset:384
	global_load_dwordx4 v[122:125], v[80:81], off offset:384
	ds_read_b128 v[90:93], v1 offset:55360
	v_mfma_f32_32x32x16_bf16 v[18:33], v[86:89], v[94:97], v[18:33]
	ds_read_b128 v[86:89], v68 offset:18496
	ds_read_b128 v[94:97], v1 offset:59968
	s_waitcnt lgkmcnt(1)
	v_mfma_f32_32x32x16_bf16 v[34:49], v[86:89], v[90:93], v[34:49]
	s_waitcnt lgkmcnt(0)
	v_mfma_f32_32x32x16_bf16 v[50:65], v[86:89], v[94:97], v[50:65]
	ds_write_b128 v66, v[118:121] offset:46080
	ds_write_b128 v66, v[114:117] offset:50688
	global_load_dwordx4 v[118:121], v[82:83], off offset:384
	global_load_dwordx4 v[114:117], v[84:85], off offset:384
	ds_read_b128 v[86:89], v68 offset:23104
	s_waitcnt lgkmcnt(0)
	v_mfma_f32_32x32x16_bf16 v[2:17], v[86:89], v[90:93], v[2:17]
	ds_read_b128 v[90:93], v1 offset:55392
	v_mfma_f32_32x32x16_bf16 v[18:33], v[86:89], v[94:97], v[18:33]
	ds_read_b128 v[86:89], v68 offset:18528
	ds_read_b128 v[94:97], v1 offset:60000
	s_waitcnt lgkmcnt(1)
	v_mfma_f32_32x32x16_bf16 v[34:49], v[86:89], v[90:93], v[34:49]
	s_waitcnt lgkmcnt(0)
	v_mfma_f32_32x32x16_bf16 v[50:65], v[86:89], v[94:97], v[50:65]
	v_mfma_f32_32x32x16_bf16 v[2:17], v[98:101], v[90:93], v[2:17]
	v_mfma_f32_32x32x16_bf16 v[18:33], v[98:101], v[94:97], v[18:33]
	s_setprio 0
	s_barrier
	ds_read_b128 v[94:97], v68
	ds_read_b128 v[98:101], v68 offset:4608
	ds_read_b128 v[126:129], v1 offset:36864
	ds_read_b128 v[130:133], v1 offset:41472
	s_setprio 1
	ds_read_b128 v[86:89], v68 offset:32
	s_waitcnt lgkmcnt(2)
	v_mfma_f32_32x32x16_bf16 v[34:49], v[94:97], v[126:129], v[34:49]
	s_waitcnt vmcnt(7)
	ds_write_b128 v66, v[140:143] offset:18432
	s_waitcnt vmcnt(6)
	ds_write_b128 v66, v[102:105] offset:23040
	global_load_dwordx4 v[140:143], v[72:73], off offset:512
	global_load_dwordx4 v[102:105], v[70:71], off offset:512
	ds_read_b128 v[90:93], v1 offset:36896
	s_waitcnt lgkmcnt(4)
	v_mfma_f32_32x32x16_bf16 v[50:65], v[94:97], v[130:133], v[50:65]
	ds_read_b128 v[94:97], v1 offset:41504
	s_waitcnt lgkmcnt(1)
	v_mfma_f32_32x32x16_bf16 v[34:49], v[86:89], v[90:93], v[34:49]
	s_waitcnt lgkmcnt(0)
	v_mfma_f32_32x32x16_bf16 v[50:65], v[86:89], v[94:97], v[50:65]
	s_waitcnt vmcnt(7)
	ds_write_b128 v66, v[106:109] offset:27648
	s_waitcnt vmcnt(6)
	ds_write_b128 v66, v[110:113] offset:32256
	global_load_dwordx4 v[106:109], v[74:75], off offset:512
	global_load_dwordx4 v[110:113], v[78:79], off offset:512
	ds_read_b128 v[86:89], v68 offset:4640
	v_mfma_f32_32x32x16_bf16 v[2:17], v[98:101], v[126:129], v[2:17]
	v_mfma_f32_32x32x16_bf16 v[18:33], v[98:101], v[130:133], v[18:33]
	ds_read_b128 v[98:101], v68 offset:4704
	s_waitcnt lgkmcnt(1)
	v_mfma_f32_32x32x16_bf16 v[2:17], v[86:89], v[90:93], v[2:17]
	s_waitcnt vmcnt(7)
	ds_write_b128 v66, v[144:147] offset:55296
	s_waitcnt vmcnt(6)
	ds_write_b128 v66, v[122:125] offset:59904
	global_load_dwordx4 v[144:147], v[76:77], off offset:512
	global_load_dwordx4 v[122:125], v[80:81], off offset:512
	ds_read_b128 v[90:93], v1 offset:36928
	v_mfma_f32_32x32x16_bf16 v[18:33], v[86:89], v[94:97], v[18:33]
	ds_read_b128 v[86:89], v68 offset:64
	ds_read_b128 v[94:97], v1 offset:41536
	s_waitcnt lgkmcnt(1)
	v_mfma_f32_32x32x16_bf16 v[34:49], v[86:89], v[90:93], v[34:49]
	s_waitcnt lgkmcnt(0)
	v_mfma_f32_32x32x16_bf16 v[50:65], v[86:89], v[94:97], v[50:65]
	s_waitcnt vmcnt(7)
	ds_write_b128 v66, v[118:121] offset:64512
	s_waitcnt vmcnt(6)
	ds_write_b128 v69, v[114:117] offset:32256
	global_load_dwordx4 v[118:121], v[82:83], off offset:512
	global_load_dwordx4 v[114:117], v[84:85], off offset:512
	ds_read_b128 v[86:89], v68 offset:4672
	s_waitcnt lgkmcnt(0)
	v_mfma_f32_32x32x16_bf16 v[2:17], v[86:89], v[90:93], v[2:17]
	ds_read_b128 v[90:93], v1 offset:36960
	v_mfma_f32_32x32x16_bf16 v[18:33], v[86:89], v[94:97], v[18:33]
	ds_read_b128 v[86:89], v68 offset:96
	ds_read_b128 v[94:97], v1 offset:41568
	s_waitcnt lgkmcnt(1)
	v_mfma_f32_32x32x16_bf16 v[34:49], v[86:89], v[90:93], v[34:49]
	s_waitcnt lgkmcnt(0)
	v_mfma_f32_32x32x16_bf16 v[50:65], v[86:89], v[94:97], v[50:65]
	v_mfma_f32_32x32x16_bf16 v[2:17], v[98:101], v[90:93], v[2:17]
	v_mfma_f32_32x32x16_bf16 v[18:33], v[98:101], v[94:97], v[18:33]
	s_setprio 0
	s_barrier
; #define MFMA(a, b, c) __builtin_amdgcn_mfma_f32_32x32x16_bf16((a), (b), (c), 0, 0, 0)
; template <int TM, int TN>
; DI void gemm_mainloop(const u16* __restrict__ A, long lda, const u16* __restrict__ Bt, long ldb, int K, char* smem,
;                       f32x16 (&acc)[TM][TN]) {
;     ...
;   for (int kt = 0; kt < nk; kt++) {
;     const int buf = kt & 1;
;     const u16* cA = sA + buf * BM * LD + (wm * 32 * TM + r) * LD + h * 8;
;     const u16* cB = sB + buf * BN * LD + (wn * 32 * TN + r) * LD + h * 8;
;     bf16x8 af[TM], bfr[TN];
; #pragma unroll
;     for (int tm = 0; tm < TM; tm++) af[tm] = *(const bf16x8*)(cA + tm * 32 * LD);
; #pragma unroll
;     for (int tn = 0; tn < TN; tn++) bfr[tn] = *(const bf16x8*)(cB + tn * 32 * LD);
;     if (kt + 1 < nk) GEMM_SSTORE(buf ^ 1)
;     __builtin_amdgcn_sched_barrier(0);
;     __builtin_amdgcn_s_setprio(1);
; #pragma unroll
;     for (int tm = 0; tm < TM; tm++)
; #pragma unroll
;       for (int tn = 0; tn < TN; tn++) acc[tm][tn] = MFMA(af[tm], bfr[tn], acc[tm][tn]);
; #pragma unroll
;     for (int tm = 0; tm < TM; tm++) af[tm] = *(const bf16x8*)(cA + tm * 32 * LD + 16);
; #pragma unroll
;     for (int tn = 0; tn < TN; tn++) bfr[tn] = *(const bf16x8*)(cB + tn * 32 * LD + 16);
; #pragma unroll
;     for (int tm = 0; tm < TM; tm++)
; #pragma unroll
;       for (int tn = 0; tn < TN; tn++) acc[tm][tn] = MFMA(af[tm], bfr[tn], acc[tm][tn]);
;     __builtin_amdgcn_sched_group_barrier(0x8, 4, 0);
;     if (kt + 2 < nk) GEMM_GLOAD((kt + 2) * 64)
; #pragma unroll
;     for (int ks = 2; ks < 4; ks++) {
; #pragma unroll
;       for (int tm = 0; tm < TM; tm++) af[tm] = *(const bf16x8*)(cA + tm * 32 * LD + ks * 16);
; #pragma unroll
;       for (int tn = 0; tn < TN; tn++) bfr[tn] = *(const bf16x8*)(cB + tn * 32 * LD + ks * 16);
; #pragma unroll
;       for (int tm = 0; tm < TM; tm++)
; #pragma unroll
;         for (int tn = 0; tn < TN; tn++) acc[tm][tn] = MFMA(af[tm], bfr[tn], acc[tm][tn]);
;     }
;     __builtin_amdgcn_s_setprio(0);
;     __syncthreads();
;   }
	ds_read_b128 v[94:97], v68 offset:18432
	ds_read_b128 v[98:101], v68 offset:23040
	ds_read_b128 v[126:129], v1 offset:55296
	ds_read_b128 v[130:133], v1 offset:59904
	s_setprio 1
	ds_read_b128 v[86:89], v68 offset:18464
	s_waitcnt lgkmcnt(2)
	v_mfma_f32_32x32x16_bf16 v[34:49], v[94:97], v[126:129], v[34:49]
	s_waitcnt vmcnt(7)
	ds_write_b128 v66, v[140:143]
	s_waitcnt vmcnt(6)
	ds_write_b128 v66, v[102:105] offset:4608
	global_load_dwordx4 v[140:143], v[72:73], off offset:640
	global_load_dwordx4 v[102:105], v[70:71], off offset:640
	ds_read_b128 v[90:93], v1 offset:55328
	s_waitcnt lgkmcnt(4)
	v_mfma_f32_32x32x16_bf16 v[50:65], v[94:97], v[130:133], v[50:65]
	ds_read_b128 v[94:97], v1 offset:59936
	s_waitcnt lgkmcnt(1)
	v_mfma_f32_32x32x16_bf16 v[34:49], v[86:89], v[90:93], v[34:49]
	s_waitcnt lgkmcnt(0)
	v_mfma_f32_32x32x16_bf16 v[50:65], v[86:89], v[94:97], v[50:65]
	s_waitcnt vmcnt(7)
	ds_write_b128 v66, v[106:109] offset:9216
	s_waitcnt vmcnt(6)
	ds_write_b128 v66, v[110:113] offset:13824
	global_load_dwordx4 v[106:109], v[74:75], off offset:640
	global_load_dwordx4 v[110:113], v[78:79], off offset:640
	ds_read_b128 v[86:89], v68 offset:23072
	v_mfma_f32_32x32x16_bf16 v[2:17], v[98:101], v[126:129], v[2:17]
	v_mfma_f32_32x32x16_bf16 v[18:33], v[98:101], v[130:133], v[18:33]
	ds_read_b128 v[98:101], v68 offset:23136
	s_waitcnt lgkmcnt(1)
	v_mfma_f32_32x32x16_bf16 v[2:17], v[86:89], v[90:93], v[2:17]
	s_waitcnt vmcnt(7)
	ds_write_b128 v66, v[144:147] offset:36864
	s_waitcnt vmcnt(6)
	ds_write_b128 v66, v[122:125] offset:41472
	global_load_dwordx4 v[144:147], v[76:77], off offset:640
	global_load_dwordx4 v[122:125], v[80:81], off offset:640
	ds_read_b128 v[90:93], v1 offset:55360
	v_mfma_f32_32x32x16_bf16 v[18:33], v[86:89], v[94:97], v[18:33]
	ds_read_b128 v[86:89], v68 offset:18496
	ds_read_b128 v[94:97], v1 offset:59968
	s_waitcnt lgkmcnt(1)
	v_mfma_f32_32x32x16_bf16 v[34:49], v[86:89], v[90:93], v[34:49]
	s_waitcnt lgkmcnt(0)
	v_mfma_f32_32x32x16_bf16 v[50:65], v[86:89], v[94:97], v[50:65]
	s_waitcnt vmcnt(7)
	ds_write_b128 v66, v[118:121] offset:46080
	s_waitcnt vmcnt(6)
	ds_write_b128 v66, v[114:117] offset:50688
	global_load_dwordx4 v[118:121], v[82:83], off offset:640
	global_load_dwordx4 v[114:117], v[84:85], off offset:640
	ds_read_b128 v[86:89], v68 offset:23104
	s_waitcnt lgkmcnt(0)
	v_mfma_f32_32x32x16_bf16 v[2:17], v[86:89], v[90:93], v[2:17]
	ds_read_b128 v[90:93], v1 offset:55392
	v_mfma_f32_32x32x16_bf16 v[18:33], v[86:89], v[94:97], v[18:33]
	ds_read_b128 v[86:89], v68 offset:18528
	ds_read_b128 v[94:97], v1 offset:60000
	s_waitcnt lgkmcnt(1)
	v_mfma_f32_32x32x16_bf16 v[34:49], v[86:89], v[90:93], v[34:49]
	s_waitcnt lgkmcnt(0)
	v_mfma_f32_32x32x16_bf16 v[50:65], v[86:89], v[94:97], v[50:65]
	v_mfma_f32_32x32x16_bf16 v[2:17], v[98:101], v[90:93], v[2:17]
	v_mfma_f32_32x32x16_bf16 v[18:33], v[98:101], v[94:97], v[18:33]
	s_setprio 0
	s_barrier
	ds_read_b128 v[94:97], v68
	ds_read_b128 v[98:101], v68 offset:4608
	ds_read_b128 v[126:129], v1 offset:36864
	ds_read_b128 v[130:133], v1 offset:41472
	s_setprio 1
	ds_read_b128 v[86:89], v68 offset:32
	s_waitcnt lgkmcnt(2)
	v_mfma_f32_32x32x16_bf16 v[34:49], v[94:97], v[126:129], v[34:49]
	s_waitcnt vmcnt(7)
	ds_write_b128 v66, v[140:143] offset:18432
	s_waitcnt vmcnt(6)
	ds_write_b128 v66, v[102:105] offset:23040
	global_load_dwordx4 v[140:143], v[72:73], off offset:768
	global_load_dwordx4 v[102:105], v[70:71], off offset:768
	ds_read_b128 v[90:93], v1 offset:36896
	s_waitcnt lgkmcnt(4)
	v_mfma_f32_32x32x16_bf16 v[50:65], v[94:97], v[130:133], v[50:65]
	ds_read_b128 v[94:97], v1 offset:41504
	s_waitcnt lgkmcnt(1)
	v_mfma_f32_32x32x16_bf16 v[34:49], v[86:89], v[90:93], v[34:49]
	s_waitcnt lgkmcnt(0)
	v_mfma_f32_32x32x16_bf16 v[50:65], v[86:89], v[94:97], v[50:65]
	s_waitcnt vmcnt(7)
	ds_write_b128 v66, v[106:109] offset:27648
	s_waitcnt vmcnt(6)
	ds_write_b128 v66, v[110:113] offset:32256
	global_load_dwordx4 v[106:109], v[74:75], off offset:768
	global_load_dwordx4 v[110:113], v[78:79], off offset:768
	ds_read_b128 v[86:89], v68 offset:4640
	v_mfma_f32_32x32x16_bf16 v[2:17], v[98:101], v[126:129], v[2:17]
	v_mfma_f32_32x32x16_bf16 v[18:33], v[98:101], v[130:133], v[18:33]
	ds_read_b128 v[98:101], v68 offset:4704
	s_waitcnt lgkmcnt(1)
	v_mfma_f32_32x32x16_bf16 v[2:17], v[86:89], v[90:93], v[2:17]
	s_waitcnt vmcnt(7)
	ds_write_b128 v66, v[144:147] offset:55296
	s_waitcnt vmcnt(6)
	ds_write_b128 v66, v[122:125] offset:59904
	global_load_dwordx4 v[144:147], v[76:77], off offset:768
	global_load_dwordx4 v[122:125], v[80:81], off offset:768
	ds_read_b128 v[90:93], v1 offset:36928
	v_mfma_f32_32x32x16_bf16 v[18:33], v[86:89], v[94:97], v[18:33]
	ds_read_b128 v[86:89], v68 offset:64
	ds_read_b128 v[94:97], v1 offset:41536
	s_waitcnt lgkmcnt(1)
	v_mfma_f32_32x32x16_bf16 v[34:49], v[86:89], v[90:93], v[34:49]
	s_waitcnt lgkmcnt(0)
	v_mfma_f32_32x32x16_bf16 v[50:65], v[86:89], v[94:97], v[50:65]
	s_waitcnt vmcnt(7)
	ds_write_b128 v66, v[118:121] offset:64512
	s_waitcnt vmcnt(6)
	ds_write_b128 v69, v[114:117] offset:32256
	global_load_dwordx4 v[118:121], v[82:83], off offset:768
	global_load_dwordx4 v[114:117], v[84:85], off offset:768
	ds_read_b128 v[86:89], v68 offset:4672
	s_waitcnt lgkmcnt(0)
	v_mfma_f32_32x32x16_bf16 v[2:17], v[86:89], v[90:93], v[2:17]
	ds_read_b128 v[90:93], v1 offset:36960
	v_mfma_f32_32x32x16_bf16 v[18:33], v[86:89], v[94:97], v[18:33]
	ds_read_b128 v[86:89], v68 offset:96
	ds_read_b128 v[94:97], v1 offset:41568
	s_waitcnt lgkmcnt(1)
	v_mfma_f32_32x32x16_bf16 v[34:49], v[86:89], v[90:93], v[34:49]
	s_waitcnt lgkmcnt(0)
	v_mfma_f32_32x32x16_bf16 v[50:65], v[86:89], v[94:97], v[50:65]
	v_mfma_f32_32x32x16_bf16 v[2:17], v[98:101], v[90:93], v[2:17]
	v_mfma_f32_32x32x16_bf16 v[18:33], v[98:101], v[94:97], v[18:33]
	s_setprio 0
	s_barrier
; #define MFMA(a, b, c) __builtin_amdgcn_mfma_f32_32x32x16_bf16((a), (b), (c), 0, 0, 0)
; template <int TM, int TN>
; DI void gemm_mainloop(const u16* __restrict__ A, long lda, const u16* __restrict__ Bt, long ldb, int K, char* smem,
;                       f32x16 (&acc)[TM][TN]) {
;     ...
;   for (int kt = 0; kt < nk; kt++) {
;     const int buf = kt & 1;
;     const u16* cA = sA + buf * BM * LD + (wm * 32 * TM + r) * LD + h * 8;
;     const u16* cB = sB + buf * BN * LD + (wn * 32 * TN + r) * LD + h * 8;
;     bf16x8 af[TM], bfr[TN];
; #pragma unroll
;     for (int tm = 0; tm < TM; tm++) af[tm] = *(const bf16x8*)(cA + tm * 32 * LD);
; #pragma unroll
;     for (int tn = 0; tn < TN; tn++) bfr[tn] = *(const bf16x8*)(cB + tn * 32 * LD);
;     if (kt + 1 < nk) GEMM_SSTORE(buf ^ 1)
;     __builtin_amdgcn_sched_barrier(0);
;     __builtin_amdgcn_s_setprio(1);
; #pragma unroll
;     for (int tm = 0; tm < TM; tm++)
; #pragma unroll
;       for (int tn = 0; tn < TN; tn++) acc[tm][tn] = MFMA(af[tm], bfr[tn], acc[tm][tn]);
; #pragma unroll
;     for (int tm = 0; tm < TM; tm++) af[tm] = *(const bf16x8*)(cA + tm * 32 * LD + 16);
; #pragma unroll
;     for (int tn = 0; tn < TN; tn++) bfr[tn] = *(const bf16x8*)(cB + tn * 32 * LD + 16);
; #pragma unroll
;     for (int tm = 0; tm < TM; tm++)
; #pragma unroll
;       for (int tn = 0; tn < TN; tn++) acc[tm][tn] = MFMA(af[tm], bfr[tn], acc[tm][tn]);
;     __builtin_amdgcn_sched_group_barrier(0x8, 4, 0);
;     if (kt + 2 < nk) GEMM_GLOAD((kt + 2) * 64)
; #pragma unroll
;     for (int ks = 2; ks < 4; ks++) {
; #pragma unroll
;       for (int tm = 0; tm < TM; tm++) af[tm] = *(const bf16x8*)(cA + tm * 32 * LD + ks * 16);
; #pragma unroll
;       for (int tn = 0; tn < TN; tn++) bfr[tn] = *(const bf16x8*)(cB + tn * 32 * LD + ks * 16);
; #pragma unroll
;       for (int tm = 0; tm < TM; tm++)
; #pragma unroll
;         for (int tn = 0; tn < TN; tn++) acc[tm][tn] = MFMA(af[tm], bfr[tn], acc[tm][tn]);
;     }
;     __builtin_amdgcn_s_setprio(0);
;     __syncthreads();
;   }
	ds_read_b128 v[94:97], v68 offset:18432
	ds_read_b128 v[98:101], v68 offset:23040
	ds_read_b128 v[126:129], v1 offset:55296
	ds_read_b128 v[130:133], v1 offset:59904
	s_setprio 1
	ds_read_b128 v[86:89], v68 offset:18464
	s_waitcnt lgkmcnt(2)
	v_mfma_f32_32x32x16_bf16 v[34:49], v[94:97], v[126:129], v[34:49]
	s_waitcnt vmcnt(7)
	ds_write_b128 v66, v[140:143]
	s_waitcnt vmcnt(6)
	ds_write_b128 v66, v[102:105] offset:4608
	global_load_dwordx4 v[140:143], v[72:73], off offset:896
	global_load_dwordx4 v[102:105], v[70:71], off offset:896
	ds_read_b128 v[90:93], v1 offset:55328
	s_waitcnt lgkmcnt(4)
	v_mfma_f32_32x32x16_bf16 v[50:65], v[94:97], v[130:133], v[50:65]
	ds_read_b128 v[94:97], v1 offset:59936
	s_waitcnt lgkmcnt(1)
	v_mfma_f32_32x32x16_bf16 v[34:49], v[86:89], v[90:93], v[34:49]
	s_waitcnt lgkmcnt(0)
	v_mfma_f32_32x32x16_bf16 v[50:65], v[86:89], v[94:97], v[50:65]
	s_waitcnt vmcnt(7)
	ds_write_b128 v66, v[106:109] offset:9216
	s_waitcnt vmcnt(6)
	ds_write_b128 v66, v[110:113] offset:13824
	global_load_dwordx4 v[106:109], v[74:75], off offset:896
	global_load_dwordx4 v[110:113], v[78:79], off offset:896
	ds_read_b128 v[86:89], v68 offset:23072
	v_mfma_f32_32x32x16_bf16 v[2:17], v[98:101], v[126:129], v[2:17]
	v_mfma_f32_32x32x16_bf16 v[18:33], v[98:101], v[130:133], v[18:33]
	ds_read_b128 v[98:101], v68 offset:23136
	s_waitcnt lgkmcnt(1)
	v_mfma_f32_32x32x16_bf16 v[2:17], v[86:89], v[90:93], v[2:17]
	s_waitcnt vmcnt(7)
	ds_write_b128 v66, v[144:147] offset:36864
	s_waitcnt vmcnt(6)
	ds_write_b128 v66, v[122:125] offset:41472
	global_load_dwordx4 v[144:147], v[76:77], off offset:896
	global_load_dwordx4 v[122:125], v[80:81], off offset:896
	ds_read_b128 v[90:93], v1 offset:55360
	v_mfma_f32_32x32x16_bf16 v[18:33], v[86:89], v[94:97], v[18:33]
	ds_read_b128 v[86:89], v68 offset:18496
	ds_read_b128 v[94:97], v1 offset:59968
	s_waitcnt lgkmcnt(1)
	v_mfma_f32_32x32x16_bf16 v[34:49], v[86:89], v[90:93], v[34:49]
	s_waitcnt lgkmcnt(0)
	v_mfma_f32_32x32x16_bf16 v[50:65], v[86:89], v[94:97], v[50:65]
	s_waitcnt vmcnt(7)
	ds_write_b128 v66, v[118:121] offset:46080
	s_waitcnt vmcnt(6)
	ds_write_b128 v66, v[114:117] offset:50688
	global_load_dwordx4 v[118:121], v[82:83], off offset:896
	global_load_dwordx4 v[114:117], v[84:85], off offset:896
	ds_read_b128 v[86:89], v68 offset:23104
	s_waitcnt lgkmcnt(0)
	v_mfma_f32_32x32x16_bf16 v[2:17], v[86:89], v[90:93], v[2:17]
	ds_read_b128 v[90:93], v1 offset:55392
	v_mfma_f32_32x32x16_bf16 v[18:33], v[86:89], v[94:97], v[18:33]
	ds_read_b128 v[86:89], v68 offset:18528
	ds_read_b128 v[94:97], v1 offset:60000
	s_waitcnt lgkmcnt(1)
	v_mfma_f32_32x32x16_bf16 v[34:49], v[86:89], v[90:93], v[34:49]
	s_waitcnt lgkmcnt(0)
	v_mfma_f32_32x32x16_bf16 v[50:65], v[86:89], v[94:97], v[50:65]
	v_mfma_f32_32x32x16_bf16 v[2:17], v[98:101], v[90:93], v[2:17]
	v_mfma_f32_32x32x16_bf16 v[18:33], v[98:101], v[94:97], v[18:33]
	s_setprio 0
	s_barrier
	ds_read_b128 v[94:97], v68
	ds_read_b128 v[98:101], v68 offset:4608
	ds_read_b128 v[126:129], v1 offset:36864
	ds_read_b128 v[130:133], v1 offset:41472
	s_setprio 1
	ds_read_b128 v[86:89], v68 offset:32
	s_waitcnt lgkmcnt(2)
	v_mfma_f32_32x32x16_bf16 v[34:49], v[94:97], v[126:129], v[34:49]
	s_waitcnt vmcnt(7)
	ds_write_b128 v66, v[140:143] offset:18432
	s_waitcnt vmcnt(6)
	ds_write_b128 v66, v[102:105] offset:23040
	global_load_dwordx4 v[140:143], v[72:73], off offset:1024
	global_load_dwordx4 v[102:105], v[70:71], off offset:1024
	ds_read_b128 v[90:93], v1 offset:36896
	s_waitcnt lgkmcnt(4)
	v_mfma_f32_32x32x16_bf16 v[50:65], v[94:97], v[130:133], v[50:65]
	ds_read_b128 v[94:97], v1 offset:41504
	s_waitcnt lgkmcnt(1)
	v_mfma_f32_32x32x16_bf16 v[34:49], v[86:89], v[90:93], v[34:49]
	s_waitcnt lgkmcnt(0)
	v_mfma_f32_32x32x16_bf16 v[50:65], v[86:89], v[94:97], v[50:65]
	s_waitcnt vmcnt(7)
	ds_write_b128 v66, v[106:109] offset:27648
	s_waitcnt vmcnt(6)
	ds_write_b128 v66, v[110:113] offset:32256
	global_load_dwordx4 v[106:109], v[74:75], off offset:1024
	global_load_dwordx4 v[110:113], v[78:79], off offset:1024
	ds_read_b128 v[86:89], v68 offset:4640
	v_mfma_f32_32x32x16_bf16 v[2:17], v[98:101], v[126:129], v[2:17]
	v_mfma_f32_32x32x16_bf16 v[18:33], v[98:101], v[130:133], v[18:33]
	ds_read_b128 v[98:101], v68 offset:4704
	s_waitcnt lgkmcnt(1)
	v_mfma_f32_32x32x16_bf16 v[2:17], v[86:89], v[90:93], v[2:17]
	s_waitcnt vmcnt(7)
	ds_write_b128 v66, v[144:147] offset:55296
	s_waitcnt vmcnt(6)
	ds_write_b128 v66, v[122:125] offset:59904
	global_load_dwordx4 v[144:147], v[76:77], off offset:1024
	global_load_dwordx4 v[122:125], v[80:81], off offset:1024
	ds_read_b128 v[90:93], v1 offset:36928
	v_mfma_f32_32x32x16_bf16 v[18:33], v[86:89], v[94:97], v[18:33]
	ds_read_b128 v[86:89], v68 offset:64
	ds_read_b128 v[94:97], v1 offset:41536
	s_waitcnt lgkmcnt(1)
	v_mfma_f32_32x32x16_bf16 v[34:49], v[86:89], v[90:93], v[34:49]
	s_waitcnt lgkmcnt(0)
	v_mfma_f32_32x32x16_bf16 v[50:65], v[86:89], v[94:97], v[50:65]
	s_waitcnt vmcnt(7)
	ds_write_b128 v66, v[118:121] offset:64512
	s_waitcnt vmcnt(6)
	ds_write_b128 v69, v[114:117] offset:32256
	global_load_dwordx4 v[118:121], v[82:83], off offset:1024
	global_load_dwordx4 v[114:117], v[84:85], off offset:1024
	ds_read_b128 v[86:89], v68 offset:4672
	s_waitcnt lgkmcnt(0)
	v_mfma_f32_32x32x16_bf16 v[2:17], v[86:89], v[90:93], v[2:17]
	ds_read_b128 v[90:93], v1 offset:36960
	v_mfma_f32_32x32x16_bf16 v[18:33], v[86:89], v[94:97], v[18:33]
	ds_read_b128 v[86:89], v68 offset:96
	ds_read_b128 v[94:97], v1 offset:41568
	s_waitcnt lgkmcnt(1)
	v_mfma_f32_32x32x16_bf16 v[34:49], v[86:89], v[90:93], v[34:49]
	s_waitcnt lgkmcnt(0)
	v_mfma_f32_32x32x16_bf16 v[50:65], v[86:89], v[94:97], v[50:65]
	v_mfma_f32_32x32x16_bf16 v[2:17], v[98:101], v[90:93], v[2:17]
	v_mfma_f32_32x32x16_bf16 v[18:33], v[98:101], v[94:97], v[18:33]
	s_setprio 0
	s_barrier
; #define MFMA(a, b, c) __builtin_amdgcn_mfma_f32_32x32x16_bf16((a), (b), (c), 0, 0, 0)
; template <int TM, int TN>
; DI void gemm_mainloop(const u16* __restrict__ A, long lda, const u16* __restrict__ Bt, long ldb, int K, char* smem,
;                       f32x16 (&acc)[TM][TN]) {
;     ...
;   for (int kt = 0; kt < nk; kt++) {
;     const int buf = kt & 1;
;     const u16* cA = sA + buf * BM * LD + (wm * 32 * TM + r) * LD + h * 8;
;     const u16* cB = sB + buf * BN * LD + (wn * 32 * TN + r) * LD + h * 8;
;     bf16x8 af[TM], bfr[TN];
; #pragma unroll
;     for (int tm = 0; tm < TM; tm++) af[tm] = *(const bf16x8*)(cA + tm * 32 * LD);
; #pragma unroll
;     for (int tn = 0; tn < TN; tn++) bfr[tn] = *(const bf16x8*)(cB + tn * 32 * LD);
;     if (kt + 1 < nk) GEMM_SSTORE(buf ^ 1)
;     __builtin_amdgcn_sched_barrier(0);
;     __builtin_amdgcn_s_setprio(1);
; #pragma unroll
;     for (int tm = 0; tm < TM; tm++)
; #pragma unroll
;       for (int tn = 0; tn < TN; tn++) acc[tm][tn] = MFMA(af[tm], bfr[tn], acc[tm][tn]);
; #pragma unroll
;     for (int tm = 0; tm < TM; tm++) af[tm] = *(const bf16x8*)(cA + tm * 32 * LD + 16);
; #pragma unroll
;     for (int tn = 0; tn < TN; tn++) bfr[tn] = *(const bf16x8*)(cB + tn * 32 * LD + 16);
; #pragma unroll
;     for (int tm = 0; tm < TM; tm++)
; #pragma unroll
;       for (int tn = 0; tn < TN; tn++) acc[tm][tn] = MFMA(af[tm], bfr[tn], acc[tm][tn]);
;     __builtin_amdgcn_sched_group_barrier(0x8, 4, 0);
;     if (kt + 2 < nk) GEMM_GLOAD((kt + 2) * 64)
; #pragma unroll
;     for (int ks = 2; ks < 4; ks++) {
; #pragma unroll
;       for (int tm = 0; tm < TM; tm++) af[tm] = *(const bf16x8*)(cA + tm * 32 * LD + ks * 16);
; #pragma unroll
;       for (int tn = 0; tn < TN; tn++) bfr[tn] = *(const bf16x8*)(cB + tn * 32 * LD + ks * 16);
; #pragma unroll
;       for (int tm = 0; tm < TM; tm++)
; #pragma unroll
;         for (int tn = 0; tn < TN; tn++) acc[tm][tn] = MFMA(af[tm], bfr[tn], acc[tm][tn]);
;     }
;     __builtin_amdgcn_s_setprio(0);
;     __syncthreads();
;   }
	ds_read_b128 v[94:97], v68 offset:18432
	ds_read_b128 v[98:101], v68 offset:23040
	ds_read_b128 v[126:129], v1 offset:55296
	ds_read_b128 v[130:133], v1 offset:59904
	s_setprio 1
	ds_read_b128 v[86:89], v68 offset:18464
	s_waitcnt lgkmcnt(2)
	v_mfma_f32_32x32x16_bf16 v[34:49], v[94:97], v[126:129], v[34:49]
	s_waitcnt vmcnt(7)
	ds_write_b128 v66, v[140:143]
	s_waitcnt vmcnt(6)
	ds_write_b128 v66, v[102:105] offset:4608
	global_load_dwordx4 v[140:143], v[72:73], off offset:1152
	global_load_dwordx4 v[102:105], v[70:71], off offset:1152
	ds_read_b128 v[90:93], v1 offset:55328
	s_waitcnt lgkmcnt(4)
	v_mfma_f32_32x32x16_bf16 v[50:65], v[94:97], v[130:133], v[50:65]
	ds_read_b128 v[94:97], v1 offset:59936
	s_waitcnt lgkmcnt(1)
	v_mfma_f32_32x32x16_bf16 v[34:49], v[86:89], v[90:93], v[34:49]
	s_waitcnt lgkmcnt(0)
	v_mfma_f32_32x32x16_bf16 v[50:65], v[86:89], v[94:97], v[50:65]
	s_waitcnt vmcnt(7)
	ds_write_b128 v66, v[106:109] offset:9216
	s_waitcnt vmcnt(6)
	ds_write_b128 v66, v[110:113] offset:13824
	global_load_dwordx4 v[106:109], v[74:75], off offset:1152
	global_load_dwordx4 v[110:113], v[78:79], off offset:1152
	ds_read_b128 v[86:89], v68 offset:23072
	v_mfma_f32_32x32x16_bf16 v[2:17], v[98:101], v[126:129], v[2:17]
	v_mfma_f32_32x32x16_bf16 v[18:33], v[98:101], v[130:133], v[18:33]
	ds_read_b128 v[98:101], v68 offset:23136
	s_waitcnt lgkmcnt(1)
	v_mfma_f32_32x32x16_bf16 v[2:17], v[86:89], v[90:93], v[2:17]
	s_waitcnt vmcnt(7)
	ds_write_b128 v66, v[144:147] offset:36864
	s_waitcnt vmcnt(6)
	ds_write_b128 v66, v[122:125] offset:41472
	global_load_dwordx4 v[144:147], v[76:77], off offset:1152
	global_load_dwordx4 v[122:125], v[80:81], off offset:1152
	ds_read_b128 v[90:93], v1 offset:55360
	v_mfma_f32_32x32x16_bf16 v[18:33], v[86:89], v[94:97], v[18:33]
	ds_read_b128 v[86:89], v68 offset:18496
	ds_read_b128 v[94:97], v1 offset:59968
	s_waitcnt lgkmcnt(1)
	v_mfma_f32_32x32x16_bf16 v[34:49], v[86:89], v[90:93], v[34:49]
	s_waitcnt lgkmcnt(0)
	v_mfma_f32_32x32x16_bf16 v[50:65], v[86:89], v[94:97], v[50:65]
	s_waitcnt vmcnt(7)
	ds_write_b128 v66, v[118:121] offset:46080
	s_waitcnt vmcnt(6)
	ds_write_b128 v66, v[114:117] offset:50688
	global_load_dwordx4 v[118:121], v[82:83], off offset:1152
	global_load_dwordx4 v[114:117], v[84:85], off offset:1152
	ds_read_b128 v[86:89], v68 offset:23104
	s_waitcnt lgkmcnt(0)
	v_mfma_f32_32x32x16_bf16 v[2:17], v[86:89], v[90:93], v[2:17]
	ds_read_b128 v[90:93], v1 offset:55392
	v_mfma_f32_32x32x16_bf16 v[18:33], v[86:89], v[94:97], v[18:33]
	ds_read_b128 v[86:89], v68 offset:18528
	ds_read_b128 v[94:97], v1 offset:60000
	s_waitcnt lgkmcnt(1)
	v_mfma_f32_32x32x16_bf16 v[34:49], v[86:89], v[90:93], v[34:49]
	s_waitcnt lgkmcnt(0)
	v_mfma_f32_32x32x16_bf16 v[50:65], v[86:89], v[94:97], v[50:65]
	v_mfma_f32_32x32x16_bf16 v[2:17], v[98:101], v[90:93], v[2:17]
	v_mfma_f32_32x32x16_bf16 v[18:33], v[98:101], v[94:97], v[18:33]
	s_setprio 0
	s_barrier
	ds_read_b128 v[94:97], v68
	ds_read_b128 v[98:101], v68 offset:4608
	ds_read_b128 v[126:129], v1 offset:36864
	ds_read_b128 v[130:133], v1 offset:41472
	s_setprio 1
	ds_read_b128 v[86:89], v68 offset:32
	s_waitcnt lgkmcnt(2)
	v_mfma_f32_32x32x16_bf16 v[34:49], v[94:97], v[126:129], v[34:49]
	s_waitcnt vmcnt(7)
	ds_write_b128 v66, v[140:143] offset:18432
	s_waitcnt vmcnt(6)
	ds_write_b128 v66, v[102:105] offset:23040
	global_load_dwordx4 v[140:143], v[72:73], off offset:1280
	global_load_dwordx4 v[102:105], v[70:71], off offset:1280
	ds_read_b128 v[90:93], v1 offset:36896
	s_waitcnt lgkmcnt(4)
	v_mfma_f32_32x32x16_bf16 v[50:65], v[94:97], v[130:133], v[50:65]
	ds_read_b128 v[94:97], v1 offset:41504
	s_waitcnt lgkmcnt(1)
	v_mfma_f32_32x32x16_bf16 v[34:49], v[86:89], v[90:93], v[34:49]
	s_waitcnt lgkmcnt(0)
	v_mfma_f32_32x32x16_bf16 v[50:65], v[86:89], v[94:97], v[50:65]
	s_waitcnt vmcnt(7)
	ds_write_b128 v66, v[106:109] offset:27648
	s_waitcnt vmcnt(6)
	ds_write_b128 v66, v[110:113] offset:32256
	global_load_dwordx4 v[106:109], v[74:75], off offset:1280
	global_load_dwordx4 v[110:113], v[78:79], off offset:1280
	ds_read_b128 v[86:89], v68 offset:4640
	v_mfma_f32_32x32x16_bf16 v[2:17], v[98:101], v[126:129], v[2:17]
	v_mfma_f32_32x32x16_bf16 v[18:33], v[98:101], v[130:133], v[18:33]
	ds_read_b128 v[98:101], v68 offset:4704
	s_waitcnt lgkmcnt(1)
	v_mfma_f32_32x32x16_bf16 v[2:17], v[86:89], v[90:93], v[2:17]
	s_waitcnt vmcnt(7)
	ds_write_b128 v66, v[144:147] offset:55296
	s_waitcnt vmcnt(6)
	ds_write_b128 v66, v[122:125] offset:59904
	global_load_dwordx4 v[144:147], v[76:77], off offset:1280
	global_load_dwordx4 v[122:125], v[80:81], off offset:1280
	ds_read_b128 v[90:93], v1 offset:36928
	v_mfma_f32_32x32x16_bf16 v[18:33], v[86:89], v[94:97], v[18:33]
	ds_read_b128 v[86:89], v68 offset:64
	ds_read_b128 v[94:97], v1 offset:41536
	s_waitcnt lgkmcnt(1)
	v_mfma_f32_32x32x16_bf16 v[34:49], v[86:89], v[90:93], v[34:49]
	s_waitcnt lgkmcnt(0)
	v_mfma_f32_32x32x16_bf16 v[50:65], v[86:89], v[94:97], v[50:65]
	s_waitcnt vmcnt(7)
	ds_write_b128 v66, v[118:121] offset:64512
	s_waitcnt vmcnt(6)
	ds_write_b128 v69, v[114:117] offset:32256
	global_load_dwordx4 v[118:121], v[82:83], off offset:1280
	global_load_dwordx4 v[114:117], v[84:85], off offset:1280
	ds_read_b128 v[86:89], v68 offset:4672
	s_waitcnt lgkmcnt(0)
	v_mfma_f32_32x32x16_bf16 v[2:17], v[86:89], v[90:93], v[2:17]
	ds_read_b128 v[90:93], v1 offset:36960
	v_mfma_f32_32x32x16_bf16 v[18:33], v[86:89], v[94:97], v[18:33]
	ds_read_b128 v[86:89], v68 offset:96
	ds_read_b128 v[94:97], v1 offset:41568
	s_waitcnt lgkmcnt(1)
	v_mfma_f32_32x32x16_bf16 v[34:49], v[86:89], v[90:93], v[34:49]
	s_waitcnt lgkmcnt(0)
	v_mfma_f32_32x32x16_bf16 v[50:65], v[86:89], v[94:97], v[50:65]
	v_mfma_f32_32x32x16_bf16 v[2:17], v[98:101], v[90:93], v[2:17]
	v_mfma_f32_32x32x16_bf16 v[18:33], v[98:101], v[94:97], v[18:33]
	s_setprio 0
	s_barrier
; #define MFMA(a, b, c) __builtin_amdgcn_mfma_f32_32x32x16_bf16((a), (b), (c), 0, 0, 0)
; template <int TM, int TN>
; DI void gemm_mainloop(const u16* __restrict__ A, long lda, const u16* __restrict__ Bt, long ldb, int K, char* smem,
;                       f32x16 (&acc)[TM][TN]) {
;     ...
;   for (int kt = 0; kt < nk; kt++) {
;     const int buf = kt & 1;
;     const u16* cA = sA + buf * BM * LD + (wm * 32 * TM + r) * LD + h * 8;
;     const u16* cB = sB + buf * BN * LD + (wn * 32 * TN + r) * LD + h * 8;
;     bf16x8 af[TM], bfr[TN];
; #pragma unroll
;     for (int tm = 0; tm < TM; tm++) af[tm] = *(const bf16x8*)(cA + tm * 32 * LD);
; #pragma unroll
;     for (int tn = 0; tn < TN; tn++) bfr[tn] = *(const bf16x8*)(cB + tn * 32 * LD);
;     if (kt + 1 < nk) GEMM_SSTORE(buf ^ 1)
;     __builtin_amdgcn_sched_barrier(0);
;     __builtin_amdgcn_s_setprio(1);
; #pragma unroll
;     for (int tm = 0; tm < TM; tm++)
; #pragma unroll
;       for (int tn = 0; tn < TN; tn++) acc[tm][tn] = MFMA(af[tm], bfr[tn], acc[tm][tn]);
; #pragma unroll
;     for (int tm = 0; tm < TM; tm++) af[tm] = *(const bf16x8*)(cA + tm * 32 * LD + 16);
; #pragma unroll
;     for (int tn = 0; tn < TN; tn++) bfr[tn] = *(const bf16x8*)(cB + tn * 32 * LD + 16);
; #pragma unroll
;     for (int tm = 0; tm < TM; tm++)
; #pragma unroll
;       for (int tn = 0; tn < TN; tn++) acc[tm][tn] = MFMA(af[tm], bfr[tn], acc[tm][tn]);
;     __builtin_amdgcn_sched_group_barrier(0x8, 4, 0);
;     if (kt + 2 < nk) GEMM_GLOAD((kt + 2) * 64)
; #pragma unroll
;     for (int ks = 2; ks < 4; ks++) {
; #pragma unroll
;       for (int tm = 0; tm < TM; tm++) af[tm] = *(const bf16x8*)(cA + tm * 32 * LD + ks * 16);
; #pragma unroll
;       for (int tn = 0; tn < TN; tn++) bfr[tn] = *(const bf16x8*)(cB + tn * 32 * LD + ks * 16);
; #pragma unroll
;       for (int tm = 0; tm < TM; tm++)
; #pragma unroll
;         for (int tn = 0; tn < TN; tn++) acc[tm][tn] = MFMA(af[tm], bfr[tn], acc[tm][tn]);
;     }
;     __builtin_amdgcn_s_setprio(0);
;     __syncthreads();
;   }
	ds_read_b128 v[94:97], v68 offset:18432
	ds_read_b128 v[98:101], v68 offset:23040
	ds_read_b128 v[126:129], v1 offset:55296
	ds_read_b128 v[130:133], v1 offset:59904
	s_setprio 1
	ds_read_b128 v[86:89], v68 offset:18464
	s_waitcnt lgkmcnt(2)
	v_mfma_f32_32x32x16_bf16 v[34:49], v[94:97], v[126:129], v[34:49]
	s_waitcnt vmcnt(7)
	ds_write_b128 v66, v[140:143]
	s_waitcnt vmcnt(6)
	ds_write_b128 v66, v[102:105] offset:4608
	global_load_dwordx4 v[140:143], v[72:73], off offset:1408
	global_load_dwordx4 v[102:105], v[70:71], off offset:1408
	ds_read_b128 v[90:93], v1 offset:55328
	s_waitcnt lgkmcnt(4)
	v_mfma_f32_32x32x16_bf16 v[50:65], v[94:97], v[130:133], v[50:65]
	ds_read_b128 v[94:97], v1 offset:59936
	s_waitcnt lgkmcnt(1)
	v_mfma_f32_32x32x16_bf16 v[34:49], v[86:89], v[90:93], v[34:49]
	s_waitcnt lgkmcnt(0)
	v_mfma_f32_32x32x16_bf16 v[50:65], v[86:89], v[94:97], v[50:65]
	s_waitcnt vmcnt(7)
	ds_write_b128 v66, v[106:109] offset:9216
	s_waitcnt vmcnt(6)
	ds_write_b128 v66, v[110:113] offset:13824
	global_load_dwordx4 v[106:109], v[74:75], off offset:1408
	global_load_dwordx4 v[110:113], v[78:79], off offset:1408
	ds_read_b128 v[86:89], v68 offset:23072
	v_mfma_f32_32x32x16_bf16 v[2:17], v[98:101], v[126:129], v[2:17]
	v_mfma_f32_32x32x16_bf16 v[18:33], v[98:101], v[130:133], v[18:33]
	ds_read_b128 v[98:101], v68 offset:23136
	s_waitcnt lgkmcnt(1)
	v_mfma_f32_32x32x16_bf16 v[2:17], v[86:89], v[90:93], v[2:17]
	s_waitcnt vmcnt(7)
	ds_write_b128 v66, v[144:147] offset:36864
	s_waitcnt vmcnt(6)
	ds_write_b128 v66, v[122:125] offset:41472
	global_load_dwordx4 v[144:147], v[76:77], off offset:1408
	global_load_dwordx4 v[122:125], v[80:81], off offset:1408
	ds_read_b128 v[90:93], v1 offset:55360
	v_mfma_f32_32x32x16_bf16 v[18:33], v[86:89], v[94:97], v[18:33]
	ds_read_b128 v[86:89], v68 offset:18496
	ds_read_b128 v[94:97], v1 offset:59968
	s_waitcnt lgkmcnt(1)
	v_mfma_f32_32x32x16_bf16 v[34:49], v[86:89], v[90:93], v[34:49]
	s_waitcnt lgkmcnt(0)
	v_mfma_f32_32x32x16_bf16 v[50:65], v[86:89], v[94:97], v[50:65]
	s_waitcnt vmcnt(7)
	ds_write_b128 v66, v[118:121] offset:46080
	s_waitcnt vmcnt(6)
	ds_write_b128 v66, v[114:117] offset:50688
	global_load_dwordx4 v[118:121], v[82:83], off offset:1408
	global_load_dwordx4 v[114:117], v[84:85], off offset:1408
	ds_read_b128 v[86:89], v68 offset:23104
	s_waitcnt lgkmcnt(0)
	v_mfma_f32_32x32x16_bf16 v[2:17], v[86:89], v[90:93], v[2:17]
	ds_read_b128 v[90:93], v1 offset:55392
	v_mfma_f32_32x32x16_bf16 v[18:33], v[86:89], v[94:97], v[18:33]
	ds_read_b128 v[86:89], v68 offset:18528
	ds_read_b128 v[94:97], v1 offset:60000
	s_waitcnt lgkmcnt(1)
	v_mfma_f32_32x32x16_bf16 v[34:49], v[86:89], v[90:93], v[34:49]
	s_waitcnt lgkmcnt(0)
	v_mfma_f32_32x32x16_bf16 v[50:65], v[86:89], v[94:97], v[50:65]
	v_mfma_f32_32x32x16_bf16 v[2:17], v[98:101], v[90:93], v[2:17]
	v_mfma_f32_32x32x16_bf16 v[18:33], v[98:101], v[94:97], v[18:33]
	s_setprio 0
	s_barrier
	ds_read_b128 v[94:97], v68
	ds_read_b128 v[98:101], v68 offset:4608
	ds_read_b128 v[126:129], v1 offset:36864
	ds_read_b128 v[130:133], v1 offset:41472
	s_setprio 1
	ds_read_b128 v[86:89], v68 offset:32
	s_waitcnt lgkmcnt(2)
	v_mfma_f32_32x32x16_bf16 v[34:49], v[94:97], v[126:129], v[34:49]
	s_waitcnt vmcnt(7)
	ds_write_b128 v66, v[140:143] offset:18432
	s_waitcnt vmcnt(6)
	ds_write_b128 v66, v[102:105] offset:23040
	global_load_dwordx4 v[140:143], v[72:73], off offset:1536
	global_load_dwordx4 v[102:105], v[70:71], off offset:1536
	ds_read_b128 v[90:93], v1 offset:36896
	s_waitcnt lgkmcnt(4)
	v_mfma_f32_32x32x16_bf16 v[50:65], v[94:97], v[130:133], v[50:65]
	ds_read_b128 v[94:97], v1 offset:41504
	s_waitcnt lgkmcnt(1)
	v_mfma_f32_32x32x16_bf16 v[34:49], v[86:89], v[90:93], v[34:49]
	s_waitcnt lgkmcnt(0)
	v_mfma_f32_32x32x16_bf16 v[50:65], v[86:89], v[94:97], v[50:65]
	s_waitcnt vmcnt(7)
	ds_write_b128 v66, v[106:109] offset:27648
	s_waitcnt vmcnt(6)
	ds_write_b128 v66, v[110:113] offset:32256
	global_load_dwordx4 v[106:109], v[74:75], off offset:1536
	global_load_dwordx4 v[110:113], v[78:79], off offset:1536
	ds_read_b128 v[86:89], v68 offset:4640
	v_mfma_f32_32x32x16_bf16 v[2:17], v[98:101], v[126:129], v[2:17]
	v_mfma_f32_32x32x16_bf16 v[18:33], v[98:101], v[130:133], v[18:33]
	ds_read_b128 v[98:101], v68 offset:4704
	s_waitcnt lgkmcnt(1)
	v_mfma_f32_32x32x16_bf16 v[2:17], v[86:89], v[90:93], v[2:17]
	s_waitcnt vmcnt(7)
	ds_write_b128 v66, v[144:147] offset:55296
	s_waitcnt vmcnt(6)
	ds_write_b128 v66, v[122:125] offset:59904
	global_load_dwordx4 v[144:147], v[76:77], off offset:1536
	global_load_dwordx4 v[122:125], v[80:81], off offset:1536
	ds_read_b128 v[90:93], v1 offset:36928
	v_mfma_f32_32x32x16_bf16 v[18:33], v[86:89], v[94:97], v[18:33]
	ds_read_b128 v[86:89], v68 offset:64
	ds_read_b128 v[94:97], v1 offset:41536
	s_waitcnt lgkmcnt(1)
	v_mfma_f32_32x32x16_bf16 v[34:49], v[86:89], v[90:93], v[34:49]
	s_waitcnt lgkmcnt(0)
	v_mfma_f32_32x32x16_bf16 v[50:65], v[86:89], v[94:97], v[50:65]
	s_waitcnt vmcnt(7)
	ds_write_b128 v66, v[118:121] offset:64512
	s_waitcnt vmcnt(6)
	ds_write_b128 v69, v[114:117] offset:32256
	global_load_dwordx4 v[118:121], v[82:83], off offset:1536
	global_load_dwordx4 v[114:117], v[84:85], off offset:1536
	ds_read_b128 v[86:89], v68 offset:4672
	s_waitcnt lgkmcnt(0)
	v_mfma_f32_32x32x16_bf16 v[2:17], v[86:89], v[90:93], v[2:17]
	ds_read_b128 v[90:93], v1 offset:36960
	v_mfma_f32_32x32x16_bf16 v[18:33], v[86:89], v[94:97], v[18:33]
	ds_read_b128 v[86:89], v68 offset:96
	ds_read_b128 v[94:97], v1 offset:41568
	s_waitcnt lgkmcnt(1)
	v_mfma_f32_32x32x16_bf16 v[34:49], v[86:89], v[90:93], v[34:49]
	s_waitcnt lgkmcnt(0)
	v_mfma_f32_32x32x16_bf16 v[50:65], v[86:89], v[94:97], v[50:65]
	v_mfma_f32_32x32x16_bf16 v[2:17], v[98:101], v[90:93], v[2:17]
	v_mfma_f32_32x32x16_bf16 v[18:33], v[98:101], v[94:97], v[18:33]
	s_setprio 0
	s_barrier
; #define MFMA(a, b, c) __builtin_amdgcn_mfma_f32_32x32x16_bf16((a), (b), (c), 0, 0, 0)
; template <int TM, int TN>
; DI void gemm_mainloop(const u16* __restrict__ A, long lda, const u16* __restrict__ Bt, long ldb, int K, char* smem,
;                       f32x16 (&acc)[TM][TN]) {
;     ...
;   for (int kt = 0; kt < nk; kt++) {
;     const int buf = kt & 1;
;     const u16* cA = sA + buf * BM * LD + (wm * 32 * TM + r) * LD + h * 8;
;     const u16* cB = sB + buf * BN * LD + (wn * 32 * TN + r) * LD + h * 8;
;     bf16x8 af[TM], bfr[TN];
; #pragma unroll
;     for (int tm = 0; tm < TM; tm++) af[tm] = *(const bf16x8*)(cA + tm * 32 * LD);
; #pragma unroll
;     for (int tn = 0; tn < TN; tn++) bfr[tn] = *(const bf16x8*)(cB + tn * 32 * LD);
;     if (kt + 1 < nk) GEMM_SSTORE(buf ^ 1)
;     __builtin_amdgcn_sched_barrier(0);
;     __builtin_amdgcn_s_setprio(1);
; #pragma unroll
;     for (int tm = 0; tm < TM; tm++)
; #pragma unroll
;       for (int tn = 0; tn < TN; tn++) acc[tm][tn] = MFMA(af[tm], bfr[tn], acc[tm][tn]);
; #pragma unroll
;     for (int tm = 0; tm < TM; tm++) af[tm] = *(const bf16x8*)(cA + tm * 32 * LD + 16);
; #pragma unroll
;     for (int tn = 0; tn < TN; tn++) bfr[tn] = *(const bf16x8*)(cB + tn * 32 * LD + 16);
; #pragma unroll
;     for (int tm = 0; tm < TM; tm++)
; #pragma unroll
;       for (int tn = 0; tn < TN; tn++) acc[tm][tn] = MFMA(af[tm], bfr[tn], acc[tm][tn]);
;     __builtin_amdgcn_sched_group_barrier(0x8, 4, 0);
;     if (kt + 2 < nk) GEMM_GLOAD((kt + 2) * 64)
; #pragma unroll
;     for (int ks = 2; ks < 4; ks++) {
; #pragma unroll
;       for (int tm = 0; tm < TM; tm++) af[tm] = *(const bf16x8*)(cA + tm * 32 * LD + ks * 16);
; #pragma unroll
;       for (int tn = 0; tn < TN; tn++) bfr[tn] = *(const bf16x8*)(cB + tn * 32 * LD + ks * 16);
; #pragma unroll
;       for (int tm = 0; tm < TM; tm++)
; #pragma unroll
;         for (int tn = 0; tn < TN; tn++) acc[tm][tn] = MFMA(af[tm], bfr[tn], acc[tm][tn]);
;     }
;     __builtin_amdgcn_s_setprio(0);
;     __syncthreads();
;   }
	ds_read_b128 v[94:97], v68 offset:18432
	ds_read_b128 v[98:101], v68 offset:23040
	ds_read_b128 v[126:129], v1 offset:55296
	ds_read_b128 v[130:133], v1 offset:59904
	s_setprio 1
	ds_read_b128 v[86:89], v68 offset:18464
	s_waitcnt lgkmcnt(2)
	v_mfma_f32_32x32x16_bf16 v[34:49], v[94:97], v[126:129], v[34:49]
	s_waitcnt vmcnt(7)
	ds_write_b128 v66, v[140:143]
	s_waitcnt vmcnt(6)
	ds_write_b128 v66, v[102:105] offset:4608
	global_load_dwordx4 v[140:143], v[72:73], off offset:1664
	global_load_dwordx4 v[102:105], v[70:71], off offset:1664
	ds_read_b128 v[90:93], v1 offset:55328
	s_waitcnt lgkmcnt(4)
	v_mfma_f32_32x32x16_bf16 v[50:65], v[94:97], v[130:133], v[50:65]
	ds_read_b128 v[94:97], v1 offset:59936
	s_waitcnt lgkmcnt(1)
	v_mfma_f32_32x32x16_bf16 v[34:49], v[86:89], v[90:93], v[34:49]
	s_waitcnt lgkmcnt(0)
	v_mfma_f32_32x32x16_bf16 v[50:65], v[86:89], v[94:97], v[50:65]
	s_waitcnt vmcnt(7)
	ds_write_b128 v66, v[106:109] offset:9216
	s_waitcnt vmcnt(6)
	ds_write_b128 v66, v[110:113] offset:13824
	global_load_dwordx4 v[106:109], v[74:75], off offset:1664
	global_load_dwordx4 v[110:113], v[78:79], off offset:1664
	ds_read_b128 v[86:89], v68 offset:23072
	v_mfma_f32_32x32x16_bf16 v[2:17], v[98:101], v[126:129], v[2:17]
	v_mfma_f32_32x32x16_bf16 v[18:33], v[98:101], v[130:133], v[18:33]
	ds_read_b128 v[98:101], v68 offset:23136
	s_waitcnt lgkmcnt(1)
	v_mfma_f32_32x32x16_bf16 v[2:17], v[86:89], v[90:93], v[2:17]
	s_waitcnt vmcnt(7)
	ds_write_b128 v66, v[144:147] offset:36864
	s_waitcnt vmcnt(6)
	ds_write_b128 v66, v[122:125] offset:41472
	global_load_dwordx4 v[144:147], v[76:77], off offset:1664
	global_load_dwordx4 v[122:125], v[80:81], off offset:1664
	ds_read_b128 v[90:93], v1 offset:55360
	v_mfma_f32_32x32x16_bf16 v[18:33], v[86:89], v[94:97], v[18:33]
	ds_read_b128 v[86:89], v68 offset:18496
	ds_read_b128 v[94:97], v1 offset:59968
	s_waitcnt lgkmcnt(1)
	v_mfma_f32_32x32x16_bf16 v[34:49], v[86:89], v[90:93], v[34:49]
	s_waitcnt lgkmcnt(0)
	v_mfma_f32_32x32x16_bf16 v[50:65], v[86:89], v[94:97], v[50:65]
	s_waitcnt vmcnt(7)
	ds_write_b128 v66, v[118:121] offset:46080
	s_waitcnt vmcnt(6)
	ds_write_b128 v66, v[114:117] offset:50688
	global_load_dwordx4 v[118:121], v[82:83], off offset:1664
	global_load_dwordx4 v[114:117], v[84:85], off offset:1664
	ds_read_b128 v[86:89], v68 offset:23104
	s_waitcnt lgkmcnt(0)
	v_mfma_f32_32x32x16_bf16 v[2:17], v[86:89], v[90:93], v[2:17]
	ds_read_b128 v[90:93], v1 offset:55392
	v_mfma_f32_32x32x16_bf16 v[18:33], v[86:89], v[94:97], v[18:33]
	ds_read_b128 v[86:89], v68 offset:18528
	ds_read_b128 v[94:97], v1 offset:60000
	s_waitcnt lgkmcnt(1)
	v_mfma_f32_32x32x16_bf16 v[34:49], v[86:89], v[90:93], v[34:49]
	s_waitcnt lgkmcnt(0)
	v_mfma_f32_32x32x16_bf16 v[50:65], v[86:89], v[94:97], v[50:65]
	v_mfma_f32_32x32x16_bf16 v[2:17], v[98:101], v[90:93], v[2:17]
	v_mfma_f32_32x32x16_bf16 v[18:33], v[98:101], v[94:97], v[18:33]
	s_setprio 0
	s_barrier
	ds_read_b128 v[94:97], v68
	ds_read_b128 v[98:101], v68 offset:4608
	ds_read_b128 v[126:129], v1 offset:36864
	ds_read_b128 v[130:133], v1 offset:41472
	s_setprio 1
	ds_read_b128 v[86:89], v68 offset:32
	s_waitcnt lgkmcnt(2)
	v_mfma_f32_32x32x16_bf16 v[34:49], v[94:97], v[126:129], v[34:49]
	s_waitcnt vmcnt(7)
	ds_write_b128 v66, v[140:143] offset:18432
	s_waitcnt vmcnt(6)
	ds_write_b128 v66, v[102:105] offset:23040
	global_load_dwordx4 v[140:143], v[72:73], off offset:1792
	global_load_dwordx4 v[102:105], v[70:71], off offset:1792
	ds_read_b128 v[90:93], v1 offset:36896
	s_waitcnt lgkmcnt(4)
	v_mfma_f32_32x32x16_bf16 v[50:65], v[94:97], v[130:133], v[50:65]
	ds_read_b128 v[94:97], v1 offset:41504
	s_waitcnt lgkmcnt(1)
	v_mfma_f32_32x32x16_bf16 v[34:49], v[86:89], v[90:93], v[34:49]
	s_waitcnt lgkmcnt(0)
	v_mfma_f32_32x32x16_bf16 v[50:65], v[86:89], v[94:97], v[50:65]
	s_waitcnt vmcnt(7)
	ds_write_b128 v66, v[106:109] offset:27648
	s_waitcnt vmcnt(6)
	ds_write_b128 v66, v[110:113] offset:32256
	global_load_dwordx4 v[106:109], v[74:75], off offset:1792
	global_load_dwordx4 v[110:113], v[78:79], off offset:1792
	ds_read_b128 v[86:89], v68 offset:4640
	v_mfma_f32_32x32x16_bf16 v[2:17], v[98:101], v[126:129], v[2:17]
	v_mfma_f32_32x32x16_bf16 v[18:33], v[98:101], v[130:133], v[18:33]
	ds_read_b128 v[98:101], v68 offset:4704
	s_waitcnt lgkmcnt(1)
	v_mfma_f32_32x32x16_bf16 v[2:17], v[86:89], v[90:93], v[2:17]
	s_waitcnt vmcnt(7)
	ds_write_b128 v66, v[144:147] offset:55296
	s_waitcnt vmcnt(6)
	ds_write_b128 v66, v[122:125] offset:59904
	global_load_dwordx4 v[144:147], v[76:77], off offset:1792
	global_load_dwordx4 v[122:125], v[80:81], off offset:1792
	ds_read_b128 v[90:93], v1 offset:36928
	v_mfma_f32_32x32x16_bf16 v[18:33], v[86:89], v[94:97], v[18:33]
	ds_read_b128 v[86:89], v68 offset:64
	ds_read_b128 v[94:97], v1 offset:41536
	s_waitcnt lgkmcnt(1)
	v_mfma_f32_32x32x16_bf16 v[34:49], v[86:89], v[90:93], v[34:49]
	s_waitcnt lgkmcnt(0)
	v_mfma_f32_32x32x16_bf16 v[50:65], v[86:89], v[94:97], v[50:65]
	s_waitcnt vmcnt(7)
	ds_write_b128 v66, v[118:121] offset:64512
	s_waitcnt vmcnt(6)
	ds_write_b128 v69, v[114:117] offset:32256
	global_load_dwordx4 v[118:121], v[82:83], off offset:1792
	global_load_dwordx4 v[114:117], v[84:85], off offset:1792
	ds_read_b128 v[86:89], v68 offset:4672
	s_waitcnt lgkmcnt(0)
	v_mfma_f32_32x32x16_bf16 v[2:17], v[86:89], v[90:93], v[2:17]
	ds_read_b128 v[90:93], v1 offset:36960
	v_mfma_f32_32x32x16_bf16 v[18:33], v[86:89], v[94:97], v[18:33]
	ds_read_b128 v[86:89], v68 offset:96
	ds_read_b128 v[94:97], v1 offset:41568
	s_waitcnt lgkmcnt(1)
	v_mfma_f32_32x32x16_bf16 v[34:49], v[86:89], v[90:93], v[34:49]
	s_waitcnt lgkmcnt(0)
	v_mfma_f32_32x32x16_bf16 v[50:65], v[86:89], v[94:97], v[50:65]
	v_mfma_f32_32x32x16_bf16 v[2:17], v[98:101], v[90:93], v[2:17]
	v_mfma_f32_32x32x16_bf16 v[18:33], v[98:101], v[94:97], v[18:33]
	s_setprio 0
	s_barrier
; #define MFMA(a, b, c) __builtin_amdgcn_mfma_f32_32x32x16_bf16((a), (b), (c), 0, 0, 0)
; template <int TM, int TN>
; DI void gemm_mainloop(const u16* __restrict__ A, long lda, const u16* __restrict__ Bt, long ldb, int K, char* smem,
;                       f32x16 (&acc)[TM][TN]) {
;     ...
;   for (int kt = 0; kt < nk; kt++) {
;     const int buf = kt & 1;
;     const u16* cA = sA + buf * BM * LD + (wm * 32 * TM + r) * LD + h * 8;
;     const u16* cB = sB + buf * BN * LD + (wn * 32 * TN + r) * LD + h * 8;
;     bf16x8 af[TM], bfr[TN];
; #pragma unroll
;     for (int tm = 0; tm < TM; tm++) af[tm] = *(const bf16x8*)(cA + tm * 32 * LD);
; #pragma unroll
;     for (int tn = 0; tn < TN; tn++) bfr[tn] = *(const bf16x8*)(cB + tn * 32 * LD);
;     if (kt + 1 < nk) GEMM_SSTORE(buf ^ 1)
;     __builtin_amdgcn_sched_barrier(0);
;     __builtin_amdgcn_s_setprio(1);
; #pragma unroll
;     for (int tm = 0; tm < TM; tm++)
; #pragma unroll
;       for (int tn = 0; tn < TN; tn++) acc[tm][tn] = MFMA(af[tm], bfr[tn], acc[tm][tn]);
; #pragma unroll
;     for (int tm = 0; tm < TM; tm++) af[tm] = *(const bf16x8*)(cA + tm * 32 * LD + 16);
; #pragma unroll
;     for (int tn = 0; tn < TN; tn++) bfr[tn] = *(const bf16x8*)(cB + tn * 32 * LD + 16);
; #pragma unroll
;     for (int tm = 0; tm < TM; tm++)
; #pragma unroll
;       for (int tn = 0; tn < TN; tn++) acc[tm][tn] = MFMA(af[tm], bfr[tn], acc[tm][tn]);
;     __builtin_amdgcn_sched_group_barrier(0x8, 4, 0);
;     if (kt + 2 < nk) GEMM_GLOAD((kt + 2) * 64)
; #pragma unroll
;     for (int ks = 2; ks < 4; ks++) {
; #pragma unroll
;       for (int tm = 0; tm < TM; tm++) af[tm] = *(const bf16x8*)(cA + tm * 32 * LD + ks * 16);
; #pragma unroll
;       for (int tn = 0; tn < TN; tn++) bfr[tn] = *(const bf16x8*)(cB + tn * 32 * LD + ks * 16);
; #pragma unroll
;       for (int tm = 0; tm < TM; tm++)
; #pragma unroll
;         for (int tn = 0; tn < TN; tn++) acc[tm][tn] = MFMA(af[tm], bfr[tn], acc[tm][tn]);
;     }
;     __builtin_amdgcn_s_setprio(0);
;     __syncthreads();
;   }
	ds_read_b128 v[94:97], v68 offset:18432
	ds_read_b128 v[98:101], v68 offset:23040
	ds_read_b128 v[126:129], v1 offset:55296
	ds_read_b128 v[130:133], v1 offset:59904
	s_setprio 1
	ds_read_b128 v[86:89], v68 offset:18464
	s_waitcnt lgkmcnt(2)
	v_mfma_f32_32x32x16_bf16 v[34:49], v[94:97], v[126:129], v[34:49]
	s_waitcnt vmcnt(7)
	ds_write_b128 v66, v[140:143]
	s_waitcnt vmcnt(6)
	ds_write_b128 v66, v[102:105] offset:4608
	global_load_dwordx4 v[140:143], v[72:73], off offset:1920
	global_load_dwordx4 v[102:105], v[70:71], off offset:1920
	ds_read_b128 v[90:93], v1 offset:55328
	s_waitcnt lgkmcnt(4)
	v_mfma_f32_32x32x16_bf16 v[50:65], v[94:97], v[130:133], v[50:65]
	ds_read_b128 v[94:97], v1 offset:59936
	s_waitcnt lgkmcnt(1)
	v_mfma_f32_32x32x16_bf16 v[34:49], v[86:89], v[90:93], v[34:49]
	s_waitcnt lgkmcnt(0)
	v_mfma_f32_32x32x16_bf16 v[50:65], v[86:89], v[94:97], v[50:65]
	s_waitcnt vmcnt(7)
	ds_write_b128 v66, v[106:109] offset:9216
	s_waitcnt vmcnt(6)
	ds_write_b128 v66, v[110:113] offset:13824
	global_load_dwordx4 v[106:109], v[74:75], off offset:1920
	global_load_dwordx4 v[110:113], v[78:79], off offset:1920
	ds_read_b128 v[86:89], v68 offset:23072
	v_mfma_f32_32x32x16_bf16 v[2:17], v[98:101], v[126:129], v[2:17]
	v_mfma_f32_32x32x16_bf16 v[18:33], v[98:101], v[130:133], v[18:33]
	ds_read_b128 v[98:101], v68 offset:23136
	s_waitcnt lgkmcnt(1)
	v_mfma_f32_32x32x16_bf16 v[2:17], v[86:89], v[90:93], v[2:17]
	s_waitcnt vmcnt(7)
	ds_write_b128 v66, v[144:147] offset:36864
	s_waitcnt vmcnt(6)
	ds_write_b128 v66, v[122:125] offset:41472
	global_load_dwordx4 v[144:147], v[76:77], off offset:1920
	global_load_dwordx4 v[122:125], v[80:81], off offset:1920
	ds_read_b128 v[90:93], v1 offset:55360
	v_mfma_f32_32x32x16_bf16 v[18:33], v[86:89], v[94:97], v[18:33]
	ds_read_b128 v[86:89], v68 offset:18496
	ds_read_b128 v[94:97], v1 offset:59968
	s_waitcnt lgkmcnt(1)
	v_mfma_f32_32x32x16_bf16 v[34:49], v[86:89], v[90:93], v[34:49]
	s_waitcnt lgkmcnt(0)
	v_mfma_f32_32x32x16_bf16 v[50:65], v[86:89], v[94:97], v[50:65]
	s_waitcnt vmcnt(7)
	ds_write_b128 v66, v[118:121] offset:46080
	s_waitcnt vmcnt(6)
	ds_write_b128 v66, v[114:117] offset:50688
	global_load_dwordx4 v[118:121], v[82:83], off offset:1920
	global_load_dwordx4 v[114:117], v[84:85], off offset:1920
	ds_read_b128 v[86:89], v68 offset:23104
	s_waitcnt lgkmcnt(0)
	v_mfma_f32_32x32x16_bf16 v[2:17], v[86:89], v[90:93], v[2:17]
	ds_read_b128 v[90:93], v1 offset:55392
	v_mfma_f32_32x32x16_bf16 v[18:33], v[86:89], v[94:97], v[18:33]
	ds_read_b128 v[86:89], v68 offset:18528
	ds_read_b128 v[94:97], v1 offset:60000
	s_waitcnt lgkmcnt(1)
	v_mfma_f32_32x32x16_bf16 v[34:49], v[86:89], v[90:93], v[34:49]
	s_waitcnt lgkmcnt(0)
	v_mfma_f32_32x32x16_bf16 v[50:65], v[86:89], v[94:97], v[50:65]
	s_nop 0
	v_mfma_f32_32x32x16_bf16 v[2:17], v[98:101], v[90:93], v[2:17]
	v_mfma_f32_32x32x16_bf16 v[18:33], v[98:101], v[94:97], v[18:33]
	s_setprio 0
	s_barrier
	ds_read_b128 v[74:77], v68
	ds_read_b128 v[78:81], v68 offset:4608
	ds_read_b128 v[82:85], v1 offset:36864
	ds_read_b128 v[90:93], v1 offset:41472
	s_setprio 1
	ds_read_b128 v[70:73], v68 offset:32
	s_waitcnt lgkmcnt(2)
	v_mfma_f32_32x32x16_bf16 v[34:49], v[74:77], v[82:85], v[34:49]
	s_waitcnt vmcnt(7)
	ds_write_b128 v66, v[140:143] offset:18432
	s_waitcnt vmcnt(6)
	ds_write_b128 v66, v[102:105] offset:23040
	s_waitcnt lgkmcnt(3)
	v_mfma_f32_32x32x16_bf16 v[50:65], v[74:77], v[90:93], v[50:65]
	ds_read_b128 v[74:77], v1 offset:36896
	v_mfma_f32_32x32x16_bf16 v[2:17], v[78:81], v[82:85], v[2:17]
	v_mfma_f32_32x32x16_bf16 v[18:33], v[78:81], v[90:93], v[18:33]
	s_waitcnt vmcnt(5)
	ds_write_b128 v66, v[106:109] offset:27648
	s_waitcnt vmcnt(4)
	ds_write_b128 v66, v[110:113] offset:32256
	ds_read_b128 v[78:81], v1 offset:41504
	s_waitcnt lgkmcnt(3)
	v_mfma_f32_32x32x16_bf16 v[34:49], v[70:73], v[74:77], v[34:49]
	s_waitcnt lgkmcnt(0)
	v_mfma_f32_32x32x16_bf16 v[50:65], v[70:73], v[78:81], v[50:65]
	ds_read_b128 v[70:73], v68 offset:4640
	s_waitcnt lgkmcnt(0)
	v_mfma_f32_32x32x16_bf16 v[2:17], v[70:73], v[74:77], v[2:17]
	s_waitcnt vmcnt(3)
	ds_write_b128 v66, v[144:147] offset:55296
	s_waitcnt vmcnt(2)
	ds_write_b128 v66, v[122:125] offset:59904
	ds_read_b128 v[74:77], v1 offset:36928
	v_mfma_f32_32x32x16_bf16 v[18:33], v[70:73], v[78:81], v[18:33]
	ds_read_b128 v[70:73], v68 offset:64
	ds_read_b128 v[78:81], v1 offset:41536
	s_waitcnt lgkmcnt(1)
	v_mfma_f32_32x32x16_bf16 v[34:49], v[70:73], v[74:77], v[34:49]
	s_waitcnt lgkmcnt(0)
	v_mfma_f32_32x32x16_bf16 v[50:65], v[70:73], v[78:81], v[50:65]
	s_waitcnt vmcnt(1)
	ds_write_b128 v66, v[118:121] offset:64512
	s_waitcnt vmcnt(0)
	ds_write_b128 v69, v[114:117] offset:32256
	ds_read_b128 v[70:73], v68 offset:4672
	s_waitcnt lgkmcnt(0)
	v_mfma_f32_32x32x16_bf16 v[2:17], v[70:73], v[74:77], v[2:17]
	ds_read_b128 v[74:77], v1 offset:36960
	v_mfma_f32_32x32x16_bf16 v[18:33], v[70:73], v[78:81], v[18:33]
	ds_read_b128 v[70:73], v68 offset:96
	ds_read_b128 v[78:81], v1 offset:41568
	s_waitcnt lgkmcnt(1)
	v_mfma_f32_32x32x16_bf16 v[34:49], v[70:73], v[74:77], v[34:49]
	s_waitcnt lgkmcnt(0)
	v_mfma_f32_32x32x16_bf16 v[50:65], v[70:73], v[78:81], v[50:65]
	ds_read_b128 v[70:73], v68 offset:4704
	s_waitcnt lgkmcnt(0)
	v_mfma_f32_32x32x16_bf16 v[2:17], v[70:73], v[74:77], v[2:17]
	v_mfma_f32_32x32x16_bf16 v[18:33], v[70:73], v[78:81], v[18:33]
	s_setprio 0
	s_barrier
; #define MFMA(a, b, c) __builtin_amdgcn_mfma_f32_32x32x16_bf16((a), (b), (c), 0, 0, 0)
; DI int tidx() { int t = (int)threadIdx.x; asm volatile("" : "+v"(t)); return t; }
; DI int crow(int i, int h) { return (i & 3) + 8 * (i >> 2) + 4 * h; }
; template <int TM, int TN>
; DI void gemm_mainloop(const u16* __restrict__ A, long lda, const u16* __restrict__ Bt, long ldb, int K, char* smem,
;                       f32x16 (&acc)[TM][TN]) {
;     ...
;     for (int tm = 0; tm < TM; tm++)
; #pragma unroll
;       for (int tn = 0; tn < TN; tn++) acc[tm][tn] = MFMA(af[tm], bfr[tn], acc[tm][tn]);
; #pragma unroll
;     for (int tm = 0; tm < TM; tm++) af[tm] = *(const bf16x8*)(cA + tm * 32 * LD + 16);
; #pragma unroll
;     for (int tn = 0; tn < TN; tn++) bfr[tn] = *(const bf16x8*)(cB + tn * 32 * LD + 16);
; #pragma unroll
;     for (int tm = 0; tm < TM; tm++)
; #pragma unroll
;       for (int tn = 0; tn < TN; tn++) acc[tm][tn] = MFMA(af[tm], bfr[tn], acc[tm][tn]);
;     __builtin_amdgcn_sched_group_barrier(0x8, 4, 0);
;     if (kt + 2 < nk) GEMM_GLOAD((kt + 2) * 64)
; #pragma unroll
;     for (int ks = 2; ks < 4; ks++) {
; #pragma unroll
;       for (int tm = 0; tm < TM; tm++) af[tm] = *(const bf16x8*)(cA + tm * 32 * LD + ks * 16);
; #pragma unroll
;       for (int tn = 0; tn < TN; tn++) bfr[tn] = *(const bf16x8*)(cB + tn * 32 * LD + ks * 16);
; #pragma unroll
;       for (int tm = 0; tm < TM; tm++)
; #pragma unroll
;         for (int tn = 0; tn < TN; tn++) acc[tm][tn] = MFMA(af[tm], bfr[tn], acc[tm][tn]);
;     }
;     __builtin_amdgcn_s_setprio(0);
;     __syncthreads();
;   }
; template <int TM, int TN, class Epi>
; DI void gemm_tile(const u16* A, long lda, const u16* Bt, long ldb, int K, int m0, int n0, char* smem, const Epi& epi) {
;     ...
;   const int tid = tidx(), lane = tid & 63, w = tid >> 6, r = lane & 31, h = lane >> 5;
;   const int wm = w >> 1, wn = w & 1;
;   float* Ct = (float*)smem;
; #pragma unroll
;   for (int tm = 0; tm < TM; tm++)
; #pragma unroll
;     for (int tn = 0; tn < TN; tn++)
; #pragma unroll
;       for (int i = 0; i < 16; i++)
;         Ct[(wm * 32 * TM + tm * 32 + crow(i, h)) * LDC + wn * 32 * TN + tn * 32 + r] = acc[tm][tn][i];
;   __syncthreads();
	ds_read_b128 v[70:73], v68 offset:18432
	ds_read_b128 v[74:77], v68 offset:23040
	ds_read_b128 v[78:81], v1 offset:55296
	ds_read_b128 v[82:85], v1 offset:59904
	s_setprio 1
	s_waitcnt lgkmcnt(1)
	v_mfma_f32_32x32x16_bf16 v[34:49], v[70:73], v[78:81], v[34:49]
	s_waitcnt lgkmcnt(0)
	v_mfma_f32_32x32x16_bf16 v[50:65], v[70:73], v[82:85], v[50:65]
	ds_read_b128 v[70:73], v68 offset:18464
	v_mfma_f32_32x32x16_bf16 v[2:17], v[74:77], v[78:81], v[2:17]
	ds_read_b128 v[78:81], v1 offset:59936
	v_mfma_f32_32x32x16_bf16 v[18:33], v[74:77], v[82:85], v[18:33]
	ds_read_b128 v[74:77], v1 offset:55328
	s_waitcnt lgkmcnt(0)
	v_mfma_f32_32x32x16_bf16 v[34:49], v[70:73], v[74:77], v[34:49]
	v_mfma_f32_32x32x16_bf16 v[50:65], v[70:73], v[78:81], v[50:65]
	ds_read_b128 v[70:73], v68 offset:23072
	s_waitcnt lgkmcnt(0)
	v_mfma_f32_32x32x16_bf16 v[2:17], v[70:73], v[74:77], v[2:17]
	ds_read_b128 v[74:77], v1 offset:55360
	v_mfma_f32_32x32x16_bf16 v[18:33], v[70:73], v[78:81], v[18:33]
	ds_read_b128 v[70:73], v68 offset:18496
	ds_read_b128 v[78:81], v1 offset:59968
	s_waitcnt lgkmcnt(1)
	v_mfma_f32_32x32x16_bf16 v[34:49], v[70:73], v[74:77], v[34:49]
	s_waitcnt lgkmcnt(0)
	v_mfma_f32_32x32x16_bf16 v[50:65], v[70:73], v[78:81], v[50:65]
	ds_read_b128 v[70:73], v68 offset:23104
	s_waitcnt lgkmcnt(0)
	v_mfma_f32_32x32x16_bf16 v[2:17], v[70:73], v[74:77], v[2:17]
	ds_read_b128 v[74:77], v1 offset:55392
	v_mfma_f32_32x32x16_bf16 v[18:33], v[70:73], v[78:81], v[18:33]
	ds_read_b128 v[70:73], v68 offset:18528
	ds_read_b128 v[78:81], v1 offset:60000
	s_waitcnt lgkmcnt(1)
	v_mfma_f32_32x32x16_bf16 v[34:49], v[70:73], v[74:77], v[34:49]
	s_waitcnt lgkmcnt(0)
	v_mfma_f32_32x32x16_bf16 v[50:65], v[70:73], v[78:81], v[50:65]
	ds_read_b128 v[68:71], v68 offset:23136
	s_waitcnt lgkmcnt(0)
	v_mfma_f32_32x32x16_bf16 v[2:17], v[68:71], v[74:77], v[2:17]
	v_mfma_f32_32x32x16_bf16 v[18:33], v[68:71], v[78:81], v[18:33]
	s_setprio 0
	v_mov_b32_e32 v1, v0
	s_barrier
	s_lshl_b64 s[4:5], s[6:7], 1
	v_lshrrev_b32_e32 v66, 1, v1
	v_and_b32_e32 v66, 0xfffffc0, v66
	v_lshrrev_b32_e32 v68, 3, v1
	v_and_or_b32 v66, v68, 4, v66
	v_and_b32_e32 v68, 0x5f, v1
	v_mul_lo_u32 v66, v66, s24
	v_lshl_add_u32 v66, v68, 2, v66
	ds_write2_b32 v66, v34, v50 offset1:32
	v_add_u32_e32 v34, 0x400, v66
	ds_write2_b32 v34, v36, v52 offset0:8 offset1:40
	ds_write2_b32 v34, v37, v53 offset0:140 offset1:172
	v_add_u32_e32 v34, 0x1000, v66
	ds_write2_b32 v34, v38, v54 offset0:32 offset1:64
	ds_write2_b32 v34, v39, v55 offset0:164 offset1:196
	v_add_u32_e32 v34, 0x1400, v66
	ds_write2_b32 v34, v40, v56 offset0:40 offset1:72
	ds_write2_b32 v34, v41, v57 offset0:172 offset1:204
	v_add_u32_e32 v34, 0x2000, v66
	ds_write2_b32 v34, v42, v58 offset0:64 offset1:96
	ds_write2_b32 v34, v43, v59 offset0:196 offset1:228
	v_add_u32_e32 v34, 0x2400, v66
	ds_write2_b32 v34, v44, v60 offset0:72 offset1:104
	ds_write2_b32 v34, v45, v61 offset0:204 offset1:236
	v_add_u32_e32 v34, 0x3000, v66
	ds_write2_b32 v34, v46, v62 offset0:96 offset1:128
	v_add_u32_e32 v34, 0x3200, v66
	ds_write2_b32 v34, v47, v63 offset0:100 offset1:132
	v_add_u32_e32 v34, 0x3400, v66
	ds_write2_b32 v34, v48, v64 offset0:104 offset1:136
	v_add_u32_e32 v34, 0x3600, v66
	ds_write2_b32 v34, v49, v65 offset0:108 offset1:140
	v_add_u32_e32 v34, 0x4000, v66
	ds_write2_b32 v34, v2, v18 offset0:128 offset1:160
	v_add_u32_e32 v2, 0x4400, v66
	ds_write2_b32 v2, v3, v19 offset0:4 offset1:36
	ds_write2_b32 v2, v4, v20 offset0:136 offset1:168
	v_add_u32_e32 v2, 0x4800, v66
	ds_write2_b32 v2, v5, v21 offset0:12 offset1:44
	v_add_u32_e32 v2, 0x5000, v66
	ds_write2_b32 v2, v6, v22 offset0:160 offset1:192
	v_add_u32_e32 v2, 0x5400, v66
	ds_write2_b32 v2, v7, v23 offset0:36 offset1:68
	ds_write2_b32 v2, v8, v24 offset0:168 offset1:200
	v_add_u32_e32 v2, 0x5800, v66
	ds_write2_b32 v2, v9, v25 offset0:44 offset1:76
	v_add_u32_e32 v2, 0x6000, v66
	ds_write2_b32 v2, v10, v26 offset0:192 offset1:224
	v_add_u32_e32 v2, 0x6400, v66
	ds_write2_b32 v2, v11, v27 offset0:68 offset1:100
	ds_write2_b32 v2, v12, v28 offset0:200 offset1:232
	v_add_u32_e32 v2, 0x6800, v66
	ds_write2_b32 v2, v13, v29 offset0:76 offset1:108
	v_add_u32_e32 v2, 0x7200, v66
	ds_write2_b32 v2, v14, v30 offset0:96 offset1:128
	v_add_u32_e32 v2, 0x7400, v66
	ds_write2_b32 v2, v15, v31 offset0:100 offset1:132
	v_add_u32_e32 v2, 0x7600, v66
	ds_write2_b32 v2, v16, v32 offset0:104 offset1:136
	v_add_u32_e32 v2, 0x7800, v66
	ds_write2_b32 v2, v17, v33 offset0:108 offset1:140
	v_lshlrev_b32_e32 v2, 3, v1
	v_and_b32_e32 v3, 0x78, v2
	s_add_u32 s4, s3, s4
	ds_write2_b32 v66, v35, v51 offset0:132 offset1:164
	s_addc_u32 s5, s14, s5
	v_lshlrev_b32_e32 v66, 1, v3
	v_lshlrev_b32_e32 v2, 2, v3
	v_lshl_add_u64 v[4:5], s[4:5], 0, v[66:67]
	s_mov_b32 s4, 0
	s_waitcnt lgkmcnt(0)
	s_barrier

; #define MFMA(a, b, c) __builtin_amdgcn_mfma_f32_32x32x16_bf16((a), (b), (c), 0, 0, 0)
; template <int TM, int TN>
; DI void gemm_mainloop(const u16* __restrict__ A, long lda, const u16* __restrict__ Bt, long ldb, int K, char* smem,
;                       f32x16 (&acc)[TM][TN]) {
;     ...
;   const int nk = K / 64;
;   const int lrow = tid >> 3, lch = (tid & 7) * 8;
;   const u16* gA = A + (long)lrow * lda + lch;
;   const u16* gB = Bt + (long)lrow * ldb + lch;
;   const int soff = lrow * LD + lch;
;     ...
;   GEMM_GLOAD(0)
;   __syncthreads();
;   GEMM_SSTORE(0)
;   if (nk > 1) GEMM_GLOAD(64)
;   __syncthreads();
;   for (int kt = 0; kt < nk; kt++) {
;     const int buf = kt & 1;
;     const u16* cA = sA + buf * BM * LD + (wm * 32 * TM + r) * LD + h * 8;
;     const u16* cB = sB + buf * BN * LD + (wn * 32 * TN + r) * LD + h * 8;
;     bf16x8 af[TM], bfr[TN];
; #pragma unroll
;     for (int tm = 0; tm < TM; tm++) af[tm] = *(const bf16x8*)(cA + tm * 32 * LD);
; #pragma unroll
;     for (int tn = 0; tn < TN; tn++) bfr[tn] = *(const bf16x8*)(cB + tn * 32 * LD);
;     if (kt + 1 < nk) GEMM_SSTORE(buf ^ 1)
;     __builtin_amdgcn_sched_barrier(0);
;     __builtin_amdgcn_s_setprio(1);
; #pragma unroll
;     for (int tm = 0; tm < TM; tm++)
; #pragma unroll
;       for (int tn = 0; tn < TN; tn++) acc[tm][tn] = MFMA(af[tm], bfr[tn], acc[tm][tn]);
; #pragma unroll
;     for (int tm = 0; tm < TM; tm++) af[tm] = *(const bf16x8*)(cA + tm * 32 * LD + 16);
; #pragma unroll
;     for (int tn = 0; tn < TN; tn++) bfr[tn] = *(const bf16x8*)(cB + tn * 32 * LD + 16);
; #pragma unroll
;     for (int tm = 0; tm < TM; tm++)
; #pragma unroll
;       for (int tn = 0; tn < TN; tn++) acc[tm][tn] = MFMA(af[tm], bfr[tn], acc[tm][tn]);
;     __builtin_amdgcn_sched_group_barrier(0x8, 4, 0);
;     if (kt + 2 < nk) GEMM_GLOAD((kt + 2) * 64)
; #pragma unroll
;     for (int ks = 2; ks < 4; ks++) {
; #pragma unroll
;       for (int tm = 0; tm < TM; tm++) af[tm] = *(const bf16x8*)(cA + tm * 32 * LD + ks * 16);
; #pragma unroll
;       for (int tn = 0; tn < TN; tn++) bfr[tn] = *(const bf16x8*)(cB + tn * 32 * LD + ks * 16);
; #pragma unroll
;       for (int tm = 0; tm < TM; tm++)
; #pragma unroll
;         for (int tn = 0; tn < TN; tn++) acc[tm][tn] = MFMA(af[tm], bfr[tn], acc[tm][tn]);
;     }
;     __builtin_amdgcn_s_setprio(0);
;     __syncthreads();
;   }
.LBB0_1553:
	s_mul_hi_u32 s4, s38, 0xcccccccd
	s_lshr_b32 s4, s4, 2
	s_mul_i32 s5, s4, 5
	s_sub_i32 s5, s38, s5
	s_lshl_b32 s39, s4, 11
	s_add_i32 s39, s39, s21
	s_lshl_b32 s6, s5, 9
	s_add_i32 s6, s6, s22
	s_mul_i32 s4, s39, 0x880
	s_mul_hi_i32 s5, s39, 0x880
	s_add_u32 s4, s8, s4
	v_mov_b32_e32 v1, v0
	s_addc_u32 s5, s9, s5
	s_mul_i32 s7, s6, 0x880
	v_lshlrev_b32_e32 v2, 3, v1
	v_ashrrev_i32_e32 v68, 3, v1
	v_and_b32_e32 v69, 56, v2
	v_mov_b64_e32 v[2:3], s[4:5]
	v_mad_i64_i32 v[2:3], s[4:5], v68, s23, v[2:3]
	v_lshlrev_b32_e32 v66, 1, v69
	v_lshl_add_u64 v[72:73], v[2:3], 0, v[66:67]
	s_ashr_i32 s17, s7, 31
	v_add_co_u32_e32 v70, vcc, s25, v72
	s_add_u32 s16, s3, s7
	s_nop 0
	v_addc_co_u32_e32 v71, vcc, 0, v73, vcc
	s_addc_u32 s17, s20, s17
	v_add_co_u32_e32 v74, vcc, s26, v72
	v_mov_b64_e32 v[2:3], s[16:17]
	s_nop 0
	v_addc_co_u32_e32 v75, vcc, 0, v73, vcc
	v_mad_i64_i32 v[18:19], s[4:5], v68, s23, v[2:3]
	v_add_co_u32_e32 v76, vcc, s27, v72
	v_lshl_add_u64 v[78:79], v[18:19], 0, v[66:67]
	s_nop 0
	v_addc_co_u32_e32 v77, vcc, 0, v73, vcc
	v_add_co_u32_e32 v80, vcc, s25, v78
	global_load_dwordx4 v[2:5], v[72:73], off
	s_nop 0
	v_addc_co_u32_e32 v81, vcc, 0, v79, vcc
	v_add_co_u32_e32 v82, vcc, s26, v78
	global_load_dwordx4 v[6:9], v[70:71], off
	s_nop 0
	v_addc_co_u32_e32 v83, vcc, 0, v79, vcc
	v_add_co_u32_e32 v84, vcc, s27, v78
	global_load_dwordx4 v[10:13], v[74:75], off
	s_nop 0
	v_addc_co_u32_e32 v85, vcc, 0, v79, vcc
	global_load_dwordx4 v[14:17], v[76:77], off
	global_load_dwordx4 v[18:21], v[78:79], off
	global_load_dwordx4 v[22:25], v[80:81], off
	global_load_dwordx4 v[26:29], v[82:83], off
	global_load_dwordx4 v[30:33], v[84:85], off
	s_barrier
	global_load_dwordx4 v[34:37], v[72:73], off offset:128
	global_load_dwordx4 v[38:41], v[70:71], off offset:128
	global_load_dwordx4 v[42:45], v[74:75], off offset:128
	global_load_dwordx4 v[46:49], v[76:77], off offset:128
	global_load_dwordx4 v[50:53], v[78:79], off offset:128
	global_load_dwordx4 v[54:57], v[80:81], off offset:128
	global_load_dwordx4 v[58:61], v[82:83], off offset:128
	global_load_dwordx4 v[62:65], v[84:85], off offset:128
	v_and_b32_e32 v66, 31, v1
	v_lshrrev_b32_e32 v86, 1, v1
	v_and_b32_e32 v1, 0x5f, v1
	v_mul_lo_u32 v68, v68, s24
	v_and_or_b32 v87, v86, s28, v66
	v_and_b32_e32 v86, 16, v86
	v_add_lshl_u32 v66, v68, v69, 1
	v_mad_u64_u32 v[68:69], s[4:5], v87, s29, v[86:87]
	v_mad_u32_u24 v1, v1, s29, v86
	v_add_u32_e32 v69, 0x9000, v66
	s_waitcnt vmcnt(15)
	ds_write_b128 v66, v[2:5]
	s_waitcnt vmcnt(14)
	ds_write_b128 v66, v[6:9] offset:4608
	s_waitcnt vmcnt(13)
	ds_write_b128 v66, v[10:13] offset:9216
	s_waitcnt vmcnt(12)
	ds_write_b128 v66, v[14:17] offset:13824
	s_waitcnt vmcnt(11)
	ds_write_b128 v66, v[18:21] offset:36864
	s_waitcnt vmcnt(10)
	ds_write_b128 v66, v[22:25] offset:41472
	s_waitcnt vmcnt(9)
	ds_write_b128 v66, v[26:29] offset:46080
	s_waitcnt vmcnt(8)
	ds_write_b128 v66, v[30:33] offset:50688
	s_waitcnt lgkmcnt(0)
	s_barrier
	ds_read_b128 v[2:5], v68
	ds_read_b128 v[18:21], v68 offset:4608
	ds_read_b128 v[6:9], v1 offset:36864
	ds_read_b128 v[22:25], v1 offset:41472
	s_waitcnt vmcnt(7)
	ds_write_b128 v66, v[34:37] offset:18432
	s_waitcnt vmcnt(6)
	ds_write_b128 v66, v[38:41] offset:23040
	s_waitcnt vmcnt(5)
	ds_write_b128 v66, v[42:45] offset:27648
	s_waitcnt vmcnt(4)
	ds_write_b128 v66, v[46:49] offset:32256
	s_waitcnt vmcnt(3)
	ds_write_b128 v66, v[50:53] offset:55296
	s_waitcnt vmcnt(2)
	ds_write_b128 v66, v[54:57] offset:59904
	s_waitcnt vmcnt(1)
	ds_write_b128 v66, v[58:61] offset:64512
	s_waitcnt vmcnt(0)
	ds_write_b128 v69, v[62:65] offset:32256
	s_setprio 1
	ds_read_b128 v[86:89], v68 offset:32
	s_waitcnt lgkmcnt(10)
	v_mfma_f32_32x32x16_bf16 v[34:49], v[2:5], v[6:9], 0
	ds_read_b128 v[90:93], v1 offset:36896
	ds_read_b128 v[94:97], v1 offset:41504
	ds_read_b128 v[98:101], v68 offset:4704
	global_load_dwordx4 v[102:105], v[70:71], off offset:256
	global_load_dwordx4 v[106:109], v[74:75], off offset:256
	global_load_dwordx4 v[110:113], v[76:77], off offset:256
	global_load_dwordx4 v[114:117], v[84:85], off offset:256
	s_waitcnt lgkmcnt(12)
	v_mfma_f32_32x32x16_bf16 v[50:65], v[2:5], v[22:25], 0
	global_load_dwordx4 v[118:121], v[82:83], off offset:256
	global_load_dwordx4 v[122:125], v[80:81], off offset:256
	global_load_dwordx4 v[140:143], v[72:73], off offset:256
	global_load_dwordx4 v[144:147], v[78:79], off offset:256
	s_waitcnt lgkmcnt(2)
	v_mfma_f32_32x32x16_bf16 v[34:49], v[86:89], v[90:93], v[34:49]
	s_waitcnt lgkmcnt(1)
	v_mfma_f32_32x32x16_bf16 v[50:65], v[86:89], v[94:97], v[50:65]
	ds_read_b128 v[86:89], v68 offset:4640
	v_mfma_f32_32x32x16_bf16 v[2:17], v[18:21], v[6:9], 0
	v_mfma_f32_32x32x16_bf16 v[18:33], v[18:21], v[22:25], 0
	s_waitcnt lgkmcnt(0)
	v_mfma_f32_32x32x16_bf16 v[2:17], v[86:89], v[90:93], v[2:17]
	ds_read_b128 v[90:93], v1 offset:36928
	v_mfma_f32_32x32x16_bf16 v[18:33], v[86:89], v[94:97], v[18:33]
	ds_read_b128 v[86:89], v68 offset:64
	ds_read_b128 v[94:97], v1 offset:41536
	s_waitcnt lgkmcnt(1)
	v_mfma_f32_32x32x16_bf16 v[34:49], v[86:89], v[90:93], v[34:49]
	s_waitcnt lgkmcnt(0)
	v_mfma_f32_32x32x16_bf16 v[50:65], v[86:89], v[94:97], v[50:65]
	ds_read_b128 v[86:89], v68 offset:4672
	s_waitcnt lgkmcnt(0)
	v_mfma_f32_32x32x16_bf16 v[2:17], v[86:89], v[90:93], v[2:17]
	ds_read_b128 v[90:93], v1 offset:36960
	v_mfma_f32_32x32x16_bf16 v[18:33], v[86:89], v[94:97], v[18:33]
	ds_read_b128 v[86:89], v68 offset:96
	ds_read_b128 v[94:97], v1 offset:41568
	s_waitcnt lgkmcnt(1)
	v_mfma_f32_32x32x16_bf16 v[34:49], v[86:89], v[90:93], v[34:49]
	s_waitcnt lgkmcnt(0)
	v_mfma_f32_32x32x16_bf16 v[50:65], v[86:89], v[94:97], v[50:65]
	v_mfma_f32_32x32x16_bf16 v[2:17], v[98:101], v[90:93], v[2:17]
	v_mfma_f32_32x32x16_bf16 v[18:33], v[98:101], v[94:97], v[18:33]
	s_setprio 0
	s_barrier
; #define MFMA(a, b, c) __builtin_amdgcn_mfma_f32_32x32x16_bf16((a), (b), (c), 0, 0, 0)
; template <int TM, int TN>
; DI void gemm_mainloop(const u16* __restrict__ A, long lda, const u16* __restrict__ Bt, long ldb, int K, char* smem,
;                       f32x16 (&acc)[TM][TN]) {
;     ...
;   for (int kt = 0; kt < nk; kt++) {
;     const int buf = kt & 1;
;     const u16* cA = sA + buf * BM * LD + (wm * 32 * TM + r) * LD + h * 8;
;     const u16* cB = sB + buf * BN * LD + (wn * 32 * TN + r) * LD + h * 8;
;     bf16x8 af[TM], bfr[TN];
; #pragma unroll
;     for (int tm = 0; tm < TM; tm++) af[tm] = *(const bf16x8*)(cA + tm * 32 * LD);
; #pragma unroll
;     for (int tn = 0; tn < TN; tn++) bfr[tn] = *(const bf16x8*)(cB + tn * 32 * LD);
;     if (kt + 1 < nk) GEMM_SSTORE(buf ^ 1)
;     __builtin_amdgcn_sched_barrier(0);
;     __builtin_amdgcn_s_setprio(1);
; #pragma unroll
;     for (int tm = 0; tm < TM; tm++)
; #pragma unroll
;       for (int tn = 0; tn < TN; tn++) acc[tm][tn] = MFMA(af[tm], bfr[tn], acc[tm][tn]);
; #pragma unroll
;     for (int tm = 0; tm < TM; tm++) af[tm] = *(const bf16x8*)(cA + tm * 32 * LD + 16);
; #pragma unroll
;     for (int tn = 0; tn < TN; tn++) bfr[tn] = *(const bf16x8*)(cB + tn * 32 * LD + 16);
; #pragma unroll
;     for (int tm = 0; tm < TM; tm++)
; #pragma unroll
;       for (int tn = 0; tn < TN; tn++) acc[tm][tn] = MFMA(af[tm], bfr[tn], acc[tm][tn]);
;     __builtin_amdgcn_sched_group_barrier(0x8, 4, 0);
;     if (kt + 2 < nk) GEMM_GLOAD((kt + 2) * 64)
; #pragma unroll
;     for (int ks = 2; ks < 4; ks++) {
; #pragma unroll
;       for (int tm = 0; tm < TM; tm++) af[tm] = *(const bf16x8*)(cA + tm * 32 * LD + ks * 16);
; #pragma unroll
;       for (int tn = 0; tn < TN; tn++) bfr[tn] = *(const bf16x8*)(cB + tn * 32 * LD + ks * 16);
; #pragma unroll
;       for (int tm = 0; tm < TM; tm++)
; #pragma unroll
;         for (int tn = 0; tn < TN; tn++) acc[tm][tn] = MFMA(af[tm], bfr[tn], acc[tm][tn]);
;     }
;     __builtin_amdgcn_s_setprio(0);
;     __syncthreads();
;   }
	ds_read_b128 v[94:97], v68 offset:18432
	ds_read_b128 v[98:101], v68 offset:23040
	ds_read_b128 v[126:129], v1 offset:55296
	ds_read_b128 v[130:133], v1 offset:59904
	s_setprio 1
	ds_read_b128 v[86:89], v68 offset:18464
	s_waitcnt lgkmcnt(2)
	v_mfma_f32_32x32x16_bf16 v[34:49], v[94:97], v[126:129], v[34:49]
	s_waitcnt vmcnt(1)
	ds_write_b128 v66, v[140:143]
	ds_write_b128 v66, v[102:105] offset:4608
	global_load_dwordx4 v[140:143], v[72:73], off offset:384
	global_load_dwordx4 v[102:105], v[70:71], off offset:384
	ds_read_b128 v[90:93], v1 offset:55328
	s_waitcnt lgkmcnt(4)
	v_mfma_f32_32x32x16_bf16 v[50:65], v[94:97], v[130:133], v[50:65]
	ds_read_b128 v[94:97], v1 offset:59936
	s_waitcnt lgkmcnt(1)
	v_mfma_f32_32x32x16_bf16 v[34:49], v[86:89], v[90:93], v[34:49]
	s_waitcnt lgkmcnt(0)
	v_mfma_f32_32x32x16_bf16 v[50:65], v[86:89], v[94:97], v[50:65]
	ds_write_b128 v66, v[106:109] offset:9216
	ds_write_b128 v66, v[110:113] offset:13824
	global_load_dwordx4 v[106:109], v[74:75], off offset:384
	global_load_dwordx4 v[110:113], v[76:77], off offset:384
	ds_read_b128 v[86:89], v68 offset:23072
	v_mfma_f32_32x32x16_bf16 v[2:17], v[98:101], v[126:129], v[2:17]
	v_mfma_f32_32x32x16_bf16 v[18:33], v[98:101], v[130:133], v[18:33]
	ds_read_b128 v[98:101], v68 offset:23136
	s_waitcnt lgkmcnt(1)
	v_mfma_f32_32x32x16_bf16 v[2:17], v[86:89], v[90:93], v[2:17]
	s_waitcnt vmcnt(4)
	ds_write_b128 v66, v[144:147] offset:36864
	ds_write_b128 v66, v[122:125] offset:41472
	global_load_dwordx4 v[144:147], v[78:79], off offset:384
	global_load_dwordx4 v[122:125], v[80:81], off offset:384
	ds_read_b128 v[90:93], v1 offset:55360
	v_mfma_f32_32x32x16_bf16 v[18:33], v[86:89], v[94:97], v[18:33]
	ds_read_b128 v[86:89], v68 offset:18496
	ds_read_b128 v[94:97], v1 offset:59968
	s_waitcnt lgkmcnt(1)
	v_mfma_f32_32x32x16_bf16 v[34:49], v[86:89], v[90:93], v[34:49]
	s_waitcnt lgkmcnt(0)
	v_mfma_f32_32x32x16_bf16 v[50:65], v[86:89], v[94:97], v[50:65]
	ds_write_b128 v66, v[118:121] offset:46080
	ds_write_b128 v66, v[114:117] offset:50688
	global_load_dwordx4 v[118:121], v[82:83], off offset:384
	global_load_dwordx4 v[114:117], v[84:85], off offset:384
	ds_read_b128 v[86:89], v68 offset:23104
	s_waitcnt lgkmcnt(0)
	v_mfma_f32_32x32x16_bf16 v[2:17], v[86:89], v[90:93], v[2:17]
	ds_read_b128 v[90:93], v1 offset:55392
	v_mfma_f32_32x32x16_bf16 v[18:33], v[86:89], v[94:97], v[18:33]
	ds_read_b128 v[86:89], v68 offset:18528
	ds_read_b128 v[94:97], v1 offset:60000
	s_waitcnt lgkmcnt(1)
	v_mfma_f32_32x32x16_bf16 v[34:49], v[86:89], v[90:93], v[34:49]
	s_waitcnt lgkmcnt(0)
	v_mfma_f32_32x32x16_bf16 v[50:65], v[86:89], v[94:97], v[50:65]
	v_mfma_f32_32x32x16_bf16 v[2:17], v[98:101], v[90:93], v[2:17]
	v_mfma_f32_32x32x16_bf16 v[18:33], v[98:101], v[94:97], v[18:33]
	s_setprio 0
	s_barrier
	ds_read_b128 v[94:97], v68
	ds_read_b128 v[98:101], v68 offset:4608
	ds_read_b128 v[126:129], v1 offset:36864
	ds_read_b128 v[130:133], v1 offset:41472
	s_setprio 1
	ds_read_b128 v[86:89], v68 offset:32
	s_waitcnt lgkmcnt(2)
	v_mfma_f32_32x32x16_bf16 v[34:49], v[94:97], v[126:129], v[34:49]
	s_waitcnt vmcnt(7)
	ds_write_b128 v66, v[140:143] offset:18432
	s_waitcnt vmcnt(6)
	ds_write_b128 v66, v[102:105] offset:23040
	global_load_dwordx4 v[140:143], v[72:73], off offset:512
	global_load_dwordx4 v[102:105], v[70:71], off offset:512
	ds_read_b128 v[90:93], v1 offset:36896
	s_waitcnt lgkmcnt(4)
	v_mfma_f32_32x32x16_bf16 v[50:65], v[94:97], v[130:133], v[50:65]
	ds_read_b128 v[94:97], v1 offset:41504
	s_waitcnt lgkmcnt(1)
	v_mfma_f32_32x32x16_bf16 v[34:49], v[86:89], v[90:93], v[34:49]
	s_waitcnt lgkmcnt(0)
	v_mfma_f32_32x32x16_bf16 v[50:65], v[86:89], v[94:97], v[50:65]
	s_waitcnt vmcnt(7)
	ds_write_b128 v66, v[106:109] offset:27648
	s_waitcnt vmcnt(6)
	ds_write_b128 v66, v[110:113] offset:32256
	global_load_dwordx4 v[106:109], v[74:75], off offset:512
	global_load_dwordx4 v[110:113], v[76:77], off offset:512
	ds_read_b128 v[86:89], v68 offset:4640
	v_mfma_f32_32x32x16_bf16 v[2:17], v[98:101], v[126:129], v[2:17]
	v_mfma_f32_32x32x16_bf16 v[18:33], v[98:101], v[130:133], v[18:33]
	ds_read_b128 v[98:101], v68 offset:4704
	s_waitcnt lgkmcnt(1)
	v_mfma_f32_32x32x16_bf16 v[2:17], v[86:89], v[90:93], v[2:17]
	s_waitcnt vmcnt(7)
	ds_write_b128 v66, v[144:147] offset:55296
	s_waitcnt vmcnt(6)
	ds_write_b128 v66, v[122:125] offset:59904
	global_load_dwordx4 v[144:147], v[78:79], off offset:512
	global_load_dwordx4 v[122:125], v[80:81], off offset:512
	ds_read_b128 v[90:93], v1 offset:36928
	v_mfma_f32_32x32x16_bf16 v[18:33], v[86:89], v[94:97], v[18:33]
	ds_read_b128 v[86:89], v68 offset:64
	ds_read_b128 v[94:97], v1 offset:41536
	s_waitcnt lgkmcnt(1)
	v_mfma_f32_32x32x16_bf16 v[34:49], v[86:89], v[90:93], v[34:49]
	s_waitcnt lgkmcnt(0)
	v_mfma_f32_32x32x16_bf16 v[50:65], v[86:89], v[94:97], v[50:65]
	s_waitcnt vmcnt(7)
	ds_write_b128 v66, v[118:121] offset:64512
	s_waitcnt vmcnt(6)
	ds_write_b128 v69, v[114:117] offset:32256
	global_load_dwordx4 v[118:121], v[82:83], off offset:512
	global_load_dwordx4 v[114:117], v[84:85], off offset:512
	ds_read_b128 v[86:89], v68 offset:4672
	s_waitcnt lgkmcnt(0)
	v_mfma_f32_32x32x16_bf16 v[2:17], v[86:89], v[90:93], v[2:17]
	ds_read_b128 v[90:93], v1 offset:36960
	v_mfma_f32_32x32x16_bf16 v[18:33], v[86:89], v[94:97], v[18:33]
	ds_read_b128 v[86:89], v68 offset:96
	ds_read_b128 v[94:97], v1 offset:41568
	s_waitcnt lgkmcnt(1)
	v_mfma_f32_32x32x16_bf16 v[34:49], v[86:89], v[90:93], v[34:49]
	s_waitcnt lgkmcnt(0)
	v_mfma_f32_32x32x16_bf16 v[50:65], v[86:89], v[94:97], v[50:65]
	v_mfma_f32_32x32x16_bf16 v[2:17], v[98:101], v[90:93], v[2:17]
	v_mfma_f32_32x32x16_bf16 v[18:33], v[98:101], v[94:97], v[18:33]
	s_setprio 0
	s_barrier
; #define MFMA(a, b, c) __builtin_amdgcn_mfma_f32_32x32x16_bf16((a), (b), (c), 0, 0, 0)
; template <int TM, int TN>
; DI void gemm_mainloop(const u16* __restrict__ A, long lda, const u16* __restrict__ Bt, long ldb, int K, char* smem,
;                       f32x16 (&acc)[TM][TN]) {
;     ...
;   for (int kt = 0; kt < nk; kt++) {
;     const int buf = kt & 1;
;     const u16* cA = sA + buf * BM * LD + (wm * 32 * TM + r) * LD + h * 8;
;     const u16* cB = sB + buf * BN * LD + (wn * 32 * TN + r) * LD + h * 8;
;     bf16x8 af[TM], bfr[TN];
; #pragma unroll
;     for (int tm = 0; tm < TM; tm++) af[tm] = *(const bf16x8*)(cA + tm * 32 * LD);
; #pragma unroll
;     for (int tn = 0; tn < TN; tn++) bfr[tn] = *(const bf16x8*)(cB + tn * 32 * LD);
;     if (kt + 1 < nk) GEMM_SSTORE(buf ^ 1)
;     __builtin_amdgcn_sched_barrier(0);
;     __builtin_amdgcn_s_setprio(1);
; #pragma unroll
;     for (int tm = 0; tm < TM; tm++)
; #pragma unroll
;       for (int tn = 0; tn < TN; tn++) acc[tm][tn] = MFMA(af[tm], bfr[tn], acc[tm][tn]);
; #pragma unroll
;     for (int tm = 0; tm < TM; tm++) af[tm] = *(const bf16x8*)(cA + tm * 32 * LD + 16);
; #pragma unroll
;     for (int tn = 0; tn < TN; tn++) bfr[tn] = *(const bf16x8*)(cB + tn * 32 * LD + 16);
; #pragma unroll
;     for (int tm = 0; tm < TM; tm++)
; #pragma unroll
;       for (int tn = 0; tn < TN; tn++) acc[tm][tn] = MFMA(af[tm], bfr[tn], acc[tm][tn]);
;     __builtin_amdgcn_sched_group_barrier(0x8, 4, 0);
;     if (kt + 2 < nk) GEMM_GLOAD((kt + 2) * 64)
; #pragma unroll
;     for (int ks = 2; ks < 4; ks++) {
; #pragma unroll
;       for (int tm = 0; tm < TM; tm++) af[tm] = *(const bf16x8*)(cA + tm * 32 * LD + ks * 16);
; #pragma unroll
;       for (int tn = 0; tn < TN; tn++) bfr[tn] = *(const bf16x8*)(cB + tn * 32 * LD + ks * 16);
; #pragma unroll
;       for (int tm = 0; tm < TM; tm++)
; #pragma unroll
;         for (int tn = 0; tn < TN; tn++) acc[tm][tn] = MFMA(af[tm], bfr[tn], acc[tm][tn]);
;     }
;     __builtin_amdgcn_s_setprio(0);
;     __syncthreads();
;   }
	ds_read_b128 v[94:97], v68 offset:18432
	ds_read_b128 v[98:101], v68 offset:23040
	ds_read_b128 v[126:129], v1 offset:55296
	ds_read_b128 v[130:133], v1 offset:59904
	s_setprio 1
	ds_read_b128 v[86:89], v68 offset:18464
	s_waitcnt lgkmcnt(2)
	v_mfma_f32_32x32x16_bf16 v[34:49], v[94:97], v[126:129], v[34:49]
	s_waitcnt vmcnt(7)
	ds_write_b128 v66, v[140:143]
	s_waitcnt vmcnt(6)
	ds_write_b128 v66, v[102:105] offset:4608
	global_load_dwordx4 v[140:143], v[72:73], off offset:640
	global_load_dwordx4 v[102:105], v[70:71], off offset:640
	ds_read_b128 v[90:93], v1 offset:55328
	s_waitcnt lgkmcnt(4)
	v_mfma_f32_32x32x16_bf16 v[50:65], v[94:97], v[130:133], v[50:65]
	ds_read_b128 v[94:97], v1 offset:59936
	s_waitcnt lgkmcnt(1)
	v_mfma_f32_32x32x16_bf16 v[34:49], v[86:89], v[90:93], v[34:49]
	s_waitcnt lgkmcnt(0)
	v_mfma_f32_32x32x16_bf16 v[50:65], v[86:89], v[94:97], v[50:65]
	s_waitcnt vmcnt(7)
	ds_write_b128 v66, v[106:109] offset:9216
	s_waitcnt vmcnt(6)
	ds_write_b128 v66, v[110:113] offset:13824
	global_load_dwordx4 v[106:109], v[74:75], off offset:640
	global_load_dwordx4 v[110:113], v[76:77], off offset:640
	ds_read_b128 v[86:89], v68 offset:23072
	v_mfma_f32_32x32x16_bf16 v[2:17], v[98:101], v[126:129], v[2:17]
	v_mfma_f32_32x32x16_bf16 v[18:33], v[98:101], v[130:133], v[18:33]
	ds_read_b128 v[98:101], v68 offset:23136
	s_waitcnt lgkmcnt(1)
	v_mfma_f32_32x32x16_bf16 v[2:17], v[86:89], v[90:93], v[2:17]
	s_waitcnt vmcnt(7)
	ds_write_b128 v66, v[144:147] offset:36864
	s_waitcnt vmcnt(6)
	ds_write_b128 v66, v[122:125] offset:41472
	global_load_dwordx4 v[144:147], v[78:79], off offset:640
	global_load_dwordx4 v[122:125], v[80:81], off offset:640
	ds_read_b128 v[90:93], v1 offset:55360
	v_mfma_f32_32x32x16_bf16 v[18:33], v[86:89], v[94:97], v[18:33]
	ds_read_b128 v[86:89], v68 offset:18496
	ds_read_b128 v[94:97], v1 offset:59968
	s_waitcnt lgkmcnt(1)
	v_mfma_f32_32x32x16_bf16 v[34:49], v[86:89], v[90:93], v[34:49]
	s_waitcnt lgkmcnt(0)
	v_mfma_f32_32x32x16_bf16 v[50:65], v[86:89], v[94:97], v[50:65]
	s_waitcnt vmcnt(7)
	ds_write_b128 v66, v[118:121] offset:46080
	s_waitcnt vmcnt(6)
	ds_write_b128 v66, v[114:117] offset:50688
	global_load_dwordx4 v[118:121], v[82:83], off offset:640
	global_load_dwordx4 v[114:117], v[84:85], off offset:640
	ds_read_b128 v[86:89], v68 offset:23104
	s_waitcnt lgkmcnt(0)
	v_mfma_f32_32x32x16_bf16 v[2:17], v[86:89], v[90:93], v[2:17]
	ds_read_b128 v[90:93], v1 offset:55392
	v_mfma_f32_32x32x16_bf16 v[18:33], v[86:89], v[94:97], v[18:33]
	ds_read_b128 v[86:89], v68 offset:18528
	ds_read_b128 v[94:97], v1 offset:60000
	s_waitcnt lgkmcnt(1)
	v_mfma_f32_32x32x16_bf16 v[34:49], v[86:89], v[90:93], v[34:49]
	s_waitcnt lgkmcnt(0)
	v_mfma_f32_32x32x16_bf16 v[50:65], v[86:89], v[94:97], v[50:65]
	v_mfma_f32_32x32x16_bf16 v[2:17], v[98:101], v[90:93], v[2:17]
	v_mfma_f32_32x32x16_bf16 v[18:33], v[98:101], v[94:97], v[18:33]
	s_setprio 0
	s_barrier
	ds_read_b128 v[94:97], v68
	ds_read_b128 v[98:101], v68 offset:4608
	ds_read_b128 v[126:129], v1 offset:36864
	ds_read_b128 v[130:133], v1 offset:41472
	s_setprio 1
	ds_read_b128 v[86:89], v68 offset:32
	s_waitcnt lgkmcnt(2)
	v_mfma_f32_32x32x16_bf16 v[34:49], v[94:97], v[126:129], v[34:49]
	s_waitcnt vmcnt(7)
	ds_write_b128 v66, v[140:143] offset:18432
	s_waitcnt vmcnt(6)
	ds_write_b128 v66, v[102:105] offset:23040
	global_load_dwordx4 v[140:143], v[72:73], off offset:768
	global_load_dwordx4 v[102:105], v[70:71], off offset:768
	ds_read_b128 v[90:93], v1 offset:36896
	s_waitcnt lgkmcnt(4)
	v_mfma_f32_32x32x16_bf16 v[50:65], v[94:97], v[130:133], v[50:65]
	ds_read_b128 v[94:97], v1 offset:41504
	s_waitcnt lgkmcnt(1)
	v_mfma_f32_32x32x16_bf16 v[34:49], v[86:89], v[90:93], v[34:49]
	s_waitcnt lgkmcnt(0)
	v_mfma_f32_32x32x16_bf16 v[50:65], v[86:89], v[94:97], v[50:65]
	s_waitcnt vmcnt(7)
	ds_write_b128 v66, v[106:109] offset:27648
	s_waitcnt vmcnt(6)
	ds_write_b128 v66, v[110:113] offset:32256
	global_load_dwordx4 v[106:109], v[74:75], off offset:768
	global_load_dwordx4 v[110:113], v[76:77], off offset:768
	ds_read_b128 v[86:89], v68 offset:4640
	v_mfma_f32_32x32x16_bf16 v[2:17], v[98:101], v[126:129], v[2:17]
	v_mfma_f32_32x32x16_bf16 v[18:33], v[98:101], v[130:133], v[18:33]
	ds_read_b128 v[98:101], v68 offset:4704
	s_waitcnt lgkmcnt(1)
	v_mfma_f32_32x32x16_bf16 v[2:17], v[86:89], v[90:93], v[2:17]
	s_waitcnt vmcnt(7)
	ds_write_b128 v66, v[144:147] offset:55296
	s_waitcnt vmcnt(6)
	ds_write_b128 v66, v[122:125] offset:59904
	global_load_dwordx4 v[144:147], v[78:79], off offset:768
	global_load_dwordx4 v[122:125], v[80:81], off offset:768
	ds_read_b128 v[90:93], v1 offset:36928
	v_mfma_f32_32x32x16_bf16 v[18:33], v[86:89], v[94:97], v[18:33]
	ds_read_b128 v[86:89], v68 offset:64
	ds_read_b128 v[94:97], v1 offset:41536
	s_waitcnt lgkmcnt(1)
	v_mfma_f32_32x32x16_bf16 v[34:49], v[86:89], v[90:93], v[34:49]
	s_waitcnt lgkmcnt(0)
	v_mfma_f32_32x32x16_bf16 v[50:65], v[86:89], v[94:97], v[50:65]
	s_waitcnt vmcnt(7)
	ds_write_b128 v66, v[118:121] offset:64512
	s_waitcnt vmcnt(6)
	ds_write_b128 v69, v[114:117] offset:32256
	global_load_dwordx4 v[118:121], v[82:83], off offset:768
	global_load_dwordx4 v[114:117], v[84:85], off offset:768
	ds_read_b128 v[86:89], v68 offset:4672
	s_waitcnt lgkmcnt(0)
	v_mfma_f32_32x32x16_bf16 v[2:17], v[86:89], v[90:93], v[2:17]
	ds_read_b128 v[90:93], v1 offset:36960
	v_mfma_f32_32x32x16_bf16 v[18:33], v[86:89], v[94:97], v[18:33]
	ds_read_b128 v[86:89], v68 offset:96
	ds_read_b128 v[94:97], v1 offset:41568
	s_waitcnt lgkmcnt(1)
	v_mfma_f32_32x32x16_bf16 v[34:49], v[86:89], v[90:93], v[34:49]
	s_waitcnt lgkmcnt(0)
	v_mfma_f32_32x32x16_bf16 v[50:65], v[86:89], v[94:97], v[50:65]
	v_mfma_f32_32x32x16_bf16 v[2:17], v[98:101], v[90:93], v[2:17]
	v_mfma_f32_32x32x16_bf16 v[18:33], v[98:101], v[94:97], v[18:33]
	s_setprio 0
	s_barrier
; #define MFMA(a, b, c) __builtin_amdgcn_mfma_f32_32x32x16_bf16((a), (b), (c), 0, 0, 0)
; template <int TM, int TN>
; DI void gemm_mainloop(const u16* __restrict__ A, long lda, const u16* __restrict__ Bt, long ldb, int K, char* smem,
;                       f32x16 (&acc)[TM][TN]) {
;     ...
;   for (int kt = 0; kt < nk; kt++) {
;     const int buf = kt & 1;
;     const u16* cA = sA + buf * BM * LD + (wm * 32 * TM + r) * LD + h * 8;
;     const u16* cB = sB + buf * BN * LD + (wn * 32 * TN + r) * LD + h * 8;
;     bf16x8 af[TM], bfr[TN];
; #pragma unroll
;     for (int tm = 0; tm < TM; tm++) af[tm] = *(const bf16x8*)(cA + tm * 32 * LD);
; #pragma unroll
;     for (int tn = 0; tn < TN; tn++) bfr[tn] = *(const bf16x8*)(cB + tn * 32 * LD);
;     if (kt + 1 < nk) GEMM_SSTORE(buf ^ 1)
;     __builtin_amdgcn_sched_barrier(0);
;     __builtin_amdgcn_s_setprio(1);
; #pragma unroll
;     for (int tm = 0; tm < TM; tm++)
; #pragma unroll
;       for (int tn = 0; tn < TN; tn++) acc[tm][tn] = MFMA(af[tm], bfr[tn], acc[tm][tn]);
; #pragma unroll
;     for (int tm = 0; tm < TM; tm++) af[tm] = *(const bf16x8*)(cA + tm * 32 * LD + 16);
; #pragma unroll
;     for (int tn = 0; tn < TN; tn++) bfr[tn] = *(const bf16x8*)(cB + tn * 32 * LD + 16);
; #pragma unroll
;     for (int tm = 0; tm < TM; tm++)
; #pragma unroll
;       for (int tn = 0; tn < TN; tn++) acc[tm][tn] = MFMA(af[tm], bfr[tn], acc[tm][tn]);
;     __builtin_amdgcn_sched_group_barrier(0x8, 4, 0);
;     if (kt + 2 < nk) GEMM_GLOAD((kt + 2) * 64)
; #pragma unroll
;     for (int ks = 2; ks < 4; ks++) {
; #pragma unroll
;       for (int tm = 0; tm < TM; tm++) af[tm] = *(const bf16x8*)(cA + tm * 32 * LD + ks * 16);
; #pragma unroll
;       for (int tn = 0; tn < TN; tn++) bfr[tn] = *(const bf16x8*)(cB + tn * 32 * LD + ks * 16);
; #pragma unroll
;       for (int tm = 0; tm < TM; tm++)
; #pragma unroll
;         for (int tn = 0; tn < TN; tn++) acc[tm][tn] = MFMA(af[tm], bfr[tn], acc[tm][tn]);
;     }
;     __builtin_amdgcn_s_setprio(0);
;     __syncthreads();
;   }
	ds_read_b128 v[94:97], v68 offset:18432
	ds_read_b128 v[98:101], v68 offset:23040
	ds_read_b128 v[126:129], v1 offset:55296
	ds_read_b128 v[130:133], v1 offset:59904
	s_setprio 1
	ds_read_b128 v[86:89], v68 offset:18464
	s_waitcnt lgkmcnt(2)
	v_mfma_f32_32x32x16_bf16 v[34:49], v[94:97], v[126:129], v[34:49]
	s_waitcnt vmcnt(7)
	ds_write_b128 v66, v[140:143]
	s_waitcnt vmcnt(6)
	ds_write_b128 v66, v[102:105] offset:4608
	global_load_dwordx4 v[140:143], v[72:73], off offset:896
	global_load_dwordx4 v[102:105], v[70:71], off offset:896
	ds_read_b128 v[90:93], v1 offset:55328
	s_waitcnt lgkmcnt(4)
	v_mfma_f32_32x32x16_bf16 v[50:65], v[94:97], v[130:133], v[50:65]
	ds_read_b128 v[94:97], v1 offset:59936
	s_waitcnt lgkmcnt(1)
	v_mfma_f32_32x32x16_bf16 v[34:49], v[86:89], v[90:93], v[34:49]
	s_waitcnt lgkmcnt(0)
	v_mfma_f32_32x32x16_bf16 v[50:65], v[86:89], v[94:97], v[50:65]
	s_waitcnt vmcnt(7)
	ds_write_b128 v66, v[106:109] offset:9216
	s_waitcnt vmcnt(6)
	ds_write_b128 v66, v[110:113] offset:13824
	global_load_dwordx4 v[106:109], v[74:75], off offset:896
	global_load_dwordx4 v[110:113], v[76:77], off offset:896
	ds_read_b128 v[86:89], v68 offset:23072
	v_mfma_f32_32x32x16_bf16 v[2:17], v[98:101], v[126:129], v[2:17]
	v_mfma_f32_32x32x16_bf16 v[18:33], v[98:101], v[130:133], v[18:33]
	ds_read_b128 v[98:101], v68 offset:23136
	s_waitcnt lgkmcnt(1)
	v_mfma_f32_32x32x16_bf16 v[2:17], v[86:89], v[90:93], v[2:17]
	s_waitcnt vmcnt(7)
	ds_write_b128 v66, v[144:147] offset:36864
	s_waitcnt vmcnt(6)
	ds_write_b128 v66, v[122:125] offset:41472
	global_load_dwordx4 v[144:147], v[78:79], off offset:896
	global_load_dwordx4 v[122:125], v[80:81], off offset:896
	ds_read_b128 v[90:93], v1 offset:55360
	v_mfma_f32_32x32x16_bf16 v[18:33], v[86:89], v[94:97], v[18:33]
	ds_read_b128 v[86:89], v68 offset:18496
	ds_read_b128 v[94:97], v1 offset:59968
	s_waitcnt lgkmcnt(1)
	v_mfma_f32_32x32x16_bf16 v[34:49], v[86:89], v[90:93], v[34:49]
	s_waitcnt lgkmcnt(0)
	v_mfma_f32_32x32x16_bf16 v[50:65], v[86:89], v[94:97], v[50:65]
	s_waitcnt vmcnt(7)
	ds_write_b128 v66, v[118:121] offset:46080
	s_waitcnt vmcnt(6)
	ds_write_b128 v66, v[114:117] offset:50688
	global_load_dwordx4 v[118:121], v[82:83], off offset:896
	global_load_dwordx4 v[114:117], v[84:85], off offset:896
	ds_read_b128 v[86:89], v68 offset:23104
	s_waitcnt lgkmcnt(0)
	v_mfma_f32_32x32x16_bf16 v[2:17], v[86:89], v[90:93], v[2:17]
	ds_read_b128 v[90:93], v1 offset:55392
	v_mfma_f32_32x32x16_bf16 v[18:33], v[86:89], v[94:97], v[18:33]
	ds_read_b128 v[86:89], v68 offset:18528
	ds_read_b128 v[94:97], v1 offset:60000
	s_waitcnt lgkmcnt(1)
	v_mfma_f32_32x32x16_bf16 v[34:49], v[86:89], v[90:93], v[34:49]
	s_waitcnt lgkmcnt(0)
	v_mfma_f32_32x32x16_bf16 v[50:65], v[86:89], v[94:97], v[50:65]
	v_mfma_f32_32x32x16_bf16 v[2:17], v[98:101], v[90:93], v[2:17]
	v_mfma_f32_32x32x16_bf16 v[18:33], v[98:101], v[94:97], v[18:33]
	s_setprio 0
	s_barrier
	ds_read_b128 v[94:97], v68
	ds_read_b128 v[98:101], v68 offset:4608
	ds_read_b128 v[126:129], v1 offset:36864
	ds_read_b128 v[130:133], v1 offset:41472
	s_setprio 1
	ds_read_b128 v[86:89], v68 offset:32
	s_waitcnt lgkmcnt(2)
	v_mfma_f32_32x32x16_bf16 v[34:49], v[94:97], v[126:129], v[34:49]
	s_waitcnt vmcnt(7)
	ds_write_b128 v66, v[140:143] offset:18432
	s_waitcnt vmcnt(6)
	ds_write_b128 v66, v[102:105] offset:23040
	global_load_dwordx4 v[140:143], v[72:73], off offset:1024
	global_load_dwordx4 v[102:105], v[70:71], off offset:1024
	ds_read_b128 v[90:93], v1 offset:36896
	s_waitcnt lgkmcnt(4)
	v_mfma_f32_32x32x16_bf16 v[50:65], v[94:97], v[130:133], v[50:65]
	ds_read_b128 v[94:97], v1 offset:41504
	s_waitcnt lgkmcnt(1)
	v_mfma_f32_32x32x16_bf16 v[34:49], v[86:89], v[90:93], v[34:49]
	s_waitcnt lgkmcnt(0)
	v_mfma_f32_32x32x16_bf16 v[50:65], v[86:89], v[94:97], v[50:65]
	s_waitcnt vmcnt(7)
	ds_write_b128 v66, v[106:109] offset:27648
	s_waitcnt vmcnt(6)
	ds_write_b128 v66, v[110:113] offset:32256
	global_load_dwordx4 v[106:109], v[74:75], off offset:1024
	global_load_dwordx4 v[110:113], v[76:77], off offset:1024
	ds_read_b128 v[86:89], v68 offset:4640
	v_mfma_f32_32x32x16_bf16 v[2:17], v[98:101], v[126:129], v[2:17]
	v_mfma_f32_32x32x16_bf16 v[18:33], v[98:101], v[130:133], v[18:33]
	ds_read_b128 v[98:101], v68 offset:4704
	s_waitcnt lgkmcnt(1)
	v_mfma_f32_32x32x16_bf16 v[2:17], v[86:89], v[90:93], v[2:17]
	s_waitcnt vmcnt(7)
	ds_write_b128 v66, v[144:147] offset:55296
	s_waitcnt vmcnt(6)
	ds_write_b128 v66, v[122:125] offset:59904
	global_load_dwordx4 v[144:147], v[78:79], off offset:1024
	global_load_dwordx4 v[122:125], v[80:81], off offset:1024
	ds_read_b128 v[90:93], v1 offset:36928
	v_mfma_f32_32x32x16_bf16 v[18:33], v[86:89], v[94:97], v[18:33]
	ds_read_b128 v[86:89], v68 offset:64
	ds_read_b128 v[94:97], v1 offset:41536
	s_waitcnt lgkmcnt(1)
	v_mfma_f32_32x32x16_bf16 v[34:49], v[86:89], v[90:93], v[34:49]
	s_waitcnt lgkmcnt(0)
	v_mfma_f32_32x32x16_bf16 v[50:65], v[86:89], v[94:97], v[50:65]
	s_waitcnt vmcnt(7)
	ds_write_b128 v66, v[118:121] offset:64512
	s_waitcnt vmcnt(6)
	ds_write_b128 v69, v[114:117] offset:32256
	global_load_dwordx4 v[118:121], v[82:83], off offset:1024
	global_load_dwordx4 v[114:117], v[84:85], off offset:1024
	ds_read_b128 v[86:89], v68 offset:4672
	s_waitcnt lgkmcnt(0)
	v_mfma_f32_32x32x16_bf16 v[2:17], v[86:89], v[90:93], v[2:17]
	ds_read_b128 v[90:93], v1 offset:36960
	v_mfma_f32_32x32x16_bf16 v[18:33], v[86:89], v[94:97], v[18:33]
	ds_read_b128 v[86:89], v68 offset:96
	ds_read_b128 v[94:97], v1 offset:41568
	s_waitcnt lgkmcnt(1)
	v_mfma_f32_32x32x16_bf16 v[34:49], v[86:89], v[90:93], v[34:49]
	s_waitcnt lgkmcnt(0)
	v_mfma_f32_32x32x16_bf16 v[50:65], v[86:89], v[94:97], v[50:65]
	v_mfma_f32_32x32x16_bf16 v[2:17], v[98:101], v[90:93], v[2:17]
	v_mfma_f32_32x32x16_bf16 v[18:33], v[98:101], v[94:97], v[18:33]
	s_setprio 0
	s_barrier
; #define MFMA(a, b, c) __builtin_amdgcn_mfma_f32_32x32x16_bf16((a), (b), (c), 0, 0, 0)
; template <int TM, int TN>
; DI void gemm_mainloop(const u16* __restrict__ A, long lda, const u16* __restrict__ Bt, long ldb, int K, char* smem,
;                       f32x16 (&acc)[TM][TN]) {
;     ...
;   for (int kt = 0; kt < nk; kt++) {
;     const int buf = kt & 1;
;     const u16* cA = sA + buf * BM * LD + (wm * 32 * TM + r) * LD + h * 8;
;     const u16* cB = sB + buf * BN * LD + (wn * 32 * TN + r) * LD + h * 8;
;     bf16x8 af[TM], bfr[TN];
; #pragma unroll
;     for (int tm = 0; tm < TM; tm++) af[tm] = *(const bf16x8*)(cA + tm * 32 * LD);
; #pragma unroll
;     for (int tn = 0; tn < TN; tn++) bfr[tn] = *(const bf16x8*)(cB + tn * 32 * LD);
;     if (kt + 1 < nk) GEMM_SSTORE(buf ^ 1)
;     __builtin_amdgcn_sched_barrier(0);
;     __builtin_amdgcn_s_setprio(1);
; #pragma unroll
;     for (int tm = 0; tm < TM; tm++)
; #pragma unroll
;       for (int tn = 0; tn < TN; tn++) acc[tm][tn] = MFMA(af[tm], bfr[tn], acc[tm][tn]);
; #pragma unroll
;     for (int tm = 0; tm < TM; tm++) af[tm] = *(const bf16x8*)(cA + tm * 32 * LD + 16);
; #pragma unroll
;     for (int tn = 0; tn < TN; tn++) bfr[tn] = *(const bf16x8*)(cB + tn * 32 * LD + 16);
; #pragma unroll
;     for (int tm = 0; tm < TM; tm++)
; #pragma unroll
;       for (int tn = 0; tn < TN; tn++) acc[tm][tn] = MFMA(af[tm], bfr[tn], acc[tm][tn]);
;     __builtin_amdgcn_sched_group_barrier(0x8, 4, 0);
;     if (kt + 2 < nk) GEMM_GLOAD((kt + 2) * 64)
; #pragma unroll
;     for (int ks = 2; ks < 4; ks++) {
; #pragma unroll
;       for (int tm = 0; tm < TM; tm++) af[tm] = *(const bf16x8*)(cA + tm * 32 * LD + ks * 16);
; #pragma unroll
;       for (int tn = 0; tn < TN; tn++) bfr[tn] = *(const bf16x8*)(cB + tn * 32 * LD + ks * 16);
; #pragma unroll
;       for (int tm = 0; tm < TM; tm++)
; #pragma unroll
;         for (int tn = 0; tn < TN; tn++) acc[tm][tn] = MFMA(af[tm], bfr[tn], acc[tm][tn]);
;     }
;     __builtin_amdgcn_s_setprio(0);
;     __syncthreads();
;   }
	ds_read_b128 v[94:97], v68 offset:18432
	ds_read_b128 v[98:101], v68 offset:23040
	ds_read_b128 v[126:129], v1 offset:55296
	ds_read_b128 v[130:133], v1 offset:59904
	s_setprio 1
	ds_read_b128 v[86:89], v68 offset:18464
	s_waitcnt lgkmcnt(2)
	v_mfma_f32_32x32x16_bf16 v[34:49], v[94:97], v[126:129], v[34:49]
	s_waitcnt vmcnt(7)
	ds_write_b128 v66, v[140:143]
	s_waitcnt vmcnt(6)
	ds_write_b128 v66, v[102:105] offset:4608
	global_load_dwordx4 v[140:143], v[72:73], off offset:1152
	global_load_dwordx4 v[102:105], v[70:71], off offset:1152
	ds_read_b128 v[90:93], v1 offset:55328
	s_waitcnt lgkmcnt(4)
	v_mfma_f32_32x32x16_bf16 v[50:65], v[94:97], v[130:133], v[50:65]
	ds_read_b128 v[94:97], v1 offset:59936
	s_waitcnt lgkmcnt(1)
	v_mfma_f32_32x32x16_bf16 v[34:49], v[86:89], v[90:93], v[34:49]
	s_waitcnt lgkmcnt(0)
	v_mfma_f32_32x32x16_bf16 v[50:65], v[86:89], v[94:97], v[50:65]
	s_waitcnt vmcnt(7)
	ds_write_b128 v66, v[106:109] offset:9216
	s_waitcnt vmcnt(6)
	ds_write_b128 v66, v[110:113] offset:13824
	global_load_dwordx4 v[106:109], v[74:75], off offset:1152
	global_load_dwordx4 v[110:113], v[76:77], off offset:1152
	ds_read_b128 v[86:89], v68 offset:23072
	v_mfma_f32_32x32x16_bf16 v[2:17], v[98:101], v[126:129], v[2:17]
	v_mfma_f32_32x32x16_bf16 v[18:33], v[98:101], v[130:133], v[18:33]
	ds_read_b128 v[98:101], v68 offset:23136
	s_waitcnt lgkmcnt(1)
	v_mfma_f32_32x32x16_bf16 v[2:17], v[86:89], v[90:93], v[2:17]
	s_waitcnt vmcnt(7)
	ds_write_b128 v66, v[144:147] offset:36864
	s_waitcnt vmcnt(6)
	ds_write_b128 v66, v[122:125] offset:41472
	global_load_dwordx4 v[144:147], v[78:79], off offset:1152
	global_load_dwordx4 v[122:125], v[80:81], off offset:1152
	ds_read_b128 v[90:93], v1 offset:55360
	v_mfma_f32_32x32x16_bf16 v[18:33], v[86:89], v[94:97], v[18:33]
	ds_read_b128 v[86:89], v68 offset:18496
	ds_read_b128 v[94:97], v1 offset:59968
	s_waitcnt lgkmcnt(1)
	v_mfma_f32_32x32x16_bf16 v[34:49], v[86:89], v[90:93], v[34:49]
	s_waitcnt lgkmcnt(0)
	v_mfma_f32_32x32x16_bf16 v[50:65], v[86:89], v[94:97], v[50:65]
	s_waitcnt vmcnt(7)
	ds_write_b128 v66, v[118:121] offset:46080
	s_waitcnt vmcnt(6)
	ds_write_b128 v66, v[114:117] offset:50688
	global_load_dwordx4 v[118:121], v[82:83], off offset:1152
	global_load_dwordx4 v[114:117], v[84:85], off offset:1152
	ds_read_b128 v[86:89], v68 offset:23104
	s_waitcnt lgkmcnt(0)
	v_mfma_f32_32x32x16_bf16 v[2:17], v[86:89], v[90:93], v[2:17]
	ds_read_b128 v[90:93], v1 offset:55392
	v_mfma_f32_32x32x16_bf16 v[18:33], v[86:89], v[94:97], v[18:33]
	ds_read_b128 v[86:89], v68 offset:18528
	ds_read_b128 v[94:97], v1 offset:60000
	s_waitcnt lgkmcnt(1)
	v_mfma_f32_32x32x16_bf16 v[34:49], v[86:89], v[90:93], v[34:49]
	s_waitcnt lgkmcnt(0)
	v_mfma_f32_32x32x16_bf16 v[50:65], v[86:89], v[94:97], v[50:65]
	v_mfma_f32_32x32x16_bf16 v[2:17], v[98:101], v[90:93], v[2:17]
	v_mfma_f32_32x32x16_bf16 v[18:33], v[98:101], v[94:97], v[18:33]
	s_setprio 0
	s_barrier
	ds_read_b128 v[94:97], v68
	ds_read_b128 v[98:101], v68 offset:4608
	ds_read_b128 v[126:129], v1 offset:36864
	ds_read_b128 v[130:133], v1 offset:41472
	s_setprio 1
	ds_read_b128 v[86:89], v68 offset:32
	s_waitcnt lgkmcnt(2)
	v_mfma_f32_32x32x16_bf16 v[34:49], v[94:97], v[126:129], v[34:49]
	s_waitcnt vmcnt(7)
	ds_write_b128 v66, v[140:143] offset:18432
	s_waitcnt vmcnt(6)
	ds_write_b128 v66, v[102:105] offset:23040
	global_load_dwordx4 v[140:143], v[72:73], off offset:1280
	global_load_dwordx4 v[102:105], v[70:71], off offset:1280
	ds_read_b128 v[90:93], v1 offset:36896
	s_waitcnt lgkmcnt(4)
	v_mfma_f32_32x32x16_bf16 v[50:65], v[94:97], v[130:133], v[50:65]
	ds_read_b128 v[94:97], v1 offset:41504
	s_waitcnt lgkmcnt(1)
	v_mfma_f32_32x32x16_bf16 v[34:49], v[86:89], v[90:93], v[34:49]
	s_waitcnt lgkmcnt(0)
	v_mfma_f32_32x32x16_bf16 v[50:65], v[86:89], v[94:97], v[50:65]
	s_waitcnt vmcnt(7)
	ds_write_b128 v66, v[106:109] offset:27648
	s_waitcnt vmcnt(6)
	ds_write_b128 v66, v[110:113] offset:32256
	global_load_dwordx4 v[106:109], v[74:75], off offset:1280
	global_load_dwordx4 v[110:113], v[76:77], off offset:1280
	ds_read_b128 v[86:89], v68 offset:4640
	v_mfma_f32_32x32x16_bf16 v[2:17], v[98:101], v[126:129], v[2:17]
	v_mfma_f32_32x32x16_bf16 v[18:33], v[98:101], v[130:133], v[18:33]
	ds_read_b128 v[98:101], v68 offset:4704
	s_waitcnt lgkmcnt(1)
	v_mfma_f32_32x32x16_bf16 v[2:17], v[86:89], v[90:93], v[2:17]
	s_waitcnt vmcnt(7)
	ds_write_b128 v66, v[144:147] offset:55296
	s_waitcnt vmcnt(6)
	ds_write_b128 v66, v[122:125] offset:59904
	global_load_dwordx4 v[144:147], v[78:79], off offset:1280
	global_load_dwordx4 v[122:125], v[80:81], off offset:1280
	ds_read_b128 v[90:93], v1 offset:36928
	v_mfma_f32_32x32x16_bf16 v[18:33], v[86:89], v[94:97], v[18:33]
	ds_read_b128 v[86:89], v68 offset:64
	ds_read_b128 v[94:97], v1 offset:41536
	s_waitcnt lgkmcnt(1)
	v_mfma_f32_32x32x16_bf16 v[34:49], v[86:89], v[90:93], v[34:49]
	s_waitcnt lgkmcnt(0)
	v_mfma_f32_32x32x16_bf16 v[50:65], v[86:89], v[94:97], v[50:65]
	s_waitcnt vmcnt(7)
	ds_write_b128 v66, v[118:121] offset:64512
	s_waitcnt vmcnt(6)
	ds_write_b128 v69, v[114:117] offset:32256
	global_load_dwordx4 v[118:121], v[82:83], off offset:1280
	global_load_dwordx4 v[114:117], v[84:85], off offset:1280
	ds_read_b128 v[86:89], v68 offset:4672
	s_waitcnt lgkmcnt(0)
	v_mfma_f32_32x32x16_bf16 v[2:17], v[86:89], v[90:93], v[2:17]
	ds_read_b128 v[90:93], v1 offset:36960
	v_mfma_f32_32x32x16_bf16 v[18:33], v[86:89], v[94:97], v[18:33]
	ds_read_b128 v[86:89], v68 offset:96
	ds_read_b128 v[94:97], v1 offset:41568
	s_waitcnt lgkmcnt(1)
	v_mfma_f32_32x32x16_bf16 v[34:49], v[86:89], v[90:93], v[34:49]
	s_waitcnt lgkmcnt(0)
	v_mfma_f32_32x32x16_bf16 v[50:65], v[86:89], v[94:97], v[50:65]
	v_mfma_f32_32x32x16_bf16 v[2:17], v[98:101], v[90:93], v[2:17]
	v_mfma_f32_32x32x16_bf16 v[18:33], v[98:101], v[94:97], v[18:33]
	s_setprio 0
	s_barrier
; #define MFMA(a, b, c) __builtin_amdgcn_mfma_f32_32x32x16_bf16((a), (b), (c), 0, 0, 0)
; template <int TM, int TN>
; DI void gemm_mainloop(const u16* __restrict__ A, long lda, const u16* __restrict__ Bt, long ldb, int K, char* smem,
;                       f32x16 (&acc)[TM][TN]) {
;     ...
;   for (int kt = 0; kt < nk; kt++) {
;     const int buf = kt & 1;
;     const u16* cA = sA + buf * BM * LD + (wm * 32 * TM + r) * LD + h * 8;
;     const u16* cB = sB + buf * BN * LD + (wn * 32 * TN + r) * LD + h * 8;
;     bf16x8 af[TM], bfr[TN];
; #pragma unroll
;     for (int tm = 0; tm < TM; tm++) af[tm] = *(const bf16x8*)(cA + tm * 32 * LD);
; #pragma unroll
;     for (int tn = 0; tn < TN; tn++) bfr[tn] = *(const bf16x8*)(cB + tn * 32 * LD);
;     if (kt + 1 < nk) GEMM_SSTORE(buf ^ 1)
;     __builtin_amdgcn_sched_barrier(0);
;     __builtin_amdgcn_s_setprio(1);
; #pragma unroll
;     for (int tm = 0; tm < TM; tm++)
; #pragma unroll
;       for (int tn = 0; tn < TN; tn++) acc[tm][tn] = MFMA(af[tm], bfr[tn], acc[tm][tn]);
; #pragma unroll
;     for (int tm = 0; tm < TM; tm++) af[tm] = *(const bf16x8*)(cA + tm * 32 * LD + 16);
; #pragma unroll
;     for (int tn = 0; tn < TN; tn++) bfr[tn] = *(const bf16x8*)(cB + tn * 32 * LD + 16);
; #pragma unroll
;     for (int tm = 0; tm < TM; tm++)
; #pragma unroll
;       for (int tn = 0; tn < TN; tn++) acc[tm][tn] = MFMA(af[tm], bfr[tn], acc[tm][tn]);
;     __builtin_amdgcn_sched_group_barrier(0x8, 4, 0);
;     if (kt + 2 < nk) GEMM_GLOAD((kt + 2) * 64)
; #pragma unroll
;     for (int ks = 2; ks < 4; ks++) {
; #pragma unroll
;       for (int tm = 0; tm < TM; tm++) af[tm] = *(const bf16x8*)(cA + tm * 32 * LD + ks * 16);
; #pragma unroll
;       for (int tn = 0; tn < TN; tn++) bfr[tn] = *(const bf16x8*)(cB + tn * 32 * LD + ks * 16);
; #pragma unroll
;       for (int tm = 0; tm < TM; tm++)
; #pragma unroll
;         for (int tn = 0; tn < TN; tn++) acc[tm][tn] = MFMA(af[tm], bfr[tn], acc[tm][tn]);
;     }
;     __builtin_amdgcn_s_setprio(0);
;     __syncthreads();
;   }
	ds_read_b128 v[94:97], v68 offset:18432
	ds_read_b128 v[98:101], v68 offset:23040
	ds_read_b128 v[126:129], v1 offset:55296
	ds_read_b128 v[130:133], v1 offset:59904
	s_setprio 1
	ds_read_b128 v[86:89], v68 offset:18464
	s_waitcnt lgkmcnt(2)
	v_mfma_f32_32x32x16_bf16 v[34:49], v[94:97], v[126:129], v[34:49]
	s_waitcnt vmcnt(7)
	ds_write_b128 v66, v[140:143]
	s_waitcnt vmcnt(6)
	ds_write_b128 v66, v[102:105] offset:4608
	global_load_dwordx4 v[140:143], v[72:73], off offset:1408
	global_load_dwordx4 v[102:105], v[70:71], off offset:1408
	ds_read_b128 v[90:93], v1 offset:55328
	s_waitcnt lgkmcnt(4)
	v_mfma_f32_32x32x16_bf16 v[50:65], v[94:97], v[130:133], v[50:65]
	ds_read_b128 v[94:97], v1 offset:59936
	s_waitcnt lgkmcnt(1)
	v_mfma_f32_32x32x16_bf16 v[34:49], v[86:89], v[90:93], v[34:49]
	s_waitcnt lgkmcnt(0)
	v_mfma_f32_32x32x16_bf16 v[50:65], v[86:89], v[94:97], v[50:65]
	s_waitcnt vmcnt(7)
	ds_write_b128 v66, v[106:109] offset:9216
	s_waitcnt vmcnt(6)
	ds_write_b128 v66, v[110:113] offset:13824
	global_load_dwordx4 v[106:109], v[74:75], off offset:1408
	global_load_dwordx4 v[110:113], v[76:77], off offset:1408
	ds_read_b128 v[86:89], v68 offset:23072
	v_mfma_f32_32x32x16_bf16 v[2:17], v[98:101], v[126:129], v[2:17]
	v_mfma_f32_32x32x16_bf16 v[18:33], v[98:101], v[130:133], v[18:33]
	ds_read_b128 v[98:101], v68 offset:23136
	s_waitcnt lgkmcnt(1)
	v_mfma_f32_32x32x16_bf16 v[2:17], v[86:89], v[90:93], v[2:17]
	s_waitcnt vmcnt(7)
	ds_write_b128 v66, v[144:147] offset:36864
	s_waitcnt vmcnt(6)
	ds_write_b128 v66, v[122:125] offset:41472
	global_load_dwordx4 v[144:147], v[78:79], off offset:1408
	global_load_dwordx4 v[122:125], v[80:81], off offset:1408
	ds_read_b128 v[90:93], v1 offset:55360
	v_mfma_f32_32x32x16_bf16 v[18:33], v[86:89], v[94:97], v[18:33]
	ds_read_b128 v[86:89], v68 offset:18496
	ds_read_b128 v[94:97], v1 offset:59968
	s_waitcnt lgkmcnt(1)
	v_mfma_f32_32x32x16_bf16 v[34:49], v[86:89], v[90:93], v[34:49]
	s_waitcnt lgkmcnt(0)
	v_mfma_f32_32x32x16_bf16 v[50:65], v[86:89], v[94:97], v[50:65]
	s_waitcnt vmcnt(7)
	ds_write_b128 v66, v[118:121] offset:46080
	s_waitcnt vmcnt(6)
	ds_write_b128 v66, v[114:117] offset:50688
	global_load_dwordx4 v[118:121], v[82:83], off offset:1408
	global_load_dwordx4 v[114:117], v[84:85], off offset:1408
	ds_read_b128 v[86:89], v68 offset:23104
	s_waitcnt lgkmcnt(0)
	v_mfma_f32_32x32x16_bf16 v[2:17], v[86:89], v[90:93], v[2:17]
	ds_read_b128 v[90:93], v1 offset:55392
	v_mfma_f32_32x32x16_bf16 v[18:33], v[86:89], v[94:97], v[18:33]
	ds_read_b128 v[86:89], v68 offset:18528
	ds_read_b128 v[94:97], v1 offset:60000
	s_waitcnt lgkmcnt(1)
	v_mfma_f32_32x32x16_bf16 v[34:49], v[86:89], v[90:93], v[34:49]
	s_waitcnt lgkmcnt(0)
	v_mfma_f32_32x32x16_bf16 v[50:65], v[86:89], v[94:97], v[50:65]
	v_mfma_f32_32x32x16_bf16 v[2:17], v[98:101], v[90:93], v[2:17]
	v_mfma_f32_32x32x16_bf16 v[18:33], v[98:101], v[94:97], v[18:33]
	s_setprio 0
	s_barrier
	ds_read_b128 v[94:97], v68
	ds_read_b128 v[98:101], v68 offset:4608
	ds_read_b128 v[126:129], v1 offset:36864
	ds_read_b128 v[130:133], v1 offset:41472
	s_setprio 1
	ds_read_b128 v[86:89], v68 offset:32
	s_waitcnt lgkmcnt(2)
	v_mfma_f32_32x32x16_bf16 v[34:49], v[94:97], v[126:129], v[34:49]
	s_waitcnt vmcnt(7)
	ds_write_b128 v66, v[140:143] offset:18432
	s_waitcnt vmcnt(6)
	ds_write_b128 v66, v[102:105] offset:23040
	global_load_dwordx4 v[140:143], v[72:73], off offset:1536
	global_load_dwordx4 v[102:105], v[70:71], off offset:1536
	ds_read_b128 v[90:93], v1 offset:36896
	s_waitcnt lgkmcnt(4)
	v_mfma_f32_32x32x16_bf16 v[50:65], v[94:97], v[130:133], v[50:65]
	ds_read_b128 v[94:97], v1 offset:41504
	s_waitcnt lgkmcnt(1)
	v_mfma_f32_32x32x16_bf16 v[34:49], v[86:89], v[90:93], v[34:49]
	s_waitcnt lgkmcnt(0)
	v_mfma_f32_32x32x16_bf16 v[50:65], v[86:89], v[94:97], v[50:65]
	s_waitcnt vmcnt(7)
	ds_write_b128 v66, v[106:109] offset:27648
	s_waitcnt vmcnt(6)
	ds_write_b128 v66, v[110:113] offset:32256
	global_load_dwordx4 v[106:109], v[74:75], off offset:1536
	global_load_dwordx4 v[110:113], v[76:77], off offset:1536
	ds_read_b128 v[86:89], v68 offset:4640
	v_mfma_f32_32x32x16_bf16 v[2:17], v[98:101], v[126:129], v[2:17]
	v_mfma_f32_32x32x16_bf16 v[18:33], v[98:101], v[130:133], v[18:33]
	ds_read_b128 v[98:101], v68 offset:4704
	s_waitcnt lgkmcnt(1)
	v_mfma_f32_32x32x16_bf16 v[2:17], v[86:89], v[90:93], v[2:17]
	s_waitcnt vmcnt(7)
	ds_write_b128 v66, v[144:147] offset:55296
	s_waitcnt vmcnt(6)
	ds_write_b128 v66, v[122:125] offset:59904
	global_load_dwordx4 v[144:147], v[78:79], off offset:1536
	global_load_dwordx4 v[122:125], v[80:81], off offset:1536
	ds_read_b128 v[90:93], v1 offset:36928
	v_mfma_f32_32x32x16_bf16 v[18:33], v[86:89], v[94:97], v[18:33]
	ds_read_b128 v[86:89], v68 offset:64
	ds_read_b128 v[94:97], v1 offset:41536
	s_waitcnt lgkmcnt(1)
	v_mfma_f32_32x32x16_bf16 v[34:49], v[86:89], v[90:93], v[34:49]
	s_waitcnt lgkmcnt(0)
	v_mfma_f32_32x32x16_bf16 v[50:65], v[86:89], v[94:97], v[50:65]
	s_waitcnt vmcnt(7)
	ds_write_b128 v66, v[118:121] offset:64512
	s_waitcnt vmcnt(6)
	ds_write_b128 v69, v[114:117] offset:32256
	global_load_dwordx4 v[118:121], v[82:83], off offset:1536
	global_load_dwordx4 v[114:117], v[84:85], off offset:1536
	ds_read_b128 v[86:89], v68 offset:4672
	s_waitcnt lgkmcnt(0)
	v_mfma_f32_32x32x16_bf16 v[2:17], v[86:89], v[90:93], v[2:17]
	ds_read_b128 v[90:93], v1 offset:36960
	v_mfma_f32_32x32x16_bf16 v[18:33], v[86:89], v[94:97], v[18:33]
	ds_read_b128 v[86:89], v68 offset:96
	ds_read_b128 v[94:97], v1 offset:41568
	s_waitcnt lgkmcnt(1)
	v_mfma_f32_32x32x16_bf16 v[34:49], v[86:89], v[90:93], v[34:49]
	s_waitcnt lgkmcnt(0)
	v_mfma_f32_32x32x16_bf16 v[50:65], v[86:89], v[94:97], v[50:65]
	v_mfma_f32_32x32x16_bf16 v[2:17], v[98:101], v[90:93], v[2:17]
	v_mfma_f32_32x32x16_bf16 v[18:33], v[98:101], v[94:97], v[18:33]
	s_setprio 0
	s_barrier
; #define MFMA(a, b, c) __builtin_amdgcn_mfma_f32_32x32x16_bf16((a), (b), (c), 0, 0, 0)
; template <int TM, int TN>
; DI void gemm_mainloop(const u16* __restrict__ A, long lda, const u16* __restrict__ Bt, long ldb, int K, char* smem,
;                       f32x16 (&acc)[TM][TN]) {
;     ...
;   for (int kt = 0; kt < nk; kt++) {
;     const int buf = kt & 1;
;     const u16* cA = sA + buf * BM * LD + (wm * 32 * TM + r) * LD + h * 8;
;     const u16* cB = sB + buf * BN * LD + (wn * 32 * TN + r) * LD + h * 8;
;     bf16x8 af[TM], bfr[TN];
; #pragma unroll
;     for (int tm = 0; tm < TM; tm++) af[tm] = *(const bf16x8*)(cA + tm * 32 * LD);
; #pragma unroll
;     for (int tn = 0; tn < TN; tn++) bfr[tn] = *(const bf16x8*)(cB + tn * 32 * LD);
;     if (kt + 1 < nk) GEMM_SSTORE(buf ^ 1)
;     __builtin_amdgcn_sched_barrier(0);
;     __builtin_amdgcn_s_setprio(1);
; #pragma unroll
;     for (int tm = 0; tm < TM; tm++)
; #pragma unroll
;       for (int tn = 0; tn < TN; tn++) acc[tm][tn] = MFMA(af[tm], bfr[tn], acc[tm][tn]);
; #pragma unroll
;     for (int tm = 0; tm < TM; tm++) af[tm] = *(const bf16x8*)(cA + tm * 32 * LD + 16);
; #pragma unroll
;     for (int tn = 0; tn < TN; tn++) bfr[tn] = *(const bf16x8*)(cB + tn * 32 * LD + 16);
; #pragma unroll
;     for (int tm = 0; tm < TM; tm++)
; #pragma unroll
;       for (int tn = 0; tn < TN; tn++) acc[tm][tn] = MFMA(af[tm], bfr[tn], acc[tm][tn]);
;     __builtin_amdgcn_sched_group_barrier(0x8, 4, 0);
;     if (kt + 2 < nk) GEMM_GLOAD((kt + 2) * 64)
; #pragma unroll
;     for (int ks = 2; ks < 4; ks++) {
; #pragma unroll
;       for (int tm = 0; tm < TM; tm++) af[tm] = *(const bf16x8*)(cA + tm * 32 * LD + ks * 16);
; #pragma unroll
;       for (int tn = 0; tn < TN; tn++) bfr[tn] = *(const bf16x8*)(cB + tn * 32 * LD + ks * 16);
; #pragma unroll
;       for (int tm = 0; tm < TM; tm++)
; #pragma unroll
;         for (int tn = 0; tn < TN; tn++) acc[tm][tn] = MFMA(af[tm], bfr[tn], acc[tm][tn]);
;     }
;     __builtin_amdgcn_s_setprio(0);
;     __syncthreads();
;   }
	ds_read_b128 v[94:97], v68 offset:18432
	ds_read_b128 v[98:101], v68 offset:23040
	ds_read_b128 v[126:129], v1 offset:55296
	ds_read_b128 v[130:133], v1 offset:59904
	s_setprio 1
	ds_read_b128 v[86:89], v68 offset:18464
	s_waitcnt lgkmcnt(2)
	v_mfma_f32_32x32x16_bf16 v[34:49], v[94:97], v[126:129], v[34:49]
	s_waitcnt vmcnt(7)
	ds_write_b128 v66, v[140:143]
	s_waitcnt vmcnt(6)
	ds_write_b128 v66, v[102:105] offset:4608
	global_load_dwordx4 v[140:143], v[72:73], off offset:1664
	global_load_dwordx4 v[102:105], v[70:71], off offset:1664
	ds_read_b128 v[90:93], v1 offset:55328
	s_waitcnt lgkmcnt(4)
	v_mfma_f32_32x32x16_bf16 v[50:65], v[94:97], v[130:133], v[50:65]
	ds_read_b128 v[94:97], v1 offset:59936
	s_waitcnt lgkmcnt(1)
	v_mfma_f32_32x32x16_bf16 v[34:49], v[86:89], v[90:93], v[34:49]
	s_waitcnt lgkmcnt(0)
	v_mfma_f32_32x32x16_bf16 v[50:65], v[86:89], v[94:97], v[50:65]
	s_waitcnt vmcnt(7)
	ds_write_b128 v66, v[106:109] offset:9216
	s_waitcnt vmcnt(6)
	ds_write_b128 v66, v[110:113] offset:13824
	global_load_dwordx4 v[106:109], v[74:75], off offset:1664
	global_load_dwordx4 v[110:113], v[76:77], off offset:1664
	ds_read_b128 v[86:89], v68 offset:23072
	v_mfma_f32_32x32x16_bf16 v[2:17], v[98:101], v[126:129], v[2:17]
	v_mfma_f32_32x32x16_bf16 v[18:33], v[98:101], v[130:133], v[18:33]
	ds_read_b128 v[98:101], v68 offset:23136
	s_waitcnt lgkmcnt(1)
	v_mfma_f32_32x32x16_bf16 v[2:17], v[86:89], v[90:93], v[2:17]
	s_waitcnt vmcnt(7)
	ds_write_b128 v66, v[144:147] offset:36864
	s_waitcnt vmcnt(6)
	ds_write_b128 v66, v[122:125] offset:41472
	global_load_dwordx4 v[144:147], v[78:79], off offset:1664
	global_load_dwordx4 v[122:125], v[80:81], off offset:1664
	ds_read_b128 v[90:93], v1 offset:55360
	v_mfma_f32_32x32x16_bf16 v[18:33], v[86:89], v[94:97], v[18:33]
	ds_read_b128 v[86:89], v68 offset:18496
	ds_read_b128 v[94:97], v1 offset:59968
	s_waitcnt lgkmcnt(1)
	v_mfma_f32_32x32x16_bf16 v[34:49], v[86:89], v[90:93], v[34:49]
	s_waitcnt lgkmcnt(0)
	v_mfma_f32_32x32x16_bf16 v[50:65], v[86:89], v[94:97], v[50:65]
	s_waitcnt vmcnt(7)
	ds_write_b128 v66, v[118:121] offset:46080
	s_waitcnt vmcnt(6)
	ds_write_b128 v66, v[114:117] offset:50688
	global_load_dwordx4 v[118:121], v[82:83], off offset:1664
	global_load_dwordx4 v[114:117], v[84:85], off offset:1664
	ds_read_b128 v[86:89], v68 offset:23104
	s_waitcnt lgkmcnt(0)
	v_mfma_f32_32x32x16_bf16 v[2:17], v[86:89], v[90:93], v[2:17]
	ds_read_b128 v[90:93], v1 offset:55392
	v_mfma_f32_32x32x16_bf16 v[18:33], v[86:89], v[94:97], v[18:33]
	ds_read_b128 v[86:89], v68 offset:18528
	ds_read_b128 v[94:97], v1 offset:60000
	s_waitcnt lgkmcnt(1)
	v_mfma_f32_32x32x16_bf16 v[34:49], v[86:89], v[90:93], v[34:49]
	s_waitcnt lgkmcnt(0)
	v_mfma_f32_32x32x16_bf16 v[50:65], v[86:89], v[94:97], v[50:65]
	v_mfma_f32_32x32x16_bf16 v[2:17], v[98:101], v[90:93], v[2:17]
	v_mfma_f32_32x32x16_bf16 v[18:33], v[98:101], v[94:97], v[18:33]
	s_setprio 0
	s_barrier
	ds_read_b128 v[94:97], v68
	ds_read_b128 v[98:101], v68 offset:4608
	ds_read_b128 v[126:129], v1 offset:36864
	ds_read_b128 v[130:133], v1 offset:41472
	s_setprio 1
	ds_read_b128 v[86:89], v68 offset:32
	s_waitcnt lgkmcnt(2)
	v_mfma_f32_32x32x16_bf16 v[34:49], v[94:97], v[126:129], v[34:49]
	s_waitcnt vmcnt(7)
	ds_write_b128 v66, v[140:143] offset:18432
	s_waitcnt vmcnt(6)
	ds_write_b128 v66, v[102:105] offset:23040
	global_load_dwordx4 v[140:143], v[72:73], off offset:1792
	global_load_dwordx4 v[102:105], v[70:71], off offset:1792
	ds_read_b128 v[90:93], v1 offset:36896
	s_waitcnt lgkmcnt(4)
	v_mfma_f32_32x32x16_bf16 v[50:65], v[94:97], v[130:133], v[50:65]
	ds_read_b128 v[94:97], v1 offset:41504
	s_waitcnt lgkmcnt(1)
	v_mfma_f32_32x32x16_bf16 v[34:49], v[86:89], v[90:93], v[34:49]
	s_waitcnt lgkmcnt(0)
	v_mfma_f32_32x32x16_bf16 v[50:65], v[86:89], v[94:97], v[50:65]
	s_waitcnt vmcnt(7)
	ds_write_b128 v66, v[106:109] offset:27648
	s_waitcnt vmcnt(6)
	ds_write_b128 v66, v[110:113] offset:32256
	global_load_dwordx4 v[106:109], v[74:75], off offset:1792
	global_load_dwordx4 v[110:113], v[76:77], off offset:1792
	ds_read_b128 v[86:89], v68 offset:4640
	v_mfma_f32_32x32x16_bf16 v[2:17], v[98:101], v[126:129], v[2:17]
	v_mfma_f32_32x32x16_bf16 v[18:33], v[98:101], v[130:133], v[18:33]
	ds_read_b128 v[98:101], v68 offset:4704
	s_waitcnt lgkmcnt(1)
	v_mfma_f32_32x32x16_bf16 v[2:17], v[86:89], v[90:93], v[2:17]
	s_waitcnt vmcnt(7)
	ds_write_b128 v66, v[144:147] offset:55296
	s_waitcnt vmcnt(6)
	ds_write_b128 v66, v[122:125] offset:59904
	global_load_dwordx4 v[144:147], v[78:79], off offset:1792
	global_load_dwordx4 v[122:125], v[80:81], off offset:1792
	ds_read_b128 v[90:93], v1 offset:36928
	v_mfma_f32_32x32x16_bf16 v[18:33], v[86:89], v[94:97], v[18:33]
	ds_read_b128 v[86:89], v68 offset:64
	ds_read_b128 v[94:97], v1 offset:41536
	s_waitcnt lgkmcnt(1)
	v_mfma_f32_32x32x16_bf16 v[34:49], v[86:89], v[90:93], v[34:49]
	s_waitcnt lgkmcnt(0)
	v_mfma_f32_32x32x16_bf16 v[50:65], v[86:89], v[94:97], v[50:65]
	s_waitcnt vmcnt(7)
	ds_write_b128 v66, v[118:121] offset:64512
	s_waitcnt vmcnt(6)
	ds_write_b128 v69, v[114:117] offset:32256
	global_load_dwordx4 v[118:121], v[82:83], off offset:1792
	global_load_dwordx4 v[114:117], v[84:85], off offset:1792
	ds_read_b128 v[86:89], v68 offset:4672
	s_waitcnt lgkmcnt(0)
	v_mfma_f32_32x32x16_bf16 v[2:17], v[86:89], v[90:93], v[2:17]
	ds_read_b128 v[90:93], v1 offset:36960
	v_mfma_f32_32x32x16_bf16 v[18:33], v[86:89], v[94:97], v[18:33]
	ds_read_b128 v[86:89], v68 offset:96
	ds_read_b128 v[94:97], v1 offset:41568
	s_waitcnt lgkmcnt(1)
	v_mfma_f32_32x32x16_bf16 v[34:49], v[86:89], v[90:93], v[34:49]
	s_waitcnt lgkmcnt(0)
	v_mfma_f32_32x32x16_bf16 v[50:65], v[86:89], v[94:97], v[50:65]
	v_mfma_f32_32x32x16_bf16 v[2:17], v[98:101], v[90:93], v[2:17]
	v_mfma_f32_32x32x16_bf16 v[18:33], v[98:101], v[94:97], v[18:33]
	s_setprio 0
	s_barrier
; #define MFMA(a, b, c) __builtin_amdgcn_mfma_f32_32x32x16_bf16((a), (b), (c), 0, 0, 0)
; template <int TM, int TN>
; DI void gemm_mainloop(const u16* __restrict__ A, long lda, const u16* __restrict__ Bt, long ldb, int K, char* smem,
;                       f32x16 (&acc)[TM][TN]) {
;     ...
;   for (int kt = 0; kt < nk; kt++) {
;     const int buf = kt & 1;
;     const u16* cA = sA + buf * BM * LD + (wm * 32 * TM + r) * LD + h * 8;
;     const u16* cB = sB + buf * BN * LD + (wn * 32 * TN + r) * LD + h * 8;
;     bf16x8 af[TM], bfr[TN];
; #pragma unroll
;     for (int tm = 0; tm < TM; tm++) af[tm] = *(const bf16x8*)(cA + tm * 32 * LD);
; #pragma unroll
;     for (int tn = 0; tn < TN; tn++) bfr[tn] = *(const bf16x8*)(cB + tn * 32 * LD);
;     if (kt + 1 < nk) GEMM_SSTORE(buf ^ 1)
;     __builtin_amdgcn_sched_barrier(0);
;     __builtin_amdgcn_s_setprio(1);
; #pragma unroll
;     for (int tm = 0; tm < TM; tm++)
; #pragma unroll
;       for (int tn = 0; tn < TN; tn++) acc[tm][tn] = MFMA(af[tm], bfr[tn], acc[tm][tn]);
; #pragma unroll
;     for (int tm = 0; tm < TM; tm++) af[tm] = *(const bf16x8*)(cA + tm * 32 * LD + 16);
; #pragma unroll
;     for (int tn = 0; tn < TN; tn++) bfr[tn] = *(const bf16x8*)(cB + tn * 32 * LD + 16);
; #pragma unroll
;     for (int tm = 0; tm < TM; tm++)
; #pragma unroll
;       for (int tn = 0; tn < TN; tn++) acc[tm][tn] = MFMA(af[tm], bfr[tn], acc[tm][tn]);
;     __builtin_amdgcn_sched_group_barrier(0x8, 4, 0);
;     if (kt + 2 < nk) GEMM_GLOAD((kt + 2) * 64)
; #pragma unroll
;     for (int ks = 2; ks < 4; ks++) {
; #pragma unroll
;       for (int tm = 0; tm < TM; tm++) af[tm] = *(const bf16x8*)(cA + tm * 32 * LD + ks * 16);
; #pragma unroll
;       for (int tn = 0; tn < TN; tn++) bfr[tn] = *(const bf16x8*)(cB + tn * 32 * LD + ks * 16);
; #pragma unroll
;       for (int tm = 0; tm < TM; tm++)
; #pragma unroll
;         for (int tn = 0; tn < TN; tn++) acc[tm][tn] = MFMA(af[tm], bfr[tn], acc[tm][tn]);
;     }
;     __builtin_amdgcn_s_setprio(0);
;     __syncthreads();
;   }
	ds_read_b128 v[94:97], v68 offset:18432
	ds_read_b128 v[98:101], v68 offset:23040
	ds_read_b128 v[126:129], v1 offset:55296
	ds_read_b128 v[130:133], v1 offset:59904
	s_setprio 1
	ds_read_b128 v[86:89], v68 offset:18464
	s_waitcnt lgkmcnt(2)
	v_mfma_f32_32x32x16_bf16 v[34:49], v[94:97], v[126:129], v[34:49]
	s_waitcnt vmcnt(7)
	ds_write_b128 v66, v[140:143]
	s_waitcnt vmcnt(6)
	ds_write_b128 v66, v[102:105] offset:4608
	global_load_dwordx4 v[140:143], v[72:73], off offset:1920
	global_load_dwordx4 v[102:105], v[70:71], off offset:1920
	ds_read_b128 v[90:93], v1 offset:55328
	s_waitcnt lgkmcnt(4)
	v_mfma_f32_32x32x16_bf16 v[50:65], v[94:97], v[130:133], v[50:65]
	ds_read_b128 v[94:97], v1 offset:59936
	s_waitcnt lgkmcnt(1)
	v_mfma_f32_32x32x16_bf16 v[34:49], v[86:89], v[90:93], v[34:49]
	s_waitcnt lgkmcnt(0)
	v_mfma_f32_32x32x16_bf16 v[50:65], v[86:89], v[94:97], v[50:65]
	s_waitcnt vmcnt(7)
	ds_write_b128 v66, v[106:109] offset:9216
	s_waitcnt vmcnt(6)
	ds_write_b128 v66, v[110:113] offset:13824
	global_load_dwordx4 v[106:109], v[74:75], off offset:1920
	global_load_dwordx4 v[110:113], v[76:77], off offset:1920
	ds_read_b128 v[86:89], v68 offset:23072
	v_mfma_f32_32x32x16_bf16 v[2:17], v[98:101], v[126:129], v[2:17]
	v_mfma_f32_32x32x16_bf16 v[18:33], v[98:101], v[130:133], v[18:33]
	ds_read_b128 v[98:101], v68 offset:23136
	s_waitcnt lgkmcnt(1)
	v_mfma_f32_32x32x16_bf16 v[2:17], v[86:89], v[90:93], v[2:17]
	s_waitcnt vmcnt(7)
	ds_write_b128 v66, v[144:147] offset:36864
	s_waitcnt vmcnt(6)
	ds_write_b128 v66, v[122:125] offset:41472
	global_load_dwordx4 v[144:147], v[78:79], off offset:1920
	global_load_dwordx4 v[122:125], v[80:81], off offset:1920
	ds_read_b128 v[90:93], v1 offset:55360
	v_mfma_f32_32x32x16_bf16 v[18:33], v[86:89], v[94:97], v[18:33]
	ds_read_b128 v[86:89], v68 offset:18496
	ds_read_b128 v[94:97], v1 offset:59968
	s_waitcnt lgkmcnt(1)
	v_mfma_f32_32x32x16_bf16 v[34:49], v[86:89], v[90:93], v[34:49]
	s_waitcnt lgkmcnt(0)
	v_mfma_f32_32x32x16_bf16 v[50:65], v[86:89], v[94:97], v[50:65]
	s_waitcnt vmcnt(7)
	ds_write_b128 v66, v[118:121] offset:46080
	s_waitcnt vmcnt(6)
	ds_write_b128 v66, v[114:117] offset:50688
	global_load_dwordx4 v[118:121], v[82:83], off offset:1920
	global_load_dwordx4 v[114:117], v[84:85], off offset:1920
	ds_read_b128 v[86:89], v68 offset:23104
	s_waitcnt lgkmcnt(0)
	v_mfma_f32_32x32x16_bf16 v[2:17], v[86:89], v[90:93], v[2:17]
	ds_read_b128 v[90:93], v1 offset:55392
	v_mfma_f32_32x32x16_bf16 v[18:33], v[86:89], v[94:97], v[18:33]
	ds_read_b128 v[86:89], v68 offset:18528
	ds_read_b128 v[94:97], v1 offset:60000
	s_waitcnt lgkmcnt(1)
	v_mfma_f32_32x32x16_bf16 v[34:49], v[86:89], v[90:93], v[34:49]
	s_waitcnt lgkmcnt(0)
	v_mfma_f32_32x32x16_bf16 v[50:65], v[86:89], v[94:97], v[50:65]
	s_nop 0
	v_mfma_f32_32x32x16_bf16 v[2:17], v[98:101], v[90:93], v[2:17]
	v_mfma_f32_32x32x16_bf16 v[18:33], v[98:101], v[94:97], v[18:33]
	s_setprio 0
	s_barrier
	ds_read_b128 v[74:77], v68
	ds_read_b128 v[78:81], v68 offset:4608
	ds_read_b128 v[82:85], v1 offset:36864
	ds_read_b128 v[90:93], v1 offset:41472
	s_setprio 1
	ds_read_b128 v[70:73], v68 offset:32
	s_waitcnt lgkmcnt(2)
	v_mfma_f32_32x32x16_bf16 v[34:49], v[74:77], v[82:85], v[34:49]
	s_waitcnt vmcnt(7)
	ds_write_b128 v66, v[140:143] offset:18432
	s_waitcnt vmcnt(6)
	ds_write_b128 v66, v[102:105] offset:23040
	s_waitcnt lgkmcnt(3)
	v_mfma_f32_32x32x16_bf16 v[50:65], v[74:77], v[90:93], v[50:65]
	ds_read_b128 v[74:77], v1 offset:36896
	v_mfma_f32_32x32x16_bf16 v[2:17], v[78:81], v[82:85], v[2:17]
	v_mfma_f32_32x32x16_bf16 v[18:33], v[78:81], v[90:93], v[18:33]
	s_waitcnt vmcnt(5)
	ds_write_b128 v66, v[106:109] offset:27648
	s_waitcnt vmcnt(4)
	ds_write_b128 v66, v[110:113] offset:32256
	ds_read_b128 v[78:81], v1 offset:41504
	s_waitcnt lgkmcnt(3)
	v_mfma_f32_32x32x16_bf16 v[34:49], v[70:73], v[74:77], v[34:49]
	s_waitcnt lgkmcnt(0)
	v_mfma_f32_32x32x16_bf16 v[50:65], v[70:73], v[78:81], v[50:65]
	ds_read_b128 v[70:73], v68 offset:4640
	s_waitcnt lgkmcnt(0)
	v_mfma_f32_32x32x16_bf16 v[2:17], v[70:73], v[74:77], v[2:17]
	s_waitcnt vmcnt(3)
	ds_write_b128 v66, v[144:147] offset:55296
	s_waitcnt vmcnt(2)
	ds_write_b128 v66, v[122:125] offset:59904
	ds_read_b128 v[74:77], v1 offset:36928
	v_mfma_f32_32x32x16_bf16 v[18:33], v[70:73], v[78:81], v[18:33]
	ds_read_b128 v[70:73], v68 offset:64
	ds_read_b128 v[78:81], v1 offset:41536
	s_waitcnt lgkmcnt(1)
	v_mfma_f32_32x32x16_bf16 v[34:49], v[70:73], v[74:77], v[34:49]
	s_waitcnt lgkmcnt(0)
	v_mfma_f32_32x32x16_bf16 v[50:65], v[70:73], v[78:81], v[50:65]
	s_waitcnt vmcnt(1)
	ds_write_b128 v66, v[118:121] offset:64512
	s_waitcnt vmcnt(0)
	ds_write_b128 v69, v[114:117] offset:32256
	ds_read_b128 v[70:73], v68 offset:4672
	s_waitcnt lgkmcnt(0)
	v_mfma_f32_32x32x16_bf16 v[2:17], v[70:73], v[74:77], v[2:17]
	ds_read_b128 v[74:77], v1 offset:36960
	v_mfma_f32_32x32x16_bf16 v[18:33], v[70:73], v[78:81], v[18:33]
	ds_read_b128 v[70:73], v68 offset:96
	ds_read_b128 v[78:81], v1 offset:41568
	s_waitcnt lgkmcnt(1)
	v_mfma_f32_32x32x16_bf16 v[34:49], v[70:73], v[74:77], v[34:49]
	s_waitcnt lgkmcnt(0)
	v_mfma_f32_32x32x16_bf16 v[50:65], v[70:73], v[78:81], v[50:65]
	ds_read_b128 v[70:73], v68 offset:4704
	s_waitcnt lgkmcnt(0)
	v_mfma_f32_32x32x16_bf16 v[2:17], v[70:73], v[74:77], v[2:17]
	v_mfma_f32_32x32x16_bf16 v[18:33], v[70:73], v[78:81], v[18:33]
	s_setprio 0
	s_barrier
; template <int TM, int TN>
; DI void gemm_mainloop(const u16* __restrict__ A, long lda, const u16* __restrict__ Bt, long ldb, int K, char* smem,
;                       f32x16 (&acc)[TM][TN]) {
;     ...
;     for (int tm = 0; tm < TM; tm++)
; #pragma unroll
;       for (int tn = 0; tn < TN; tn++) acc[tm][tn] = MFMA(af[tm], bfr[tn], acc[tm][tn]);
; #pragma unroll
;     for (int tm = 0; tm < TM; tm++) af[tm] = *(const bf16x8*)(cA + tm * 32 * LD + 16);
; #pragma unroll
;     for (int tn = 0; tn < TN; tn++) bfr[tn] = *(const bf16x8*)(cB + tn * 32 * LD + 16);
; #pragma unroll
;     for (int tm = 0; tm < TM; tm++)
; #pragma unroll
;       for (int tn = 0; tn < TN; tn++) acc[tm][tn] = MFMA(af[tm], bfr[tn], acc[tm][tn]);
;     __builtin_amdgcn_sched_group_barrier(0x8, 4, 0);
;     if (kt + 2 < nk) GEMM_GLOAD((kt + 2) * 64)
; #pragma unroll
;     for (int ks = 2; ks < 4; ks++) {
; #pragma unroll
;       for (int tm = 0; tm < TM; tm++) af[tm] = *(const bf16x8*)(cA + tm * 32 * LD + ks * 16);
; #pragma unroll
;       for (int tn = 0; tn < TN; tn++) bfr[tn] = *(const bf16x8*)(cB + tn * 32 * LD + ks * 16);
; #pragma unroll
;       for (int tm = 0; tm < TM; tm++)
; #pragma unroll
;         for (int tn = 0; tn < TN; tn++) acc[tm][tn] = MFMA(af[tm], bfr[tn], acc[tm][tn]);
;     }
;     __builtin_amdgcn_s_setprio(0);
;     __syncthreads();
;   }
; template <int TM, int TN, class Epi>
; DI void gemm_tile(const u16* A, long lda, const u16* Bt, long ldb, int K, int m0, int n0, char* smem, const Epi& epi) {
;     ...
;   const int tid = tidx(), lane = tid & 63, w = tid >> 6, r = lane & 31, h = lane >> 5;
;   const int wm = w >> 1, wn = w & 1;
;   float* Ct = (float*)smem;
; #pragma unroll
;   for (int tm = 0; tm < TM; tm++)
; #pragma unroll
;     for (int tn = 0; tn < TN; tn++)
; #pragma unroll
;       for (int i = 0; i < 16; i++)
;         Ct[(wm * 32 * TM + tm * 32 + crow(i, h)) * LDC + wn * 32 * TN + tn * 32 + r] = acc[tm][tn][i];
;   __syncthreads();
;   epi(Ct, LDC, m0, n0, tid, BM);
;   __syncthreads();
;   (void)BM;
; }
;   DI void operator()(const float* Ct, int ldc, int m0, int n0, int tid, int bm) const {
; #pragma unroll 4
;     for (int it = 0; it < bm / 16; it++) {
;       int id = tid + 256 * it; int row = id >> 4, c8 = (id & 15) * 8;
;       int n = n0 + c8;
;       if (n < nmax) {
;         const float* c = Ct + row * ldc + c8;
	ds_read_b128 v[70:73], v68 offset:18432
	ds_read_b128 v[74:77], v68 offset:23040
	ds_read_b128 v[78:81], v1 offset:55296
	ds_read_b128 v[82:85], v1 offset:59904
	s_setprio 1
	s_waitcnt lgkmcnt(1)
	v_mfma_f32_32x32x16_bf16 v[34:49], v[70:73], v[78:81], v[34:49]
	s_waitcnt lgkmcnt(0)
	v_mfma_f32_32x32x16_bf16 v[50:65], v[70:73], v[82:85], v[50:65]
	ds_read_b128 v[70:73], v68 offset:18464
	v_mfma_f32_32x32x16_bf16 v[2:17], v[74:77], v[78:81], v[2:17]
	ds_read_b128 v[78:81], v1 offset:59936
	v_mfma_f32_32x32x16_bf16 v[18:33], v[74:77], v[82:85], v[18:33]
	ds_read_b128 v[74:77], v1 offset:55328
	s_waitcnt lgkmcnt(0)
	v_mfma_f32_32x32x16_bf16 v[34:49], v[70:73], v[74:77], v[34:49]
	v_mfma_f32_32x32x16_bf16 v[50:65], v[70:73], v[78:81], v[50:65]
	ds_read_b128 v[70:73], v68 offset:23072
	s_waitcnt lgkmcnt(0)
	v_mfma_f32_32x32x16_bf16 v[2:17], v[70:73], v[74:77], v[2:17]
	ds_read_b128 v[74:77], v1 offset:55360
	v_mfma_f32_32x32x16_bf16 v[18:33], v[70:73], v[78:81], v[18:33]
	ds_read_b128 v[70:73], v68 offset:18496
	ds_read_b128 v[78:81], v1 offset:59968
	s_waitcnt lgkmcnt(1)
	v_mfma_f32_32x32x16_bf16 v[34:49], v[70:73], v[74:77], v[34:49]
	s_waitcnt lgkmcnt(0)
	v_mfma_f32_32x32x16_bf16 v[50:65], v[70:73], v[78:81], v[50:65]
	ds_read_b128 v[70:73], v68 offset:23104
	s_waitcnt lgkmcnt(0)
	v_mfma_f32_32x32x16_bf16 v[2:17], v[70:73], v[74:77], v[2:17]
	ds_read_b128 v[74:77], v1 offset:55392
	v_mfma_f32_32x32x16_bf16 v[18:33], v[70:73], v[78:81], v[18:33]
	ds_read_b128 v[70:73], v68 offset:18528
	ds_read_b128 v[78:81], v1 offset:60000
	s_waitcnt lgkmcnt(1)
	v_mfma_f32_32x32x16_bf16 v[34:49], v[70:73], v[74:77], v[34:49]
	s_waitcnt lgkmcnt(0)
	v_mfma_f32_32x32x16_bf16 v[50:65], v[70:73], v[78:81], v[50:65]
	ds_read_b128 v[68:71], v68 offset:23136
	s_waitcnt lgkmcnt(0)
	v_mfma_f32_32x32x16_bf16 v[2:17], v[68:71], v[74:77], v[2:17]
	v_mfma_f32_32x32x16_bf16 v[18:33], v[68:71], v[78:81], v[18:33]
	s_setprio 0
	v_mov_b32_e32 v1, v0
	s_barrier
	s_mov_b32 s4, 0
	v_lshrrev_b32_e32 v66, 1, v1
	v_and_b32_e32 v66, 0xfffffc0, v66
	v_lshrrev_b32_e32 v68, 3, v1
	v_and_or_b32 v66, v68, 4, v66
	v_and_b32_e32 v68, 0x5f, v1
	v_mul_lo_u32 v66, v66, s30
	v_lshl_add_u32 v66, v68, 2, v66
	ds_write2_b32 v66, v34, v50 offset1:32
	v_add_u32_e32 v34, 0x400, v66
	ds_write2_b32 v34, v36, v52 offset0:8 offset1:40
	ds_write2_b32 v34, v37, v53 offset0:140 offset1:172
	v_add_u32_e32 v34, 0x1000, v66
	ds_write2_b32 v34, v38, v54 offset0:32 offset1:64
	ds_write2_b32 v34, v39, v55 offset0:164 offset1:196
	v_add_u32_e32 v34, 0x1400, v66
	ds_write2_b32 v34, v40, v56 offset0:40 offset1:72
	ds_write2_b32 v34, v41, v57 offset0:172 offset1:204
	v_add_u32_e32 v34, 0x2000, v66
	ds_write2_b32 v34, v42, v58 offset0:64 offset1:96
	ds_write2_b32 v34, v43, v59 offset0:196 offset1:228
	v_add_u32_e32 v34, 0x2400, v66
	ds_write2_b32 v34, v44, v60 offset0:72 offset1:104
	ds_write2_b32 v34, v45, v61 offset0:204 offset1:236
	v_add_u32_e32 v34, 0x3000, v66
	ds_write2_b32 v34, v46, v62 offset0:96 offset1:128
	v_add_u32_e32 v34, 0x3200, v66
	ds_write2_b32 v34, v47, v63 offset0:100 offset1:132
	v_add_u32_e32 v34, 0x3400, v66
	ds_write2_b32 v34, v48, v64 offset0:104 offset1:136
	v_add_u32_e32 v34, 0x3600, v66
	ds_write2_b32 v34, v49, v65 offset0:108 offset1:140
	v_add_u32_e32 v34, 0x4000, v66
	ds_write2_b32 v34, v2, v18 offset0:128 offset1:160
	v_add_u32_e32 v2, 0x4400, v66
	ds_write2_b32 v2, v3, v19 offset0:4 offset1:36
	ds_write2_b32 v2, v4, v20 offset0:136 offset1:168
	v_add_u32_e32 v2, 0x4800, v66
	ds_write2_b32 v2, v5, v21 offset0:12 offset1:44
	v_add_u32_e32 v2, 0x5000, v66
	ds_write2_b32 v2, v6, v22 offset0:160 offset1:192
	v_add_u32_e32 v2, 0x5400, v66
	ds_write2_b32 v2, v7, v23 offset0:36 offset1:68
	ds_write2_b32 v2, v8, v24 offset0:168 offset1:200
	v_add_u32_e32 v2, 0x5800, v66
	ds_write2_b32 v2, v9, v25 offset0:44 offset1:76
	v_add_u32_e32 v2, 0x6000, v66
	ds_write2_b32 v2, v10, v26 offset0:192 offset1:224
	v_add_u32_e32 v2, 0x6400, v66
	ds_write2_b32 v2, v11, v27 offset0:68 offset1:100
	ds_write2_b32 v2, v12, v28 offset0:200 offset1:232
	v_add_u32_e32 v2, 0x6800, v66
	ds_write2_b32 v2, v13, v29 offset0:76 offset1:108
	v_add_u32_e32 v2, 0x7200, v66
	ds_write2_b32 v2, v14, v30 offset0:96 offset1:128
	v_add_u32_e32 v2, 0x7400, v66
	ds_write2_b32 v2, v15, v31 offset0:100 offset1:132
	v_add_u32_e32 v2, 0x7600, v66
	ds_write2_b32 v2, v16, v32 offset0:104 offset1:136
	v_add_u32_e32 v2, 0x7800, v66
	ds_write2_b32 v2, v17, v33 offset0:108 offset1:140
	v_lshlrev_b32_e32 v2, 3, v1
	v_and_b32_e32 v3, 0x78, v2
	v_or_b32_e32 v2, s6, v3
	v_lshlrev_b32_e32 v10, 2, v3
	v_ashrrev_i32_e32 v3, 31, v2
	v_cmp_eq_u32_e32 vcc, s31, v2
	v_cmp_gt_i32_e64 s[6:7], s36, v2
	v_lshl_add_u64 v[12:13], v[2:3], 1, s[14:15]
	ds_write2_b32 v66, v35, v51 offset0:132 offset1:164
	s_waitcnt lgkmcnt(0)
	s_barrier
	s_branch .LBB0_1555

; #define MFMA(a, b, c) __builtin_amdgcn_mfma_f32_32x32x16_bf16((a), (b), (c), 0, 0, 0)
; template <int TM, int TN>
; DI void gemm_mainloop(const u16* __restrict__ A, long lda, const u16* __restrict__ Bt, long ldb, int K, char* smem,
;                       f32x16 (&acc)[TM][TN]) {
;     ...
;   const int nk = K / 64;
;   const int lrow = tid >> 3, lch = (tid & 7) * 8;
;   const u16* gA = A + (long)lrow * lda + lch;
;   const u16* gB = Bt + (long)lrow * ldb + lch;
;   const int soff = lrow * LD + lch;
;     ...
;   GEMM_GLOAD(0)
;   __syncthreads();
;   GEMM_SSTORE(0)
;   if (nk > 1) GEMM_GLOAD(64)
;   __syncthreads();
;   for (int kt = 0; kt < nk; kt++) {
;     const int buf = kt & 1;
;     const u16* cA = sA + buf * BM * LD + (wm * 32 * TM + r) * LD + h * 8;
;     const u16* cB = sB + buf * BN * LD + (wn * 32 * TN + r) * LD + h * 8;
;     bf16x8 af[TM], bfr[TN];
; #pragma unroll
;     for (int tm = 0; tm < TM; tm++) af[tm] = *(const bf16x8*)(cA + tm * 32 * LD);
; #pragma unroll
;     for (int tn = 0; tn < TN; tn++) bfr[tn] = *(const bf16x8*)(cB + tn * 32 * LD);
;     if (kt + 1 < nk) GEMM_SSTORE(buf ^ 1)
;     __builtin_amdgcn_sched_barrier(0);
;     __builtin_amdgcn_s_setprio(1);
; #pragma unroll
;     for (int tm = 0; tm < TM; tm++)
; #pragma unroll
;       for (int tn = 0; tn < TN; tn++) acc[tm][tn] = MFMA(af[tm], bfr[tn], acc[tm][tn]);
; #pragma unroll
;     for (int tm = 0; tm < TM; tm++) af[tm] = *(const bf16x8*)(cA + tm * 32 * LD + 16);
; #pragma unroll
;     for (int tn = 0; tn < TN; tn++) bfr[tn] = *(const bf16x8*)(cB + tn * 32 * LD + 16);
; #pragma unroll
;     for (int tm = 0; tm < TM; tm++)
; #pragma unroll
;       for (int tn = 0; tn < TN; tn++) acc[tm][tn] = MFMA(af[tm], bfr[tn], acc[tm][tn]);
;     __builtin_amdgcn_sched_group_barrier(0x8, 4, 0);
;     if (kt + 2 < nk) GEMM_GLOAD((kt + 2) * 64)
; #pragma unroll
;     for (int ks = 2; ks < 4; ks++) {
; #pragma unroll
;       for (int tm = 0; tm < TM; tm++) af[tm] = *(const bf16x8*)(cA + tm * 32 * LD + ks * 16);
; #pragma unroll
;       for (int tn = 0; tn < TN; tn++) bfr[tn] = *(const bf16x8*)(cB + tn * 32 * LD + ks * 16);
; #pragma unroll
;       for (int tm = 0; tm < TM; tm++)
; #pragma unroll
;         for (int tn = 0; tn < TN; tn++) acc[tm][tn] = MFMA(af[tm], bfr[tn], acc[tm][tn]);
;     }
;     __builtin_amdgcn_s_setprio(0);
;     __syncthreads();
;   }
.LBB0_2474:
	s_lshl_b32 s25, s24, 10
	s_add_i32 s25, s25, s10
	s_mul_i32 s6, s25, 0x880
	s_mul_hi_i32 s7, s25, 0x880
	s_add_u32 s6, s4, s6
	v_mov_b32_e32 v1, v0
	s_addc_u32 s7, s5, s7
	s_nop 0
	v_lshlrev_b32_e32 v2, 3, v1
	v_ashrrev_i32_e32 v70, 3, v1
	v_and_b32_e32 v71, 56, v2
	v_mov_b64_e32 v[2:3], s[6:7]
	v_mad_i64_i32 v[2:3], s[6:7], v70, s15, v[2:3]
	v_lshlrev_b32_e32 v66, 1, v71
	v_lshl_add_u64 v[74:75], v[2:3], 0, v[66:67]
	v_add_co_u32_e32 v72, vcc, s17, v74
	v_mad_i64_i32 v[10:11], s[6:7], v70, s15, v[68:69]
	s_nop 0
	v_addc_co_u32_e32 v73, vcc, 0, v75, vcc
	v_add_co_u32_e32 v76, vcc, s18, v74
	v_lshl_add_u64 v[78:79], v[10:11], 0, v[66:67]
	s_nop 0
	v_addc_co_u32_e32 v77, vcc, 0, v75, vcc
	v_add_co_u32_e32 v80, vcc, s17, v78
	global_load_dwordx4 v[2:5], v[74:75], off
	s_nop 0
	v_addc_co_u32_e32 v81, vcc, 0, v79, vcc
	v_add_co_u32_e32 v82, vcc, s18, v78
	global_load_dwordx4 v[6:9], v[72:73], off
	s_nop 0
	v_addc_co_u32_e32 v83, vcc, 0, v79, vcc
	v_add_co_u32_e32 v84, vcc, s19, v78
	global_load_dwordx4 v[10:13], v[78:79], off
	s_nop 0
	v_addc_co_u32_e32 v85, vcc, 0, v79, vcc
	v_add_co_u32_e32 v86, vcc, s19, v74
	global_load_dwordx4 v[14:17], v[80:81], off
	s_nop 0
	v_addc_co_u32_e32 v87, vcc, 0, v75, vcc
	global_load_dwordx4 v[18:21], v[82:83], off
	global_load_dwordx4 v[22:25], v[84:85], off
	global_load_dwordx4 v[26:29], v[76:77], off
	global_load_dwordx4 v[30:33], v[86:87], off
	s_barrier
	global_load_dwordx4 v[34:37], v[74:75], off offset:128
	global_load_dwordx4 v[38:41], v[72:73], off offset:128
	global_load_dwordx4 v[42:45], v[76:77], off offset:128
	global_load_dwordx4 v[46:49], v[86:87], off offset:128
	global_load_dwordx4 v[50:53], v[78:79], off offset:128
	global_load_dwordx4 v[54:57], v[80:81], off offset:128
	global_load_dwordx4 v[58:61], v[82:83], off offset:128
	global_load_dwordx4 v[62:65], v[84:85], off offset:128
	v_and_b32_e32 v66, 31, v1
	v_lshrrev_b32_e32 v88, 1, v1
	v_mul_lo_u32 v70, v70, s16
	v_and_or_b32 v89, v88, s20, v66
	v_and_b32_e32 v88, 16, v88
	v_and_b32_e32 v1, 0x5f, v1
	v_add_lshl_u32 v66, v70, v71, 1
	v_mad_u64_u32 v[70:71], s[6:7], v89, s21, v[88:89]
	v_mad_u32_u24 v1, v1, s21, v88
	v_add_u32_e32 v71, 0x9000, v66
	s_waitcnt vmcnt(15)
	ds_write_b128 v66, v[2:5]
	s_waitcnt vmcnt(14)
	ds_write_b128 v66, v[6:9] offset:4608
	s_waitcnt vmcnt(13)
	ds_write_b128 v66, v[10:13] offset:36864
	s_waitcnt vmcnt(12)
	ds_write_b128 v66, v[14:17] offset:41472
	s_waitcnt vmcnt(11)
	ds_write_b128 v66, v[18:21] offset:46080
	s_waitcnt vmcnt(10)
	ds_write_b128 v66, v[22:25] offset:50688
	s_waitcnt vmcnt(9)
	ds_write_b128 v66, v[26:29] offset:9216
	s_waitcnt vmcnt(8)
	ds_write_b128 v66, v[30:33] offset:13824
	s_waitcnt lgkmcnt(0)
	s_barrier
	ds_read_b128 v[2:5], v70
	ds_read_b128 v[18:21], v70 offset:4608
	ds_read_b128 v[6:9], v1 offset:36864
	ds_read_b128 v[22:25], v1 offset:41472
	s_waitcnt vmcnt(7)
	ds_write_b128 v66, v[34:37] offset:18432
	s_waitcnt vmcnt(6)
	ds_write_b128 v66, v[38:41] offset:23040
	s_waitcnt vmcnt(5)
	ds_write_b128 v66, v[42:45] offset:27648
	s_waitcnt vmcnt(4)
	ds_write_b128 v66, v[46:49] offset:32256
	s_waitcnt vmcnt(3)
	ds_write_b128 v66, v[50:53] offset:55296
	s_waitcnt vmcnt(2)
	ds_write_b128 v66, v[54:57] offset:59904
	s_waitcnt vmcnt(1)
	ds_write_b128 v66, v[58:61] offset:64512
	s_waitcnt vmcnt(0)
	ds_write_b128 v71, v[62:65] offset:32256
	s_setprio 1
	ds_read_b128 v[88:91], v70 offset:32
	s_waitcnt lgkmcnt(10)
	v_mfma_f32_32x32x16_bf16 v[34:49], v[2:5], v[6:9], 0
	ds_read_b128 v[92:95], v1 offset:36896
	ds_read_b128 v[96:99], v1 offset:41504
	ds_read_b128 v[100:103], v70 offset:4704
	global_load_dwordx4 v[104:107], v[72:73], off offset:256
	global_load_dwordx4 v[108:111], v[76:77], off offset:256
	global_load_dwordx4 v[112:115], v[86:87], off offset:256
	global_load_dwordx4 v[116:119], v[84:85], off offset:256
	s_waitcnt lgkmcnt(12)
	v_mfma_f32_32x32x16_bf16 v[50:65], v[2:5], v[22:25], 0
	global_load_dwordx4 v[120:123], v[82:83], off offset:256
	global_load_dwordx4 v[124:127], v[80:81], off offset:256
	global_load_dwordx4 v[140:143], v[74:75], off offset:256
	global_load_dwordx4 v[144:147], v[78:79], off offset:256
	s_waitcnt lgkmcnt(2)
	v_mfma_f32_32x32x16_bf16 v[34:49], v[88:91], v[92:95], v[34:49]
	s_waitcnt lgkmcnt(1)
	v_mfma_f32_32x32x16_bf16 v[50:65], v[88:91], v[96:99], v[50:65]
	ds_read_b128 v[88:91], v70 offset:4640
	v_mfma_f32_32x32x16_bf16 v[2:17], v[18:21], v[6:9], 0
	v_mfma_f32_32x32x16_bf16 v[18:33], v[18:21], v[22:25], 0
	s_waitcnt lgkmcnt(0)
	v_mfma_f32_32x32x16_bf16 v[2:17], v[88:91], v[92:95], v[2:17]
	ds_read_b128 v[92:95], v1 offset:36928
	v_mfma_f32_32x32x16_bf16 v[18:33], v[88:91], v[96:99], v[18:33]
	ds_read_b128 v[88:91], v70 offset:64
	ds_read_b128 v[96:99], v1 offset:41536
	s_waitcnt lgkmcnt(1)
	v_mfma_f32_32x32x16_bf16 v[34:49], v[88:91], v[92:95], v[34:49]
	s_waitcnt lgkmcnt(0)
	v_mfma_f32_32x32x16_bf16 v[50:65], v[88:91], v[96:99], v[50:65]
	ds_read_b128 v[88:91], v70 offset:4672
	s_waitcnt lgkmcnt(0)
	v_mfma_f32_32x32x16_bf16 v[2:17], v[88:91], v[92:95], v[2:17]
	ds_read_b128 v[92:95], v1 offset:36960
	v_mfma_f32_32x32x16_bf16 v[18:33], v[88:91], v[96:99], v[18:33]
	ds_read_b128 v[88:91], v70 offset:96
	ds_read_b128 v[96:99], v1 offset:41568
	s_waitcnt lgkmcnt(1)
	v_mfma_f32_32x32x16_bf16 v[34:49], v[88:91], v[92:95], v[34:49]
	s_waitcnt lgkmcnt(0)
	v_mfma_f32_32x32x16_bf16 v[50:65], v[88:91], v[96:99], v[50:65]
	v_mfma_f32_32x32x16_bf16 v[2:17], v[100:103], v[92:95], v[2:17]
	v_mfma_f32_32x32x16_bf16 v[18:33], v[100:103], v[96:99], v[18:33]
	s_setprio 0
	s_barrier
; #define MFMA(a, b, c) __builtin_amdgcn_mfma_f32_32x32x16_bf16((a), (b), (c), 0, 0, 0)
; template <int TM, int TN>
; DI void gemm_mainloop(const u16* __restrict__ A, long lda, const u16* __restrict__ Bt, long ldb, int K, char* smem,
;                       f32x16 (&acc)[TM][TN]) {
;     ...
;   for (int kt = 0; kt < nk; kt++) {
;     const int buf = kt & 1;
;     const u16* cA = sA + buf * BM * LD + (wm * 32 * TM + r) * LD + h * 8;
;     const u16* cB = sB + buf * BN * LD + (wn * 32 * TN + r) * LD + h * 8;
;     bf16x8 af[TM], bfr[TN];
; #pragma unroll
;     for (int tm = 0; tm < TM; tm++) af[tm] = *(const bf16x8*)(cA + tm * 32 * LD);
; #pragma unroll
;     for (int tn = 0; tn < TN; tn++) bfr[tn] = *(const bf16x8*)(cB + tn * 32 * LD);
;     if (kt + 1 < nk) GEMM_SSTORE(buf ^ 1)
;     __builtin_amdgcn_sched_barrier(0);
;     __builtin_amdgcn_s_setprio(1);
; #pragma unroll
;     for (int tm = 0; tm < TM; tm++)
; #pragma unroll
;       for (int tn = 0; tn < TN; tn++) acc[tm][tn] = MFMA(af[tm], bfr[tn], acc[tm][tn]);
; #pragma unroll
;     for (int tm = 0; tm < TM; tm++) af[tm] = *(const bf16x8*)(cA + tm * 32 * LD + 16);
; #pragma unroll
;     for (int tn = 0; tn < TN; tn++) bfr[tn] = *(const bf16x8*)(cB + tn * 32 * LD + 16);
; #pragma unroll
;     for (int tm = 0; tm < TM; tm++)
; #pragma unroll
;       for (int tn = 0; tn < TN; tn++) acc[tm][tn] = MFMA(af[tm], bfr[tn], acc[tm][tn]);
;     __builtin_amdgcn_sched_group_barrier(0x8, 4, 0);
;     if (kt + 2 < nk) GEMM_GLOAD((kt + 2) * 64)
; #pragma unroll
;     for (int ks = 2; ks < 4; ks++) {
; #pragma unroll
;       for (int tm = 0; tm < TM; tm++) af[tm] = *(const bf16x8*)(cA + tm * 32 * LD + ks * 16);
; #pragma unroll
;       for (int tn = 0; tn < TN; tn++) bfr[tn] = *(const bf16x8*)(cB + tn * 32 * LD + ks * 16);
; #pragma unroll
;       for (int tm = 0; tm < TM; tm++)
; #pragma unroll
;         for (int tn = 0; tn < TN; tn++) acc[tm][tn] = MFMA(af[tm], bfr[tn], acc[tm][tn]);
;     }
;     __builtin_amdgcn_s_setprio(0);
;     __syncthreads();
;   }
	ds_read_b128 v[96:99], v70 offset:18432
	ds_read_b128 v[100:103], v70 offset:23040
	ds_read_b128 v[128:131], v1 offset:55296
	ds_read_b128 v[132:135], v1 offset:59904
	s_setprio 1
	ds_read_b128 v[88:91], v70 offset:18464
	s_waitcnt lgkmcnt(2)
	v_mfma_f32_32x32x16_bf16 v[34:49], v[96:99], v[128:131], v[34:49]
	s_waitcnt vmcnt(1)
	ds_write_b128 v66, v[140:143]
	ds_write_b128 v66, v[104:107] offset:4608
	global_load_dwordx4 v[140:143], v[74:75], off offset:384
	global_load_dwordx4 v[104:107], v[72:73], off offset:384
	ds_read_b128 v[92:95], v1 offset:55328
	s_waitcnt lgkmcnt(4)
	v_mfma_f32_32x32x16_bf16 v[50:65], v[96:99], v[132:135], v[50:65]
	ds_read_b128 v[96:99], v1 offset:59936
	s_waitcnt lgkmcnt(1)
	v_mfma_f32_32x32x16_bf16 v[34:49], v[88:91], v[92:95], v[34:49]
	s_waitcnt lgkmcnt(0)
	v_mfma_f32_32x32x16_bf16 v[50:65], v[88:91], v[96:99], v[50:65]
	ds_write_b128 v66, v[108:111] offset:9216
	ds_write_b128 v66, v[112:115] offset:13824
	global_load_dwordx4 v[108:111], v[76:77], off offset:384
	global_load_dwordx4 v[112:115], v[86:87], off offset:384
	ds_read_b128 v[88:91], v70 offset:23072
	v_mfma_f32_32x32x16_bf16 v[2:17], v[100:103], v[128:131], v[2:17]
	v_mfma_f32_32x32x16_bf16 v[18:33], v[100:103], v[132:135], v[18:33]
	ds_read_b128 v[100:103], v70 offset:23136
	s_waitcnt lgkmcnt(1)
	v_mfma_f32_32x32x16_bf16 v[2:17], v[88:91], v[92:95], v[2:17]
	s_waitcnt vmcnt(4)
	ds_write_b128 v66, v[144:147] offset:36864
	ds_write_b128 v66, v[124:127] offset:41472
	global_load_dwordx4 v[144:147], v[78:79], off offset:384
	global_load_dwordx4 v[124:127], v[80:81], off offset:384
	ds_read_b128 v[92:95], v1 offset:55360
	v_mfma_f32_32x32x16_bf16 v[18:33], v[88:91], v[96:99], v[18:33]
	ds_read_b128 v[88:91], v70 offset:18496
	ds_read_b128 v[96:99], v1 offset:59968
	s_waitcnt lgkmcnt(1)
	v_mfma_f32_32x32x16_bf16 v[34:49], v[88:91], v[92:95], v[34:49]
	s_waitcnt lgkmcnt(0)
	v_mfma_f32_32x32x16_bf16 v[50:65], v[88:91], v[96:99], v[50:65]
	ds_write_b128 v66, v[120:123] offset:46080
	ds_write_b128 v66, v[116:119] offset:50688
	global_load_dwordx4 v[120:123], v[82:83], off offset:384
	global_load_dwordx4 v[116:119], v[84:85], off offset:384
	ds_read_b128 v[88:91], v70 offset:23104
	s_waitcnt lgkmcnt(0)
	v_mfma_f32_32x32x16_bf16 v[2:17], v[88:91], v[92:95], v[2:17]
	ds_read_b128 v[92:95], v1 offset:55392
	v_mfma_f32_32x32x16_bf16 v[18:33], v[88:91], v[96:99], v[18:33]
	ds_read_b128 v[88:91], v70 offset:18528
	ds_read_b128 v[96:99], v1 offset:60000
	s_waitcnt lgkmcnt(1)
	v_mfma_f32_32x32x16_bf16 v[34:49], v[88:91], v[92:95], v[34:49]
	s_waitcnt lgkmcnt(0)
	v_mfma_f32_32x32x16_bf16 v[50:65], v[88:91], v[96:99], v[50:65]
	v_mfma_f32_32x32x16_bf16 v[2:17], v[100:103], v[92:95], v[2:17]
	v_mfma_f32_32x32x16_bf16 v[18:33], v[100:103], v[96:99], v[18:33]
	s_setprio 0
	s_barrier
	ds_read_b128 v[96:99], v70
	ds_read_b128 v[100:103], v70 offset:4608
	ds_read_b128 v[128:131], v1 offset:36864
	ds_read_b128 v[132:135], v1 offset:41472
	s_setprio 1
	ds_read_b128 v[88:91], v70 offset:32
	s_waitcnt lgkmcnt(2)
	v_mfma_f32_32x32x16_bf16 v[34:49], v[96:99], v[128:131], v[34:49]
	s_waitcnt vmcnt(7)
	ds_write_b128 v66, v[140:143] offset:18432
	s_waitcnt vmcnt(6)
	ds_write_b128 v66, v[104:107] offset:23040
	global_load_dwordx4 v[140:143], v[74:75], off offset:512
	global_load_dwordx4 v[104:107], v[72:73], off offset:512
	ds_read_b128 v[92:95], v1 offset:36896
	s_waitcnt lgkmcnt(4)
	v_mfma_f32_32x32x16_bf16 v[50:65], v[96:99], v[132:135], v[50:65]
	ds_read_b128 v[96:99], v1 offset:41504
	s_waitcnt lgkmcnt(1)
	v_mfma_f32_32x32x16_bf16 v[34:49], v[88:91], v[92:95], v[34:49]
	s_waitcnt lgkmcnt(0)
	v_mfma_f32_32x32x16_bf16 v[50:65], v[88:91], v[96:99], v[50:65]
	s_waitcnt vmcnt(7)
	ds_write_b128 v66, v[108:111] offset:27648
	s_waitcnt vmcnt(6)
	ds_write_b128 v66, v[112:115] offset:32256
	global_load_dwordx4 v[108:111], v[76:77], off offset:512
	global_load_dwordx4 v[112:115], v[86:87], off offset:512
	ds_read_b128 v[88:91], v70 offset:4640
	v_mfma_f32_32x32x16_bf16 v[2:17], v[100:103], v[128:131], v[2:17]
	v_mfma_f32_32x32x16_bf16 v[18:33], v[100:103], v[132:135], v[18:33]
	ds_read_b128 v[100:103], v70 offset:4704
	s_waitcnt lgkmcnt(1)
	v_mfma_f32_32x32x16_bf16 v[2:17], v[88:91], v[92:95], v[2:17]
	s_waitcnt vmcnt(7)
	ds_write_b128 v66, v[144:147] offset:55296
	s_waitcnt vmcnt(6)
	ds_write_b128 v66, v[124:127] offset:59904
	global_load_dwordx4 v[144:147], v[78:79], off offset:512
	global_load_dwordx4 v[124:127], v[80:81], off offset:512
	ds_read_b128 v[92:95], v1 offset:36928
	v_mfma_f32_32x32x16_bf16 v[18:33], v[88:91], v[96:99], v[18:33]
	ds_read_b128 v[88:91], v70 offset:64
	ds_read_b128 v[96:99], v1 offset:41536
	s_waitcnt lgkmcnt(1)
	v_mfma_f32_32x32x16_bf16 v[34:49], v[88:91], v[92:95], v[34:49]
	s_waitcnt lgkmcnt(0)
	v_mfma_f32_32x32x16_bf16 v[50:65], v[88:91], v[96:99], v[50:65]
	s_waitcnt vmcnt(7)
	ds_write_b128 v66, v[120:123] offset:64512
	s_waitcnt vmcnt(6)
	ds_write_b128 v71, v[116:119] offset:32256
	global_load_dwordx4 v[120:123], v[82:83], off offset:512
	global_load_dwordx4 v[116:119], v[84:85], off offset:512
	ds_read_b128 v[88:91], v70 offset:4672
	s_waitcnt lgkmcnt(0)
	v_mfma_f32_32x32x16_bf16 v[2:17], v[88:91], v[92:95], v[2:17]
	ds_read_b128 v[92:95], v1 offset:36960
	v_mfma_f32_32x32x16_bf16 v[18:33], v[88:91], v[96:99], v[18:33]
	ds_read_b128 v[88:91], v70 offset:96
	ds_read_b128 v[96:99], v1 offset:41568
	s_waitcnt lgkmcnt(1)
	v_mfma_f32_32x32x16_bf16 v[34:49], v[88:91], v[92:95], v[34:49]
	s_waitcnt lgkmcnt(0)
	v_mfma_f32_32x32x16_bf16 v[50:65], v[88:91], v[96:99], v[50:65]
	v_mfma_f32_32x32x16_bf16 v[2:17], v[100:103], v[92:95], v[2:17]
	v_mfma_f32_32x32x16_bf16 v[18:33], v[100:103], v[96:99], v[18:33]
	s_setprio 0
	s_barrier
; #define MFMA(a, b, c) __builtin_amdgcn_mfma_f32_32x32x16_bf16((a), (b), (c), 0, 0, 0)
; template <int TM, int TN>
; DI void gemm_mainloop(const u16* __restrict__ A, long lda, const u16* __restrict__ Bt, long ldb, int K, char* smem,
;                       f32x16 (&acc)[TM][TN]) {
;     ...
;   for (int kt = 0; kt < nk; kt++) {
;     const int buf = kt & 1;
;     const u16* cA = sA + buf * BM * LD + (wm * 32 * TM + r) * LD + h * 8;
;     const u16* cB = sB + buf * BN * LD + (wn * 32 * TN + r) * LD + h * 8;
;     bf16x8 af[TM], bfr[TN];
; #pragma unroll
;     for (int tm = 0; tm < TM; tm++) af[tm] = *(const bf16x8*)(cA + tm * 32 * LD);
; #pragma unroll
;     for (int tn = 0; tn < TN; tn++) bfr[tn] = *(const bf16x8*)(cB + tn * 32 * LD);
;     if (kt + 1 < nk) GEMM_SSTORE(buf ^ 1)
;     __builtin_amdgcn_sched_barrier(0);
;     __builtin_amdgcn_s_setprio(1);
; #pragma unroll
;     for (int tm = 0; tm < TM; tm++)
; #pragma unroll
;       for (int tn = 0; tn < TN; tn++) acc[tm][tn] = MFMA(af[tm], bfr[tn], acc[tm][tn]);
; #pragma unroll
;     for (int tm = 0; tm < TM; tm++) af[tm] = *(const bf16x8*)(cA + tm * 32 * LD + 16);
; #pragma unroll
;     for (int tn = 0; tn < TN; tn++) bfr[tn] = *(const bf16x8*)(cB + tn * 32 * LD + 16);
; #pragma unroll
;     for (int tm = 0; tm < TM; tm++)
; #pragma unroll
;       for (int tn = 0; tn < TN; tn++) acc[tm][tn] = MFMA(af[tm], bfr[tn], acc[tm][tn]);
;     __builtin_amdgcn_sched_group_barrier(0x8, 4, 0);
;     if (kt + 2 < nk) GEMM_GLOAD((kt + 2) * 64)
; #pragma unroll
;     for (int ks = 2; ks < 4; ks++) {
; #pragma unroll
;       for (int tm = 0; tm < TM; tm++) af[tm] = *(const bf16x8*)(cA + tm * 32 * LD + ks * 16);
; #pragma unroll
;       for (int tn = 0; tn < TN; tn++) bfr[tn] = *(const bf16x8*)(cB + tn * 32 * LD + ks * 16);
; #pragma unroll
;       for (int tm = 0; tm < TM; tm++)
; #pragma unroll
;         for (int tn = 0; tn < TN; tn++) acc[tm][tn] = MFMA(af[tm], bfr[tn], acc[tm][tn]);
;     }
;     __builtin_amdgcn_s_setprio(0);
;     __syncthreads();
;   }
	ds_read_b128 v[96:99], v70 offset:18432
	ds_read_b128 v[100:103], v70 offset:23040
	ds_read_b128 v[128:131], v1 offset:55296
	ds_read_b128 v[132:135], v1 offset:59904
	s_setprio 1
	ds_read_b128 v[88:91], v70 offset:18464
	s_waitcnt lgkmcnt(2)
	v_mfma_f32_32x32x16_bf16 v[34:49], v[96:99], v[128:131], v[34:49]
	s_waitcnt vmcnt(7)
	ds_write_b128 v66, v[140:143]
	s_waitcnt vmcnt(6)
	ds_write_b128 v66, v[104:107] offset:4608
	global_load_dwordx4 v[140:143], v[74:75], off offset:640
	global_load_dwordx4 v[104:107], v[72:73], off offset:640
	ds_read_b128 v[92:95], v1 offset:55328
	s_waitcnt lgkmcnt(4)
	v_mfma_f32_32x32x16_bf16 v[50:65], v[96:99], v[132:135], v[50:65]
	ds_read_b128 v[96:99], v1 offset:59936
	s_waitcnt lgkmcnt(1)
	v_mfma_f32_32x32x16_bf16 v[34:49], v[88:91], v[92:95], v[34:49]
	s_waitcnt lgkmcnt(0)
	v_mfma_f32_32x32x16_bf16 v[50:65], v[88:91], v[96:99], v[50:65]
	s_waitcnt vmcnt(7)
	ds_write_b128 v66, v[108:111] offset:9216
	s_waitcnt vmcnt(6)
	ds_write_b128 v66, v[112:115] offset:13824
	global_load_dwordx4 v[108:111], v[76:77], off offset:640
	global_load_dwordx4 v[112:115], v[86:87], off offset:640
	ds_read_b128 v[88:91], v70 offset:23072
	v_mfma_f32_32x32x16_bf16 v[2:17], v[100:103], v[128:131], v[2:17]
	v_mfma_f32_32x32x16_bf16 v[18:33], v[100:103], v[132:135], v[18:33]
	ds_read_b128 v[100:103], v70 offset:23136
	s_waitcnt lgkmcnt(1)
	v_mfma_f32_32x32x16_bf16 v[2:17], v[88:91], v[92:95], v[2:17]
	s_waitcnt vmcnt(7)
	ds_write_b128 v66, v[144:147] offset:36864
	s_waitcnt vmcnt(6)
	ds_write_b128 v66, v[124:127] offset:41472
	global_load_dwordx4 v[144:147], v[78:79], off offset:640
	global_load_dwordx4 v[124:127], v[80:81], off offset:640
	ds_read_b128 v[92:95], v1 offset:55360
	v_mfma_f32_32x32x16_bf16 v[18:33], v[88:91], v[96:99], v[18:33]
	ds_read_b128 v[88:91], v70 offset:18496
	ds_read_b128 v[96:99], v1 offset:59968
	s_waitcnt lgkmcnt(1)
	v_mfma_f32_32x32x16_bf16 v[34:49], v[88:91], v[92:95], v[34:49]
	s_waitcnt lgkmcnt(0)
	v_mfma_f32_32x32x16_bf16 v[50:65], v[88:91], v[96:99], v[50:65]
	s_waitcnt vmcnt(7)
	ds_write_b128 v66, v[120:123] offset:46080
	s_waitcnt vmcnt(6)
	ds_write_b128 v66, v[116:119] offset:50688
	global_load_dwordx4 v[120:123], v[82:83], off offset:640
	global_load_dwordx4 v[116:119], v[84:85], off offset:640
	ds_read_b128 v[88:91], v70 offset:23104
	s_waitcnt lgkmcnt(0)
	v_mfma_f32_32x32x16_bf16 v[2:17], v[88:91], v[92:95], v[2:17]
	ds_read_b128 v[92:95], v1 offset:55392
	v_mfma_f32_32x32x16_bf16 v[18:33], v[88:91], v[96:99], v[18:33]
	ds_read_b128 v[88:91], v70 offset:18528
	ds_read_b128 v[96:99], v1 offset:60000
	s_waitcnt lgkmcnt(1)
	v_mfma_f32_32x32x16_bf16 v[34:49], v[88:91], v[92:95], v[34:49]
	s_waitcnt lgkmcnt(0)
	v_mfma_f32_32x32x16_bf16 v[50:65], v[88:91], v[96:99], v[50:65]
	v_mfma_f32_32x32x16_bf16 v[2:17], v[100:103], v[92:95], v[2:17]
	v_mfma_f32_32x32x16_bf16 v[18:33], v[100:103], v[96:99], v[18:33]
	s_setprio 0
	s_barrier
	ds_read_b128 v[96:99], v70
	ds_read_b128 v[100:103], v70 offset:4608
	ds_read_b128 v[128:131], v1 offset:36864
	ds_read_b128 v[132:135], v1 offset:41472
	s_setprio 1
	ds_read_b128 v[88:91], v70 offset:32
	s_waitcnt lgkmcnt(2)
	v_mfma_f32_32x32x16_bf16 v[34:49], v[96:99], v[128:131], v[34:49]
	s_waitcnt vmcnt(7)
	ds_write_b128 v66, v[140:143] offset:18432
	s_waitcnt vmcnt(6)
	ds_write_b128 v66, v[104:107] offset:23040
	global_load_dwordx4 v[140:143], v[74:75], off offset:768
	global_load_dwordx4 v[104:107], v[72:73], off offset:768
	ds_read_b128 v[92:95], v1 offset:36896
	s_waitcnt lgkmcnt(4)
	v_mfma_f32_32x32x16_bf16 v[50:65], v[96:99], v[132:135], v[50:65]
	ds_read_b128 v[96:99], v1 offset:41504
	s_waitcnt lgkmcnt(1)
	v_mfma_f32_32x32x16_bf16 v[34:49], v[88:91], v[92:95], v[34:49]
	s_waitcnt lgkmcnt(0)
	v_mfma_f32_32x32x16_bf16 v[50:65], v[88:91], v[96:99], v[50:65]
	s_waitcnt vmcnt(7)
	ds_write_b128 v66, v[108:111] offset:27648
	s_waitcnt vmcnt(6)
	ds_write_b128 v66, v[112:115] offset:32256
	global_load_dwordx4 v[108:111], v[76:77], off offset:768
	global_load_dwordx4 v[112:115], v[86:87], off offset:768
	ds_read_b128 v[88:91], v70 offset:4640
	v_mfma_f32_32x32x16_bf16 v[2:17], v[100:103], v[128:131], v[2:17]
	v_mfma_f32_32x32x16_bf16 v[18:33], v[100:103], v[132:135], v[18:33]
	ds_read_b128 v[100:103], v70 offset:4704
	s_waitcnt lgkmcnt(1)
	v_mfma_f32_32x32x16_bf16 v[2:17], v[88:91], v[92:95], v[2:17]
	s_waitcnt vmcnt(7)
	ds_write_b128 v66, v[144:147] offset:55296
	s_waitcnt vmcnt(6)
	ds_write_b128 v66, v[124:127] offset:59904
	global_load_dwordx4 v[144:147], v[78:79], off offset:768
	global_load_dwordx4 v[124:127], v[80:81], off offset:768
	ds_read_b128 v[92:95], v1 offset:36928
	v_mfma_f32_32x32x16_bf16 v[18:33], v[88:91], v[96:99], v[18:33]
	ds_read_b128 v[88:91], v70 offset:64
	ds_read_b128 v[96:99], v1 offset:41536
	s_waitcnt lgkmcnt(1)
	v_mfma_f32_32x32x16_bf16 v[34:49], v[88:91], v[92:95], v[34:49]
	s_waitcnt lgkmcnt(0)
	v_mfma_f32_32x32x16_bf16 v[50:65], v[88:91], v[96:99], v[50:65]
	s_waitcnt vmcnt(7)
	ds_write_b128 v66, v[120:123] offset:64512
	s_waitcnt vmcnt(6)
	ds_write_b128 v71, v[116:119] offset:32256
	global_load_dwordx4 v[120:123], v[82:83], off offset:768
	global_load_dwordx4 v[116:119], v[84:85], off offset:768
	ds_read_b128 v[88:91], v70 offset:4672
	s_waitcnt lgkmcnt(0)
	v_mfma_f32_32x32x16_bf16 v[2:17], v[88:91], v[92:95], v[2:17]
	ds_read_b128 v[92:95], v1 offset:36960
	v_mfma_f32_32x32x16_bf16 v[18:33], v[88:91], v[96:99], v[18:33]
	ds_read_b128 v[88:91], v70 offset:96
	ds_read_b128 v[96:99], v1 offset:41568
	s_waitcnt lgkmcnt(1)
	v_mfma_f32_32x32x16_bf16 v[34:49], v[88:91], v[92:95], v[34:49]
	s_waitcnt lgkmcnt(0)
	v_mfma_f32_32x32x16_bf16 v[50:65], v[88:91], v[96:99], v[50:65]
	v_mfma_f32_32x32x16_bf16 v[2:17], v[100:103], v[92:95], v[2:17]
	v_mfma_f32_32x32x16_bf16 v[18:33], v[100:103], v[96:99], v[18:33]
	s_setprio 0
	s_barrier
; #define MFMA(a, b, c) __builtin_amdgcn_mfma_f32_32x32x16_bf16((a), (b), (c), 0, 0, 0)
; template <int TM, int TN>
; DI void gemm_mainloop(const u16* __restrict__ A, long lda, const u16* __restrict__ Bt, long ldb, int K, char* smem,
;                       f32x16 (&acc)[TM][TN]) {
;     ...
;   for (int kt = 0; kt < nk; kt++) {
;     const int buf = kt & 1;
;     const u16* cA = sA + buf * BM * LD + (wm * 32 * TM + r) * LD + h * 8;
;     const u16* cB = sB + buf * BN * LD + (wn * 32 * TN + r) * LD + h * 8;
;     bf16x8 af[TM], bfr[TN];
; #pragma unroll
;     for (int tm = 0; tm < TM; tm++) af[tm] = *(const bf16x8*)(cA + tm * 32 * LD);
; #pragma unroll
;     for (int tn = 0; tn < TN; tn++) bfr[tn] = *(const bf16x8*)(cB + tn * 32 * LD);
;     if (kt + 1 < nk) GEMM_SSTORE(buf ^ 1)
;     __builtin_amdgcn_sched_barrier(0);
;     __builtin_amdgcn_s_setprio(1);
; #pragma unroll
;     for (int tm = 0; tm < TM; tm++)
; #pragma unroll
;       for (int tn = 0; tn < TN; tn++) acc[tm][tn] = MFMA(af[tm], bfr[tn], acc[tm][tn]);
; #pragma unroll
;     for (int tm = 0; tm < TM; tm++) af[tm] = *(const bf16x8*)(cA + tm * 32 * LD + 16);
; #pragma unroll
;     for (int tn = 0; tn < TN; tn++) bfr[tn] = *(const bf16x8*)(cB + tn * 32 * LD + 16);
; #pragma unroll
;     for (int tm = 0; tm < TM; tm++)
; #pragma unroll
;       for (int tn = 0; tn < TN; tn++) acc[tm][tn] = MFMA(af[tm], bfr[tn], acc[tm][tn]);
;     __builtin_amdgcn_sched_group_barrier(0x8, 4, 0);
;     if (kt + 2 < nk) GEMM_GLOAD((kt + 2) * 64)
; #pragma unroll
;     for (int ks = 2; ks < 4; ks++) {
; #pragma unroll
;       for (int tm = 0; tm < TM; tm++) af[tm] = *(const bf16x8*)(cA + tm * 32 * LD + ks * 16);
; #pragma unroll
;       for (int tn = 0; tn < TN; tn++) bfr[tn] = *(const bf16x8*)(cB + tn * 32 * LD + ks * 16);
; #pragma unroll
;       for (int tm = 0; tm < TM; tm++)
; #pragma unroll
;         for (int tn = 0; tn < TN; tn++) acc[tm][tn] = MFMA(af[tm], bfr[tn], acc[tm][tn]);
;     }
;     __builtin_amdgcn_s_setprio(0);
;     __syncthreads();
;   }
	ds_read_b128 v[96:99], v70 offset:18432
	ds_read_b128 v[100:103], v70 offset:23040
	ds_read_b128 v[128:131], v1 offset:55296
	ds_read_b128 v[132:135], v1 offset:59904
	s_setprio 1
	ds_read_b128 v[88:91], v70 offset:18464
	s_waitcnt lgkmcnt(2)
	v_mfma_f32_32x32x16_bf16 v[34:49], v[96:99], v[128:131], v[34:49]
	s_waitcnt vmcnt(7)
	ds_write_b128 v66, v[140:143]
	s_waitcnt vmcnt(6)
	ds_write_b128 v66, v[104:107] offset:4608
	global_load_dwordx4 v[140:143], v[74:75], off offset:896
	global_load_dwordx4 v[104:107], v[72:73], off offset:896
	ds_read_b128 v[92:95], v1 offset:55328
	s_waitcnt lgkmcnt(4)
	v_mfma_f32_32x32x16_bf16 v[50:65], v[96:99], v[132:135], v[50:65]
	ds_read_b128 v[96:99], v1 offset:59936
	s_waitcnt lgkmcnt(1)
	v_mfma_f32_32x32x16_bf16 v[34:49], v[88:91], v[92:95], v[34:49]
	s_waitcnt lgkmcnt(0)
	v_mfma_f32_32x32x16_bf16 v[50:65], v[88:91], v[96:99], v[50:65]
	s_waitcnt vmcnt(7)
	ds_write_b128 v66, v[108:111] offset:9216
	s_waitcnt vmcnt(6)
	ds_write_b128 v66, v[112:115] offset:13824
	global_load_dwordx4 v[108:111], v[76:77], off offset:896
	global_load_dwordx4 v[112:115], v[86:87], off offset:896
	ds_read_b128 v[88:91], v70 offset:23072
	v_mfma_f32_32x32x16_bf16 v[2:17], v[100:103], v[128:131], v[2:17]
	v_mfma_f32_32x32x16_bf16 v[18:33], v[100:103], v[132:135], v[18:33]
	ds_read_b128 v[100:103], v70 offset:23136
	s_waitcnt lgkmcnt(1)
	v_mfma_f32_32x32x16_bf16 v[2:17], v[88:91], v[92:95], v[2:17]
	s_waitcnt vmcnt(7)
	ds_write_b128 v66, v[144:147] offset:36864
	s_waitcnt vmcnt(6)
	ds_write_b128 v66, v[124:127] offset:41472
	global_load_dwordx4 v[144:147], v[78:79], off offset:896
	global_load_dwordx4 v[124:127], v[80:81], off offset:896
	ds_read_b128 v[92:95], v1 offset:55360
	v_mfma_f32_32x32x16_bf16 v[18:33], v[88:91], v[96:99], v[18:33]
	ds_read_b128 v[88:91], v70 offset:18496
	ds_read_b128 v[96:99], v1 offset:59968
	s_waitcnt lgkmcnt(1)
	v_mfma_f32_32x32x16_bf16 v[34:49], v[88:91], v[92:95], v[34:49]
	s_waitcnt lgkmcnt(0)
	v_mfma_f32_32x32x16_bf16 v[50:65], v[88:91], v[96:99], v[50:65]
	s_waitcnt vmcnt(7)
	ds_write_b128 v66, v[120:123] offset:46080
	s_waitcnt vmcnt(6)
	ds_write_b128 v66, v[116:119] offset:50688
	global_load_dwordx4 v[120:123], v[82:83], off offset:896
	global_load_dwordx4 v[116:119], v[84:85], off offset:896
	ds_read_b128 v[88:91], v70 offset:23104
	s_waitcnt lgkmcnt(0)
	v_mfma_f32_32x32x16_bf16 v[2:17], v[88:91], v[92:95], v[2:17]
	ds_read_b128 v[92:95], v1 offset:55392
	v_mfma_f32_32x32x16_bf16 v[18:33], v[88:91], v[96:99], v[18:33]
	ds_read_b128 v[88:91], v70 offset:18528
	ds_read_b128 v[96:99], v1 offset:60000
	s_waitcnt lgkmcnt(1)
	v_mfma_f32_32x32x16_bf16 v[34:49], v[88:91], v[92:95], v[34:49]
	s_waitcnt lgkmcnt(0)
	v_mfma_f32_32x32x16_bf16 v[50:65], v[88:91], v[96:99], v[50:65]
	v_mfma_f32_32x32x16_bf16 v[2:17], v[100:103], v[92:95], v[2:17]
	v_mfma_f32_32x32x16_bf16 v[18:33], v[100:103], v[96:99], v[18:33]
	s_setprio 0
	s_barrier
	ds_read_b128 v[96:99], v70
	ds_read_b128 v[100:103], v70 offset:4608
	ds_read_b128 v[128:131], v1 offset:36864
	ds_read_b128 v[132:135], v1 offset:41472
	s_setprio 1
	ds_read_b128 v[88:91], v70 offset:32
	s_waitcnt lgkmcnt(2)
	v_mfma_f32_32x32x16_bf16 v[34:49], v[96:99], v[128:131], v[34:49]
	s_waitcnt vmcnt(7)
	ds_write_b128 v66, v[140:143] offset:18432
	s_waitcnt vmcnt(6)
	ds_write_b128 v66, v[104:107] offset:23040
	global_load_dwordx4 v[140:143], v[74:75], off offset:1024
	global_load_dwordx4 v[104:107], v[72:73], off offset:1024
	ds_read_b128 v[92:95], v1 offset:36896
	s_waitcnt lgkmcnt(4)
	v_mfma_f32_32x32x16_bf16 v[50:65], v[96:99], v[132:135], v[50:65]
	ds_read_b128 v[96:99], v1 offset:41504
	s_waitcnt lgkmcnt(1)
	v_mfma_f32_32x32x16_bf16 v[34:49], v[88:91], v[92:95], v[34:49]
	s_waitcnt lgkmcnt(0)
	v_mfma_f32_32x32x16_bf16 v[50:65], v[88:91], v[96:99], v[50:65]
	s_waitcnt vmcnt(7)
	ds_write_b128 v66, v[108:111] offset:27648
	s_waitcnt vmcnt(6)
	ds_write_b128 v66, v[112:115] offset:32256
	global_load_dwordx4 v[108:111], v[76:77], off offset:1024
	global_load_dwordx4 v[112:115], v[86:87], off offset:1024
	ds_read_b128 v[88:91], v70 offset:4640
	v_mfma_f32_32x32x16_bf16 v[2:17], v[100:103], v[128:131], v[2:17]
	v_mfma_f32_32x32x16_bf16 v[18:33], v[100:103], v[132:135], v[18:33]
	ds_read_b128 v[100:103], v70 offset:4704
	s_waitcnt lgkmcnt(1)
	v_mfma_f32_32x32x16_bf16 v[2:17], v[88:91], v[92:95], v[2:17]
	s_waitcnt vmcnt(7)
	ds_write_b128 v66, v[144:147] offset:55296
	s_waitcnt vmcnt(6)
	ds_write_b128 v66, v[124:127] offset:59904
	global_load_dwordx4 v[144:147], v[78:79], off offset:1024
	global_load_dwordx4 v[124:127], v[80:81], off offset:1024
	ds_read_b128 v[92:95], v1 offset:36928
	v_mfma_f32_32x32x16_bf16 v[18:33], v[88:91], v[96:99], v[18:33]
	ds_read_b128 v[88:91], v70 offset:64
	ds_read_b128 v[96:99], v1 offset:41536
	s_waitcnt lgkmcnt(1)
	v_mfma_f32_32x32x16_bf16 v[34:49], v[88:91], v[92:95], v[34:49]
	s_waitcnt lgkmcnt(0)
	v_mfma_f32_32x32x16_bf16 v[50:65], v[88:91], v[96:99], v[50:65]
	s_waitcnt vmcnt(7)
	ds_write_b128 v66, v[120:123] offset:64512
	s_waitcnt vmcnt(6)
	ds_write_b128 v71, v[116:119] offset:32256
	global_load_dwordx4 v[120:123], v[82:83], off offset:1024
	global_load_dwordx4 v[116:119], v[84:85], off offset:1024
	ds_read_b128 v[88:91], v70 offset:4672
	s_waitcnt lgkmcnt(0)
	v_mfma_f32_32x32x16_bf16 v[2:17], v[88:91], v[92:95], v[2:17]
	ds_read_b128 v[92:95], v1 offset:36960
	v_mfma_f32_32x32x16_bf16 v[18:33], v[88:91], v[96:99], v[18:33]
	ds_read_b128 v[88:91], v70 offset:96
	ds_read_b128 v[96:99], v1 offset:41568
	s_waitcnt lgkmcnt(1)
	v_mfma_f32_32x32x16_bf16 v[34:49], v[88:91], v[92:95], v[34:49]
	s_waitcnt lgkmcnt(0)
	v_mfma_f32_32x32x16_bf16 v[50:65], v[88:91], v[96:99], v[50:65]
	v_mfma_f32_32x32x16_bf16 v[2:17], v[100:103], v[92:95], v[2:17]
	v_mfma_f32_32x32x16_bf16 v[18:33], v[100:103], v[96:99], v[18:33]
	s_setprio 0
	s_barrier
; #define MFMA(a, b, c) __builtin_amdgcn_mfma_f32_32x32x16_bf16((a), (b), (c), 0, 0, 0)
; template <int TM, int TN>
; DI void gemm_mainloop(const u16* __restrict__ A, long lda, const u16* __restrict__ Bt, long ldb, int K, char* smem,
;                       f32x16 (&acc)[TM][TN]) {
;     ...
;   for (int kt = 0; kt < nk; kt++) {
;     const int buf = kt & 1;
;     const u16* cA = sA + buf * BM * LD + (wm * 32 * TM + r) * LD + h * 8;
;     const u16* cB = sB + buf * BN * LD + (wn * 32 * TN + r) * LD + h * 8;
;     bf16x8 af[TM], bfr[TN];
; #pragma unroll
;     for (int tm = 0; tm < TM; tm++) af[tm] = *(const bf16x8*)(cA + tm * 32 * LD);
; #pragma unroll
;     for (int tn = 0; tn < TN; tn++) bfr[tn] = *(const bf16x8*)(cB + tn * 32 * LD);
;     if (kt + 1 < nk) GEMM_SSTORE(buf ^ 1)
;     __builtin_amdgcn_sched_barrier(0);
;     __builtin_amdgcn_s_setprio(1);
; #pragma unroll
;     for (int tm = 0; tm < TM; tm++)
; #pragma unroll
;       for (int tn = 0; tn < TN; tn++) acc[tm][tn] = MFMA(af[tm], bfr[tn], acc[tm][tn]);
; #pragma unroll
;     for (int tm = 0; tm < TM; tm++) af[tm] = *(const bf16x8*)(cA + tm * 32 * LD + 16);
; #pragma unroll
;     for (int tn = 0; tn < TN; tn++) bfr[tn] = *(const bf16x8*)(cB + tn * 32 * LD + 16);
; #pragma unroll
;     for (int tm = 0; tm < TM; tm++)
; #pragma unroll
;       for (int tn = 0; tn < TN; tn++) acc[tm][tn] = MFMA(af[tm], bfr[tn], acc[tm][tn]);
;     __builtin_amdgcn_sched_group_barrier(0x8, 4, 0);
;     if (kt + 2 < nk) GEMM_GLOAD((kt + 2) * 64)
; #pragma unroll
;     for (int ks = 2; ks < 4; ks++) {
; #pragma unroll
;       for (int tm = 0; tm < TM; tm++) af[tm] = *(const bf16x8*)(cA + tm * 32 * LD + ks * 16);
; #pragma unroll
;       for (int tn = 0; tn < TN; tn++) bfr[tn] = *(const bf16x8*)(cB + tn * 32 * LD + ks * 16);
; #pragma unroll
;       for (int tm = 0; tm < TM; tm++)
; #pragma unroll
;         for (int tn = 0; tn < TN; tn++) acc[tm][tn] = MFMA(af[tm], bfr[tn], acc[tm][tn]);
;     }
;     __builtin_amdgcn_s_setprio(0);
;     __syncthreads();
;   }
	ds_read_b128 v[96:99], v70 offset:18432
	ds_read_b128 v[100:103], v70 offset:23040
	ds_read_b128 v[128:131], v1 offset:55296
	ds_read_b128 v[132:135], v1 offset:59904
	s_setprio 1
	ds_read_b128 v[88:91], v70 offset:18464
	s_waitcnt lgkmcnt(2)
	v_mfma_f32_32x32x16_bf16 v[34:49], v[96:99], v[128:131], v[34:49]
	s_waitcnt vmcnt(7)
	ds_write_b128 v66, v[140:143]
	s_waitcnt vmcnt(6)
	ds_write_b128 v66, v[104:107] offset:4608
	global_load_dwordx4 v[140:143], v[74:75], off offset:1152
	global_load_dwordx4 v[104:107], v[72:73], off offset:1152
	ds_read_b128 v[92:95], v1 offset:55328
	s_waitcnt lgkmcnt(4)
	v_mfma_f32_32x32x16_bf16 v[50:65], v[96:99], v[132:135], v[50:65]
	ds_read_b128 v[96:99], v1 offset:59936
	s_waitcnt lgkmcnt(1)
	v_mfma_f32_32x32x16_bf16 v[34:49], v[88:91], v[92:95], v[34:49]
	s_waitcnt lgkmcnt(0)
	v_mfma_f32_32x32x16_bf16 v[50:65], v[88:91], v[96:99], v[50:65]
	s_waitcnt vmcnt(7)
	ds_write_b128 v66, v[108:111] offset:9216
	s_waitcnt vmcnt(6)
	ds_write_b128 v66, v[112:115] offset:13824
	global_load_dwordx4 v[108:111], v[76:77], off offset:1152
	global_load_dwordx4 v[112:115], v[86:87], off offset:1152
	ds_read_b128 v[88:91], v70 offset:23072
	v_mfma_f32_32x32x16_bf16 v[2:17], v[100:103], v[128:131], v[2:17]
	v_mfma_f32_32x32x16_bf16 v[18:33], v[100:103], v[132:135], v[18:33]
	ds_read_b128 v[100:103], v70 offset:23136
	s_waitcnt lgkmcnt(1)
	v_mfma_f32_32x32x16_bf16 v[2:17], v[88:91], v[92:95], v[2:17]
	s_waitcnt vmcnt(7)
	ds_write_b128 v66, v[144:147] offset:36864
	s_waitcnt vmcnt(6)
	ds_write_b128 v66, v[124:127] offset:41472
	global_load_dwordx4 v[144:147], v[78:79], off offset:1152
	global_load_dwordx4 v[124:127], v[80:81], off offset:1152
	ds_read_b128 v[92:95], v1 offset:55360
	v_mfma_f32_32x32x16_bf16 v[18:33], v[88:91], v[96:99], v[18:33]
	ds_read_b128 v[88:91], v70 offset:18496
	ds_read_b128 v[96:99], v1 offset:59968
	s_waitcnt lgkmcnt(1)
	v_mfma_f32_32x32x16_bf16 v[34:49], v[88:91], v[92:95], v[34:49]
	s_waitcnt lgkmcnt(0)
	v_mfma_f32_32x32x16_bf16 v[50:65], v[88:91], v[96:99], v[50:65]
	s_waitcnt vmcnt(7)
	ds_write_b128 v66, v[120:123] offset:46080
	s_waitcnt vmcnt(6)
	ds_write_b128 v66, v[116:119] offset:50688
	global_load_dwordx4 v[120:123], v[82:83], off offset:1152
	global_load_dwordx4 v[116:119], v[84:85], off offset:1152
	ds_read_b128 v[88:91], v70 offset:23104
	s_waitcnt lgkmcnt(0)
	v_mfma_f32_32x32x16_bf16 v[2:17], v[88:91], v[92:95], v[2:17]
	ds_read_b128 v[92:95], v1 offset:55392
	v_mfma_f32_32x32x16_bf16 v[18:33], v[88:91], v[96:99], v[18:33]
	ds_read_b128 v[88:91], v70 offset:18528
	ds_read_b128 v[96:99], v1 offset:60000
	s_waitcnt lgkmcnt(1)
	v_mfma_f32_32x32x16_bf16 v[34:49], v[88:91], v[92:95], v[34:49]
	s_waitcnt lgkmcnt(0)
	v_mfma_f32_32x32x16_bf16 v[50:65], v[88:91], v[96:99], v[50:65]
	v_mfma_f32_32x32x16_bf16 v[2:17], v[100:103], v[92:95], v[2:17]
	v_mfma_f32_32x32x16_bf16 v[18:33], v[100:103], v[96:99], v[18:33]
	s_setprio 0
	s_barrier
	ds_read_b128 v[96:99], v70
	ds_read_b128 v[100:103], v70 offset:4608
	ds_read_b128 v[128:131], v1 offset:36864
	ds_read_b128 v[132:135], v1 offset:41472
	s_setprio 1
	ds_read_b128 v[88:91], v70 offset:32
	s_waitcnt lgkmcnt(2)
	v_mfma_f32_32x32x16_bf16 v[34:49], v[96:99], v[128:131], v[34:49]
	s_waitcnt vmcnt(7)
	ds_write_b128 v66, v[140:143] offset:18432
	s_waitcnt vmcnt(6)
	ds_write_b128 v66, v[104:107] offset:23040
	global_load_dwordx4 v[140:143], v[74:75], off offset:1280
	global_load_dwordx4 v[104:107], v[72:73], off offset:1280
	ds_read_b128 v[92:95], v1 offset:36896
	s_waitcnt lgkmcnt(4)
	v_mfma_f32_32x32x16_bf16 v[50:65], v[96:99], v[132:135], v[50:65]
	ds_read_b128 v[96:99], v1 offset:41504
	s_waitcnt lgkmcnt(1)
	v_mfma_f32_32x32x16_bf16 v[34:49], v[88:91], v[92:95], v[34:49]
	s_waitcnt lgkmcnt(0)
	v_mfma_f32_32x32x16_bf16 v[50:65], v[88:91], v[96:99], v[50:65]
	s_waitcnt vmcnt(7)
	ds_write_b128 v66, v[108:111] offset:27648
	s_waitcnt vmcnt(6)
	ds_write_b128 v66, v[112:115] offset:32256
	global_load_dwordx4 v[108:111], v[76:77], off offset:1280
	global_load_dwordx4 v[112:115], v[86:87], off offset:1280
	ds_read_b128 v[88:91], v70 offset:4640
	v_mfma_f32_32x32x16_bf16 v[2:17], v[100:103], v[128:131], v[2:17]
	v_mfma_f32_32x32x16_bf16 v[18:33], v[100:103], v[132:135], v[18:33]
	ds_read_b128 v[100:103], v70 offset:4704
	s_waitcnt lgkmcnt(1)
	v_mfma_f32_32x32x16_bf16 v[2:17], v[88:91], v[92:95], v[2:17]
	s_waitcnt vmcnt(7)
	ds_write_b128 v66, v[144:147] offset:55296
	s_waitcnt vmcnt(6)
	ds_write_b128 v66, v[124:127] offset:59904
	global_load_dwordx4 v[144:147], v[78:79], off offset:1280
	global_load_dwordx4 v[124:127], v[80:81], off offset:1280
	ds_read_b128 v[92:95], v1 offset:36928
	v_mfma_f32_32x32x16_bf16 v[18:33], v[88:91], v[96:99], v[18:33]
	ds_read_b128 v[88:91], v70 offset:64
	ds_read_b128 v[96:99], v1 offset:41536
	s_waitcnt lgkmcnt(1)
	v_mfma_f32_32x32x16_bf16 v[34:49], v[88:91], v[92:95], v[34:49]
	s_waitcnt lgkmcnt(0)
	v_mfma_f32_32x32x16_bf16 v[50:65], v[88:91], v[96:99], v[50:65]
	s_waitcnt vmcnt(7)
	ds_write_b128 v66, v[120:123] offset:64512
	s_waitcnt vmcnt(6)
	ds_write_b128 v71, v[116:119] offset:32256
	global_load_dwordx4 v[120:123], v[82:83], off offset:1280
	global_load_dwordx4 v[116:119], v[84:85], off offset:1280
	ds_read_b128 v[88:91], v70 offset:4672
	s_waitcnt lgkmcnt(0)
	v_mfma_f32_32x32x16_bf16 v[2:17], v[88:91], v[92:95], v[2:17]
	ds_read_b128 v[92:95], v1 offset:36960
	v_mfma_f32_32x32x16_bf16 v[18:33], v[88:91], v[96:99], v[18:33]
	ds_read_b128 v[88:91], v70 offset:96
	ds_read_b128 v[96:99], v1 offset:41568
	s_waitcnt lgkmcnt(1)
	v_mfma_f32_32x32x16_bf16 v[34:49], v[88:91], v[92:95], v[34:49]
	s_waitcnt lgkmcnt(0)
	v_mfma_f32_32x32x16_bf16 v[50:65], v[88:91], v[96:99], v[50:65]
	v_mfma_f32_32x32x16_bf16 v[2:17], v[100:103], v[92:95], v[2:17]
	v_mfma_f32_32x32x16_bf16 v[18:33], v[100:103], v[96:99], v[18:33]
	s_setprio 0
	s_barrier
; #define MFMA(a, b, c) __builtin_amdgcn_mfma_f32_32x32x16_bf16((a), (b), (c), 0, 0, 0)
; template <int TM, int TN>
; DI void gemm_mainloop(const u16* __restrict__ A, long lda, const u16* __restrict__ Bt, long ldb, int K, char* smem,
;                       f32x16 (&acc)[TM][TN]) {
;     ...
;   for (int kt = 0; kt < nk; kt++) {
;     const int buf = kt & 1;
;     const u16* cA = sA + buf * BM * LD + (wm * 32 * TM + r) * LD + h * 8;
;     const u16* cB = sB + buf * BN * LD + (wn * 32 * TN + r) * LD + h * 8;
;     bf16x8 af[TM], bfr[TN];
; #pragma unroll
;     for (int tm = 0; tm < TM; tm++) af[tm] = *(const bf16x8*)(cA + tm * 32 * LD);
; #pragma unroll
;     for (int tn = 0; tn < TN; tn++) bfr[tn] = *(const bf16x8*)(cB + tn * 32 * LD);
;     if (kt + 1 < nk) GEMM_SSTORE(buf ^ 1)
;     __builtin_amdgcn_sched_barrier(0);
;     __builtin_amdgcn_s_setprio(1);
; #pragma unroll
;     for (int tm = 0; tm < TM; tm++)
; #pragma unroll
;       for (int tn = 0; tn < TN; tn++) acc[tm][tn] = MFMA(af[tm], bfr[tn], acc[tm][tn]);
; #pragma unroll
;     for (int tm = 0; tm < TM; tm++) af[tm] = *(const bf16x8*)(cA + tm * 32 * LD + 16);
; #pragma unroll
;     for (int tn = 0; tn < TN; tn++) bfr[tn] = *(const bf16x8*)(cB + tn * 32 * LD + 16);
; #pragma unroll
;     for (int tm = 0; tm < TM; tm++)
; #pragma unroll
;       for (int tn = 0; tn < TN; tn++) acc[tm][tn] = MFMA(af[tm], bfr[tn], acc[tm][tn]);
;     __builtin_amdgcn_sched_group_barrier(0x8, 4, 0);
;     if (kt + 2 < nk) GEMM_GLOAD((kt + 2) * 64)
; #pragma unroll
;     for (int ks = 2; ks < 4; ks++) {
; #pragma unroll
;       for (int tm = 0; tm < TM; tm++) af[tm] = *(const bf16x8*)(cA + tm * 32 * LD + ks * 16);
; #pragma unroll
;       for (int tn = 0; tn < TN; tn++) bfr[tn] = *(const bf16x8*)(cB + tn * 32 * LD + ks * 16);
; #pragma unroll
;       for (int tm = 0; tm < TM; tm++)
; #pragma unroll
;         for (int tn = 0; tn < TN; tn++) acc[tm][tn] = MFMA(af[tm], bfr[tn], acc[tm][tn]);
;     }
;     __builtin_amdgcn_s_setprio(0);
;     __syncthreads();
;   }
	ds_read_b128 v[96:99], v70 offset:18432
	ds_read_b128 v[100:103], v70 offset:23040
	ds_read_b128 v[128:131], v1 offset:55296
	ds_read_b128 v[132:135], v1 offset:59904
	s_setprio 1
	ds_read_b128 v[88:91], v70 offset:18464
	s_waitcnt lgkmcnt(2)
	v_mfma_f32_32x32x16_bf16 v[34:49], v[96:99], v[128:131], v[34:49]
	s_waitcnt vmcnt(7)
	ds_write_b128 v66, v[140:143]
	s_waitcnt vmcnt(6)
	ds_write_b128 v66, v[104:107] offset:4608
	global_load_dwordx4 v[140:143], v[74:75], off offset:1408
	global_load_dwordx4 v[104:107], v[72:73], off offset:1408
	ds_read_b128 v[92:95], v1 offset:55328
	s_waitcnt lgkmcnt(4)
	v_mfma_f32_32x32x16_bf16 v[50:65], v[96:99], v[132:135], v[50:65]
	ds_read_b128 v[96:99], v1 offset:59936
	s_waitcnt lgkmcnt(1)
	v_mfma_f32_32x32x16_bf16 v[34:49], v[88:91], v[92:95], v[34:49]
	s_waitcnt lgkmcnt(0)
	v_mfma_f32_32x32x16_bf16 v[50:65], v[88:91], v[96:99], v[50:65]
	s_waitcnt vmcnt(7)
	ds_write_b128 v66, v[108:111] offset:9216
	s_waitcnt vmcnt(6)
	ds_write_b128 v66, v[112:115] offset:13824
	global_load_dwordx4 v[108:111], v[76:77], off offset:1408
	global_load_dwordx4 v[112:115], v[86:87], off offset:1408
	ds_read_b128 v[88:91], v70 offset:23072
	v_mfma_f32_32x32x16_bf16 v[2:17], v[100:103], v[128:131], v[2:17]
	v_mfma_f32_32x32x16_bf16 v[18:33], v[100:103], v[132:135], v[18:33]
	ds_read_b128 v[100:103], v70 offset:23136
	s_waitcnt lgkmcnt(1)
	v_mfma_f32_32x32x16_bf16 v[2:17], v[88:91], v[92:95], v[2:17]
	s_waitcnt vmcnt(7)
	ds_write_b128 v66, v[144:147] offset:36864
	s_waitcnt vmcnt(6)
	ds_write_b128 v66, v[124:127] offset:41472
	global_load_dwordx4 v[144:147], v[78:79], off offset:1408
	global_load_dwordx4 v[124:127], v[80:81], off offset:1408
	ds_read_b128 v[92:95], v1 offset:55360
	v_mfma_f32_32x32x16_bf16 v[18:33], v[88:91], v[96:99], v[18:33]
	ds_read_b128 v[88:91], v70 offset:18496
	ds_read_b128 v[96:99], v1 offset:59968
	s_waitcnt lgkmcnt(1)
	v_mfma_f32_32x32x16_bf16 v[34:49], v[88:91], v[92:95], v[34:49]
	s_waitcnt lgkmcnt(0)
	v_mfma_f32_32x32x16_bf16 v[50:65], v[88:91], v[96:99], v[50:65]
	s_waitcnt vmcnt(7)
	ds_write_b128 v66, v[120:123] offset:46080
	s_waitcnt vmcnt(6)
	ds_write_b128 v66, v[116:119] offset:50688
	global_load_dwordx4 v[120:123], v[82:83], off offset:1408
	global_load_dwordx4 v[116:119], v[84:85], off offset:1408
	ds_read_b128 v[88:91], v70 offset:23104
	s_waitcnt lgkmcnt(0)
	v_mfma_f32_32x32x16_bf16 v[2:17], v[88:91], v[92:95], v[2:17]
	ds_read_b128 v[92:95], v1 offset:55392
	v_mfma_f32_32x32x16_bf16 v[18:33], v[88:91], v[96:99], v[18:33]
	ds_read_b128 v[88:91], v70 offset:18528
	ds_read_b128 v[96:99], v1 offset:60000
	s_waitcnt lgkmcnt(1)
	v_mfma_f32_32x32x16_bf16 v[34:49], v[88:91], v[92:95], v[34:49]
	s_waitcnt lgkmcnt(0)
	v_mfma_f32_32x32x16_bf16 v[50:65], v[88:91], v[96:99], v[50:65]
	v_mfma_f32_32x32x16_bf16 v[2:17], v[100:103], v[92:95], v[2:17]
	v_mfma_f32_32x32x16_bf16 v[18:33], v[100:103], v[96:99], v[18:33]
	s_setprio 0
	s_barrier
	ds_read_b128 v[96:99], v70
	ds_read_b128 v[100:103], v70 offset:4608
	ds_read_b128 v[128:131], v1 offset:36864
	ds_read_b128 v[132:135], v1 offset:41472
	s_setprio 1
	ds_read_b128 v[88:91], v70 offset:32
	s_waitcnt lgkmcnt(2)
	v_mfma_f32_32x32x16_bf16 v[34:49], v[96:99], v[128:131], v[34:49]
	s_waitcnt vmcnt(7)
	ds_write_b128 v66, v[140:143] offset:18432
	s_waitcnt vmcnt(6)
	ds_write_b128 v66, v[104:107] offset:23040
	global_load_dwordx4 v[140:143], v[74:75], off offset:1536
	global_load_dwordx4 v[104:107], v[72:73], off offset:1536
	ds_read_b128 v[92:95], v1 offset:36896
	s_waitcnt lgkmcnt(4)
	v_mfma_f32_32x32x16_bf16 v[50:65], v[96:99], v[132:135], v[50:65]
	ds_read_b128 v[96:99], v1 offset:41504
	s_waitcnt lgkmcnt(1)
	v_mfma_f32_32x32x16_bf16 v[34:49], v[88:91], v[92:95], v[34:49]
	s_waitcnt lgkmcnt(0)
	v_mfma_f32_32x32x16_bf16 v[50:65], v[88:91], v[96:99], v[50:65]
	s_waitcnt vmcnt(7)
	ds_write_b128 v66, v[108:111] offset:27648
	s_waitcnt vmcnt(6)
	ds_write_b128 v66, v[112:115] offset:32256
	global_load_dwordx4 v[108:111], v[76:77], off offset:1536
	global_load_dwordx4 v[112:115], v[86:87], off offset:1536
	ds_read_b128 v[88:91], v70 offset:4640
	v_mfma_f32_32x32x16_bf16 v[2:17], v[100:103], v[128:131], v[2:17]
	v_mfma_f32_32x32x16_bf16 v[18:33], v[100:103], v[132:135], v[18:33]
	ds_read_b128 v[100:103], v70 offset:4704
	s_waitcnt lgkmcnt(1)
	v_mfma_f32_32x32x16_bf16 v[2:17], v[88:91], v[92:95], v[2:17]
	s_waitcnt vmcnt(7)
	ds_write_b128 v66, v[144:147] offset:55296
	s_waitcnt vmcnt(6)
	ds_write_b128 v66, v[124:127] offset:59904
	global_load_dwordx4 v[144:147], v[78:79], off offset:1536
	global_load_dwordx4 v[124:127], v[80:81], off offset:1536
	ds_read_b128 v[92:95], v1 offset:36928
	v_mfma_f32_32x32x16_bf16 v[18:33], v[88:91], v[96:99], v[18:33]
	ds_read_b128 v[88:91], v70 offset:64
	ds_read_b128 v[96:99], v1 offset:41536
	s_waitcnt lgkmcnt(1)
	v_mfma_f32_32x32x16_bf16 v[34:49], v[88:91], v[92:95], v[34:49]
	s_waitcnt lgkmcnt(0)
	v_mfma_f32_32x32x16_bf16 v[50:65], v[88:91], v[96:99], v[50:65]
	s_waitcnt vmcnt(7)
	ds_write_b128 v66, v[120:123] offset:64512
	s_waitcnt vmcnt(6)
	ds_write_b128 v71, v[116:119] offset:32256
	global_load_dwordx4 v[120:123], v[82:83], off offset:1536
	global_load_dwordx4 v[116:119], v[84:85], off offset:1536
	ds_read_b128 v[88:91], v70 offset:4672
	s_waitcnt lgkmcnt(0)
	v_mfma_f32_32x32x16_bf16 v[2:17], v[88:91], v[92:95], v[2:17]
	ds_read_b128 v[92:95], v1 offset:36960
	v_mfma_f32_32x32x16_bf16 v[18:33], v[88:91], v[96:99], v[18:33]
	ds_read_b128 v[88:91], v70 offset:96
	ds_read_b128 v[96:99], v1 offset:41568
	s_waitcnt lgkmcnt(1)
	v_mfma_f32_32x32x16_bf16 v[34:49], v[88:91], v[92:95], v[34:49]
	s_waitcnt lgkmcnt(0)
	v_mfma_f32_32x32x16_bf16 v[50:65], v[88:91], v[96:99], v[50:65]
	v_mfma_f32_32x32x16_bf16 v[2:17], v[100:103], v[92:95], v[2:17]
	v_mfma_f32_32x32x16_bf16 v[18:33], v[100:103], v[96:99], v[18:33]
	s_setprio 0
	s_barrier
; #define MFMA(a, b, c) __builtin_amdgcn_mfma_f32_32x32x16_bf16((a), (b), (c), 0, 0, 0)
; template <int TM, int TN>
; DI void gemm_mainloop(const u16* __restrict__ A, long lda, const u16* __restrict__ Bt, long ldb, int K, char* smem,
;                       f32x16 (&acc)[TM][TN]) {
;     ...
;   for (int kt = 0; kt < nk; kt++) {
;     const int buf = kt & 1;
;     const u16* cA = sA + buf * BM * LD + (wm * 32 * TM + r) * LD + h * 8;
;     const u16* cB = sB + buf * BN * LD + (wn * 32 * TN + r) * LD + h * 8;
;     bf16x8 af[TM], bfr[TN];
; #pragma unroll
;     for (int tm = 0; tm < TM; tm++) af[tm] = *(const bf16x8*)(cA + tm * 32 * LD);
; #pragma unroll
;     for (int tn = 0; tn < TN; tn++) bfr[tn] = *(const bf16x8*)(cB + tn * 32 * LD);
;     if (kt + 1 < nk) GEMM_SSTORE(buf ^ 1)
;     __builtin_amdgcn_sched_barrier(0);
;     __builtin_amdgcn_s_setprio(1);
; #pragma unroll
;     for (int tm = 0; tm < TM; tm++)
; #pragma unroll
;       for (int tn = 0; tn < TN; tn++) acc[tm][tn] = MFMA(af[tm], bfr[tn], acc[tm][tn]);
; #pragma unroll
;     for (int tm = 0; tm < TM; tm++) af[tm] = *(const bf16x8*)(cA + tm * 32 * LD + 16);
; #pragma unroll
;     for (int tn = 0; tn < TN; tn++) bfr[tn] = *(const bf16x8*)(cB + tn * 32 * LD + 16);
; #pragma unroll
;     for (int tm = 0; tm < TM; tm++)
; #pragma unroll
;       for (int tn = 0; tn < TN; tn++) acc[tm][tn] = MFMA(af[tm], bfr[tn], acc[tm][tn]);
;     __builtin_amdgcn_sched_group_barrier(0x8, 4, 0);
;     if (kt + 2 < nk) GEMM_GLOAD((kt + 2) * 64)
; #pragma unroll
;     for (int ks = 2; ks < 4; ks++) {
; #pragma unroll
;       for (int tm = 0; tm < TM; tm++) af[tm] = *(const bf16x8*)(cA + tm * 32 * LD + ks * 16);
; #pragma unroll
;       for (int tn = 0; tn < TN; tn++) bfr[tn] = *(const bf16x8*)(cB + tn * 32 * LD + ks * 16);
; #pragma unroll
;       for (int tm = 0; tm < TM; tm++)
; #pragma unroll
;         for (int tn = 0; tn < TN; tn++) acc[tm][tn] = MFMA(af[tm], bfr[tn], acc[tm][tn]);
;     }
	ds_read_b128 v[96:99], v70 offset:18432
	ds_read_b128 v[100:103], v70 offset:23040
	ds_read_b128 v[128:131], v1 offset:55296
	ds_read_b128 v[132:135], v1 offset:59904
	s_setprio 1
	ds_read_b128 v[88:91], v70 offset:18464
	s_waitcnt lgkmcnt(2)
	v_mfma_f32_32x32x16_bf16 v[34:49], v[96:99], v[128:131], v[34:49]
	s_waitcnt vmcnt(7)
	ds_write_b128 v66, v[140:143]
	s_waitcnt vmcnt(6)
	ds_write_b128 v66, v[104:107] offset:4608
	global_load_dwordx4 v[140:143], v[74:75], off offset:1664
	global_load_dwordx4 v[104:107], v[72:73], off offset:1664
	ds_read_b128 v[92:95], v1 offset:55328
	s_waitcnt lgkmcnt(4)
	v_mfma_f32_32x32x16_bf16 v[50:65], v[96:99], v[132:135], v[50:65]
	ds_read_b128 v[96:99], v1 offset:59936
	s_waitcnt lgkmcnt(1)
	v_mfma_f32_32x32x16_bf16 v[34:49], v[88:91], v[92:95], v[34:49]
	s_waitcnt lgkmcnt(0)
	v_mfma_f32_32x32x16_bf16 v[50:65], v[88:91], v[96:99], v[50:65]
	s_waitcnt vmcnt(7)
	ds_write_b128 v66, v[108:111] offset:9216
	s_waitcnt vmcnt(6)
	ds_write_b128 v66, v[112:115] offset:13824
	global_load_dwordx4 v[108:111], v[76:77], off offset:1664
	global_load_dwordx4 v[112:115], v[86:87], off offset:1664
	ds_read_b128 v[88:91], v70 offset:23072
	v_mfma_f32_32x32x16_bf16 v[2:17], v[100:103], v[128:131], v[2:17]
	v_mfma_f32_32x32x16_bf16 v[18:33], v[100:103], v[132:135], v[18:33]
	ds_read_b128 v[100:103], v70 offset:23136
	s_waitcnt lgkmcnt(1)
	v_mfma_f32_32x32x16_bf16 v[2:17], v[88:91], v[92:95], v[2:17]
	s_waitcnt vmcnt(7)
	ds_write_b128 v66, v[144:147] offset:36864
	s_waitcnt vmcnt(6)
	ds_write_b128 v66, v[124:127] offset:41472
	global_load_dwordx4 v[144:147], v[78:79], off offset:1664
	global_load_dwordx4 v[124:127], v[80:81], off offset:1664
	ds_read_b128 v[92:95], v1 offset:55360
	v_mfma_f32_32x32x16_bf16 v[18:33], v[88:91], v[96:99], v[18:33]
	ds_read_b128 v[88:91], v70 offset:18496
	ds_read_b128 v[96:99], v1 offset:59968
	s_waitcnt lgkmcnt(1)
	v_mfma_f32_32x32x16_bf16 v[34:49], v[88:91], v[92:95], v[34:49]
	s_waitcnt lgkmcnt(0)
	v_mfma_f32_32x32x16_bf16 v[50:65], v[88:91], v[96:99], v[50:65]
	s_waitcnt vmcnt(7)
	ds_write_b128 v66, v[120:123] offset:46080
	s_waitcnt vmcnt(6)
	ds_write_b128 v66, v[116:119] offset:50688
	global_load_dwordx4 v[120:123], v[82:83], off offset:1664
	global_load_dwordx4 v[116:119], v[84:85], off offset:1664
	ds_read_b128 v[88:91], v70 offset:23104
	s_waitcnt lgkmcnt(0)
	v_mfma_f32_32x32x16_bf16 v[2:17], v[88:91], v[92:95], v[2:17]
	ds_read_b128 v[92:95], v1 offset:55392
	v_mfma_f32_32x32x16_bf16 v[18:33], v[88:91], v[96:99], v[18:33]
	ds_read_b128 v[88:91], v70 offset:18528
	ds_read_b128 v[96:99], v1 offset:60000
	s_waitcnt lgkmcnt(1)
	v_mfma_f32_32x32x16_bf16 v[34:49], v[88:91], v[92:95], v[34:49]
	s_waitcnt lgkmcnt(0)
	v_mfma_f32_32x32x16_bf16 v[50:65], v[88:91], v[96:99], v[50:65]
	v_mfma_f32_32x32x16_bf16 v[2:17], v[100:103], v[92:95], v[2:17]
	v_mfma_f32_32x32x16_bf16 v[18:33], v[100:103], v[96:99], v[18:33]
	s_setprio 0
	s_barrier
	ds_read_b128 v[96:99], v70
	ds_read_b128 v[100:103], v70 offset:4608
	ds_read_b128 v[128:131], v1 offset:36864
	ds_read_b128 v[132:135], v1 offset:41472
	s_setprio 1
	ds_read_b128 v[88:91], v70 offset:32
	s_waitcnt lgkmcnt(2)
	v_mfma_f32_32x32x16_bf16 v[34:49], v[96:99], v[128:131], v[34:49]
	s_waitcnt vmcnt(7)
	ds_write_b128 v66, v[140:143] offset:18432
	s_waitcnt vmcnt(6)
	ds_write_b128 v66, v[104:107] offset:23040
	global_load_dwordx4 v[140:143], v[74:75], off offset:1792
	global_load_dwordx4 v[104:107], v[72:73], off offset:1792
	ds_read_b128 v[92:95], v1 offset:36896
	s_waitcnt lgkmcnt(4)
	v_mfma_f32_32x32x16_bf16 v[50:65], v[96:99], v[132:135], v[50:65]
	ds_read_b128 v[96:99], v1 offset:41504
	s_waitcnt lgkmcnt(1)
	v_mfma_f32_32x32x16_bf16 v[34:49], v[88:91], v[92:95], v[34:49]
	s_waitcnt lgkmcnt(0)
	v_mfma_f32_32x32x16_bf16 v[50:65], v[88:91], v[96:99], v[50:65]
	s_waitcnt vmcnt(7)
	ds_write_b128 v66, v[108:111] offset:27648
	s_waitcnt vmcnt(6)
	ds_write_b128 v66, v[112:115] offset:32256
	global_load_dwordx4 v[108:111], v[76:77], off offset:1792
	global_load_dwordx4 v[112:115], v[86:87], off offset:1792
	ds_read_b128 v[88:91], v70 offset:4640
	v_mfma_f32_32x32x16_bf16 v[2:17], v[100:103], v[128:131], v[2:17]
	v_mfma_f32_32x32x16_bf16 v[18:33], v[100:103], v[132:135], v[18:33]
	ds_read_b128 v[100:103], v70 offset:4704
	s_waitcnt lgkmcnt(1)
	v_mfma_f32_32x32x16_bf16 v[2:17], v[88:91], v[92:95], v[2:17]
	s_waitcnt vmcnt(7)
	ds_write_b128 v66, v[144:147] offset:55296
	s_waitcnt vmcnt(6)
	ds_write_b128 v66, v[124:127] offset:59904
	global_load_dwordx4 v[144:147], v[78:79], off offset:1792
	global_load_dwordx4 v[124:127], v[80:81], off offset:1792
	ds_read_b128 v[92:95], v1 offset:36928
	v_mfma_f32_32x32x16_bf16 v[18:33], v[88:91], v[96:99], v[18:33]
	ds_read_b128 v[88:91], v70 offset:64
	ds_read_b128 v[96:99], v1 offset:41536
	s_waitcnt lgkmcnt(1)
	v_mfma_f32_32x32x16_bf16 v[34:49], v[88:91], v[92:95], v[34:49]
	s_waitcnt lgkmcnt(0)
	v_mfma_f32_32x32x16_bf16 v[50:65], v[88:91], v[96:99], v[50:65]
	s_waitcnt vmcnt(7)
	ds_write_b128 v66, v[120:123] offset:64512
	s_waitcnt vmcnt(6)
	ds_write_b128 v71, v[116:119] offset:32256
	global_load_dwordx4 v[120:123], v[82:83], off offset:1792
	global_load_dwordx4 v[116:119], v[84:85], off offset:1792
	ds_read_b128 v[88:91], v70 offset:4672
	s_waitcnt lgkmcnt(0)
	v_mfma_f32_32x32x16_bf16 v[2:17], v[88:91], v[92:95], v[2:17]
	ds_read_b128 v[92:95], v1 offset:36960
	v_mfma_f32_32x32x16_bf16 v[18:33], v[88:91], v[96:99], v[18:33]
	ds_read_b128 v[88:91], v70 offset:96
	ds_read_b128 v[96:99], v1 offset:41568
	s_waitcnt lgkmcnt(1)
	v_mfma_f32_32x32x16_bf16 v[34:49], v[88:91], v[92:95], v[34:49]
	s_waitcnt lgkmcnt(0)
	v_mfma_f32_32x32x16_bf16 v[50:65], v[88:91], v[96:99], v[50:65]
	v_mfma_f32_32x32x16_bf16 v[2:17], v[100:103], v[92:95], v[2:17]
	v_mfma_f32_32x32x16_bf16 v[18:33], v[100:103], v[96:99], v[18:33]
	s_setprio 0
	s_barrier
; #define MFMA(a, b, c) __builtin_amdgcn_mfma_f32_32x32x16_bf16((a), (b), (c), 0, 0, 0)
; template <int TM, int TN>
; DI void gemm_mainloop(const u16* __restrict__ A, long lda, const u16* __restrict__ Bt, long ldb, int K, char* smem,
;                       f32x16 (&acc)[TM][TN]) {
;     ...
;   for (int kt = 0; kt < nk; kt++) {
;     const int buf = kt & 1;
;     const u16* cA = sA + buf * BM * LD + (wm * 32 * TM + r) * LD + h * 8;
;     const u16* cB = sB + buf * BN * LD + (wn * 32 * TN + r) * LD + h * 8;
;     bf16x8 af[TM], bfr[TN];
; #pragma unroll
;     for (int tm = 0; tm < TM; tm++) af[tm] = *(const bf16x8*)(cA + tm * 32 * LD);
; #pragma unroll
;     for (int tn = 0; tn < TN; tn++) bfr[tn] = *(const bf16x8*)(cB + tn * 32 * LD);
;     if (kt + 1 < nk) GEMM_SSTORE(buf ^ 1)
;     __builtin_amdgcn_sched_barrier(0);
;     __builtin_amdgcn_s_setprio(1);
; #pragma unroll
;     for (int tm = 0; tm < TM; tm++)
; #pragma unroll
;       for (int tn = 0; tn < TN; tn++) acc[tm][tn] = MFMA(af[tm], bfr[tn], acc[tm][tn]);
; #pragma unroll
;     for (int tm = 0; tm < TM; tm++) af[tm] = *(const bf16x8*)(cA + tm * 32 * LD + 16);
; #pragma unroll
;     for (int tn = 0; tn < TN; tn++) bfr[tn] = *(const bf16x8*)(cB + tn * 32 * LD + 16);
; #pragma unroll
;     for (int tm = 0; tm < TM; tm++)
; #pragma unroll
;       for (int tn = 0; tn < TN; tn++) acc[tm][tn] = MFMA(af[tm], bfr[tn], acc[tm][tn]);
;     __builtin_amdgcn_sched_group_barrier(0x8, 4, 0);
;     if (kt + 2 < nk) GEMM_GLOAD((kt + 2) * 64)
; #pragma unroll
;     for (int ks = 2; ks < 4; ks++) {
; #pragma unroll
;       for (int tm = 0; tm < TM; tm++) af[tm] = *(const bf16x8*)(cA + tm * 32 * LD + ks * 16);
; #pragma unroll
;       for (int tn = 0; tn < TN; tn++) bfr[tn] = *(const bf16x8*)(cB + tn * 32 * LD + ks * 16);
; #pragma unroll
;       for (int tm = 0; tm < TM; tm++)
; #pragma unroll
;         for (int tn = 0; tn < TN; tn++) acc[tm][tn] = MFMA(af[tm], bfr[tn], acc[tm][tn]);
;     }
	ds_read_b128 v[96:99], v70 offset:18432
	ds_read_b128 v[100:103], v70 offset:23040
	ds_read_b128 v[128:131], v1 offset:55296
	ds_read_b128 v[132:135], v1 offset:59904
	s_setprio 1
	ds_read_b128 v[88:91], v70 offset:18464
	s_waitcnt lgkmcnt(2)
	v_mfma_f32_32x32x16_bf16 v[34:49], v[96:99], v[128:131], v[34:49]
	s_waitcnt vmcnt(7)
	ds_write_b128 v66, v[140:143]
	s_waitcnt vmcnt(6)
	ds_write_b128 v66, v[104:107] offset:4608
	global_load_dwordx4 v[140:143], v[74:75], off offset:1920
	global_load_dwordx4 v[104:107], v[72:73], off offset:1920
	ds_read_b128 v[92:95], v1 offset:55328
	s_waitcnt lgkmcnt(4)
	v_mfma_f32_32x32x16_bf16 v[50:65], v[96:99], v[132:135], v[50:65]
	ds_read_b128 v[96:99], v1 offset:59936
	s_waitcnt lgkmcnt(1)
	v_mfma_f32_32x32x16_bf16 v[34:49], v[88:91], v[92:95], v[34:49]
	s_waitcnt lgkmcnt(0)
	v_mfma_f32_32x32x16_bf16 v[50:65], v[88:91], v[96:99], v[50:65]
	s_waitcnt vmcnt(7)
	ds_write_b128 v66, v[108:111] offset:9216
	s_waitcnt vmcnt(6)
	ds_write_b128 v66, v[112:115] offset:13824
	global_load_dwordx4 v[108:111], v[76:77], off offset:1920
	global_load_dwordx4 v[112:115], v[86:87], off offset:1920
	ds_read_b128 v[88:91], v70 offset:23072
	v_mfma_f32_32x32x16_bf16 v[2:17], v[100:103], v[128:131], v[2:17]
	v_mfma_f32_32x32x16_bf16 v[18:33], v[100:103], v[132:135], v[18:33]
	ds_read_b128 v[100:103], v70 offset:23136
	s_waitcnt lgkmcnt(1)
	v_mfma_f32_32x32x16_bf16 v[2:17], v[88:91], v[92:95], v[2:17]
	s_waitcnt vmcnt(7)
	ds_write_b128 v66, v[144:147] offset:36864
	s_waitcnt vmcnt(6)
	ds_write_b128 v66, v[124:127] offset:41472
	global_load_dwordx4 v[144:147], v[78:79], off offset:1920
	global_load_dwordx4 v[124:127], v[80:81], off offset:1920
	ds_read_b128 v[92:95], v1 offset:55360
	v_mfma_f32_32x32x16_bf16 v[18:33], v[88:91], v[96:99], v[18:33]
	ds_read_b128 v[88:91], v70 offset:18496
	ds_read_b128 v[96:99], v1 offset:59968
	s_waitcnt lgkmcnt(1)
	v_mfma_f32_32x32x16_bf16 v[34:49], v[88:91], v[92:95], v[34:49]
	s_waitcnt lgkmcnt(0)
	v_mfma_f32_32x32x16_bf16 v[50:65], v[88:91], v[96:99], v[50:65]
	s_waitcnt vmcnt(7)
	ds_write_b128 v66, v[120:123] offset:46080
	s_waitcnt vmcnt(6)
	ds_write_b128 v66, v[116:119] offset:50688
	global_load_dwordx4 v[120:123], v[82:83], off offset:1920
	global_load_dwordx4 v[116:119], v[84:85], off offset:1920
	ds_read_b128 v[88:91], v70 offset:23104
	s_waitcnt lgkmcnt(0)
	v_mfma_f32_32x32x16_bf16 v[2:17], v[88:91], v[92:95], v[2:17]
	ds_read_b128 v[92:95], v1 offset:55392
	v_mfma_f32_32x32x16_bf16 v[18:33], v[88:91], v[96:99], v[18:33]
	ds_read_b128 v[88:91], v70 offset:18528
	ds_read_b128 v[96:99], v1 offset:60000
	s_waitcnt lgkmcnt(1)
	v_mfma_f32_32x32x16_bf16 v[34:49], v[88:91], v[92:95], v[34:49]
	s_waitcnt lgkmcnt(0)
	v_mfma_f32_32x32x16_bf16 v[50:65], v[88:91], v[96:99], v[50:65]
	s_nop 0
	v_mfma_f32_32x32x16_bf16 v[2:17], v[100:103], v[92:95], v[2:17]
	v_mfma_f32_32x32x16_bf16 v[18:33], v[100:103], v[96:99], v[18:33]
	s_setprio 0
	s_barrier
	ds_read_b128 v[76:79], v70
	ds_read_b128 v[80:83], v70 offset:4608
	ds_read_b128 v[84:87], v1 offset:36864
	ds_read_b128 v[92:95], v1 offset:41472
	s_setprio 1
	ds_read_b128 v[72:75], v70 offset:32
	s_waitcnt lgkmcnt(2)
	v_mfma_f32_32x32x16_bf16 v[34:49], v[76:79], v[84:87], v[34:49]
	s_waitcnt vmcnt(7)
	ds_write_b128 v66, v[140:143] offset:18432
	s_waitcnt vmcnt(6)
	ds_write_b128 v66, v[104:107] offset:23040
	s_waitcnt lgkmcnt(3)
	v_mfma_f32_32x32x16_bf16 v[50:65], v[76:79], v[92:95], v[50:65]
	ds_read_b128 v[76:79], v1 offset:36896
	v_mfma_f32_32x32x16_bf16 v[2:17], v[80:83], v[84:87], v[2:17]
	v_mfma_f32_32x32x16_bf16 v[18:33], v[80:83], v[92:95], v[18:33]
	s_waitcnt vmcnt(5)
	ds_write_b128 v66, v[108:111] offset:27648
	s_waitcnt vmcnt(4)
	ds_write_b128 v66, v[112:115] offset:32256
	ds_read_b128 v[80:83], v1 offset:41504
	s_waitcnt lgkmcnt(3)
	v_mfma_f32_32x32x16_bf16 v[34:49], v[72:75], v[76:79], v[34:49]
	s_waitcnt lgkmcnt(0)
	v_mfma_f32_32x32x16_bf16 v[50:65], v[72:75], v[80:83], v[50:65]
	ds_read_b128 v[72:75], v70 offset:4640
	s_waitcnt lgkmcnt(0)
	v_mfma_f32_32x32x16_bf16 v[2:17], v[72:75], v[76:79], v[2:17]
	s_waitcnt vmcnt(3)
	ds_write_b128 v66, v[144:147] offset:55296
	s_waitcnt vmcnt(2)
	ds_write_b128 v66, v[124:127] offset:59904
	ds_read_b128 v[76:79], v1 offset:36928
	v_mfma_f32_32x32x16_bf16 v[18:33], v[72:75], v[80:83], v[18:33]
	ds_read_b128 v[72:75], v70 offset:64
	ds_read_b128 v[80:83], v1 offset:41536
	s_waitcnt lgkmcnt(1)
	v_mfma_f32_32x32x16_bf16 v[34:49], v[72:75], v[76:79], v[34:49]
	s_waitcnt lgkmcnt(0)
	v_mfma_f32_32x32x16_bf16 v[50:65], v[72:75], v[80:83], v[50:65]
	s_waitcnt vmcnt(1)
	ds_write_b128 v66, v[120:123] offset:64512
	s_waitcnt vmcnt(0)
	ds_write_b128 v71, v[116:119] offset:32256
	ds_read_b128 v[72:75], v70 offset:4672
	s_waitcnt lgkmcnt(0)
	v_mfma_f32_32x32x16_bf16 v[2:17], v[72:75], v[76:79], v[2:17]
	ds_read_b128 v[76:79], v1 offset:36960
	v_mfma_f32_32x32x16_bf16 v[18:33], v[72:75], v[80:83], v[18:33]
	ds_read_b128 v[72:75], v70 offset:96
	ds_read_b128 v[80:83], v1 offset:41568
	s_waitcnt lgkmcnt(1)
	v_mfma_f32_32x32x16_bf16 v[34:49], v[72:75], v[76:79], v[34:49]
	s_waitcnt lgkmcnt(0)
	v_mfma_f32_32x32x16_bf16 v[50:65], v[72:75], v[80:83], v[50:65]
	ds_read_b128 v[72:75], v70 offset:4704
	s_waitcnt lgkmcnt(0)
	v_mfma_f32_32x32x16_bf16 v[2:17], v[72:75], v[76:79], v[2:17]
	v_mfma_f32_32x32x16_bf16 v[18:33], v[72:75], v[80:83], v[18:33]
	s_setprio 0
	s_barrier
; #define MFMA(a, b, c) __builtin_amdgcn_mfma_f32_32x32x16_bf16((a), (b), (c), 0, 0, 0)
; DI int crow(int i, int h) { return (i & 3) + 8 * (i >> 2) + 4 * h; }
; template <int TM, int TN>
; DI void gemm_mainloop(const u16* __restrict__ A, long lda, const u16* __restrict__ Bt, long ldb, int K, char* smem,
;                       f32x16 (&acc)[TM][TN]) {
;     ...
;     for (int tm = 0; tm < TM; tm++)
; #pragma unroll
;       for (int tn = 0; tn < TN; tn++) acc[tm][tn] = MFMA(af[tm], bfr[tn], acc[tm][tn]);
; #pragma unroll
;     for (int tm = 0; tm < TM; tm++) af[tm] = *(const bf16x8*)(cA + tm * 32 * LD + 16);
; #pragma unroll
;     for (int tn = 0; tn < TN; tn++) bfr[tn] = *(const bf16x8*)(cB + tn * 32 * LD + 16);
; #pragma unroll
;     for (int tm = 0; tm < TM; tm++)
; #pragma unroll
;       for (int tn = 0; tn < TN; tn++) acc[tm][tn] = MFMA(af[tm], bfr[tn], acc[tm][tn]);
;     __builtin_amdgcn_sched_group_barrier(0x8, 4, 0);
;     if (kt + 2 < nk) GEMM_GLOAD((kt + 2) * 64)
; #pragma unroll
;     for (int ks = 2; ks < 4; ks++) {
; #pragma unroll
;       for (int tm = 0; tm < TM; tm++) af[tm] = *(const bf16x8*)(cA + tm * 32 * LD + ks * 16);
; #pragma unroll
;       for (int tn = 0; tn < TN; tn++) bfr[tn] = *(const bf16x8*)(cB + tn * 32 * LD + ks * 16);
; #pragma unroll
;       for (int tm = 0; tm < TM; tm++)
; #pragma unroll
;         for (int tn = 0; tn < TN; tn++) acc[tm][tn] = MFMA(af[tm], bfr[tn], acc[tm][tn]);
;     }
;     __builtin_amdgcn_s_setprio(0);
;     __syncthreads();
;   }
; template <int TM, int TN, class Epi>
; DI void gemm_tile(const u16* A, long lda, const u16* Bt, long ldb, int K, int m0, int n0, char* smem, const Epi& epi) {
;     ...
; #pragma unroll
;   for (int tm = 0; tm < TM; tm++)
; #pragma unroll
;     for (int tn = 0; tn < TN; tn++)
; #pragma unroll
;       for (int i = 0; i < 16; i++)
;         Ct[(wm * 32 * TM + tm * 32 + crow(i, h)) * LDC + wn * 32 * TN + tn * 32 + r] = acc[tm][tn][i];
;   __syncthreads();
;   epi(Ct, LDC, m0, n0, tid, BM);
	ds_read_b128 v[72:75], v70 offset:18432
	ds_read_b128 v[76:79], v70 offset:23040
	ds_read_b128 v[80:83], v1 offset:55296
	ds_read_b128 v[84:87], v1 offset:59904
	s_setprio 1
	s_waitcnt lgkmcnt(1)
	v_mfma_f32_32x32x16_bf16 v[34:49], v[72:75], v[80:83], v[34:49]
	s_waitcnt lgkmcnt(0)
	v_mfma_f32_32x32x16_bf16 v[50:65], v[72:75], v[84:87], v[50:65]
	ds_read_b128 v[72:75], v70 offset:18464
	v_mfma_f32_32x32x16_bf16 v[2:17], v[76:79], v[80:83], v[2:17]
	ds_read_b128 v[80:83], v1 offset:59936
	v_mfma_f32_32x32x16_bf16 v[18:33], v[76:79], v[84:87], v[18:33]
	ds_read_b128 v[76:79], v1 offset:55328
	s_waitcnt lgkmcnt(0)
	v_mfma_f32_32x32x16_bf16 v[34:49], v[72:75], v[76:79], v[34:49]
	v_mfma_f32_32x32x16_bf16 v[50:65], v[72:75], v[80:83], v[50:65]
	ds_read_b128 v[72:75], v70 offset:23072
	s_waitcnt lgkmcnt(0)
	v_mfma_f32_32x32x16_bf16 v[2:17], v[72:75], v[76:79], v[2:17]
	ds_read_b128 v[76:79], v1 offset:55360
	v_mfma_f32_32x32x16_bf16 v[18:33], v[72:75], v[80:83], v[18:33]
	ds_read_b128 v[72:75], v70 offset:18496
	ds_read_b128 v[80:83], v1 offset:59968
	s_waitcnt lgkmcnt(1)
	v_mfma_f32_32x32x16_bf16 v[34:49], v[72:75], v[76:79], v[34:49]
	s_waitcnt lgkmcnt(0)
	v_mfma_f32_32x32x16_bf16 v[50:65], v[72:75], v[80:83], v[50:65]
	ds_read_b128 v[72:75], v70 offset:23104
	s_waitcnt lgkmcnt(0)
	v_mfma_f32_32x32x16_bf16 v[2:17], v[72:75], v[76:79], v[2:17]
	ds_read_b128 v[76:79], v1 offset:55392
	v_mfma_f32_32x32x16_bf16 v[18:33], v[72:75], v[80:83], v[18:33]
	ds_read_b128 v[72:75], v70 offset:18528
	ds_read_b128 v[80:83], v1 offset:60000
	s_waitcnt lgkmcnt(1)
	v_mfma_f32_32x32x16_bf16 v[34:49], v[72:75], v[76:79], v[34:49]
	s_waitcnt lgkmcnt(0)
	v_mfma_f32_32x32x16_bf16 v[50:65], v[72:75], v[80:83], v[50:65]
	ds_read_b128 v[70:73], v70 offset:23136
	s_waitcnt lgkmcnt(0)
	v_mfma_f32_32x32x16_bf16 v[2:17], v[70:73], v[76:79], v[2:17]
	v_mfma_f32_32x32x16_bf16 v[18:33], v[70:73], v[80:83], v[18:33]
	s_setprio 0
	v_mov_b32_e32 v1, v0
	s_barrier
	s_mov_b32 s26, 0
	v_lshrrev_b32_e32 v66, 1, v1
	v_and_b32_e32 v66, 0xfffffc0, v66
	v_lshrrev_b32_e32 v70, 3, v1
	v_and_or_b32 v66, v70, 4, v66
	v_and_b32_e32 v70, 0x5f, v1
	v_mul_lo_u32 v66, v66, s22
	v_lshl_add_u32 v66, v70, 2, v66
	ds_write2_b32 v66, v34, v50 offset1:32
	v_add_u32_e32 v34, 0x400, v66
	ds_write2_b32 v34, v36, v52 offset0:8 offset1:40
	ds_write2_b32 v34, v37, v53 offset0:140 offset1:172
	v_add_u32_e32 v34, 0x1000, v66
	ds_write2_b32 v34, v38, v54 offset0:32 offset1:64
	ds_write2_b32 v34, v39, v55 offset0:164 offset1:196
	v_add_u32_e32 v34, 0x1400, v66
	ds_write2_b32 v34, v40, v56 offset0:40 offset1:72
	ds_write2_b32 v34, v41, v57 offset0:172 offset1:204
	v_add_u32_e32 v34, 0x2000, v66
	ds_write2_b32 v34, v42, v58 offset0:64 offset1:96
	ds_write2_b32 v34, v43, v59 offset0:196 offset1:228
	v_add_u32_e32 v34, 0x2400, v66
	ds_write2_b32 v34, v44, v60 offset0:72 offset1:104
	ds_write2_b32 v34, v45, v61 offset0:204 offset1:236
	v_add_u32_e32 v34, 0x3000, v66
	ds_write2_b32 v34, v46, v62 offset0:96 offset1:128
	v_add_u32_e32 v34, 0x3200, v66
	ds_write2_b32 v34, v47, v63 offset0:100 offset1:132
	v_add_u32_e32 v34, 0x3400, v66
	ds_write2_b32 v34, v48, v64 offset0:104 offset1:136
	v_add_u32_e32 v34, 0x3600, v66
	ds_write2_b32 v34, v49, v65 offset0:108 offset1:140
	v_add_u32_e32 v34, 0x4000, v66
	ds_write2_b32 v34, v2, v18 offset0:128 offset1:160
	v_add_u32_e32 v2, 0x4400, v66
	ds_write2_b32 v2, v3, v19 offset0:4 offset1:36
	ds_write2_b32 v2, v4, v20 offset0:136 offset1:168
	v_add_u32_e32 v2, 0x4800, v66
	ds_write2_b32 v2, v5, v21 offset0:12 offset1:44
	v_add_u32_e32 v2, 0x5000, v66
	ds_write2_b32 v2, v6, v22 offset0:160 offset1:192
	v_add_u32_e32 v2, 0x5400, v66
	ds_write2_b32 v2, v7, v23 offset0:36 offset1:68
	ds_write2_b32 v2, v8, v24 offset0:168 offset1:200
	v_add_u32_e32 v2, 0x5800, v66
	ds_write2_b32 v2, v9, v25 offset0:44 offset1:76
	v_add_u32_e32 v2, 0x6000, v66
	ds_write2_b32 v2, v10, v26 offset0:192 offset1:224
	v_add_u32_e32 v2, 0x6400, v66
	ds_write2_b32 v2, v11, v27 offset0:68 offset1:100
	ds_write2_b32 v2, v12, v28 offset0:200 offset1:232
	v_add_u32_e32 v2, 0x6800, v66
	ds_write2_b32 v2, v13, v29 offset0:76 offset1:108
	v_add_u32_e32 v2, 0x7200, v66
	ds_write2_b32 v2, v14, v30 offset0:96 offset1:128
	v_add_u32_e32 v2, 0x7400, v66
	ds_write2_b32 v2, v15, v31 offset0:100 offset1:132
	v_add_u32_e32 v2, 0x7600, v66
	ds_write2_b32 v2, v16, v32 offset0:104 offset1:136
	v_add_u32_e32 v2, 0x7800, v66
	ds_write2_b32 v2, v17, v33 offset0:108 offset1:140
	v_lshlrev_b32_e32 v2, 3, v1
	v_and_b32_e32 v2, 0x78, v2
	v_or_b32_e32 v4, s11, v2
	v_ashrrev_i32_e32 v5, 31, v4
	v_lshlrev_b32_e32 v2, 2, v2
	v_cmp_gt_i32_e32 vcc, s23, v4
	v_lshl_add_u64 v[4:5], v[4:5], 1, s[8:9]
	ds_write2_b32 v66, v35, v51 offset0:132 offset1:164
	s_waitcnt lgkmcnt(0)
	s_barrier
	s_branch .LBB0_2476

; #define MFMA(a, b, c) __builtin_amdgcn_mfma_f32_32x32x16_bf16((a), (b), (c), 0, 0, 0)
; template <int TM, int TN>
; DI void gemm_mainloop(const u16* __restrict__ A, long lda, const u16* __restrict__ Bt, long ldb, int K, char* smem,
;                       f32x16 (&acc)[TM][TN]) {
;     ...
;   const int nk = K / 64;
;   const int lrow = tid >> 3, lch = (tid & 7) * 8;
;   const u16* gA = A + (long)lrow * lda + lch;
;   const u16* gB = Bt + (long)lrow * ldb + lch;
;   const int soff = lrow * LD + lch;
;     ...
;   GEMM_GLOAD(0)
;   __syncthreads();
;   GEMM_SSTORE(0)
;   if (nk > 1) GEMM_GLOAD(64)
;   __syncthreads();
;   for (int kt = 0; kt < nk; kt++) {
;     const int buf = kt & 1;
;     const u16* cA = sA + buf * BM * LD + (wm * 32 * TM + r) * LD + h * 8;
;     const u16* cB = sB + buf * BN * LD + (wn * 32 * TN + r) * LD + h * 8;
;     bf16x8 af[TM], bfr[TN];
; #pragma unroll
;     for (int tm = 0; tm < TM; tm++) af[tm] = *(const bf16x8*)(cA + tm * 32 * LD);
; #pragma unroll
;     for (int tn = 0; tn < TN; tn++) bfr[tn] = *(const bf16x8*)(cB + tn * 32 * LD);
;     if (kt + 1 < nk) GEMM_SSTORE(buf ^ 1)
;     __builtin_amdgcn_sched_barrier(0);
;     __builtin_amdgcn_s_setprio(1);
; #pragma unroll
;     for (int tm = 0; tm < TM; tm++)
; #pragma unroll
;       for (int tn = 0; tn < TN; tn++) acc[tm][tn] = MFMA(af[tm], bfr[tn], acc[tm][tn]);
; #pragma unroll
;     for (int tm = 0; tm < TM; tm++) af[tm] = *(const bf16x8*)(cA + tm * 32 * LD + 16);
; #pragma unroll
;     for (int tn = 0; tn < TN; tn++) bfr[tn] = *(const bf16x8*)(cB + tn * 32 * LD + 16);
; #pragma unroll
;     for (int tm = 0; tm < TM; tm++)
; #pragma unroll
;       for (int tn = 0; tn < TN; tn++) acc[tm][tn] = MFMA(af[tm], bfr[tn], acc[tm][tn]);
;     __builtin_amdgcn_sched_group_barrier(0x8, 4, 0);
;     if (kt + 2 < nk) GEMM_GLOAD((kt + 2) * 64)
.LBB0_2745:
	s_lshl_b32 s6, s24, 8
	s_and_b32 s25, s6, 0xfffffe00
	s_lshl_b32 s6, s24, 11
	s_add_i32 s25, s25, s8
	s_and_b32 s6, s6, 0x800
	s_add_i32 s6, s6, s9
	s_mul_i32 s26, s25, 0x880
	s_mul_hi_i32 s7, s25, 0x880
	s_add_u32 s26, s4, s26
	v_mov_b32_e32 v1, v0
	s_addc_u32 s27, s5, s7
	s_ashr_i32 s7, s6, 31
	v_lshlrev_b32_e32 v2, 3, v1
	v_ashrrev_i32_e32 v68, 3, v1
	v_and_b32_e32 v69, 56, v2
	v_mov_b64_e32 v[2:3], s[26:27]
	v_mad_i64_i32 v[2:3], s[26:27], v68, s15, v[2:3]
	v_lshlrev_b32_e32 v66, 1, v69
	v_lshl_add_u64 v[72:73], v[2:3], 0, v[66:67]
	s_mul_i32 s28, s6, 0x880
	v_add_co_u32_e32 v70, vcc, s17, v72
	s_mul_hi_i32 s29, s6, 0x880
	s_add_u32 s28, s11, s28
	v_addc_co_u32_e32 v71, vcc, 0, v73, vcc
	s_addc_u32 s29, s14, s29
	v_add_co_u32_e32 v74, vcc, s18, v72
	v_mov_b64_e32 v[2:3], s[28:29]
	s_nop 0
	v_addc_co_u32_e32 v75, vcc, 0, v73, vcc
	v_mad_i64_i32 v[18:19], s[26:27], v68, s15, v[2:3]
	v_add_co_u32_e32 v78, vcc, s19, v72
	v_lshl_add_u64 v[76:77], v[18:19], 0, v[66:67]
	s_nop 0
	v_addc_co_u32_e32 v79, vcc, 0, v73, vcc
	v_add_co_u32_e32 v80, vcc, s17, v76
	global_load_dwordx4 v[2:5], v[72:73], off
	s_nop 0
	v_addc_co_u32_e32 v81, vcc, 0, v77, vcc
	v_add_co_u32_e32 v82, vcc, s18, v76
	global_load_dwordx4 v[6:9], v[70:71], off
	s_nop 0
	v_addc_co_u32_e32 v83, vcc, 0, v77, vcc
	v_add_co_u32_e32 v84, vcc, s19, v76
	global_load_dwordx4 v[10:13], v[74:75], off
	s_nop 0
	v_addc_co_u32_e32 v85, vcc, 0, v77, vcc
	global_load_dwordx4 v[14:17], v[78:79], off
	global_load_dwordx4 v[18:21], v[76:77], off
	global_load_dwordx4 v[22:25], v[80:81], off
	global_load_dwordx4 v[26:29], v[82:83], off
	global_load_dwordx4 v[30:33], v[84:85], off
	s_barrier
	global_load_dwordx4 v[34:37], v[72:73], off offset:128
	global_load_dwordx4 v[38:41], v[70:71], off offset:128
	global_load_dwordx4 v[42:45], v[74:75], off offset:128
	global_load_dwordx4 v[46:49], v[78:79], off offset:128
	global_load_dwordx4 v[50:53], v[76:77], off offset:128
	global_load_dwordx4 v[54:57], v[80:81], off offset:128
	global_load_dwordx4 v[58:61], v[82:83], off offset:128
	global_load_dwordx4 v[62:65], v[84:85], off offset:128
	v_and_b32_e32 v66, 31, v1
	v_lshrrev_b32_e32 v86, 1, v1
	v_mul_lo_u32 v68, v68, s16
	v_and_or_b32 v87, v86, s20, v66
	v_and_b32_e32 v86, 16, v86
	v_and_b32_e32 v1, 0x5f, v1
	v_add_lshl_u32 v66, v68, v69, 1
	v_mad_u64_u32 v[68:69], s[26:27], v87, s21, v[86:87]
	v_mad_u32_u24 v1, v1, s21, v86
	v_add_u32_e32 v69, 0x9000, v66
	s_waitcnt vmcnt(15)
	ds_write_b128 v66, v[2:5]
	s_waitcnt vmcnt(14)
	ds_write_b128 v66, v[6:9] offset:4608
	s_waitcnt vmcnt(13)
	ds_write_b128 v66, v[10:13] offset:9216
	s_waitcnt vmcnt(12)
	ds_write_b128 v66, v[14:17] offset:13824
	s_waitcnt vmcnt(11)
	ds_write_b128 v66, v[18:21] offset:36864
	s_waitcnt vmcnt(10)
	ds_write_b128 v66, v[22:25] offset:41472
	s_waitcnt vmcnt(9)
	ds_write_b128 v66, v[26:29] offset:46080
	s_waitcnt vmcnt(8)
	ds_write_b128 v66, v[30:33] offset:50688
	s_waitcnt lgkmcnt(0)
	s_barrier
	ds_read_b128 v[2:5], v68
	ds_read_b128 v[18:21], v68 offset:4608
	ds_read_b128 v[6:9], v1 offset:36864
	ds_read_b128 v[22:25], v1 offset:41472
	s_waitcnt vmcnt(7)
	ds_write_b128 v66, v[34:37] offset:18432
	s_waitcnt vmcnt(6)
	ds_write_b128 v66, v[38:41] offset:23040
	s_waitcnt vmcnt(5)
	ds_write_b128 v66, v[42:45] offset:27648
	s_waitcnt vmcnt(4)
	ds_write_b128 v66, v[46:49] offset:32256
	s_waitcnt vmcnt(3)
	ds_write_b128 v66, v[50:53] offset:55296
	s_waitcnt vmcnt(2)
	ds_write_b128 v66, v[54:57] offset:59904
	s_waitcnt vmcnt(1)
	ds_write_b128 v66, v[58:61] offset:64512
	s_waitcnt vmcnt(0)
	ds_write_b128 v69, v[62:65] offset:32256
	s_setprio 1
	ds_read_b128 v[86:89], v68 offset:32
	s_waitcnt lgkmcnt(10)
	v_mfma_f32_32x32x16_bf16 v[34:49], v[2:5], v[6:9], 0
	ds_read_b128 v[90:93], v1 offset:36896
	ds_read_b128 v[94:97], v1 offset:41504
	ds_read_b128 v[98:101], v68 offset:4704
	global_load_dwordx4 v[102:105], v[70:71], off offset:256
	global_load_dwordx4 v[106:109], v[74:75], off offset:256
	global_load_dwordx4 v[110:113], v[78:79], off offset:256
	global_load_dwordx4 v[114:117], v[84:85], off offset:256
	s_waitcnt lgkmcnt(12)
	v_mfma_f32_32x32x16_bf16 v[50:65], v[2:5], v[22:25], 0
	global_load_dwordx4 v[118:121], v[82:83], off offset:256
	global_load_dwordx4 v[122:125], v[80:81], off offset:256
	global_load_dwordx4 v[140:143], v[72:73], off offset:256
	global_load_dwordx4 v[144:147], v[76:77], off offset:256
	s_waitcnt lgkmcnt(2)
	v_mfma_f32_32x32x16_bf16 v[34:49], v[86:89], v[90:93], v[34:49]
	s_waitcnt lgkmcnt(1)
	v_mfma_f32_32x32x16_bf16 v[50:65], v[86:89], v[94:97], v[50:65]
	ds_read_b128 v[86:89], v68 offset:4640
	v_mfma_f32_32x32x16_bf16 v[2:17], v[18:21], v[6:9], 0
	v_mfma_f32_32x32x16_bf16 v[18:33], v[18:21], v[22:25], 0
	s_waitcnt lgkmcnt(0)
	v_mfma_f32_32x32x16_bf16 v[2:17], v[86:89], v[90:93], v[2:17]
	ds_read_b128 v[90:93], v1 offset:36928
	v_mfma_f32_32x32x16_bf16 v[18:33], v[86:89], v[94:97], v[18:33]
	ds_read_b128 v[86:89], v68 offset:64
	ds_read_b128 v[94:97], v1 offset:41536
	s_waitcnt lgkmcnt(1)
	v_mfma_f32_32x32x16_bf16 v[34:49], v[86:89], v[90:93], v[34:49]
	s_waitcnt lgkmcnt(0)
	v_mfma_f32_32x32x16_bf16 v[50:65], v[86:89], v[94:97], v[50:65]
	ds_read_b128 v[86:89], v68 offset:4672
	s_waitcnt lgkmcnt(0)
	v_mfma_f32_32x32x16_bf16 v[2:17], v[86:89], v[90:93], v[2:17]
	ds_read_b128 v[90:93], v1 offset:36960
	v_mfma_f32_32x32x16_bf16 v[18:33], v[86:89], v[94:97], v[18:33]
	ds_read_b128 v[86:89], v68 offset:96
	ds_read_b128 v[94:97], v1 offset:41568
	s_waitcnt lgkmcnt(1)
	v_mfma_f32_32x32x16_bf16 v[34:49], v[86:89], v[90:93], v[34:49]
	s_waitcnt lgkmcnt(0)
	v_mfma_f32_32x32x16_bf16 v[50:65], v[86:89], v[94:97], v[50:65]
	v_mfma_f32_32x32x16_bf16 v[2:17], v[98:101], v[90:93], v[2:17]
	v_mfma_f32_32x32x16_bf16 v[18:33], v[98:101], v[94:97], v[18:33]
	s_setprio 0
	s_barrier
; #define MFMA(a, b, c) __builtin_amdgcn_mfma_f32_32x32x16_bf16((a), (b), (c), 0, 0, 0)
; template <int TM, int TN>
; DI void gemm_mainloop(const u16* __restrict__ A, long lda, const u16* __restrict__ Bt, long ldb, int K, char* smem,
;                       f32x16 (&acc)[TM][TN]) {
;     ...
;   for (int kt = 0; kt < nk; kt++) {
;     const int buf = kt & 1;
;     const u16* cA = sA + buf * BM * LD + (wm * 32 * TM + r) * LD + h * 8;
;     const u16* cB = sB + buf * BN * LD + (wn * 32 * TN + r) * LD + h * 8;
;     bf16x8 af[TM], bfr[TN];
; #pragma unroll
;     for (int tm = 0; tm < TM; tm++) af[tm] = *(const bf16x8*)(cA + tm * 32 * LD);
; #pragma unroll
;     for (int tn = 0; tn < TN; tn++) bfr[tn] = *(const bf16x8*)(cB + tn * 32 * LD);
;     if (kt + 1 < nk) GEMM_SSTORE(buf ^ 1)
;     __builtin_amdgcn_sched_barrier(0);
;     __builtin_amdgcn_s_setprio(1);
; #pragma unroll
;     for (int tm = 0; tm < TM; tm++)
; #pragma unroll
;       for (int tn = 0; tn < TN; tn++) acc[tm][tn] = MFMA(af[tm], bfr[tn], acc[tm][tn]);
; #pragma unroll
;     for (int tm = 0; tm < TM; tm++) af[tm] = *(const bf16x8*)(cA + tm * 32 * LD + 16);
; #pragma unroll
;     for (int tn = 0; tn < TN; tn++) bfr[tn] = *(const bf16x8*)(cB + tn * 32 * LD + 16);
; #pragma unroll
;     for (int tm = 0; tm < TM; tm++)
; #pragma unroll
;       for (int tn = 0; tn < TN; tn++) acc[tm][tn] = MFMA(af[tm], bfr[tn], acc[tm][tn]);
;     __builtin_amdgcn_sched_group_barrier(0x8, 4, 0);
;     if (kt + 2 < nk) GEMM_GLOAD((kt + 2) * 64)
; #pragma unroll
;     for (int ks = 2; ks < 4; ks++) {
; #pragma unroll
;       for (int tm = 0; tm < TM; tm++) af[tm] = *(const bf16x8*)(cA + tm * 32 * LD + ks * 16);
; #pragma unroll
;       for (int tn = 0; tn < TN; tn++) bfr[tn] = *(const bf16x8*)(cB + tn * 32 * LD + ks * 16);
; #pragma unroll
;       for (int tm = 0; tm < TM; tm++)
; #pragma unroll
;         for (int tn = 0; tn < TN; tn++) acc[tm][tn] = MFMA(af[tm], bfr[tn], acc[tm][tn]);
;     }
	ds_read_b128 v[94:97], v68 offset:18432
	ds_read_b128 v[98:101], v68 offset:23040
	ds_read_b128 v[126:129], v1 offset:55296
	ds_read_b128 v[130:133], v1 offset:59904
	s_setprio 1
	ds_read_b128 v[86:89], v68 offset:18464
	s_waitcnt lgkmcnt(2)
	v_mfma_f32_32x32x16_bf16 v[34:49], v[94:97], v[126:129], v[34:49]
	s_waitcnt vmcnt(1)
	ds_write_b128 v66, v[140:143]
	ds_write_b128 v66, v[102:105] offset:4608
	global_load_dwordx4 v[140:143], v[72:73], off offset:384
	global_load_dwordx4 v[102:105], v[70:71], off offset:384
	ds_read_b128 v[90:93], v1 offset:55328
	s_waitcnt lgkmcnt(4)
	v_mfma_f32_32x32x16_bf16 v[50:65], v[94:97], v[130:133], v[50:65]
	ds_read_b128 v[94:97], v1 offset:59936
	s_waitcnt lgkmcnt(1)
	v_mfma_f32_32x32x16_bf16 v[34:49], v[86:89], v[90:93], v[34:49]
	s_waitcnt lgkmcnt(0)
	v_mfma_f32_32x32x16_bf16 v[50:65], v[86:89], v[94:97], v[50:65]
	ds_write_b128 v66, v[106:109] offset:9216
	ds_write_b128 v66, v[110:113] offset:13824
	global_load_dwordx4 v[106:109], v[74:75], off offset:384
	global_load_dwordx4 v[110:113], v[78:79], off offset:384
	ds_read_b128 v[86:89], v68 offset:23072
	v_mfma_f32_32x32x16_bf16 v[2:17], v[98:101], v[126:129], v[2:17]
	v_mfma_f32_32x32x16_bf16 v[18:33], v[98:101], v[130:133], v[18:33]
	ds_read_b128 v[98:101], v68 offset:23136
	s_waitcnt lgkmcnt(1)
	v_mfma_f32_32x32x16_bf16 v[2:17], v[86:89], v[90:93], v[2:17]
	s_waitcnt vmcnt(4)
	ds_write_b128 v66, v[144:147] offset:36864
	ds_write_b128 v66, v[122:125] offset:41472
	global_load_dwordx4 v[144:147], v[76:77], off offset:384
	global_load_dwordx4 v[122:125], v[80:81], off offset:384
	ds_read_b128 v[90:93], v1 offset:55360
	v_mfma_f32_32x32x16_bf16 v[18:33], v[86:89], v[94:97], v[18:33]
	ds_read_b128 v[86:89], v68 offset:18496
	ds_read_b128 v[94:97], v1 offset:59968
	s_waitcnt lgkmcnt(1)
	v_mfma_f32_32x32x16_bf16 v[34:49], v[86:89], v[90:93], v[34:49]
	s_waitcnt lgkmcnt(0)
	v_mfma_f32_32x32x16_bf16 v[50:65], v[86:89], v[94:97], v[50:65]
	ds_write_b128 v66, v[118:121] offset:46080
	ds_write_b128 v66, v[114:117] offset:50688
	global_load_dwordx4 v[118:121], v[82:83], off offset:384
	global_load_dwordx4 v[114:117], v[84:85], off offset:384
	ds_read_b128 v[86:89], v68 offset:23104
	s_waitcnt lgkmcnt(0)
	v_mfma_f32_32x32x16_bf16 v[2:17], v[86:89], v[90:93], v[2:17]
	ds_read_b128 v[90:93], v1 offset:55392
	v_mfma_f32_32x32x16_bf16 v[18:33], v[86:89], v[94:97], v[18:33]
	ds_read_b128 v[86:89], v68 offset:18528
	ds_read_b128 v[94:97], v1 offset:60000
	s_waitcnt lgkmcnt(1)
	v_mfma_f32_32x32x16_bf16 v[34:49], v[86:89], v[90:93], v[34:49]
	s_waitcnt lgkmcnt(0)
	v_mfma_f32_32x32x16_bf16 v[50:65], v[86:89], v[94:97], v[50:65]
	v_mfma_f32_32x32x16_bf16 v[2:17], v[98:101], v[90:93], v[2:17]
	v_mfma_f32_32x32x16_bf16 v[18:33], v[98:101], v[94:97], v[18:33]
	s_setprio 0
	s_barrier
	ds_read_b128 v[94:97], v68
	ds_read_b128 v[98:101], v68 offset:4608
	ds_read_b128 v[126:129], v1 offset:36864
	ds_read_b128 v[130:133], v1 offset:41472
	s_setprio 1
	ds_read_b128 v[86:89], v68 offset:32
	s_waitcnt lgkmcnt(2)
	v_mfma_f32_32x32x16_bf16 v[34:49], v[94:97], v[126:129], v[34:49]
	s_waitcnt vmcnt(7)
	ds_write_b128 v66, v[140:143] offset:18432
	s_waitcnt vmcnt(6)
	ds_write_b128 v66, v[102:105] offset:23040
	global_load_dwordx4 v[140:143], v[72:73], off offset:512
	global_load_dwordx4 v[102:105], v[70:71], off offset:512
	ds_read_b128 v[90:93], v1 offset:36896
	s_waitcnt lgkmcnt(4)
	v_mfma_f32_32x32x16_bf16 v[50:65], v[94:97], v[130:133], v[50:65]
	ds_read_b128 v[94:97], v1 offset:41504
	s_waitcnt lgkmcnt(1)
	v_mfma_f32_32x32x16_bf16 v[34:49], v[86:89], v[90:93], v[34:49]
	s_waitcnt lgkmcnt(0)
	v_mfma_f32_32x32x16_bf16 v[50:65], v[86:89], v[94:97], v[50:65]
	s_waitcnt vmcnt(7)
	ds_write_b128 v66, v[106:109] offset:27648
	s_waitcnt vmcnt(6)
	ds_write_b128 v66, v[110:113] offset:32256
	global_load_dwordx4 v[106:109], v[74:75], off offset:512
	global_load_dwordx4 v[110:113], v[78:79], off offset:512
	ds_read_b128 v[86:89], v68 offset:4640
	v_mfma_f32_32x32x16_bf16 v[2:17], v[98:101], v[126:129], v[2:17]
	v_mfma_f32_32x32x16_bf16 v[18:33], v[98:101], v[130:133], v[18:33]
	ds_read_b128 v[98:101], v68 offset:4704
	s_waitcnt lgkmcnt(1)
	v_mfma_f32_32x32x16_bf16 v[2:17], v[86:89], v[90:93], v[2:17]
	s_waitcnt vmcnt(7)
	ds_write_b128 v66, v[144:147] offset:55296
	s_waitcnt vmcnt(6)
	ds_write_b128 v66, v[122:125] offset:59904
	global_load_dwordx4 v[144:147], v[76:77], off offset:512
	global_load_dwordx4 v[122:125], v[80:81], off offset:512
	ds_read_b128 v[90:93], v1 offset:36928
	v_mfma_f32_32x32x16_bf16 v[18:33], v[86:89], v[94:97], v[18:33]
	ds_read_b128 v[86:89], v68 offset:64
	ds_read_b128 v[94:97], v1 offset:41536
	s_waitcnt lgkmcnt(1)
	v_mfma_f32_32x32x16_bf16 v[34:49], v[86:89], v[90:93], v[34:49]
	s_waitcnt lgkmcnt(0)
	v_mfma_f32_32x32x16_bf16 v[50:65], v[86:89], v[94:97], v[50:65]
	s_waitcnt vmcnt(7)
	ds_write_b128 v66, v[118:121] offset:64512
	s_waitcnt vmcnt(6)
	ds_write_b128 v69, v[114:117] offset:32256
	global_load_dwordx4 v[118:121], v[82:83], off offset:512
	global_load_dwordx4 v[114:117], v[84:85], off offset:512
	ds_read_b128 v[86:89], v68 offset:4672
	s_waitcnt lgkmcnt(0)
	v_mfma_f32_32x32x16_bf16 v[2:17], v[86:89], v[90:93], v[2:17]
	ds_read_b128 v[90:93], v1 offset:36960
	v_mfma_f32_32x32x16_bf16 v[18:33], v[86:89], v[94:97], v[18:33]
	ds_read_b128 v[86:89], v68 offset:96
	ds_read_b128 v[94:97], v1 offset:41568
	s_waitcnt lgkmcnt(1)
	v_mfma_f32_32x32x16_bf16 v[34:49], v[86:89], v[90:93], v[34:49]
	s_waitcnt lgkmcnt(0)
	v_mfma_f32_32x32x16_bf16 v[50:65], v[86:89], v[94:97], v[50:65]
	v_mfma_f32_32x32x16_bf16 v[2:17], v[98:101], v[90:93], v[2:17]
	v_mfma_f32_32x32x16_bf16 v[18:33], v[98:101], v[94:97], v[18:33]
	s_setprio 0
	s_barrier
; #define MFMA(a, b, c) __builtin_amdgcn_mfma_f32_32x32x16_bf16((a), (b), (c), 0, 0, 0)
; template <int TM, int TN>
; DI void gemm_mainloop(const u16* __restrict__ A, long lda, const u16* __restrict__ Bt, long ldb, int K, char* smem,
;                       f32x16 (&acc)[TM][TN]) {
;     ...
;   for (int kt = 0; kt < nk; kt++) {
;     const int buf = kt & 1;
;     const u16* cA = sA + buf * BM * LD + (wm * 32 * TM + r) * LD + h * 8;
;     const u16* cB = sB + buf * BN * LD + (wn * 32 * TN + r) * LD + h * 8;
;     bf16x8 af[TM], bfr[TN];
; #pragma unroll
;     for (int tm = 0; tm < TM; tm++) af[tm] = *(const bf16x8*)(cA + tm * 32 * LD);
; #pragma unroll
;     for (int tn = 0; tn < TN; tn++) bfr[tn] = *(const bf16x8*)(cB + tn * 32 * LD);
;     if (kt + 1 < nk) GEMM_SSTORE(buf ^ 1)
;     __builtin_amdgcn_sched_barrier(0);
;     __builtin_amdgcn_s_setprio(1);
; #pragma unroll
;     for (int tm = 0; tm < TM; tm++)
; #pragma unroll
;       for (int tn = 0; tn < TN; tn++) acc[tm][tn] = MFMA(af[tm], bfr[tn], acc[tm][tn]);
; #pragma unroll
;     for (int tm = 0; tm < TM; tm++) af[tm] = *(const bf16x8*)(cA + tm * 32 * LD + 16);
; #pragma unroll
;     for (int tn = 0; tn < TN; tn++) bfr[tn] = *(const bf16x8*)(cB + tn * 32 * LD + 16);
; #pragma unroll
;     for (int tm = 0; tm < TM; tm++)
; #pragma unroll
;       for (int tn = 0; tn < TN; tn++) acc[tm][tn] = MFMA(af[tm], bfr[tn], acc[tm][tn]);
;     __builtin_amdgcn_sched_group_barrier(0x8, 4, 0);
;     if (kt + 2 < nk) GEMM_GLOAD((kt + 2) * 64)
; #pragma unroll
;     for (int ks = 2; ks < 4; ks++) {
; #pragma unroll
;       for (int tm = 0; tm < TM; tm++) af[tm] = *(const bf16x8*)(cA + tm * 32 * LD + ks * 16);
; #pragma unroll
;       for (int tn = 0; tn < TN; tn++) bfr[tn] = *(const bf16x8*)(cB + tn * 32 * LD + ks * 16);
; #pragma unroll
;       for (int tm = 0; tm < TM; tm++)
; #pragma unroll
;         for (int tn = 0; tn < TN; tn++) acc[tm][tn] = MFMA(af[tm], bfr[tn], acc[tm][tn]);
;     }
	ds_read_b128 v[94:97], v68 offset:18432
	ds_read_b128 v[98:101], v68 offset:23040
	ds_read_b128 v[126:129], v1 offset:55296
	ds_read_b128 v[130:133], v1 offset:59904
	s_setprio 1
	ds_read_b128 v[86:89], v68 offset:18464
	s_waitcnt lgkmcnt(2)
	v_mfma_f32_32x32x16_bf16 v[34:49], v[94:97], v[126:129], v[34:49]
	s_waitcnt vmcnt(7)
	ds_write_b128 v66, v[140:143]
	s_waitcnt vmcnt(6)
	ds_write_b128 v66, v[102:105] offset:4608
	global_load_dwordx4 v[140:143], v[72:73], off offset:640
	global_load_dwordx4 v[102:105], v[70:71], off offset:640
	ds_read_b128 v[90:93], v1 offset:55328
	s_waitcnt lgkmcnt(4)
	v_mfma_f32_32x32x16_bf16 v[50:65], v[94:97], v[130:133], v[50:65]
	ds_read_b128 v[94:97], v1 offset:59936
	s_waitcnt lgkmcnt(1)
	v_mfma_f32_32x32x16_bf16 v[34:49], v[86:89], v[90:93], v[34:49]
	s_waitcnt lgkmcnt(0)
	v_mfma_f32_32x32x16_bf16 v[50:65], v[86:89], v[94:97], v[50:65]
	s_waitcnt vmcnt(7)
	ds_write_b128 v66, v[106:109] offset:9216
	s_waitcnt vmcnt(6)
	ds_write_b128 v66, v[110:113] offset:13824
	global_load_dwordx4 v[106:109], v[74:75], off offset:640
	global_load_dwordx4 v[110:113], v[78:79], off offset:640
	ds_read_b128 v[86:89], v68 offset:23072
	v_mfma_f32_32x32x16_bf16 v[2:17], v[98:101], v[126:129], v[2:17]
	v_mfma_f32_32x32x16_bf16 v[18:33], v[98:101], v[130:133], v[18:33]
	ds_read_b128 v[98:101], v68 offset:23136
	s_waitcnt lgkmcnt(1)
	v_mfma_f32_32x32x16_bf16 v[2:17], v[86:89], v[90:93], v[2:17]
	s_waitcnt vmcnt(7)
	ds_write_b128 v66, v[144:147] offset:36864
	s_waitcnt vmcnt(6)
	ds_write_b128 v66, v[122:125] offset:41472
	global_load_dwordx4 v[144:147], v[76:77], off offset:640
	global_load_dwordx4 v[122:125], v[80:81], off offset:640
	ds_read_b128 v[90:93], v1 offset:55360
	v_mfma_f32_32x32x16_bf16 v[18:33], v[86:89], v[94:97], v[18:33]
	ds_read_b128 v[86:89], v68 offset:18496
	ds_read_b128 v[94:97], v1 offset:59968
	s_waitcnt lgkmcnt(1)
	v_mfma_f32_32x32x16_bf16 v[34:49], v[86:89], v[90:93], v[34:49]
	s_waitcnt lgkmcnt(0)
	v_mfma_f32_32x32x16_bf16 v[50:65], v[86:89], v[94:97], v[50:65]
	s_waitcnt vmcnt(7)
	ds_write_b128 v66, v[118:121] offset:46080
	s_waitcnt vmcnt(6)
	ds_write_b128 v66, v[114:117] offset:50688
	global_load_dwordx4 v[118:121], v[82:83], off offset:640
	global_load_dwordx4 v[114:117], v[84:85], off offset:640
	ds_read_b128 v[86:89], v68 offset:23104
	s_waitcnt lgkmcnt(0)
	v_mfma_f32_32x32x16_bf16 v[2:17], v[86:89], v[90:93], v[2:17]
	ds_read_b128 v[90:93], v1 offset:55392
	v_mfma_f32_32x32x16_bf16 v[18:33], v[86:89], v[94:97], v[18:33]
	ds_read_b128 v[86:89], v68 offset:18528
	ds_read_b128 v[94:97], v1 offset:60000
	s_waitcnt lgkmcnt(1)
	v_mfma_f32_32x32x16_bf16 v[34:49], v[86:89], v[90:93], v[34:49]
	s_waitcnt lgkmcnt(0)
	v_mfma_f32_32x32x16_bf16 v[50:65], v[86:89], v[94:97], v[50:65]
	v_mfma_f32_32x32x16_bf16 v[2:17], v[98:101], v[90:93], v[2:17]
	v_mfma_f32_32x32x16_bf16 v[18:33], v[98:101], v[94:97], v[18:33]
	s_setprio 0
	s_barrier
	ds_read_b128 v[94:97], v68
	ds_read_b128 v[98:101], v68 offset:4608
	ds_read_b128 v[126:129], v1 offset:36864
	ds_read_b128 v[130:133], v1 offset:41472
	s_setprio 1
	ds_read_b128 v[86:89], v68 offset:32
	s_waitcnt lgkmcnt(2)
	v_mfma_f32_32x32x16_bf16 v[34:49], v[94:97], v[126:129], v[34:49]
	s_waitcnt vmcnt(7)
	ds_write_b128 v66, v[140:143] offset:18432
	s_waitcnt vmcnt(6)
	ds_write_b128 v66, v[102:105] offset:23040
	global_load_dwordx4 v[140:143], v[72:73], off offset:768
	global_load_dwordx4 v[102:105], v[70:71], off offset:768
	ds_read_b128 v[90:93], v1 offset:36896
	s_waitcnt lgkmcnt(4)
	v_mfma_f32_32x32x16_bf16 v[50:65], v[94:97], v[130:133], v[50:65]
	ds_read_b128 v[94:97], v1 offset:41504
	s_waitcnt lgkmcnt(1)
	v_mfma_f32_32x32x16_bf16 v[34:49], v[86:89], v[90:93], v[34:49]
	s_waitcnt lgkmcnt(0)
	v_mfma_f32_32x32x16_bf16 v[50:65], v[86:89], v[94:97], v[50:65]
	s_waitcnt vmcnt(7)
	ds_write_b128 v66, v[106:109] offset:27648
	s_waitcnt vmcnt(6)
	ds_write_b128 v66, v[110:113] offset:32256
	global_load_dwordx4 v[106:109], v[74:75], off offset:768
	global_load_dwordx4 v[110:113], v[78:79], off offset:768
	ds_read_b128 v[86:89], v68 offset:4640
	v_mfma_f32_32x32x16_bf16 v[2:17], v[98:101], v[126:129], v[2:17]
	v_mfma_f32_32x32x16_bf16 v[18:33], v[98:101], v[130:133], v[18:33]
	ds_read_b128 v[98:101], v68 offset:4704
	s_waitcnt lgkmcnt(1)
	v_mfma_f32_32x32x16_bf16 v[2:17], v[86:89], v[90:93], v[2:17]
	s_waitcnt vmcnt(7)
	ds_write_b128 v66, v[144:147] offset:55296
	s_waitcnt vmcnt(6)
	ds_write_b128 v66, v[122:125] offset:59904
	global_load_dwordx4 v[144:147], v[76:77], off offset:768
	global_load_dwordx4 v[122:125], v[80:81], off offset:768
	ds_read_b128 v[90:93], v1 offset:36928
	v_mfma_f32_32x32x16_bf16 v[18:33], v[86:89], v[94:97], v[18:33]
	ds_read_b128 v[86:89], v68 offset:64
	ds_read_b128 v[94:97], v1 offset:41536
	s_waitcnt lgkmcnt(1)
	v_mfma_f32_32x32x16_bf16 v[34:49], v[86:89], v[90:93], v[34:49]
	s_waitcnt lgkmcnt(0)
	v_mfma_f32_32x32x16_bf16 v[50:65], v[86:89], v[94:97], v[50:65]
	s_waitcnt vmcnt(7)
	ds_write_b128 v66, v[118:121] offset:64512
	s_waitcnt vmcnt(6)
	ds_write_b128 v69, v[114:117] offset:32256
	global_load_dwordx4 v[118:121], v[82:83], off offset:768
	global_load_dwordx4 v[114:117], v[84:85], off offset:768
	ds_read_b128 v[86:89], v68 offset:4672
	s_waitcnt lgkmcnt(0)
	v_mfma_f32_32x32x16_bf16 v[2:17], v[86:89], v[90:93], v[2:17]
	ds_read_b128 v[90:93], v1 offset:36960
	v_mfma_f32_32x32x16_bf16 v[18:33], v[86:89], v[94:97], v[18:33]
	ds_read_b128 v[86:89], v68 offset:96
	ds_read_b128 v[94:97], v1 offset:41568
	s_waitcnt lgkmcnt(1)
	v_mfma_f32_32x32x16_bf16 v[34:49], v[86:89], v[90:93], v[34:49]
	s_waitcnt lgkmcnt(0)
	v_mfma_f32_32x32x16_bf16 v[50:65], v[86:89], v[94:97], v[50:65]
	v_mfma_f32_32x32x16_bf16 v[2:17], v[98:101], v[90:93], v[2:17]
	v_mfma_f32_32x32x16_bf16 v[18:33], v[98:101], v[94:97], v[18:33]
	s_setprio 0
	s_barrier
; #define MFMA(a, b, c) __builtin_amdgcn_mfma_f32_32x32x16_bf16((a), (b), (c), 0, 0, 0)
; template <int TM, int TN>
; DI void gemm_mainloop(const u16* __restrict__ A, long lda, const u16* __restrict__ Bt, long ldb, int K, char* smem,
;                       f32x16 (&acc)[TM][TN]) {
;     ...
;   for (int kt = 0; kt < nk; kt++) {
;     const int buf = kt & 1;
;     const u16* cA = sA + buf * BM * LD + (wm * 32 * TM + r) * LD + h * 8;
;     const u16* cB = sB + buf * BN * LD + (wn * 32 * TN + r) * LD + h * 8;
;     bf16x8 af[TM], bfr[TN];
; #pragma unroll
;     for (int tm = 0; tm < TM; tm++) af[tm] = *(const bf16x8*)(cA + tm * 32 * LD);
; #pragma unroll
;     for (int tn = 0; tn < TN; tn++) bfr[tn] = *(const bf16x8*)(cB + tn * 32 * LD);
;     if (kt + 1 < nk) GEMM_SSTORE(buf ^ 1)
;     __builtin_amdgcn_sched_barrier(0);
;     __builtin_amdgcn_s_setprio(1);
; #pragma unroll
;     for (int tm = 0; tm < TM; tm++)
; #pragma unroll
;       for (int tn = 0; tn < TN; tn++) acc[tm][tn] = MFMA(af[tm], bfr[tn], acc[tm][tn]);
; #pragma unroll
;     for (int tm = 0; tm < TM; tm++) af[tm] = *(const bf16x8*)(cA + tm * 32 * LD + 16);
; #pragma unroll
;     for (int tn = 0; tn < TN; tn++) bfr[tn] = *(const bf16x8*)(cB + tn * 32 * LD + 16);
; #pragma unroll
;     for (int tm = 0; tm < TM; tm++)
; #pragma unroll
;       for (int tn = 0; tn < TN; tn++) acc[tm][tn] = MFMA(af[tm], bfr[tn], acc[tm][tn]);
;     __builtin_amdgcn_sched_group_barrier(0x8, 4, 0);
;     if (kt + 2 < nk) GEMM_GLOAD((kt + 2) * 64)
; #pragma unroll
;     for (int ks = 2; ks < 4; ks++) {
; #pragma unroll
;       for (int tm = 0; tm < TM; tm++) af[tm] = *(const bf16x8*)(cA + tm * 32 * LD + ks * 16);
; #pragma unroll
;       for (int tn = 0; tn < TN; tn++) bfr[tn] = *(const bf16x8*)(cB + tn * 32 * LD + ks * 16);
; #pragma unroll
;       for (int tm = 0; tm < TM; tm++)
; #pragma unroll
;         for (int tn = 0; tn < TN; tn++) acc[tm][tn] = MFMA(af[tm], bfr[tn], acc[tm][tn]);
;     }
	ds_read_b128 v[94:97], v68 offset:18432
	ds_read_b128 v[98:101], v68 offset:23040
	ds_read_b128 v[126:129], v1 offset:55296
	ds_read_b128 v[130:133], v1 offset:59904
	s_setprio 1
	ds_read_b128 v[86:89], v68 offset:18464
	s_waitcnt lgkmcnt(2)
	v_mfma_f32_32x32x16_bf16 v[34:49], v[94:97], v[126:129], v[34:49]
	s_waitcnt vmcnt(7)
	ds_write_b128 v66, v[140:143]
	s_waitcnt vmcnt(6)
	ds_write_b128 v66, v[102:105] offset:4608
	global_load_dwordx4 v[140:143], v[72:73], off offset:896
	global_load_dwordx4 v[102:105], v[70:71], off offset:896
	ds_read_b128 v[90:93], v1 offset:55328
	s_waitcnt lgkmcnt(4)
	v_mfma_f32_32x32x16_bf16 v[50:65], v[94:97], v[130:133], v[50:65]
	ds_read_b128 v[94:97], v1 offset:59936
	s_waitcnt lgkmcnt(1)
	v_mfma_f32_32x32x16_bf16 v[34:49], v[86:89], v[90:93], v[34:49]
	s_waitcnt lgkmcnt(0)
	v_mfma_f32_32x32x16_bf16 v[50:65], v[86:89], v[94:97], v[50:65]
	s_waitcnt vmcnt(7)
	ds_write_b128 v66, v[106:109] offset:9216
	s_waitcnt vmcnt(6)
	ds_write_b128 v66, v[110:113] offset:13824
	global_load_dwordx4 v[106:109], v[74:75], off offset:896
	global_load_dwordx4 v[110:113], v[78:79], off offset:896
	ds_read_b128 v[86:89], v68 offset:23072
	v_mfma_f32_32x32x16_bf16 v[2:17], v[98:101], v[126:129], v[2:17]
	v_mfma_f32_32x32x16_bf16 v[18:33], v[98:101], v[130:133], v[18:33]
	ds_read_b128 v[98:101], v68 offset:23136
	s_waitcnt lgkmcnt(1)
	v_mfma_f32_32x32x16_bf16 v[2:17], v[86:89], v[90:93], v[2:17]
	s_waitcnt vmcnt(7)
	ds_write_b128 v66, v[144:147] offset:36864
	s_waitcnt vmcnt(6)
	ds_write_b128 v66, v[122:125] offset:41472
	global_load_dwordx4 v[144:147], v[76:77], off offset:896
	global_load_dwordx4 v[122:125], v[80:81], off offset:896
	ds_read_b128 v[90:93], v1 offset:55360
	v_mfma_f32_32x32x16_bf16 v[18:33], v[86:89], v[94:97], v[18:33]
	ds_read_b128 v[86:89], v68 offset:18496
	ds_read_b128 v[94:97], v1 offset:59968
	s_waitcnt lgkmcnt(1)
	v_mfma_f32_32x32x16_bf16 v[34:49], v[86:89], v[90:93], v[34:49]
	s_waitcnt lgkmcnt(0)
	v_mfma_f32_32x32x16_bf16 v[50:65], v[86:89], v[94:97], v[50:65]
	s_waitcnt vmcnt(7)
	ds_write_b128 v66, v[118:121] offset:46080
	s_waitcnt vmcnt(6)
	ds_write_b128 v66, v[114:117] offset:50688
	global_load_dwordx4 v[118:121], v[82:83], off offset:896
	global_load_dwordx4 v[114:117], v[84:85], off offset:896
	ds_read_b128 v[86:89], v68 offset:23104
	s_waitcnt lgkmcnt(0)
	v_mfma_f32_32x32x16_bf16 v[2:17], v[86:89], v[90:93], v[2:17]
	ds_read_b128 v[90:93], v1 offset:55392
	v_mfma_f32_32x32x16_bf16 v[18:33], v[86:89], v[94:97], v[18:33]
	ds_read_b128 v[86:89], v68 offset:18528
	ds_read_b128 v[94:97], v1 offset:60000
	s_waitcnt lgkmcnt(1)
	v_mfma_f32_32x32x16_bf16 v[34:49], v[86:89], v[90:93], v[34:49]
	s_waitcnt lgkmcnt(0)
	v_mfma_f32_32x32x16_bf16 v[50:65], v[86:89], v[94:97], v[50:65]
	v_mfma_f32_32x32x16_bf16 v[2:17], v[98:101], v[90:93], v[2:17]
	v_mfma_f32_32x32x16_bf16 v[18:33], v[98:101], v[94:97], v[18:33]
	s_setprio 0
	s_barrier
	ds_read_b128 v[94:97], v68
	ds_read_b128 v[98:101], v68 offset:4608
	ds_read_b128 v[126:129], v1 offset:36864
	ds_read_b128 v[130:133], v1 offset:41472
	s_setprio 1
	ds_read_b128 v[86:89], v68 offset:32
	s_waitcnt lgkmcnt(2)
	v_mfma_f32_32x32x16_bf16 v[34:49], v[94:97], v[126:129], v[34:49]
	s_waitcnt vmcnt(7)
	ds_write_b128 v66, v[140:143] offset:18432
	s_waitcnt vmcnt(6)
	ds_write_b128 v66, v[102:105] offset:23040
	global_load_dwordx4 v[140:143], v[72:73], off offset:1024
	global_load_dwordx4 v[102:105], v[70:71], off offset:1024
	ds_read_b128 v[90:93], v1 offset:36896
	s_waitcnt lgkmcnt(4)
	v_mfma_f32_32x32x16_bf16 v[50:65], v[94:97], v[130:133], v[50:65]
	ds_read_b128 v[94:97], v1 offset:41504
	s_waitcnt lgkmcnt(1)
	v_mfma_f32_32x32x16_bf16 v[34:49], v[86:89], v[90:93], v[34:49]
	s_waitcnt lgkmcnt(0)
	v_mfma_f32_32x32x16_bf16 v[50:65], v[86:89], v[94:97], v[50:65]
	s_waitcnt vmcnt(7)
	ds_write_b128 v66, v[106:109] offset:27648
	s_waitcnt vmcnt(6)
	ds_write_b128 v66, v[110:113] offset:32256
	global_load_dwordx4 v[106:109], v[74:75], off offset:1024
	global_load_dwordx4 v[110:113], v[78:79], off offset:1024
	ds_read_b128 v[86:89], v68 offset:4640
	v_mfma_f32_32x32x16_bf16 v[2:17], v[98:101], v[126:129], v[2:17]
	v_mfma_f32_32x32x16_bf16 v[18:33], v[98:101], v[130:133], v[18:33]
	ds_read_b128 v[98:101], v68 offset:4704
	s_waitcnt lgkmcnt(1)
	v_mfma_f32_32x32x16_bf16 v[2:17], v[86:89], v[90:93], v[2:17]
	s_waitcnt vmcnt(7)
	ds_write_b128 v66, v[144:147] offset:55296
	s_waitcnt vmcnt(6)
	ds_write_b128 v66, v[122:125] offset:59904
	global_load_dwordx4 v[144:147], v[76:77], off offset:1024
	global_load_dwordx4 v[122:125], v[80:81], off offset:1024
	ds_read_b128 v[90:93], v1 offset:36928
	v_mfma_f32_32x32x16_bf16 v[18:33], v[86:89], v[94:97], v[18:33]
	ds_read_b128 v[86:89], v68 offset:64
	ds_read_b128 v[94:97], v1 offset:41536
	s_waitcnt lgkmcnt(1)
	v_mfma_f32_32x32x16_bf16 v[34:49], v[86:89], v[90:93], v[34:49]
	s_waitcnt lgkmcnt(0)
	v_mfma_f32_32x32x16_bf16 v[50:65], v[86:89], v[94:97], v[50:65]
	s_waitcnt vmcnt(7)
	ds_write_b128 v66, v[118:121] offset:64512
	s_waitcnt vmcnt(6)
	ds_write_b128 v69, v[114:117] offset:32256
	global_load_dwordx4 v[118:121], v[82:83], off offset:1024
	global_load_dwordx4 v[114:117], v[84:85], off offset:1024
	ds_read_b128 v[86:89], v68 offset:4672
	s_waitcnt lgkmcnt(0)
	v_mfma_f32_32x32x16_bf16 v[2:17], v[86:89], v[90:93], v[2:17]
	ds_read_b128 v[90:93], v1 offset:36960
	v_mfma_f32_32x32x16_bf16 v[18:33], v[86:89], v[94:97], v[18:33]
	ds_read_b128 v[86:89], v68 offset:96
	ds_read_b128 v[94:97], v1 offset:41568
	s_waitcnt lgkmcnt(1)
	v_mfma_f32_32x32x16_bf16 v[34:49], v[86:89], v[90:93], v[34:49]
	s_waitcnt lgkmcnt(0)
	v_mfma_f32_32x32x16_bf16 v[50:65], v[86:89], v[94:97], v[50:65]
	v_mfma_f32_32x32x16_bf16 v[2:17], v[98:101], v[90:93], v[2:17]
	v_mfma_f32_32x32x16_bf16 v[18:33], v[98:101], v[94:97], v[18:33]
	s_setprio 0
	s_barrier
; #define MFMA(a, b, c) __builtin_amdgcn_mfma_f32_32x32x16_bf16((a), (b), (c), 0, 0, 0)
; template <int TM, int TN>
; DI void gemm_mainloop(const u16* __restrict__ A, long lda, const u16* __restrict__ Bt, long ldb, int K, char* smem,
;                       f32x16 (&acc)[TM][TN]) {
;     ...
;   for (int kt = 0; kt < nk; kt++) {
;     const int buf = kt & 1;
;     const u16* cA = sA + buf * BM * LD + (wm * 32 * TM + r) * LD + h * 8;
;     const u16* cB = sB + buf * BN * LD + (wn * 32 * TN + r) * LD + h * 8;
;     bf16x8 af[TM], bfr[TN];
; #pragma unroll
;     for (int tm = 0; tm < TM; tm++) af[tm] = *(const bf16x8*)(cA + tm * 32 * LD);
; #pragma unroll
;     for (int tn = 0; tn < TN; tn++) bfr[tn] = *(const bf16x8*)(cB + tn * 32 * LD);
;     if (kt + 1 < nk) GEMM_SSTORE(buf ^ 1)
;     __builtin_amdgcn_sched_barrier(0);
;     __builtin_amdgcn_s_setprio(1);
; #pragma unroll
;     for (int tm = 0; tm < TM; tm++)
; #pragma unroll
;       for (int tn = 0; tn < TN; tn++) acc[tm][tn] = MFMA(af[tm], bfr[tn], acc[tm][tn]);
; #pragma unroll
;     for (int tm = 0; tm < TM; tm++) af[tm] = *(const bf16x8*)(cA + tm * 32 * LD + 16);
; #pragma unroll
;     for (int tn = 0; tn < TN; tn++) bfr[tn] = *(const bf16x8*)(cB + tn * 32 * LD + 16);
; #pragma unroll
;     for (int tm = 0; tm < TM; tm++)
; #pragma unroll
;       for (int tn = 0; tn < TN; tn++) acc[tm][tn] = MFMA(af[tm], bfr[tn], acc[tm][tn]);
;     __builtin_amdgcn_sched_group_barrier(0x8, 4, 0);
;     if (kt + 2 < nk) GEMM_GLOAD((kt + 2) * 64)
; #pragma unroll
;     for (int ks = 2; ks < 4; ks++) {
; #pragma unroll
;       for (int tm = 0; tm < TM; tm++) af[tm] = *(const bf16x8*)(cA + tm * 32 * LD + ks * 16);
; #pragma unroll
;       for (int tn = 0; tn < TN; tn++) bfr[tn] = *(const bf16x8*)(cB + tn * 32 * LD + ks * 16);
; #pragma unroll
;       for (int tm = 0; tm < TM; tm++)
; #pragma unroll
;         for (int tn = 0; tn < TN; tn++) acc[tm][tn] = MFMA(af[tm], bfr[tn], acc[tm][tn]);
;     }
	ds_read_b128 v[94:97], v68 offset:18432
	ds_read_b128 v[98:101], v68 offset:23040
	ds_read_b128 v[126:129], v1 offset:55296
	ds_read_b128 v[130:133], v1 offset:59904
	s_setprio 1
	ds_read_b128 v[86:89], v68 offset:18464
	s_waitcnt lgkmcnt(2)
	v_mfma_f32_32x32x16_bf16 v[34:49], v[94:97], v[126:129], v[34:49]
	s_waitcnt vmcnt(7)
	ds_write_b128 v66, v[140:143]
	s_waitcnt vmcnt(6)
	ds_write_b128 v66, v[102:105] offset:4608
	global_load_dwordx4 v[140:143], v[72:73], off offset:1152
	global_load_dwordx4 v[102:105], v[70:71], off offset:1152
	ds_read_b128 v[90:93], v1 offset:55328
	s_waitcnt lgkmcnt(4)
	v_mfma_f32_32x32x16_bf16 v[50:65], v[94:97], v[130:133], v[50:65]
	ds_read_b128 v[94:97], v1 offset:59936
	s_waitcnt lgkmcnt(1)
	v_mfma_f32_32x32x16_bf16 v[34:49], v[86:89], v[90:93], v[34:49]
	s_waitcnt lgkmcnt(0)
	v_mfma_f32_32x32x16_bf16 v[50:65], v[86:89], v[94:97], v[50:65]
	s_waitcnt vmcnt(7)
	ds_write_b128 v66, v[106:109] offset:9216
	s_waitcnt vmcnt(6)
	ds_write_b128 v66, v[110:113] offset:13824
	global_load_dwordx4 v[106:109], v[74:75], off offset:1152
	global_load_dwordx4 v[110:113], v[78:79], off offset:1152
	ds_read_b128 v[86:89], v68 offset:23072
	v_mfma_f32_32x32x16_bf16 v[2:17], v[98:101], v[126:129], v[2:17]
	v_mfma_f32_32x32x16_bf16 v[18:33], v[98:101], v[130:133], v[18:33]
	ds_read_b128 v[98:101], v68 offset:23136
	s_waitcnt lgkmcnt(1)
	v_mfma_f32_32x32x16_bf16 v[2:17], v[86:89], v[90:93], v[2:17]
	s_waitcnt vmcnt(7)
	ds_write_b128 v66, v[144:147] offset:36864
	s_waitcnt vmcnt(6)
	ds_write_b128 v66, v[122:125] offset:41472
	global_load_dwordx4 v[144:147], v[76:77], off offset:1152
	global_load_dwordx4 v[122:125], v[80:81], off offset:1152
	ds_read_b128 v[90:93], v1 offset:55360
	v_mfma_f32_32x32x16_bf16 v[18:33], v[86:89], v[94:97], v[18:33]
	ds_read_b128 v[86:89], v68 offset:18496
	ds_read_b128 v[94:97], v1 offset:59968
	s_waitcnt lgkmcnt(1)
	v_mfma_f32_32x32x16_bf16 v[34:49], v[86:89], v[90:93], v[34:49]
	s_waitcnt lgkmcnt(0)
	v_mfma_f32_32x32x16_bf16 v[50:65], v[86:89], v[94:97], v[50:65]
	s_waitcnt vmcnt(7)
	ds_write_b128 v66, v[118:121] offset:46080
	s_waitcnt vmcnt(6)
	ds_write_b128 v66, v[114:117] offset:50688
	global_load_dwordx4 v[118:121], v[82:83], off offset:1152
	global_load_dwordx4 v[114:117], v[84:85], off offset:1152
	ds_read_b128 v[86:89], v68 offset:23104
	s_waitcnt lgkmcnt(0)
	v_mfma_f32_32x32x16_bf16 v[2:17], v[86:89], v[90:93], v[2:17]
	ds_read_b128 v[90:93], v1 offset:55392
	v_mfma_f32_32x32x16_bf16 v[18:33], v[86:89], v[94:97], v[18:33]
	ds_read_b128 v[86:89], v68 offset:18528
	ds_read_b128 v[94:97], v1 offset:60000
	s_waitcnt lgkmcnt(1)
	v_mfma_f32_32x32x16_bf16 v[34:49], v[86:89], v[90:93], v[34:49]
	s_waitcnt lgkmcnt(0)
	v_mfma_f32_32x32x16_bf16 v[50:65], v[86:89], v[94:97], v[50:65]
	v_mfma_f32_32x32x16_bf16 v[2:17], v[98:101], v[90:93], v[2:17]
	v_mfma_f32_32x32x16_bf16 v[18:33], v[98:101], v[94:97], v[18:33]
	s_setprio 0
	s_barrier
	ds_read_b128 v[94:97], v68
	ds_read_b128 v[98:101], v68 offset:4608
	ds_read_b128 v[126:129], v1 offset:36864
	ds_read_b128 v[130:133], v1 offset:41472
	s_setprio 1
	ds_read_b128 v[86:89], v68 offset:32
	s_waitcnt lgkmcnt(2)
	v_mfma_f32_32x32x16_bf16 v[34:49], v[94:97], v[126:129], v[34:49]
	s_waitcnt vmcnt(7)
	ds_write_b128 v66, v[140:143] offset:18432
	s_waitcnt vmcnt(6)
	ds_write_b128 v66, v[102:105] offset:23040
	global_load_dwordx4 v[140:143], v[72:73], off offset:1280
	global_load_dwordx4 v[102:105], v[70:71], off offset:1280
	ds_read_b128 v[90:93], v1 offset:36896
	s_waitcnt lgkmcnt(4)
	v_mfma_f32_32x32x16_bf16 v[50:65], v[94:97], v[130:133], v[50:65]
	ds_read_b128 v[94:97], v1 offset:41504
	s_waitcnt lgkmcnt(1)
	v_mfma_f32_32x32x16_bf16 v[34:49], v[86:89], v[90:93], v[34:49]
	s_waitcnt lgkmcnt(0)
	v_mfma_f32_32x32x16_bf16 v[50:65], v[86:89], v[94:97], v[50:65]
	s_waitcnt vmcnt(7)
	ds_write_b128 v66, v[106:109] offset:27648
	s_waitcnt vmcnt(6)
	ds_write_b128 v66, v[110:113] offset:32256
	global_load_dwordx4 v[106:109], v[74:75], off offset:1280
	global_load_dwordx4 v[110:113], v[78:79], off offset:1280
	ds_read_b128 v[86:89], v68 offset:4640
	v_mfma_f32_32x32x16_bf16 v[2:17], v[98:101], v[126:129], v[2:17]
	v_mfma_f32_32x32x16_bf16 v[18:33], v[98:101], v[130:133], v[18:33]
	ds_read_b128 v[98:101], v68 offset:4704
	s_waitcnt lgkmcnt(1)
	v_mfma_f32_32x32x16_bf16 v[2:17], v[86:89], v[90:93], v[2:17]
	s_waitcnt vmcnt(7)
	ds_write_b128 v66, v[144:147] offset:55296
	s_waitcnt vmcnt(6)
	ds_write_b128 v66, v[122:125] offset:59904
	global_load_dwordx4 v[144:147], v[76:77], off offset:1280
	global_load_dwordx4 v[122:125], v[80:81], off offset:1280
	ds_read_b128 v[90:93], v1 offset:36928
	v_mfma_f32_32x32x16_bf16 v[18:33], v[86:89], v[94:97], v[18:33]
	ds_read_b128 v[86:89], v68 offset:64
	ds_read_b128 v[94:97], v1 offset:41536
	s_waitcnt lgkmcnt(1)
	v_mfma_f32_32x32x16_bf16 v[34:49], v[86:89], v[90:93], v[34:49]
	s_waitcnt lgkmcnt(0)
	v_mfma_f32_32x32x16_bf16 v[50:65], v[86:89], v[94:97], v[50:65]
	s_waitcnt vmcnt(7)
	ds_write_b128 v66, v[118:121] offset:64512
	s_waitcnt vmcnt(6)
	ds_write_b128 v69, v[114:117] offset:32256
	global_load_dwordx4 v[118:121], v[82:83], off offset:1280
	global_load_dwordx4 v[114:117], v[84:85], off offset:1280
	ds_read_b128 v[86:89], v68 offset:4672
	s_waitcnt lgkmcnt(0)
	v_mfma_f32_32x32x16_bf16 v[2:17], v[86:89], v[90:93], v[2:17]
	ds_read_b128 v[90:93], v1 offset:36960
	v_mfma_f32_32x32x16_bf16 v[18:33], v[86:89], v[94:97], v[18:33]
	ds_read_b128 v[86:89], v68 offset:96
	ds_read_b128 v[94:97], v1 offset:41568
	s_waitcnt lgkmcnt(1)
	v_mfma_f32_32x32x16_bf16 v[34:49], v[86:89], v[90:93], v[34:49]
	s_waitcnt lgkmcnt(0)
	v_mfma_f32_32x32x16_bf16 v[50:65], v[86:89], v[94:97], v[50:65]
	v_mfma_f32_32x32x16_bf16 v[2:17], v[98:101], v[90:93], v[2:17]
	v_mfma_f32_32x32x16_bf16 v[18:33], v[98:101], v[94:97], v[18:33]
	s_setprio 0
	s_barrier
; #define MFMA(a, b, c) __builtin_amdgcn_mfma_f32_32x32x16_bf16((a), (b), (c), 0, 0, 0)
; template <int TM, int TN>
; DI void gemm_mainloop(const u16* __restrict__ A, long lda, const u16* __restrict__ Bt, long ldb, int K, char* smem,
;                       f32x16 (&acc)[TM][TN]) {
;     ...
;   for (int kt = 0; kt < nk; kt++) {
;     const int buf = kt & 1;
;     const u16* cA = sA + buf * BM * LD + (wm * 32 * TM + r) * LD + h * 8;
;     const u16* cB = sB + buf * BN * LD + (wn * 32 * TN + r) * LD + h * 8;
;     bf16x8 af[TM], bfr[TN];
; #pragma unroll
;     for (int tm = 0; tm < TM; tm++) af[tm] = *(const bf16x8*)(cA + tm * 32 * LD);
; #pragma unroll
;     for (int tn = 0; tn < TN; tn++) bfr[tn] = *(const bf16x8*)(cB + tn * 32 * LD);
;     if (kt + 1 < nk) GEMM_SSTORE(buf ^ 1)
;     __builtin_amdgcn_sched_barrier(0);
;     __builtin_amdgcn_s_setprio(1);
; #pragma unroll
;     for (int tm = 0; tm < TM; tm++)
; #pragma unroll
;       for (int tn = 0; tn < TN; tn++) acc[tm][tn] = MFMA(af[tm], bfr[tn], acc[tm][tn]);
; #pragma unroll
;     for (int tm = 0; tm < TM; tm++) af[tm] = *(const bf16x8*)(cA + tm * 32 * LD + 16);
; #pragma unroll
;     for (int tn = 0; tn < TN; tn++) bfr[tn] = *(const bf16x8*)(cB + tn * 32 * LD + 16);
; #pragma unroll
;     for (int tm = 0; tm < TM; tm++)
; #pragma unroll
;       for (int tn = 0; tn < TN; tn++) acc[tm][tn] = MFMA(af[tm], bfr[tn], acc[tm][tn]);
;     __builtin_amdgcn_sched_group_barrier(0x8, 4, 0);
;     if (kt + 2 < nk) GEMM_GLOAD((kt + 2) * 64)
; #pragma unroll
;     for (int ks = 2; ks < 4; ks++) {
; #pragma unroll
;       for (int tm = 0; tm < TM; tm++) af[tm] = *(const bf16x8*)(cA + tm * 32 * LD + ks * 16);
; #pragma unroll
;       for (int tn = 0; tn < TN; tn++) bfr[tn] = *(const bf16x8*)(cB + tn * 32 * LD + ks * 16);
; #pragma unroll
;       for (int tm = 0; tm < TM; tm++)
; #pragma unroll
;         for (int tn = 0; tn < TN; tn++) acc[tm][tn] = MFMA(af[tm], bfr[tn], acc[tm][tn]);
;     }
	ds_read_b128 v[94:97], v68 offset:18432
	ds_read_b128 v[98:101], v68 offset:23040
	ds_read_b128 v[126:129], v1 offset:55296
	ds_read_b128 v[130:133], v1 offset:59904
	s_setprio 1
	ds_read_b128 v[86:89], v68 offset:18464
	s_waitcnt lgkmcnt(2)
	v_mfma_f32_32x32x16_bf16 v[34:49], v[94:97], v[126:129], v[34:49]
	s_waitcnt vmcnt(7)
	ds_write_b128 v66, v[140:143]
	s_waitcnt vmcnt(6)
	ds_write_b128 v66, v[102:105] offset:4608
	global_load_dwordx4 v[140:143], v[72:73], off offset:1408
	global_load_dwordx4 v[102:105], v[70:71], off offset:1408
	ds_read_b128 v[90:93], v1 offset:55328
	s_waitcnt lgkmcnt(4)
	v_mfma_f32_32x32x16_bf16 v[50:65], v[94:97], v[130:133], v[50:65]
	ds_read_b128 v[94:97], v1 offset:59936
	s_waitcnt lgkmcnt(1)
	v_mfma_f32_32x32x16_bf16 v[34:49], v[86:89], v[90:93], v[34:49]
	s_waitcnt lgkmcnt(0)
	v_mfma_f32_32x32x16_bf16 v[50:65], v[86:89], v[94:97], v[50:65]
	s_waitcnt vmcnt(7)
	ds_write_b128 v66, v[106:109] offset:9216
	s_waitcnt vmcnt(6)
	ds_write_b128 v66, v[110:113] offset:13824
	global_load_dwordx4 v[106:109], v[74:75], off offset:1408
	global_load_dwordx4 v[110:113], v[78:79], off offset:1408
	ds_read_b128 v[86:89], v68 offset:23072
	v_mfma_f32_32x32x16_bf16 v[2:17], v[98:101], v[126:129], v[2:17]
	v_mfma_f32_32x32x16_bf16 v[18:33], v[98:101], v[130:133], v[18:33]
	ds_read_b128 v[98:101], v68 offset:23136
	s_waitcnt lgkmcnt(1)
	v_mfma_f32_32x32x16_bf16 v[2:17], v[86:89], v[90:93], v[2:17]
	s_waitcnt vmcnt(7)
	ds_write_b128 v66, v[144:147] offset:36864
	s_waitcnt vmcnt(6)
	ds_write_b128 v66, v[122:125] offset:41472
	global_load_dwordx4 v[144:147], v[76:77], off offset:1408
	global_load_dwordx4 v[122:125], v[80:81], off offset:1408
	ds_read_b128 v[90:93], v1 offset:55360
	v_mfma_f32_32x32x16_bf16 v[18:33], v[86:89], v[94:97], v[18:33]
	ds_read_b128 v[86:89], v68 offset:18496
	ds_read_b128 v[94:97], v1 offset:59968
	s_waitcnt lgkmcnt(1)
	v_mfma_f32_32x32x16_bf16 v[34:49], v[86:89], v[90:93], v[34:49]
	s_waitcnt lgkmcnt(0)
	v_mfma_f32_32x32x16_bf16 v[50:65], v[86:89], v[94:97], v[50:65]
	s_waitcnt vmcnt(7)
	ds_write_b128 v66, v[118:121] offset:46080
	s_waitcnt vmcnt(6)
	ds_write_b128 v66, v[114:117] offset:50688
	global_load_dwordx4 v[118:121], v[82:83], off offset:1408
	global_load_dwordx4 v[114:117], v[84:85], off offset:1408
	ds_read_b128 v[86:89], v68 offset:23104
	s_waitcnt lgkmcnt(0)
	v_mfma_f32_32x32x16_bf16 v[2:17], v[86:89], v[90:93], v[2:17]
	ds_read_b128 v[90:93], v1 offset:55392
	v_mfma_f32_32x32x16_bf16 v[18:33], v[86:89], v[94:97], v[18:33]
	ds_read_b128 v[86:89], v68 offset:18528
	ds_read_b128 v[94:97], v1 offset:60000
	s_waitcnt lgkmcnt(1)
	v_mfma_f32_32x32x16_bf16 v[34:49], v[86:89], v[90:93], v[34:49]
	s_waitcnt lgkmcnt(0)
	v_mfma_f32_32x32x16_bf16 v[50:65], v[86:89], v[94:97], v[50:65]
	v_mfma_f32_32x32x16_bf16 v[2:17], v[98:101], v[90:93], v[2:17]
	v_mfma_f32_32x32x16_bf16 v[18:33], v[98:101], v[94:97], v[18:33]
	s_setprio 0
	s_barrier
	ds_read_b128 v[94:97], v68
	ds_read_b128 v[98:101], v68 offset:4608
	ds_read_b128 v[126:129], v1 offset:36864
	ds_read_b128 v[130:133], v1 offset:41472
	s_setprio 1
	ds_read_b128 v[86:89], v68 offset:32
	s_waitcnt lgkmcnt(2)
	v_mfma_f32_32x32x16_bf16 v[34:49], v[94:97], v[126:129], v[34:49]
	s_waitcnt vmcnt(7)
	ds_write_b128 v66, v[140:143] offset:18432
	s_waitcnt vmcnt(6)
	ds_write_b128 v66, v[102:105] offset:23040
	global_load_dwordx4 v[140:143], v[72:73], off offset:1536
	global_load_dwordx4 v[102:105], v[70:71], off offset:1536
	ds_read_b128 v[90:93], v1 offset:36896
	s_waitcnt lgkmcnt(4)
	v_mfma_f32_32x32x16_bf16 v[50:65], v[94:97], v[130:133], v[50:65]
	ds_read_b128 v[94:97], v1 offset:41504
	s_waitcnt lgkmcnt(1)
	v_mfma_f32_32x32x16_bf16 v[34:49], v[86:89], v[90:93], v[34:49]
	s_waitcnt lgkmcnt(0)
	v_mfma_f32_32x32x16_bf16 v[50:65], v[86:89], v[94:97], v[50:65]
	s_waitcnt vmcnt(7)
	ds_write_b128 v66, v[106:109] offset:27648
	s_waitcnt vmcnt(6)
	ds_write_b128 v66, v[110:113] offset:32256
	global_load_dwordx4 v[106:109], v[74:75], off offset:1536
	global_load_dwordx4 v[110:113], v[78:79], off offset:1536
	ds_read_b128 v[86:89], v68 offset:4640
	v_mfma_f32_32x32x16_bf16 v[2:17], v[98:101], v[126:129], v[2:17]
	v_mfma_f32_32x32x16_bf16 v[18:33], v[98:101], v[130:133], v[18:33]
	ds_read_b128 v[98:101], v68 offset:4704
	s_waitcnt lgkmcnt(1)
	v_mfma_f32_32x32x16_bf16 v[2:17], v[86:89], v[90:93], v[2:17]
	s_waitcnt vmcnt(7)
	ds_write_b128 v66, v[144:147] offset:55296
	s_waitcnt vmcnt(6)
	ds_write_b128 v66, v[122:125] offset:59904
	global_load_dwordx4 v[144:147], v[76:77], off offset:1536
	global_load_dwordx4 v[122:125], v[80:81], off offset:1536
	ds_read_b128 v[90:93], v1 offset:36928
	v_mfma_f32_32x32x16_bf16 v[18:33], v[86:89], v[94:97], v[18:33]
	ds_read_b128 v[86:89], v68 offset:64
	ds_read_b128 v[94:97], v1 offset:41536
	s_waitcnt lgkmcnt(1)
	v_mfma_f32_32x32x16_bf16 v[34:49], v[86:89], v[90:93], v[34:49]
	s_waitcnt lgkmcnt(0)
	v_mfma_f32_32x32x16_bf16 v[50:65], v[86:89], v[94:97], v[50:65]
	s_waitcnt vmcnt(7)
	ds_write_b128 v66, v[118:121] offset:64512
	s_waitcnt vmcnt(6)
	ds_write_b128 v69, v[114:117] offset:32256
	global_load_dwordx4 v[118:121], v[82:83], off offset:1536
	global_load_dwordx4 v[114:117], v[84:85], off offset:1536
	ds_read_b128 v[86:89], v68 offset:4672
	s_waitcnt lgkmcnt(0)
	v_mfma_f32_32x32x16_bf16 v[2:17], v[86:89], v[90:93], v[2:17]
	ds_read_b128 v[90:93], v1 offset:36960
	v_mfma_f32_32x32x16_bf16 v[18:33], v[86:89], v[94:97], v[18:33]
	ds_read_b128 v[86:89], v68 offset:96
	ds_read_b128 v[94:97], v1 offset:41568
	s_waitcnt lgkmcnt(1)
	v_mfma_f32_32x32x16_bf16 v[34:49], v[86:89], v[90:93], v[34:49]
	s_waitcnt lgkmcnt(0)
	v_mfma_f32_32x32x16_bf16 v[50:65], v[86:89], v[94:97], v[50:65]
	v_mfma_f32_32x32x16_bf16 v[2:17], v[98:101], v[90:93], v[2:17]
	v_mfma_f32_32x32x16_bf16 v[18:33], v[98:101], v[94:97], v[18:33]
	s_setprio 0
	s_barrier
; #define MFMA(a, b, c) __builtin_amdgcn_mfma_f32_32x32x16_bf16((a), (b), (c), 0, 0, 0)
; template <int TM, int TN>
; DI void gemm_mainloop(const u16* __restrict__ A, long lda, const u16* __restrict__ Bt, long ldb, int K, char* smem,
;                       f32x16 (&acc)[TM][TN]) {
;     ...
;   for (int kt = 0; kt < nk; kt++) {
;     const int buf = kt & 1;
;     const u16* cA = sA + buf * BM * LD + (wm * 32 * TM + r) * LD + h * 8;
;     const u16* cB = sB + buf * BN * LD + (wn * 32 * TN + r) * LD + h * 8;
;     bf16x8 af[TM], bfr[TN];
; #pragma unroll
;     for (int tm = 0; tm < TM; tm++) af[tm] = *(const bf16x8*)(cA + tm * 32 * LD);
; #pragma unroll
;     for (int tn = 0; tn < TN; tn++) bfr[tn] = *(const bf16x8*)(cB + tn * 32 * LD);
;     if (kt + 1 < nk) GEMM_SSTORE(buf ^ 1)
;     __builtin_amdgcn_sched_barrier(0);
;     __builtin_amdgcn_s_setprio(1);
; #pragma unroll
;     for (int tm = 0; tm < TM; tm++)
; #pragma unroll
;       for (int tn = 0; tn < TN; tn++) acc[tm][tn] = MFMA(af[tm], bfr[tn], acc[tm][tn]);
; #pragma unroll
;     for (int tm = 0; tm < TM; tm++) af[tm] = *(const bf16x8*)(cA + tm * 32 * LD + 16);
; #pragma unroll
;     for (int tn = 0; tn < TN; tn++) bfr[tn] = *(const bf16x8*)(cB + tn * 32 * LD + 16);
; #pragma unroll
;     for (int tm = 0; tm < TM; tm++)
; #pragma unroll
;       for (int tn = 0; tn < TN; tn++) acc[tm][tn] = MFMA(af[tm], bfr[tn], acc[tm][tn]);
;     __builtin_amdgcn_sched_group_barrier(0x8, 4, 0);
;     if (kt + 2 < nk) GEMM_GLOAD((kt + 2) * 64)
; #pragma unroll
;     for (int ks = 2; ks < 4; ks++) {
; #pragma unroll
;       for (int tm = 0; tm < TM; tm++) af[tm] = *(const bf16x8*)(cA + tm * 32 * LD + ks * 16);
; #pragma unroll
;       for (int tn = 0; tn < TN; tn++) bfr[tn] = *(const bf16x8*)(cB + tn * 32 * LD + ks * 16);
; #pragma unroll
;       for (int tm = 0; tm < TM; tm++)
; #pragma unroll
;         for (int tn = 0; tn < TN; tn++) acc[tm][tn] = MFMA(af[tm], bfr[tn], acc[tm][tn]);
;     }
	ds_read_b128 v[94:97], v68 offset:18432
	ds_read_b128 v[98:101], v68 offset:23040
	ds_read_b128 v[126:129], v1 offset:55296
	ds_read_b128 v[130:133], v1 offset:59904
	s_setprio 1
	ds_read_b128 v[86:89], v68 offset:18464
	s_waitcnt lgkmcnt(2)
	v_mfma_f32_32x32x16_bf16 v[34:49], v[94:97], v[126:129], v[34:49]
	s_waitcnt vmcnt(7)
	ds_write_b128 v66, v[140:143]
	s_waitcnt vmcnt(6)
	ds_write_b128 v66, v[102:105] offset:4608
	global_load_dwordx4 v[140:143], v[72:73], off offset:1664
	global_load_dwordx4 v[102:105], v[70:71], off offset:1664
	ds_read_b128 v[90:93], v1 offset:55328
	s_waitcnt lgkmcnt(4)
	v_mfma_f32_32x32x16_bf16 v[50:65], v[94:97], v[130:133], v[50:65]
	ds_read_b128 v[94:97], v1 offset:59936
	s_waitcnt lgkmcnt(1)
	v_mfma_f32_32x32x16_bf16 v[34:49], v[86:89], v[90:93], v[34:49]
	s_waitcnt lgkmcnt(0)
	v_mfma_f32_32x32x16_bf16 v[50:65], v[86:89], v[94:97], v[50:65]
	s_waitcnt vmcnt(7)
	ds_write_b128 v66, v[106:109] offset:9216
	s_waitcnt vmcnt(6)
	ds_write_b128 v66, v[110:113] offset:13824
	global_load_dwordx4 v[106:109], v[74:75], off offset:1664
	global_load_dwordx4 v[110:113], v[78:79], off offset:1664
	ds_read_b128 v[86:89], v68 offset:23072
	v_mfma_f32_32x32x16_bf16 v[2:17], v[98:101], v[126:129], v[2:17]
	v_mfma_f32_32x32x16_bf16 v[18:33], v[98:101], v[130:133], v[18:33]
	ds_read_b128 v[98:101], v68 offset:23136
	s_waitcnt lgkmcnt(1)
	v_mfma_f32_32x32x16_bf16 v[2:17], v[86:89], v[90:93], v[2:17]
	s_waitcnt vmcnt(7)
	ds_write_b128 v66, v[144:147] offset:36864
	s_waitcnt vmcnt(6)
	ds_write_b128 v66, v[122:125] offset:41472
	global_load_dwordx4 v[144:147], v[76:77], off offset:1664
	global_load_dwordx4 v[122:125], v[80:81], off offset:1664
	ds_read_b128 v[90:93], v1 offset:55360
	v_mfma_f32_32x32x16_bf16 v[18:33], v[86:89], v[94:97], v[18:33]
	ds_read_b128 v[86:89], v68 offset:18496
	ds_read_b128 v[94:97], v1 offset:59968
	s_waitcnt lgkmcnt(1)
	v_mfma_f32_32x32x16_bf16 v[34:49], v[86:89], v[90:93], v[34:49]
	s_waitcnt lgkmcnt(0)
	v_mfma_f32_32x32x16_bf16 v[50:65], v[86:89], v[94:97], v[50:65]
	s_waitcnt vmcnt(7)
	ds_write_b128 v66, v[118:121] offset:46080
	s_waitcnt vmcnt(6)
	ds_write_b128 v66, v[114:117] offset:50688
	global_load_dwordx4 v[118:121], v[82:83], off offset:1664
	global_load_dwordx4 v[114:117], v[84:85], off offset:1664
	ds_read_b128 v[86:89], v68 offset:23104
	s_waitcnt lgkmcnt(0)
	v_mfma_f32_32x32x16_bf16 v[2:17], v[86:89], v[90:93], v[2:17]
	ds_read_b128 v[90:93], v1 offset:55392
	v_mfma_f32_32x32x16_bf16 v[18:33], v[86:89], v[94:97], v[18:33]
	ds_read_b128 v[86:89], v68 offset:18528
	ds_read_b128 v[94:97], v1 offset:60000
	s_waitcnt lgkmcnt(1)
	v_mfma_f32_32x32x16_bf16 v[34:49], v[86:89], v[90:93], v[34:49]
	s_waitcnt lgkmcnt(0)
	v_mfma_f32_32x32x16_bf16 v[50:65], v[86:89], v[94:97], v[50:65]
	v_mfma_f32_32x32x16_bf16 v[2:17], v[98:101], v[90:93], v[2:17]
	v_mfma_f32_32x32x16_bf16 v[18:33], v[98:101], v[94:97], v[18:33]
	s_setprio 0
	s_barrier
	ds_read_b128 v[94:97], v68
	ds_read_b128 v[98:101], v68 offset:4608
	ds_read_b128 v[126:129], v1 offset:36864
	ds_read_b128 v[130:133], v1 offset:41472
	s_setprio 1
	ds_read_b128 v[86:89], v68 offset:32
	s_waitcnt lgkmcnt(2)
	v_mfma_f32_32x32x16_bf16 v[34:49], v[94:97], v[126:129], v[34:49]
	s_waitcnt vmcnt(7)
	ds_write_b128 v66, v[140:143] offset:18432
	s_waitcnt vmcnt(6)
	ds_write_b128 v66, v[102:105] offset:23040
	global_load_dwordx4 v[140:143], v[72:73], off offset:1792
	global_load_dwordx4 v[102:105], v[70:71], off offset:1792
	ds_read_b128 v[90:93], v1 offset:36896
	s_waitcnt lgkmcnt(4)
	v_mfma_f32_32x32x16_bf16 v[50:65], v[94:97], v[130:133], v[50:65]
	ds_read_b128 v[94:97], v1 offset:41504
	s_waitcnt lgkmcnt(1)
	v_mfma_f32_32x32x16_bf16 v[34:49], v[86:89], v[90:93], v[34:49]
	s_waitcnt lgkmcnt(0)
	v_mfma_f32_32x32x16_bf16 v[50:65], v[86:89], v[94:97], v[50:65]
	s_waitcnt vmcnt(7)
	ds_write_b128 v66, v[106:109] offset:27648
	s_waitcnt vmcnt(6)
	ds_write_b128 v66, v[110:113] offset:32256
	global_load_dwordx4 v[106:109], v[74:75], off offset:1792
	global_load_dwordx4 v[110:113], v[78:79], off offset:1792
	ds_read_b128 v[86:89], v68 offset:4640
	v_mfma_f32_32x32x16_bf16 v[2:17], v[98:101], v[126:129], v[2:17]
	v_mfma_f32_32x32x16_bf16 v[18:33], v[98:101], v[130:133], v[18:33]
	ds_read_b128 v[98:101], v68 offset:4704
	s_waitcnt lgkmcnt(1)
	v_mfma_f32_32x32x16_bf16 v[2:17], v[86:89], v[90:93], v[2:17]
	s_waitcnt vmcnt(7)
	ds_write_b128 v66, v[144:147] offset:55296
	s_waitcnt vmcnt(6)
	ds_write_b128 v66, v[122:125] offset:59904
	global_load_dwordx4 v[144:147], v[76:77], off offset:1792
	global_load_dwordx4 v[122:125], v[80:81], off offset:1792
	ds_read_b128 v[90:93], v1 offset:36928
	v_mfma_f32_32x32x16_bf16 v[18:33], v[86:89], v[94:97], v[18:33]
	ds_read_b128 v[86:89], v68 offset:64
	ds_read_b128 v[94:97], v1 offset:41536
	s_waitcnt lgkmcnt(1)
	v_mfma_f32_32x32x16_bf16 v[34:49], v[86:89], v[90:93], v[34:49]
	s_waitcnt lgkmcnt(0)
	v_mfma_f32_32x32x16_bf16 v[50:65], v[86:89], v[94:97], v[50:65]
	s_waitcnt vmcnt(7)
	ds_write_b128 v66, v[118:121] offset:64512
	s_waitcnt vmcnt(6)
	ds_write_b128 v69, v[114:117] offset:32256
	global_load_dwordx4 v[118:121], v[82:83], off offset:1792
	global_load_dwordx4 v[114:117], v[84:85], off offset:1792
	ds_read_b128 v[86:89], v68 offset:4672
	s_waitcnt lgkmcnt(0)
	v_mfma_f32_32x32x16_bf16 v[2:17], v[86:89], v[90:93], v[2:17]
	ds_read_b128 v[90:93], v1 offset:36960
	v_mfma_f32_32x32x16_bf16 v[18:33], v[86:89], v[94:97], v[18:33]
	ds_read_b128 v[86:89], v68 offset:96
	ds_read_b128 v[94:97], v1 offset:41568
	s_waitcnt lgkmcnt(1)
	v_mfma_f32_32x32x16_bf16 v[34:49], v[86:89], v[90:93], v[34:49]
	s_waitcnt lgkmcnt(0)
	v_mfma_f32_32x32x16_bf16 v[50:65], v[86:89], v[94:97], v[50:65]
	v_mfma_f32_32x32x16_bf16 v[2:17], v[98:101], v[90:93], v[2:17]
	v_mfma_f32_32x32x16_bf16 v[18:33], v[98:101], v[94:97], v[18:33]
	s_setprio 0
	s_barrier
; #define MFMA(a, b, c) __builtin_amdgcn_mfma_f32_32x32x16_bf16((a), (b), (c), 0, 0, 0)
; template <int TM, int TN>
; DI void gemm_mainloop(const u16* __restrict__ A, long lda, const u16* __restrict__ Bt, long ldb, int K, char* smem,
;                       f32x16 (&acc)[TM][TN]) {
;     ...
;   for (int kt = 0; kt < nk; kt++) {
;     const int buf = kt & 1;
;     const u16* cA = sA + buf * BM * LD + (wm * 32 * TM + r) * LD + h * 8;
;     const u16* cB = sB + buf * BN * LD + (wn * 32 * TN + r) * LD + h * 8;
;     bf16x8 af[TM], bfr[TN];
; #pragma unroll
;     for (int tm = 0; tm < TM; tm++) af[tm] = *(const bf16x8*)(cA + tm * 32 * LD);
; #pragma unroll
;     for (int tn = 0; tn < TN; tn++) bfr[tn] = *(const bf16x8*)(cB + tn * 32 * LD);
;     if (kt + 1 < nk) GEMM_SSTORE(buf ^ 1)
;     __builtin_amdgcn_sched_barrier(0);
;     __builtin_amdgcn_s_setprio(1);
; #pragma unroll
;     for (int tm = 0; tm < TM; tm++)
; #pragma unroll
;       for (int tn = 0; tn < TN; tn++) acc[tm][tn] = MFMA(af[tm], bfr[tn], acc[tm][tn]);
; #pragma unroll
;     for (int tm = 0; tm < TM; tm++) af[tm] = *(const bf16x8*)(cA + tm * 32 * LD + 16);
; #pragma unroll
;     for (int tn = 0; tn < TN; tn++) bfr[tn] = *(const bf16x8*)(cB + tn * 32 * LD + 16);
; #pragma unroll
;     for (int tm = 0; tm < TM; tm++)
; #pragma unroll
;       for (int tn = 0; tn < TN; tn++) acc[tm][tn] = MFMA(af[tm], bfr[tn], acc[tm][tn]);
;     __builtin_amdgcn_sched_group_barrier(0x8, 4, 0);
;     if (kt + 2 < nk) GEMM_GLOAD((kt + 2) * 64)
; #pragma unroll
;     for (int ks = 2; ks < 4; ks++) {
; #pragma unroll
;       for (int tm = 0; tm < TM; tm++) af[tm] = *(const bf16x8*)(cA + tm * 32 * LD + ks * 16);
; #pragma unroll
;       for (int tn = 0; tn < TN; tn++) bfr[tn] = *(const bf16x8*)(cB + tn * 32 * LD + ks * 16);
; #pragma unroll
;       for (int tm = 0; tm < TM; tm++)
; #pragma unroll
;         for (int tn = 0; tn < TN; tn++) acc[tm][tn] = MFMA(af[tm], bfr[tn], acc[tm][tn]);
;     }
	ds_read_b128 v[94:97], v68 offset:18432
	ds_read_b128 v[98:101], v68 offset:23040
	ds_read_b128 v[126:129], v1 offset:55296
	ds_read_b128 v[130:133], v1 offset:59904
	s_setprio 1
	ds_read_b128 v[86:89], v68 offset:18464
	s_waitcnt lgkmcnt(2)
	v_mfma_f32_32x32x16_bf16 v[34:49], v[94:97], v[126:129], v[34:49]
	s_waitcnt vmcnt(7)
	ds_write_b128 v66, v[140:143]
	s_waitcnt vmcnt(6)
	ds_write_b128 v66, v[102:105] offset:4608
	global_load_dwordx4 v[140:143], v[72:73], off offset:1920
	global_load_dwordx4 v[102:105], v[70:71], off offset:1920
	ds_read_b128 v[90:93], v1 offset:55328
	s_waitcnt lgkmcnt(4)
	v_mfma_f32_32x32x16_bf16 v[50:65], v[94:97], v[130:133], v[50:65]
	ds_read_b128 v[94:97], v1 offset:59936
	s_waitcnt lgkmcnt(1)
	v_mfma_f32_32x32x16_bf16 v[34:49], v[86:89], v[90:93], v[34:49]
	s_waitcnt lgkmcnt(0)
	v_mfma_f32_32x32x16_bf16 v[50:65], v[86:89], v[94:97], v[50:65]
	s_waitcnt vmcnt(7)
	ds_write_b128 v66, v[106:109] offset:9216
	s_waitcnt vmcnt(6)
	ds_write_b128 v66, v[110:113] offset:13824
	global_load_dwordx4 v[106:109], v[74:75], off offset:1920
	global_load_dwordx4 v[110:113], v[78:79], off offset:1920
	ds_read_b128 v[86:89], v68 offset:23072
	v_mfma_f32_32x32x16_bf16 v[2:17], v[98:101], v[126:129], v[2:17]
	v_mfma_f32_32x32x16_bf16 v[18:33], v[98:101], v[130:133], v[18:33]
	ds_read_b128 v[98:101], v68 offset:23136
	s_waitcnt lgkmcnt(1)
	v_mfma_f32_32x32x16_bf16 v[2:17], v[86:89], v[90:93], v[2:17]
	s_waitcnt vmcnt(7)
	ds_write_b128 v66, v[144:147] offset:36864
	s_waitcnt vmcnt(6)
	ds_write_b128 v66, v[122:125] offset:41472
	global_load_dwordx4 v[144:147], v[76:77], off offset:1920
	global_load_dwordx4 v[122:125], v[80:81], off offset:1920
	ds_read_b128 v[90:93], v1 offset:55360
	v_mfma_f32_32x32x16_bf16 v[18:33], v[86:89], v[94:97], v[18:33]
	ds_read_b128 v[86:89], v68 offset:18496
	ds_read_b128 v[94:97], v1 offset:59968
	s_waitcnt lgkmcnt(1)
	v_mfma_f32_32x32x16_bf16 v[34:49], v[86:89], v[90:93], v[34:49]
	s_waitcnt lgkmcnt(0)
	v_mfma_f32_32x32x16_bf16 v[50:65], v[86:89], v[94:97], v[50:65]
	s_waitcnt vmcnt(7)
	ds_write_b128 v66, v[118:121] offset:46080
	s_waitcnt vmcnt(6)
	ds_write_b128 v66, v[114:117] offset:50688
	global_load_dwordx4 v[118:121], v[82:83], off offset:1920
	global_load_dwordx4 v[114:117], v[84:85], off offset:1920
	ds_read_b128 v[86:89], v68 offset:23104
	s_waitcnt lgkmcnt(0)
	v_mfma_f32_32x32x16_bf16 v[2:17], v[86:89], v[90:93], v[2:17]
	ds_read_b128 v[90:93], v1 offset:55392
	v_mfma_f32_32x32x16_bf16 v[18:33], v[86:89], v[94:97], v[18:33]
	ds_read_b128 v[86:89], v68 offset:18528
	ds_read_b128 v[94:97], v1 offset:60000
	s_waitcnt lgkmcnt(1)
	v_mfma_f32_32x32x16_bf16 v[34:49], v[86:89], v[90:93], v[34:49]
	s_waitcnt lgkmcnt(0)
	v_mfma_f32_32x32x16_bf16 v[50:65], v[86:89], v[94:97], v[50:65]
	s_nop 0
	v_mfma_f32_32x32x16_bf16 v[2:17], v[98:101], v[90:93], v[2:17]
	v_mfma_f32_32x32x16_bf16 v[18:33], v[98:101], v[94:97], v[18:33]
	s_setprio 0
	s_barrier
	ds_read_b128 v[74:77], v68
	ds_read_b128 v[78:81], v68 offset:4608
	ds_read_b128 v[82:85], v1 offset:36864
	ds_read_b128 v[90:93], v1 offset:41472
	s_setprio 1
	ds_read_b128 v[70:73], v68 offset:32
	s_waitcnt lgkmcnt(2)
	v_mfma_f32_32x32x16_bf16 v[34:49], v[74:77], v[82:85], v[34:49]
	s_waitcnt vmcnt(7)
	ds_write_b128 v66, v[140:143] offset:18432
	s_waitcnt vmcnt(6)
	ds_write_b128 v66, v[102:105] offset:23040
	s_waitcnt lgkmcnt(3)
	v_mfma_f32_32x32x16_bf16 v[50:65], v[74:77], v[90:93], v[50:65]
	ds_read_b128 v[74:77], v1 offset:36896
	v_mfma_f32_32x32x16_bf16 v[2:17], v[78:81], v[82:85], v[2:17]
	v_mfma_f32_32x32x16_bf16 v[18:33], v[78:81], v[90:93], v[18:33]
	s_waitcnt vmcnt(5)
	ds_write_b128 v66, v[106:109] offset:27648
	s_waitcnt vmcnt(4)
	ds_write_b128 v66, v[110:113] offset:32256
	ds_read_b128 v[78:81], v1 offset:41504
	s_waitcnt lgkmcnt(3)
	v_mfma_f32_32x32x16_bf16 v[34:49], v[70:73], v[74:77], v[34:49]
	s_waitcnt lgkmcnt(0)
	v_mfma_f32_32x32x16_bf16 v[50:65], v[70:73], v[78:81], v[50:65]
	ds_read_b128 v[70:73], v68 offset:4640
	s_waitcnt lgkmcnt(0)
	v_mfma_f32_32x32x16_bf16 v[2:17], v[70:73], v[74:77], v[2:17]
	s_waitcnt vmcnt(3)
	ds_write_b128 v66, v[144:147] offset:55296
	s_waitcnt vmcnt(2)
	ds_write_b128 v66, v[122:125] offset:59904
	ds_read_b128 v[74:77], v1 offset:36928
	v_mfma_f32_32x32x16_bf16 v[18:33], v[70:73], v[78:81], v[18:33]
	ds_read_b128 v[70:73], v68 offset:64
	ds_read_b128 v[78:81], v1 offset:41536
	s_waitcnt lgkmcnt(1)
	v_mfma_f32_32x32x16_bf16 v[34:49], v[70:73], v[74:77], v[34:49]
	s_waitcnt lgkmcnt(0)
	v_mfma_f32_32x32x16_bf16 v[50:65], v[70:73], v[78:81], v[50:65]
	s_waitcnt vmcnt(1)
	ds_write_b128 v66, v[118:121] offset:64512
	s_waitcnt vmcnt(0)
	ds_write_b128 v69, v[114:117] offset:32256
	ds_read_b128 v[70:73], v68 offset:4672
	s_waitcnt lgkmcnt(0)
	v_mfma_f32_32x32x16_bf16 v[2:17], v[70:73], v[74:77], v[2:17]
	ds_read_b128 v[74:77], v1 offset:36960
	v_mfma_f32_32x32x16_bf16 v[18:33], v[70:73], v[78:81], v[18:33]
	ds_read_b128 v[70:73], v68 offset:96
	ds_read_b128 v[78:81], v1 offset:41568
	s_waitcnt lgkmcnt(1)
	v_mfma_f32_32x32x16_bf16 v[34:49], v[70:73], v[74:77], v[34:49]
	s_waitcnt lgkmcnt(0)
	v_mfma_f32_32x32x16_bf16 v[50:65], v[70:73], v[78:81], v[50:65]
	ds_read_b128 v[70:73], v68 offset:4704
	s_waitcnt lgkmcnt(0)
	v_mfma_f32_32x32x16_bf16 v[2:17], v[70:73], v[74:77], v[2:17]
	v_mfma_f32_32x32x16_bf16 v[18:33], v[70:73], v[78:81], v[18:33]
	s_setprio 0
	s_barrier
; #define MFMA(a, b, c) __builtin_amdgcn_mfma_f32_32x32x16_bf16((a), (b), (c), 0, 0, 0)
; DI int crow(int i, int h) { return (i & 3) + 8 * (i >> 2) + 4 * h; }
; template <int TM, int TN>
; DI void gemm_mainloop(const u16* __restrict__ A, long lda, const u16* __restrict__ Bt, long ldb, int K, char* smem,
;                       f32x16 (&acc)[TM][TN]) {
;     ...
;     for (int tm = 0; tm < TM; tm++)
; #pragma unroll
;       for (int tn = 0; tn < TN; tn++) acc[tm][tn] = MFMA(af[tm], bfr[tn], acc[tm][tn]);
; #pragma unroll
;     for (int tm = 0; tm < TM; tm++) af[tm] = *(const bf16x8*)(cA + tm * 32 * LD + 16);
; #pragma unroll
;     for (int tn = 0; tn < TN; tn++) bfr[tn] = *(const bf16x8*)(cB + tn * 32 * LD + 16);
; #pragma unroll
;     for (int tm = 0; tm < TM; tm++)
; #pragma unroll
;       for (int tn = 0; tn < TN; tn++) acc[tm][tn] = MFMA(af[tm], bfr[tn], acc[tm][tn]);
;     __builtin_amdgcn_sched_group_barrier(0x8, 4, 0);
;     if (kt + 2 < nk) GEMM_GLOAD((kt + 2) * 64)
; #pragma unroll
;     for (int ks = 2; ks < 4; ks++) {
; #pragma unroll
;       for (int tm = 0; tm < TM; tm++) af[tm] = *(const bf16x8*)(cA + tm * 32 * LD + ks * 16);
; #pragma unroll
;       for (int tn = 0; tn < TN; tn++) bfr[tn] = *(const bf16x8*)(cB + tn * 32 * LD + ks * 16);
; #pragma unroll
;       for (int tm = 0; tm < TM; tm++)
; #pragma unroll
;         for (int tn = 0; tn < TN; tn++) acc[tm][tn] = MFMA(af[tm], bfr[tn], acc[tm][tn]);
;     }
;     __builtin_amdgcn_s_setprio(0);
;     __syncthreads();
;   }
; template <int TM, int TN, class Epi>
; DI void gemm_tile(const u16* A, long lda, const u16* Bt, long ldb, int K, int m0, int n0, char* smem, const Epi& epi) {
;     ...
; #pragma unroll
;   for (int tm = 0; tm < TM; tm++)
; #pragma unroll
;     for (int tn = 0; tn < TN; tn++)
; #pragma unroll
;       for (int i = 0; i < 16; i++)
;         Ct[(wm * 32 * TM + tm * 32 + crow(i, h)) * LDC + wn * 32 * TN + tn * 32 + r] = acc[tm][tn][i];
;   __syncthreads();
;   epi(Ct, LDC, m0, n0, tid, BM);
	ds_read_b128 v[70:73], v68 offset:18432
	ds_read_b128 v[74:77], v68 offset:23040
	ds_read_b128 v[78:81], v1 offset:55296
	ds_read_b128 v[82:85], v1 offset:59904
	s_setprio 1
	s_waitcnt lgkmcnt(1)
	v_mfma_f32_32x32x16_bf16 v[34:49], v[70:73], v[78:81], v[34:49]
	s_waitcnt lgkmcnt(0)
	v_mfma_f32_32x32x16_bf16 v[50:65], v[70:73], v[82:85], v[50:65]
	ds_read_b128 v[70:73], v68 offset:18464
	v_mfma_f32_32x32x16_bf16 v[2:17], v[74:77], v[78:81], v[2:17]
	ds_read_b128 v[78:81], v1 offset:59936
	v_mfma_f32_32x32x16_bf16 v[18:33], v[74:77], v[82:85], v[18:33]
	ds_read_b128 v[74:77], v1 offset:55328
	s_waitcnt lgkmcnt(0)
	v_mfma_f32_32x32x16_bf16 v[34:49], v[70:73], v[74:77], v[34:49]
	v_mfma_f32_32x32x16_bf16 v[50:65], v[70:73], v[78:81], v[50:65]
	ds_read_b128 v[70:73], v68 offset:23072
	s_waitcnt lgkmcnt(0)
	v_mfma_f32_32x32x16_bf16 v[2:17], v[70:73], v[74:77], v[2:17]
	ds_read_b128 v[74:77], v1 offset:55360
	v_mfma_f32_32x32x16_bf16 v[18:33], v[70:73], v[78:81], v[18:33]
	ds_read_b128 v[70:73], v68 offset:18496
	ds_read_b128 v[78:81], v1 offset:59968
	s_waitcnt lgkmcnt(1)
	v_mfma_f32_32x32x16_bf16 v[34:49], v[70:73], v[74:77], v[34:49]
	s_waitcnt lgkmcnt(0)
	v_mfma_f32_32x32x16_bf16 v[50:65], v[70:73], v[78:81], v[50:65]
	ds_read_b128 v[70:73], v68 offset:23104
	s_waitcnt lgkmcnt(0)
	v_mfma_f32_32x32x16_bf16 v[2:17], v[70:73], v[74:77], v[2:17]
	ds_read_b128 v[74:77], v1 offset:55392
	v_mfma_f32_32x32x16_bf16 v[18:33], v[70:73], v[78:81], v[18:33]
	ds_read_b128 v[70:73], v68 offset:18528
	ds_read_b128 v[78:81], v1 offset:60000
	s_waitcnt lgkmcnt(1)
	v_mfma_f32_32x32x16_bf16 v[34:49], v[70:73], v[74:77], v[34:49]
	s_waitcnt lgkmcnt(0)
	v_mfma_f32_32x32x16_bf16 v[50:65], v[70:73], v[78:81], v[50:65]
	ds_read_b128 v[68:71], v68 offset:23136
	s_waitcnt lgkmcnt(0)
	v_mfma_f32_32x32x16_bf16 v[2:17], v[68:71], v[74:77], v[2:17]
	v_mfma_f32_32x32x16_bf16 v[18:33], v[68:71], v[78:81], v[18:33]
	s_setprio 0
	v_mov_b32_e32 v1, v0
	s_barrier
	s_lshl_b64 s[6:7], s[6:7], 1
	v_lshrrev_b32_e32 v66, 1, v1
	v_and_b32_e32 v66, 0xfffffc0, v66
	v_lshrrev_b32_e32 v68, 3, v1
	v_and_or_b32 v66, v68, 4, v66
	v_and_b32_e32 v68, 0x5f, v1
	v_mul_lo_u32 v66, v66, s22
	v_lshl_add_u32 v66, v68, 2, v66
	ds_write2_b32 v66, v34, v50 offset1:32
	v_add_u32_e32 v34, 0x400, v66
	ds_write2_b32 v34, v36, v52 offset0:8 offset1:40
	ds_write2_b32 v34, v37, v53 offset0:140 offset1:172
	v_add_u32_e32 v34, 0x1000, v66
	ds_write2_b32 v34, v38, v54 offset0:32 offset1:64
	ds_write2_b32 v34, v39, v55 offset0:164 offset1:196
	v_add_u32_e32 v34, 0x1400, v66
	ds_write2_b32 v34, v40, v56 offset0:40 offset1:72
	ds_write2_b32 v34, v41, v57 offset0:172 offset1:204
	v_add_u32_e32 v34, 0x2000, v66
	ds_write2_b32 v34, v42, v58 offset0:64 offset1:96
	ds_write2_b32 v34, v43, v59 offset0:196 offset1:228
	v_add_u32_e32 v34, 0x2400, v66
	ds_write2_b32 v34, v44, v60 offset0:72 offset1:104
	ds_write2_b32 v34, v45, v61 offset0:204 offset1:236
	v_add_u32_e32 v34, 0x3000, v66
	ds_write2_b32 v34, v46, v62 offset0:96 offset1:128
	v_add_u32_e32 v34, 0x3200, v66
	ds_write2_b32 v34, v47, v63 offset0:100 offset1:132
	v_add_u32_e32 v34, 0x3400, v66
	ds_write2_b32 v34, v48, v64 offset0:104 offset1:136
	v_add_u32_e32 v34, 0x3600, v66
	ds_write2_b32 v34, v49, v65 offset0:108 offset1:140
	v_add_u32_e32 v34, 0x4000, v66
	ds_write2_b32 v34, v2, v18 offset0:128 offset1:160
	v_add_u32_e32 v2, 0x4400, v66
	ds_write2_b32 v2, v3, v19 offset0:4 offset1:36
	ds_write2_b32 v2, v4, v20 offset0:136 offset1:168
	v_add_u32_e32 v2, 0x4800, v66
	ds_write2_b32 v2, v5, v21 offset0:12 offset1:44
	v_add_u32_e32 v2, 0x5000, v66
	ds_write2_b32 v2, v6, v22 offset0:160 offset1:192
	v_add_u32_e32 v2, 0x5400, v66
	ds_write2_b32 v2, v7, v23 offset0:36 offset1:68
	ds_write2_b32 v2, v8, v24 offset0:168 offset1:200
	v_add_u32_e32 v2, 0x5800, v66
	ds_write2_b32 v2, v9, v25 offset0:44 offset1:76
	v_add_u32_e32 v2, 0x6000, v66
	ds_write2_b32 v2, v10, v26 offset0:192 offset1:224
	v_add_u32_e32 v2, 0x6400, v66
	ds_write2_b32 v2, v11, v27 offset0:68 offset1:100
	ds_write2_b32 v2, v12, v28 offset0:200 offset1:232
	v_add_u32_e32 v2, 0x6800, v66
	ds_write2_b32 v2, v13, v29 offset0:76 offset1:108
	v_add_u32_e32 v2, 0x7200, v66
	ds_write2_b32 v2, v14, v30 offset0:96 offset1:128
	v_add_u32_e32 v2, 0x7400, v66
	ds_write2_b32 v2, v15, v31 offset0:100 offset1:132
	v_add_u32_e32 v2, 0x7600, v66
	ds_write2_b32 v2, v16, v32 offset0:104 offset1:136
	v_add_u32_e32 v2, 0x7800, v66
	ds_write2_b32 v2, v17, v33 offset0:108 offset1:140
	v_lshlrev_b32_e32 v2, 3, v1
	v_and_b32_e32 v3, 0x78, v2
	s_add_u32 s6, s3, s6
	ds_write2_b32 v66, v35, v51 offset0:132 offset1:164
	s_addc_u32 s7, s10, s7
	v_lshlrev_b32_e32 v66, 1, v3
	v_lshlrev_b32_e32 v2, 2, v3
	v_lshl_add_u64 v[4:5], s[6:7], 0, v[66:67]
	s_mov_b32 s6, 0
	s_waitcnt lgkmcnt(0)
	s_barrier
